# all 16-byte global stores made write-through (sc0 sc1) so the grid barriers' L2 write-back finds less dirty data (cache policy only, same data), on top of v18
# baseline (speedup 1.0000x reference)
.LBB0_9:
	s_waitcnt vmcnt(30)
	ds_write2_b32 v39, v6, v7 offset1:65
	s_waitcnt vmcnt(28)
	ds_write2_b32 v39, v10, v11 offset0:130 offset1:195
	v_add_u32_e32 v6, 0x400, v39
	s_waitcnt vmcnt(26)
	ds_write2_b32 v6, v8, v9 offset0:4 offset1:69
	s_waitcnt vmcnt(24)
	ds_write2_b32 v6, v12, v13 offset0:134 offset1:199
	v_add_u32_e32 v6, 0x800, v39
	s_waitcnt vmcnt(22)
	ds_write2_b32 v6, v14, v15 offset0:8 offset1:73
	s_waitcnt vmcnt(20)
	ds_write2_b32 v6, v18, v19 offset0:138 offset1:203
	v_add_u32_e32 v6, 0xc00, v39
	s_waitcnt vmcnt(18)
	ds_write2_b32 v6, v16, v17 offset0:12 offset1:77
	s_waitcnt vmcnt(16)
	ds_write2_b32 v6, v20, v21 offset0:142 offset1:207
	v_add_u32_e32 v6, 0x1000, v39
	s_waitcnt vmcnt(14)
	ds_write2_b32 v6, v22, v23 offset0:16 offset1:81
	s_waitcnt vmcnt(12)
	ds_write2_b32 v6, v26, v27 offset0:146 offset1:211
	v_add_u32_e32 v6, 0x1400, v39
	s_waitcnt vmcnt(10)
	ds_write2_b32 v6, v24, v25 offset0:20 offset1:85
	s_waitcnt vmcnt(8)
	ds_write2_b32 v6, v28, v29 offset0:150 offset1:215
	v_add_u32_e32 v6, 0x1800, v39
	s_waitcnt vmcnt(6)
	ds_write2_b32 v6, v30, v31 offset0:24 offset1:89
	s_waitcnt vmcnt(4)
	ds_write2_b32 v6, v36, v37 offset0:154 offset1:219
	v_add_u32_e32 v6, 0x1c00, v39
	s_waitcnt vmcnt(2)
	ds_write2_b32 v6, v34, v35 offset0:28 offset1:93
	s_waitcnt vmcnt(0)
	ds_write2_b32 v6, v32, v33 offset0:158 offset1:223
	s_waitcnt lgkmcnt(0)
	v_add_u32_e32 v32, 0x400, v2
	ds_read2_b32 v[10:11], v2 offset1:16
	ds_read2_b32 v[12:13], v2 offset0:65 offset1:81
	ds_read2_b32 v[14:15], v2 offset0:130 offset1:146
	ds_read2_b32 v[16:17], v2 offset0:195 offset1:211
	ds_read2_b32 v[18:19], v32 offset0:4 offset1:20
	ds_read2_b32 v[20:21], v32 offset0:69 offset1:85
	ds_read2_b32 v[22:23], v32 offset0:134 offset1:150
	ds_read2_b32 v[24:25], v32 offset0:199 offset1:215
	v_add_u32_e32 v28, s19, v40
	v_ashrrev_i32_e32 v29, 31, v28
	v_lshl_add_u64 v[26:27], s[12:13], 1, v[4:5]
	v_lshlrev_b64 v[30:31], 11, v[28:29]
	s_waitcnt lgkmcnt(6)
	v_cvt_pk_bf16_f32 v6, v10, v12
	s_waitcnt lgkmcnt(4)
	v_cvt_pk_bf16_f32 v7, v14, v16
	s_waitcnt lgkmcnt(2)
	v_cvt_pk_bf16_f32 v8, v18, v20
	s_waitcnt lgkmcnt(0)
	v_cvt_pk_bf16_f32 v9, v22, v24
	v_lshl_add_u64 v[30:31], v[26:27], 0, v[30:31]
	v_add_u32_e32 v10, 16, v28
	global_store_dwordx4 v[30:31], v[6:9], off sc0 sc1
	s_add_i32 s18, s18, s89
	s_add_i32 s16, s16, s17
	v_cvt_pk_bf16_f32 v6, v11, v13
	v_ashrrev_i32_e32 v11, 31, v10
	v_cvt_pk_bf16_f32 v7, v15, v17
	v_cvt_pk_bf16_f32 v8, v19, v21
	v_cvt_pk_bf16_f32 v9, v23, v25
	v_lshlrev_b64 v[10:11], 11, v[10:11]
	ds_read2_b32 v[12:13], v2 offset0:32 offset1:48
	ds_read2_b32 v[14:15], v2 offset0:97 offset1:113
	ds_read2_b32 v[16:17], v2 offset0:162 offset1:178
	ds_read2_b32 v[18:19], v2 offset0:227 offset1:243
	ds_read2_b32 v[20:21], v32 offset0:36 offset1:52
	ds_read2_b32 v[22:23], v32 offset0:101 offset1:117
	ds_read2_b32 v[24:25], v32 offset0:166 offset1:182
	ds_read2_b32 v[30:31], v32 offset0:231 offset1:247
	v_lshl_add_u64 v[10:11], v[26:27], 0, v[10:11]
	global_store_dwordx4 v[10:11], v[6:9], off sc0 sc1
	v_add_u32_e32 v10, 32, v28
	v_ashrrev_i32_e32 v11, 31, v10
	v_lshlrev_b64 v[10:11], 11, v[10:11]
	s_waitcnt lgkmcnt(6)
	v_cvt_pk_bf16_f32 v6, v12, v14
	s_waitcnt lgkmcnt(4)
	v_cvt_pk_bf16_f32 v7, v16, v18
	s_waitcnt lgkmcnt(2)
	v_cvt_pk_bf16_f32 v8, v20, v22
	s_waitcnt lgkmcnt(0)
	v_cvt_pk_bf16_f32 v9, v24, v30
	v_lshl_add_u64 v[10:11], v[26:27], 0, v[10:11]
	global_store_dwordx4 v[10:11], v[6:9], off sc0 sc1
	v_add_u32_e32 v10, 48, v28
	v_ashrrev_i32_e32 v11, 31, v10
	v_lshlrev_b64 v[10:11], 11, v[10:11]
	v_cvt_pk_bf16_f32 v6, v13, v15
	v_cvt_pk_bf16_f32 v7, v17, v19
	v_cvt_pk_bf16_f32 v8, v21, v23
	v_cvt_pk_bf16_f32 v9, v25, v31
	v_lshl_add_u64 v[10:11], v[26:27], 0, v[10:11]
	global_store_dwordx4 v[10:11], v[6:9], off sc0 sc1
	s_waitcnt lgkmcnt(0)
	s_cmpk_lt_i32 s18, 0x600
	v_add_u32_e32 v41, s15, v41
	s_cbranch_scc0 .LBB0_12

.LBB0_14:
	s_ashr_i32 s8, s65, 31
	s_lshr_b32 s8, s8, 28
	s_add_i32 s8, s65, s8
	s_ashr_i32 s9, s8, 4
	s_lshl_b32 s8, s9, 5
	s_lshl_b32 s9, s9, 10
	s_sub_i32 s66, s63, s9
	s_or_b32 s10, s8, 1
	s_or_b32 s12, s8, 2
	s_or_b32 s14, s8, 3
	s_or_b32 s16, s8, 4
	s_or_b32 s18, s8, 5
	s_or_b32 s20, s8, 6
	s_or_b32 s24, s8, 8
	s_or_b32 s28, s8, 10
	s_or_b32 s30, s8, 11
	s_or_b32 s34, s8, 12
	s_or_b32 s36, s8, 13
	s_or_b32 s38, s8, 14
	v_add_u32_e32 v16, s66, v7
	s_ashr_i32 s9, s8, 31
	s_or_b32 s22, s8, 7
	s_or_b32 s26, s8, 9
	s_or_b32 s40, s8, 15
	s_or_b32 s42, s8, 16
	s_or_b32 s44, s8, 17
	s_or_b32 s46, s8, 18
	s_or_b32 s48, s8, 19
	s_or_b32 s50, s8, 20
	s_or_b32 s52, s8, 21
	s_or_b32 s54, s8, 22
	s_or_b32 s56, s8, 23
	s_or_b32 s58, s8, 24
	s_or_b32 s60, s8, 25
	s_or_b32 s68, s8, 26
	s_or_b32 s70, s8, 27
	s_or_b32 s72, s8, 28
	s_or_b32 s74, s8, 29
	s_or_b32 s76, s8, 30
	s_or_b32 s78, s8, 31
	s_ashr_i32 s11, s10, 31
	s_ashr_i32 s13, s12, 31
	s_ashr_i32 s15, s14, 31
	s_ashr_i32 s17, s16, 31
	s_ashr_i32 s19, s18, 31
	s_ashr_i32 s21, s20, 31
	s_ashr_i32 s25, s24, 31
	s_ashr_i32 s29, s28, 31
	s_ashr_i32 s31, s30, 31
	s_ashr_i32 s35, s34, 31
	s_ashr_i32 s37, s36, 31
	s_ashr_i32 s39, s38, 31
	v_ashrrev_i32_e32 v17, 31, v16
	s_lshl_b64 s[80:81], s[8:9], 12
	s_ashr_i32 s23, s22, 31
	s_ashr_i32 s27, s26, 31
	s_ashr_i32 s41, s40, 31
	s_ashr_i32 s43, s42, 31
	s_ashr_i32 s45, s44, 31
	s_ashr_i32 s47, s46, 31
	s_ashr_i32 s49, s48, 31
	s_ashr_i32 s51, s50, 31
	s_ashr_i32 s53, s52, 31
	s_ashr_i32 s55, s54, 31
	s_ashr_i32 s57, s56, 31
	s_ashr_i32 s59, s58, 31
	s_ashr_i32 s61, s60, 31
	s_ashr_i32 s69, s68, 31
	s_ashr_i32 s71, s70, 31
	s_ashr_i32 s73, s72, 31
	s_ashr_i32 s75, s74, 31
	s_ashr_i32 s77, s76, 31
	s_ashr_i32 s79, s78, 31
	s_lshl_b64 s[10:11], s[10:11], 12
	s_lshl_b64 s[12:13], s[12:13], 12
	s_lshl_b64 s[14:15], s[14:15], 12
	s_lshl_b64 s[16:17], s[16:17], 12
	s_lshl_b64 s[18:19], s[18:19], 12
	s_lshl_b64 s[20:21], s[20:21], 12
	s_lshl_b64 s[24:25], s[24:25], 12
	s_lshl_b64 s[28:29], s[28:29], 12
	s_lshl_b64 s[30:31], s[30:31], 12
	s_lshl_b64 s[34:35], s[34:35], 12
	s_lshl_b64 s[36:37], s[36:37], 12
	s_lshl_b64 s[38:39], s[38:39], 12
	s_waitcnt lgkmcnt(0)
	v_lshl_add_u64 v[16:17], v[16:17], 2, s[6:7]
	s_lshl_b64 s[22:23], s[22:23], 12
	s_lshl_b64 s[26:27], s[26:27], 12
	s_lshl_b64 s[40:41], s[40:41], 12
	s_lshl_b64 s[42:43], s[42:43], 12
	s_lshl_b64 s[44:45], s[44:45], 12
	s_lshl_b64 s[46:47], s[46:47], 12
	s_lshl_b64 s[48:49], s[48:49], 12
	s_lshl_b64 s[50:51], s[50:51], 12
	s_lshl_b64 s[52:53], s[52:53], 12
	s_lshl_b64 s[54:55], s[54:55], 12
	s_lshl_b64 s[56:57], s[56:57], 12
	s_lshl_b64 s[58:59], s[58:59], 12
	s_lshl_b64 s[60:61], s[60:61], 12
	s_lshl_b64 s[68:69], s[68:69], 12
	s_lshl_b64 s[70:71], s[70:71], 12
	s_lshl_b64 s[72:73], s[72:73], 12
	s_lshl_b64 s[74:75], s[74:75], 12
	s_lshl_b64 s[76:77], s[76:77], 12
	s_lshl_b64 s[78:79], s[78:79], 12
	v_lshl_add_u64 v[18:19], v[16:17], 0, s[80:81]
	v_lshl_add_u64 v[20:21], v[16:17], 0, s[10:11]
	v_lshl_add_u64 v[22:23], v[16:17], 0, s[12:13]
	v_lshl_add_u64 v[24:25], v[16:17], 0, s[14:15]
	v_lshl_add_u64 v[26:27], v[16:17], 0, s[16:17]
	v_lshl_add_u64 v[28:29], v[16:17], 0, s[18:19]
	v_lshl_add_u64 v[30:31], v[16:17], 0, s[20:21]
	v_lshl_add_u64 v[34:35], v[16:17], 0, s[24:25]
	v_lshl_add_u64 v[38:39], v[16:17], 0, s[28:29]
	v_lshl_add_u64 v[40:41], v[16:17], 0, s[30:31]
	v_lshl_add_u64 v[42:43], v[16:17], 0, s[34:35]
	v_lshl_add_u64 v[44:45], v[16:17], 0, s[36:37]
	v_lshl_add_u64 v[46:47], v[16:17], 0, s[38:39]
	v_lshl_add_u64 v[32:33], v[16:17], 0, s[22:23]
	v_lshl_add_u64 v[36:37], v[16:17], 0, s[26:27]
	v_lshl_add_u64 v[48:49], v[16:17], 0, s[40:41]
	v_lshl_add_u64 v[50:51], v[16:17], 0, s[42:43]
	v_lshl_add_u64 v[52:53], v[16:17], 0, s[44:45]
	v_lshl_add_u64 v[54:55], v[16:17], 0, s[46:47]
	v_lshl_add_u64 v[56:57], v[16:17], 0, s[48:49]
	v_lshl_add_u64 v[58:59], v[16:17], 0, s[50:51]
	v_lshl_add_u64 v[60:61], v[16:17], 0, s[52:53]
	v_lshl_add_u64 v[62:63], v[16:17], 0, s[54:55]
	v_lshl_add_u64 v[64:65], v[16:17], 0, s[56:57]
	v_lshl_add_u64 v[66:67], v[16:17], 0, s[58:59]
	v_lshl_add_u64 v[68:69], v[16:17], 0, s[60:61]
	global_load_dword v70, v[18:19], off
	global_load_dword v71, v[20:21], off
	v_lshl_add_u64 v[18:19], v[16:17], 0, s[68:69]
	global_load_dword v72, v[22:23], off
	global_load_dword v73, v[24:25], off
	v_lshl_add_u64 v[20:21], v[16:17], 0, s[70:71]
	global_load_dword v74, v[26:27], off
	s_nop 0
	global_load_dword v28, v[28:29], off
	v_lshl_add_u64 v[22:23], v[16:17], 0, s[72:73]
	global_load_dword v29, v[30:31], off
	s_nop 0
	global_load_dword v30, v[32:33], off
	v_lshl_add_u64 v[24:25], v[16:17], 0, s[74:75]
	global_load_dword v31, v[34:35], off
	global_load_dword v75, v[36:37], off
	v_lshl_add_u64 v[26:27], v[16:17], 0, s[76:77]
	v_lshl_add_u64 v[16:17], v[16:17], 0, s[78:79]
	global_load_dword v76, v[38:39], off
	global_load_dword v77, v[40:41], off
	global_load_dword v78, v[42:43], off
	global_load_dword v79, v[44:45], off
	global_load_dword v80, v[46:47], off
	global_load_dword v81, v[48:49], off
	global_load_dword v82, v[50:51], off
	global_load_dword v83, v[52:53], off
	global_load_dword v84, v[54:55], off
	global_load_dword v85, v[56:57], off
	global_load_dword v86, v[58:59], off
	global_load_dword v87, v[60:61], off
	global_load_dword v88, v[62:63], off
	global_load_dword v89, v[64:65], off
	global_load_dword v90, v[66:67], off
	global_load_dword v40, v[68:69], off
	global_load_dword v41, v[18:19], off
	global_load_dword v42, v[20:21], off
	global_load_dword v43, v[22:23], off
	global_load_dword v44, v[24:25], off
	global_load_dword v45, v[26:27], off
	global_load_dword v46, v[16:17], off
	v_add_u32_e32 v18, s66, v5
	v_ashrrev_i32_e32 v19, 31, v18
	v_add_u32_e32 v20, 16, v18
	v_add_u32_e32 v22, 32, v18
	v_add_u32_e32 v24, 48, v18
	v_lshl_add_u64 v[16:17], s[8:9], 1, v[2:3]
	v_lshlrev_b64 v[18:19], 11, v[18:19]
	v_ashrrev_i32_e32 v21, 31, v20
	v_ashrrev_i32_e32 v23, 31, v22
	v_ashrrev_i32_e32 v25, 31, v24
	s_waitcnt vmcnt(30)
	ds_write2_b32 v4, v70, v71 offset1:65
	s_waitcnt vmcnt(28)
	ds_write2_b32 v4, v72, v73 offset0:130 offset1:195
	s_waitcnt vmcnt(26)
	ds_write2_b32 v8, v74, v28 offset0:4 offset1:69
	s_waitcnt vmcnt(24)
	ds_write2_b32 v8, v29, v30 offset0:134 offset1:199
	s_waitcnt vmcnt(22)
	ds_write2_b32 v9, v31, v75 offset0:8 offset1:73
	s_waitcnt vmcnt(20)
	ds_write2_b32 v9, v76, v77 offset0:138 offset1:203
	s_waitcnt vmcnt(18)
	ds_write2_b32 v10, v78, v79 offset0:12 offset1:77
	s_waitcnt vmcnt(16)
	ds_write2_b32 v10, v80, v81 offset0:142 offset1:207
	s_waitcnt vmcnt(14)
	ds_write2_b32 v11, v82, v83 offset0:16 offset1:81
	s_waitcnt vmcnt(12)
	ds_write2_b32 v11, v84, v85 offset0:146 offset1:211
	s_waitcnt vmcnt(10)
	ds_write2_b32 v12, v86, v87 offset0:20 offset1:85
	s_waitcnt vmcnt(8)
	ds_write2_b32 v12, v88, v89 offset0:150 offset1:215
	s_waitcnt vmcnt(6)
	ds_write2_b32 v13, v90, v40 offset0:24 offset1:89
	s_waitcnt vmcnt(4)
	ds_write2_b32 v13, v41, v42 offset0:154 offset1:219
	s_waitcnt vmcnt(2)
	ds_write2_b32 v14, v43, v44 offset0:28 offset1:93
	s_waitcnt vmcnt(0)
	ds_write2_b32 v14, v45, v46 offset0:158 offset1:223
	v_lshl_add_u64 v[32:33], v[16:17], 0, v[18:19]
	v_lshlrev_b64 v[18:19], 11, v[20:21]
	v_lshlrev_b64 v[20:21], 11, v[22:23]
	v_lshlrev_b64 v[22:23], 11, v[24:25]
	s_waitcnt lgkmcnt(0)
	v_lshl_add_u64 v[36:37], v[16:17], 0, v[20:21]
	v_lshl_add_u64 v[38:39], v[16:17], 0, v[22:23]
	ds_read2_b32 v[20:21], v6 offset1:16
	ds_read2_b32 v[22:23], v6 offset0:65 offset1:81
	ds_read2_b32 v[24:25], v6 offset0:130 offset1:146
	ds_read2_b32 v[26:27], v6 offset0:195 offset1:211
	ds_read2_b32 v[28:29], v15 offset0:4 offset1:20
	ds_read2_b32 v[30:31], v15 offset0:69 offset1:85
	ds_read2_b32 v[40:41], v15 offset0:134 offset1:150
	ds_read2_b32 v[42:43], v15 offset0:199 offset1:215
	ds_read2_b32 v[44:45], v6 offset0:32 offset1:48
	ds_read2_b32 v[46:47], v6 offset0:97 offset1:113
	ds_read2_b32 v[48:49], v6 offset0:162 offset1:178
	ds_read2_b32 v[50:51], v6 offset0:227 offset1:243
	ds_read2_b32 v[52:53], v15 offset0:36 offset1:52
	ds_read2_b32 v[54:55], v15 offset0:101 offset1:117
	ds_read2_b32 v[56:57], v15 offset0:166 offset1:182
	ds_read2_b32 v[58:59], v15 offset0:231 offset1:247
	v_lshl_add_u64 v[34:35], v[16:17], 0, v[18:19]
	s_waitcnt lgkmcnt(14)
	v_cvt_pk_bf16_f32 v16, v20, v22
	s_waitcnt lgkmcnt(12)
	v_cvt_pk_bf16_f32 v17, v24, v26
	s_waitcnt lgkmcnt(10)
	v_cvt_pk_bf16_f32 v18, v28, v30
	s_waitcnt lgkmcnt(8)
	v_cvt_pk_bf16_f32 v19, v40, v42
	v_cvt_pk_bf16_f32 v20, v21, v23
	v_cvt_pk_bf16_f32 v21, v25, v27
	v_cvt_pk_bf16_f32 v22, v29, v31
	v_cvt_pk_bf16_f32 v23, v41, v43
	s_waitcnt lgkmcnt(6)
	v_cvt_pk_bf16_f32 v24, v44, v46
	s_waitcnt lgkmcnt(4)
	v_cvt_pk_bf16_f32 v25, v48, v50
	s_waitcnt lgkmcnt(2)
	v_cvt_pk_bf16_f32 v26, v52, v54
	s_waitcnt lgkmcnt(0)
	v_cvt_pk_bf16_f32 v27, v56, v58
	v_cvt_pk_bf16_f32 v28, v45, v47
	v_cvt_pk_bf16_f32 v29, v49, v51
	v_cvt_pk_bf16_f32 v30, v53, v55
	v_cvt_pk_bf16_f32 v31, v57, v59
	global_store_dwordx4 v[32:33], v[16:19], off sc0 sc1
	global_store_dwordx4 v[34:35], v[20:23], off sc0 sc1
	global_store_dwordx4 v[36:37], v[24:27], off sc0 sc1
	global_store_dwordx4 v[38:39], v[28:31], off sc0 sc1
	s_waitcnt lgkmcnt(0)
	s_add_i32 s65, s65, s89
	s_add_i32 s63, s63, s64
	s_cmpk_lt_i32 s65, 0x200
	s_cbranch_scc1 .LBB0_14

.LBB0_81:
	v_add_u32_e32 v130, s93, v162
	s_lshl_b32 s84, s4, 8
	s_lshl_b32 s82, s4, 2
	s_ashr_i32 s85, s84, 31
	s_ashr_i32 s83, s82, 31
	s_andn2_b64 vcc, exec, s[10:11]
	v_ashrrev_i32_e32 v131, 31, v130
	s_cbranch_vccnz .LBB0_88
	v_lshlrev_b64 v[132:133], 10, v[188:189]
	v_lshlrev_b64 v[134:135], 9, v[188:189]
	v_lshl_add_u64 v[132:133], s[20:21], 0, v[132:133]
	v_pk_mul_f32 v[136:137], v[124:125], v[190:191] op_sel_hi:[1,0]
	v_pk_mul_f32 v[124:125], v[122:123], v[190:191] op_sel_hi:[1,0]
	v_lshl_add_u64 v[122:123], s[52:53], 0, v[134:135]
	v_lshl_add_u64 v[132:133], s[84:85], 1, v[132:133]
	v_pk_mul_f32 v[126:127], v[126:127], v[190:191] op_sel_hi:[1,0]
	v_cndmask_b32_e64 v123, v133, v123, s[44:45]
	v_cndmask_b32_e64 v122, v132, v122, s[44:45]
	v_pk_mul_f32 v[128:129], v[128:129], v[190:191] op_sel_hi:[1,0]
	v_lshl_add_u64 v[132:133], v[130:131], 1, v[122:123]
	v_cvt_pk_bf16_f32 v122, v126, v127
	v_mul_f32_e32 v127, v127, v127
	v_fmac_f32_e32 v127, v126, v126
	v_mul_f32_e32 v126, v129, v129
	v_fmac_f32_e32 v126, v128, v128
	v_cvt_pk_bf16_f32 v123, v128, v129
	v_add_f32_e32 v126, v127, v126
	v_mul_f32_e32 v127, v125, v125
	v_mul_f32_e32 v128, v137, v137
	v_fmac_f32_e32 v127, v124, v124
	v_fmac_f32_e32 v128, v136, v136
	v_pk_mul_f32 v[120:121], v[120:121], v[190:191] op_sel_hi:[1,0]
	v_pk_mul_f32 v[118:119], v[118:119], v[190:191] op_sel_hi:[1,0]
	v_add_f32_e32 v127, v127, v128
	v_pk_mul_f32 v[128:129], v[114:115], v[190:191] op_sel_hi:[1,0]
	v_mul_f32_e32 v114, v119, v119
	v_mul_f32_e32 v115, v121, v121
	v_add_f32_e32 v134, v126, v127
	v_pk_mul_f32 v[126:127], v[116:117], v[190:191] op_sel_hi:[1,0]
	v_fmac_f32_e32 v114, v118, v118
	v_fmac_f32_e32 v115, v120, v120
	v_add_f32_e32 v114, v114, v115
	v_mul_f32_e32 v115, v129, v129
	v_mul_f32_e32 v116, v127, v127
	v_fmac_f32_e32 v115, v128, v128
	v_fmac_f32_e32 v116, v126, v126
	v_add_f32_e32 v115, v115, v116
	v_add_f32_e32 v114, v114, v115
	v_add_f32_e32 v114, v134, v114
	ds_bpermute_b32 v115, v232, v114
	v_cvt_pk_bf16_f32 v124, v124, v125
	v_cvt_pk_bf16_f32 v125, v136, v137
	v_cvt_pk_bf16_f32 v116, v118, v119
	v_cvt_pk_bf16_f32 v117, v120, v121
	s_waitcnt lgkmcnt(0)
	v_add_f32_e32 v114, v114, v115
	ds_bpermute_b32 v115, v231, v114
	v_cvt_pk_bf16_f32 v118, v128, v129
	v_cvt_pk_bf16_f32 v119, v126, v127
	global_store_dwordx4 v[132:133], v[122:125], off sc0 sc1
	global_store_dwordx4 v[132:133], v[116:119], off offset:256 sc0 sc1
	s_and_saveexec_b64 s[10:11], s[42:43]
	s_cbranch_execz .LBB0_87
	s_waitcnt lgkmcnt(0)
	v_add_f32_e32 v114, v114, v115
	s_andn2_b64 vcc, exec, s[80:81]
	s_mov_b64 s[12:13], -1
	s_cbranch_vccnz .LBB0_85
	v_readlane_b32 s4, v251, 57
	v_lshlrev_b64 v[116:117], 5, v[188:189]
	v_readlane_b32 s5, v251, 58
	s_lshl_b32 s76, s90, 2
	s_mov_b64 s[12:13], 0
	v_lshl_add_u64 v[116:117], s[4:5], 0, v[116:117]
	v_lshl_add_u64 v[116:117], s[82:83], 2, v[116:117]
	v_lshl_add_u64 v[116:117], v[116:117], 0, s[76:77]
	global_store_dword v[116:117], v114, off

.LBB0_92:
	s_andn2_b64 vcc, exec, s[0:1]
	s_cbranch_vccnz .LBB0_99
	v_lshlrev_b64 v[114:115], 10, v[184:185]
	v_lshlrev_b64 v[116:117], 9, v[184:185]
	v_lshl_add_u64 v[114:115], s[20:21], 0, v[114:115]
	v_pk_mul_f32 v[118:119], v[108:109], v[132:133] op_sel_hi:[1,0]
	v_pk_mul_f32 v[108:109], v[106:107], v[132:133] op_sel_hi:[1,0]
	v_lshl_add_u64 v[106:107], s[52:53], 0, v[116:117]
	v_lshl_add_u64 v[114:115], s[84:85], 1, v[114:115]
	v_pk_mul_f32 v[110:111], v[110:111], v[132:133] op_sel_hi:[1,0]
	v_cndmask_b32_e64 v107, v115, v107, s[44:45]
	v_cndmask_b32_e64 v106, v114, v106, s[44:45]
	v_pk_mul_f32 v[112:113], v[112:113], v[132:133] op_sel_hi:[1,0]
	v_lshl_add_u64 v[114:115], v[130:131], 1, v[106:107]
	v_cvt_pk_bf16_f32 v106, v110, v111
	v_mul_f32_e32 v111, v111, v111
	v_fmac_f32_e32 v111, v110, v110
	v_mul_f32_e32 v110, v113, v113
	v_fmac_f32_e32 v110, v112, v112
	v_cvt_pk_bf16_f32 v107, v112, v113
	v_add_f32_e32 v110, v111, v110
	v_mul_f32_e32 v111, v109, v109
	v_mul_f32_e32 v112, v119, v119
	v_fmac_f32_e32 v111, v108, v108
	v_fmac_f32_e32 v112, v118, v118
	v_pk_mul_f32 v[104:105], v[104:105], v[132:133] op_sel_hi:[1,0]
	v_pk_mul_f32 v[102:103], v[102:103], v[132:133] op_sel_hi:[1,0]
	v_add_f32_e32 v111, v111, v112
	v_pk_mul_f32 v[112:113], v[98:99], v[132:133] op_sel_hi:[1,0]
	v_mul_f32_e32 v98, v103, v103
	v_mul_f32_e32 v99, v105, v105
	v_add_f32_e32 v116, v110, v111
	v_pk_mul_f32 v[110:111], v[100:101], v[132:133] op_sel_hi:[1,0]
	v_fmac_f32_e32 v98, v102, v102
	v_fmac_f32_e32 v99, v104, v104
	v_add_f32_e32 v98, v98, v99
	v_mul_f32_e32 v99, v113, v113
	v_mul_f32_e32 v100, v111, v111
	v_fmac_f32_e32 v99, v112, v112
	v_fmac_f32_e32 v100, v110, v110
	v_add_f32_e32 v99, v99, v100
	v_add_f32_e32 v98, v98, v99
	v_add_f32_e32 v98, v116, v98
	ds_bpermute_b32 v99, v232, v98
	v_cvt_pk_bf16_f32 v108, v108, v109
	v_cvt_pk_bf16_f32 v109, v118, v119
	v_cvt_pk_bf16_f32 v100, v102, v103
	v_cvt_pk_bf16_f32 v101, v104, v105
	s_waitcnt lgkmcnt(0)
	v_add_f32_e32 v98, v98, v99
	ds_bpermute_b32 v99, v231, v98
	v_cvt_pk_bf16_f32 v102, v112, v113
	v_cvt_pk_bf16_f32 v103, v110, v111
	global_store_dwordx4 v[114:115], v[106:109], off sc0 sc1
	global_store_dwordx4 v[114:115], v[100:103], off offset:256 sc0 sc1
	s_and_saveexec_b64 s[0:1], s[42:43]
	s_cbranch_execz .LBB0_98
	s_waitcnt lgkmcnt(0)
	v_add_f32_e32 v98, v98, v99
	s_andn2_b64 vcc, exec, s[80:81]
	s_mov_b64 s[10:11], -1
	s_cbranch_vccnz .LBB0_96
	v_readlane_b32 s4, v251, 57
	v_lshlrev_b64 v[100:101], 5, v[184:185]
	v_readlane_b32 s5, v251, 58
	s_lshl_b32 s76, s90, 2
	s_mov_b64 s[10:11], 0
	v_lshl_add_u64 v[100:101], s[4:5], 0, v[100:101]
	v_lshl_add_u64 v[100:101], s[82:83], 2, v[100:101]
	v_lshl_add_u64 v[100:101], v[100:101], 0, s[76:77]
	global_store_dword v[100:101], v98, off

.LBB0_103:
	s_andn2_b64 vcc, exec, s[0:1]
	s_cbranch_vccnz .LBB0_110
	v_lshlrev_b64 v[98:99], 10, v[180:181]
	v_lshlrev_b64 v[100:101], 9, v[180:181]
	v_lshl_add_u64 v[98:99], s[20:21], 0, v[98:99]
	v_pk_mul_f32 v[102:103], v[92:93], v[114:115] op_sel_hi:[1,0]
	v_pk_mul_f32 v[92:93], v[90:91], v[114:115] op_sel_hi:[1,0]
	v_lshl_add_u64 v[90:91], s[52:53], 0, v[100:101]
	v_lshl_add_u64 v[98:99], s[84:85], 1, v[98:99]
	v_pk_mul_f32 v[94:95], v[94:95], v[114:115] op_sel_hi:[1,0]
	v_cndmask_b32_e64 v91, v99, v91, s[44:45]
	v_cndmask_b32_e64 v90, v98, v90, s[44:45]
	v_pk_mul_f32 v[96:97], v[96:97], v[114:115] op_sel_hi:[1,0]
	v_lshl_add_u64 v[98:99], v[130:131], 1, v[90:91]
	v_cvt_pk_bf16_f32 v90, v94, v95
	v_mul_f32_e32 v95, v95, v95
	v_fmac_f32_e32 v95, v94, v94
	v_mul_f32_e32 v94, v97, v97
	v_fmac_f32_e32 v94, v96, v96
	v_cvt_pk_bf16_f32 v91, v96, v97
	v_add_f32_e32 v94, v95, v94
	v_mul_f32_e32 v95, v93, v93
	v_mul_f32_e32 v96, v103, v103
	v_fmac_f32_e32 v95, v92, v92
	v_fmac_f32_e32 v96, v102, v102
	v_pk_mul_f32 v[88:89], v[88:89], v[114:115] op_sel_hi:[1,0]
	v_pk_mul_f32 v[86:87], v[86:87], v[114:115] op_sel_hi:[1,0]
	v_add_f32_e32 v95, v95, v96
	v_pk_mul_f32 v[96:97], v[82:83], v[114:115] op_sel_hi:[1,0]
	v_mul_f32_e32 v82, v87, v87
	v_mul_f32_e32 v83, v89, v89
	v_add_f32_e32 v100, v94, v95
	v_pk_mul_f32 v[94:95], v[84:85], v[114:115] op_sel_hi:[1,0]
	v_fmac_f32_e32 v82, v86, v86
	v_fmac_f32_e32 v83, v88, v88
	v_add_f32_e32 v82, v82, v83
	v_mul_f32_e32 v83, v97, v97
	v_mul_f32_e32 v84, v95, v95
	v_fmac_f32_e32 v83, v96, v96
	v_fmac_f32_e32 v84, v94, v94
	v_add_f32_e32 v83, v83, v84
	v_add_f32_e32 v82, v82, v83
	v_add_f32_e32 v82, v100, v82
	ds_bpermute_b32 v83, v232, v82
	v_cvt_pk_bf16_f32 v92, v92, v93
	v_cvt_pk_bf16_f32 v93, v102, v103
	v_cvt_pk_bf16_f32 v84, v86, v87
	v_cvt_pk_bf16_f32 v85, v88, v89
	s_waitcnt lgkmcnt(0)
	v_add_f32_e32 v82, v82, v83
	ds_bpermute_b32 v83, v231, v82
	v_cvt_pk_bf16_f32 v86, v96, v97
	v_cvt_pk_bf16_f32 v87, v94, v95
	global_store_dwordx4 v[98:99], v[90:93], off sc0 sc1
	global_store_dwordx4 v[98:99], v[84:87], off offset:256 sc0 sc1
	s_and_saveexec_b64 s[0:1], s[42:43]
	s_cbranch_execz .LBB0_109
	s_waitcnt lgkmcnt(0)
	v_add_f32_e32 v82, v82, v83
	s_andn2_b64 vcc, exec, s[80:81]
	s_mov_b64 s[10:11], -1
	s_cbranch_vccnz .LBB0_107
	v_readlane_b32 s4, v251, 57
	v_lshlrev_b64 v[84:85], 5, v[180:181]
	v_readlane_b32 s5, v251, 58
	s_lshl_b32 s76, s90, 2
	s_mov_b64 s[10:11], 0
	v_lshl_add_u64 v[84:85], s[4:5], 0, v[84:85]
	v_lshl_add_u64 v[84:85], s[82:83], 2, v[84:85]
	v_lshl_add_u64 v[84:85], v[84:85], 0, s[76:77]
	global_store_dword v[84:85], v82, off

.LBB0_114:
	s_andn2_b64 vcc, exec, s[0:1]
	s_cbranch_vccnz .LBB0_121
	v_lshlrev_b64 v[82:83], 10, v[176:177]
	v_lshlrev_b64 v[84:85], 9, v[176:177]
	v_lshl_add_u64 v[82:83], s[20:21], 0, v[82:83]
	v_pk_mul_f32 v[86:87], v[76:77], v[98:99] op_sel_hi:[1,0]
	v_pk_mul_f32 v[76:77], v[74:75], v[98:99] op_sel_hi:[1,0]
	v_lshl_add_u64 v[74:75], s[52:53], 0, v[84:85]
	v_lshl_add_u64 v[82:83], s[84:85], 1, v[82:83]
	v_pk_mul_f32 v[78:79], v[78:79], v[98:99] op_sel_hi:[1,0]
	v_cndmask_b32_e64 v75, v83, v75, s[44:45]
	v_cndmask_b32_e64 v74, v82, v74, s[44:45]
	v_pk_mul_f32 v[80:81], v[80:81], v[98:99] op_sel_hi:[1,0]
	v_lshl_add_u64 v[82:83], v[130:131], 1, v[74:75]
	v_cvt_pk_bf16_f32 v74, v78, v79
	v_mul_f32_e32 v79, v79, v79
	v_fmac_f32_e32 v79, v78, v78
	v_mul_f32_e32 v78, v81, v81
	v_fmac_f32_e32 v78, v80, v80
	v_cvt_pk_bf16_f32 v75, v80, v81
	v_add_f32_e32 v78, v79, v78
	v_mul_f32_e32 v79, v77, v77
	v_mul_f32_e32 v80, v87, v87
	v_fmac_f32_e32 v79, v76, v76
	v_fmac_f32_e32 v80, v86, v86
	v_pk_mul_f32 v[72:73], v[72:73], v[98:99] op_sel_hi:[1,0]
	v_pk_mul_f32 v[70:71], v[70:71], v[98:99] op_sel_hi:[1,0]
	v_add_f32_e32 v79, v79, v80
	v_pk_mul_f32 v[80:81], v[66:67], v[98:99] op_sel_hi:[1,0]
	v_mul_f32_e32 v66, v71, v71
	v_mul_f32_e32 v67, v73, v73
	v_add_f32_e32 v84, v78, v79
	v_pk_mul_f32 v[78:79], v[68:69], v[98:99] op_sel_hi:[1,0]
	v_fmac_f32_e32 v66, v70, v70
	v_fmac_f32_e32 v67, v72, v72
	v_add_f32_e32 v66, v66, v67
	v_mul_f32_e32 v67, v81, v81
	v_mul_f32_e32 v68, v79, v79
	v_fmac_f32_e32 v67, v80, v80
	v_fmac_f32_e32 v68, v78, v78
	v_add_f32_e32 v67, v67, v68
	v_add_f32_e32 v66, v66, v67
	v_add_f32_e32 v66, v84, v66
	ds_bpermute_b32 v67, v232, v66
	v_cvt_pk_bf16_f32 v76, v76, v77
	v_cvt_pk_bf16_f32 v77, v86, v87
	v_cvt_pk_bf16_f32 v68, v70, v71
	v_cvt_pk_bf16_f32 v69, v72, v73
	s_waitcnt lgkmcnt(0)
	v_add_f32_e32 v66, v66, v67
	ds_bpermute_b32 v67, v231, v66
	v_cvt_pk_bf16_f32 v70, v80, v81
	v_cvt_pk_bf16_f32 v71, v78, v79
	global_store_dwordx4 v[82:83], v[74:77], off sc0 sc1
	global_store_dwordx4 v[82:83], v[68:71], off offset:256 sc0 sc1
	s_and_saveexec_b64 s[0:1], s[42:43]
	s_cbranch_execz .LBB0_120
	s_waitcnt lgkmcnt(0)
	v_add_f32_e32 v66, v66, v67
	s_andn2_b64 vcc, exec, s[80:81]
	s_mov_b64 s[10:11], -1
	s_cbranch_vccnz .LBB0_118
	v_readlane_b32 s4, v251, 57
	v_lshlrev_b64 v[68:69], 5, v[176:177]
	v_readlane_b32 s5, v251, 58
	s_lshl_b32 s76, s90, 2
	s_mov_b64 s[10:11], 0
	v_lshl_add_u64 v[68:69], s[4:5], 0, v[68:69]
	v_lshl_add_u64 v[68:69], s[82:83], 2, v[68:69]
	v_lshl_add_u64 v[68:69], v[68:69], 0, s[76:77]
	global_store_dword v[68:69], v66, off

.LBB0_125:
	s_andn2_b64 vcc, exec, s[0:1]
	s_cbranch_vccnz .LBB0_132
	v_lshlrev_b64 v[66:67], 10, v[172:173]
	v_lshlrev_b64 v[68:69], 9, v[172:173]
	v_lshl_add_u64 v[66:67], s[20:21], 0, v[66:67]
	v_pk_mul_f32 v[70:71], v[60:61], v[82:83] op_sel_hi:[1,0]
	v_pk_mul_f32 v[60:61], v[58:59], v[82:83] op_sel_hi:[1,0]
	v_lshl_add_u64 v[58:59], s[52:53], 0, v[68:69]
	v_lshl_add_u64 v[66:67], s[84:85], 1, v[66:67]
	v_pk_mul_f32 v[62:63], v[62:63], v[82:83] op_sel_hi:[1,0]
	v_cndmask_b32_e64 v59, v67, v59, s[44:45]
	v_cndmask_b32_e64 v58, v66, v58, s[44:45]
	v_pk_mul_f32 v[64:65], v[64:65], v[82:83] op_sel_hi:[1,0]
	v_lshl_add_u64 v[66:67], v[130:131], 1, v[58:59]
	v_cvt_pk_bf16_f32 v58, v62, v63
	v_mul_f32_e32 v63, v63, v63
	v_fmac_f32_e32 v63, v62, v62
	v_mul_f32_e32 v62, v65, v65
	v_fmac_f32_e32 v62, v64, v64
	v_cvt_pk_bf16_f32 v59, v64, v65
	v_add_f32_e32 v62, v63, v62
	v_mul_f32_e32 v63, v61, v61
	v_mul_f32_e32 v64, v71, v71
	v_fmac_f32_e32 v63, v60, v60
	v_fmac_f32_e32 v64, v70, v70
	v_pk_mul_f32 v[56:57], v[56:57], v[82:83] op_sel_hi:[1,0]
	v_pk_mul_f32 v[54:55], v[54:55], v[82:83] op_sel_hi:[1,0]
	v_add_f32_e32 v63, v63, v64
	v_pk_mul_f32 v[64:65], v[50:51], v[82:83] op_sel_hi:[1,0]
	v_mul_f32_e32 v50, v55, v55
	v_mul_f32_e32 v51, v57, v57
	v_add_f32_e32 v68, v62, v63
	v_pk_mul_f32 v[62:63], v[52:53], v[82:83] op_sel_hi:[1,0]
	v_fmac_f32_e32 v50, v54, v54
	v_fmac_f32_e32 v51, v56, v56
	v_add_f32_e32 v50, v50, v51
	v_mul_f32_e32 v51, v65, v65
	v_mul_f32_e32 v52, v63, v63
	v_fmac_f32_e32 v51, v64, v64
	v_fmac_f32_e32 v52, v62, v62
	v_add_f32_e32 v51, v51, v52
	v_add_f32_e32 v50, v50, v51
	v_add_f32_e32 v50, v68, v50
	ds_bpermute_b32 v51, v232, v50
	v_cvt_pk_bf16_f32 v60, v60, v61
	v_cvt_pk_bf16_f32 v61, v70, v71
	v_cvt_pk_bf16_f32 v52, v54, v55
	v_cvt_pk_bf16_f32 v53, v56, v57
	s_waitcnt lgkmcnt(0)
	v_add_f32_e32 v50, v50, v51
	ds_bpermute_b32 v51, v231, v50
	v_cvt_pk_bf16_f32 v54, v64, v65
	v_cvt_pk_bf16_f32 v55, v62, v63
	global_store_dwordx4 v[66:67], v[58:61], off sc0 sc1
	global_store_dwordx4 v[66:67], v[52:55], off offset:256 sc0 sc1
	s_and_saveexec_b64 s[0:1], s[42:43]
	s_cbranch_execz .LBB0_131
	s_waitcnt lgkmcnt(0)
	v_add_f32_e32 v50, v50, v51
	s_andn2_b64 vcc, exec, s[80:81]
	s_mov_b64 s[10:11], -1
	s_cbranch_vccnz .LBB0_129
	v_readlane_b32 s4, v251, 57
	v_lshlrev_b64 v[52:53], 5, v[172:173]
	v_readlane_b32 s5, v251, 58
	s_lshl_b32 s76, s90, 2
	s_mov_b64 s[10:11], 0
	v_lshl_add_u64 v[52:53], s[4:5], 0, v[52:53]
	v_lshl_add_u64 v[52:53], s[82:83], 2, v[52:53]
	v_lshl_add_u64 v[52:53], v[52:53], 0, s[76:77]
	global_store_dword v[52:53], v50, off

.LBB0_136:
	s_andn2_b64 vcc, exec, s[0:1]
	s_cbranch_vccnz .LBB0_143
	v_lshlrev_b64 v[50:51], 10, v[168:169]
	v_lshlrev_b64 v[52:53], 9, v[168:169]
	v_lshl_add_u64 v[50:51], s[20:21], 0, v[50:51]
	v_pk_mul_f32 v[54:55], v[44:45], v[66:67] op_sel_hi:[1,0]
	v_pk_mul_f32 v[44:45], v[42:43], v[66:67] op_sel_hi:[1,0]
	v_lshl_add_u64 v[42:43], s[52:53], 0, v[52:53]
	v_lshl_add_u64 v[50:51], s[84:85], 1, v[50:51]
	v_pk_mul_f32 v[46:47], v[46:47], v[66:67] op_sel_hi:[1,0]
	v_cndmask_b32_e64 v43, v51, v43, s[44:45]
	v_cndmask_b32_e64 v42, v50, v42, s[44:45]
	v_pk_mul_f32 v[48:49], v[48:49], v[66:67] op_sel_hi:[1,0]
	v_lshl_add_u64 v[50:51], v[130:131], 1, v[42:43]
	v_cvt_pk_bf16_f32 v42, v46, v47
	v_mul_f32_e32 v47, v47, v47
	v_fmac_f32_e32 v47, v46, v46
	v_mul_f32_e32 v46, v49, v49
	v_fmac_f32_e32 v46, v48, v48
	v_cvt_pk_bf16_f32 v43, v48, v49
	v_add_f32_e32 v46, v47, v46
	v_mul_f32_e32 v47, v45, v45
	v_mul_f32_e32 v48, v55, v55
	v_fmac_f32_e32 v47, v44, v44
	v_fmac_f32_e32 v48, v54, v54
	v_pk_mul_f32 v[40:41], v[40:41], v[66:67] op_sel_hi:[1,0]
	v_pk_mul_f32 v[38:39], v[38:39], v[66:67] op_sel_hi:[1,0]
	v_add_f32_e32 v47, v47, v48
	v_pk_mul_f32 v[48:49], v[34:35], v[66:67] op_sel_hi:[1,0]
	v_mul_f32_e32 v34, v39, v39
	v_mul_f32_e32 v35, v41, v41
	v_add_f32_e32 v52, v46, v47
	v_pk_mul_f32 v[46:47], v[36:37], v[66:67] op_sel_hi:[1,0]
	v_fmac_f32_e32 v34, v38, v38
	v_fmac_f32_e32 v35, v40, v40
	v_add_f32_e32 v34, v34, v35
	v_mul_f32_e32 v35, v49, v49
	v_mul_f32_e32 v36, v47, v47
	v_fmac_f32_e32 v35, v48, v48
	v_fmac_f32_e32 v36, v46, v46
	v_add_f32_e32 v35, v35, v36
	v_add_f32_e32 v34, v34, v35
	v_add_f32_e32 v34, v52, v34
	ds_bpermute_b32 v35, v232, v34
	v_cvt_pk_bf16_f32 v44, v44, v45
	v_cvt_pk_bf16_f32 v45, v54, v55
	v_cvt_pk_bf16_f32 v36, v38, v39
	v_cvt_pk_bf16_f32 v37, v40, v41
	s_waitcnt lgkmcnt(0)
	v_add_f32_e32 v34, v34, v35
	ds_bpermute_b32 v35, v231, v34
	v_cvt_pk_bf16_f32 v38, v48, v49
	v_cvt_pk_bf16_f32 v39, v46, v47
	global_store_dwordx4 v[50:51], v[42:45], off sc0 sc1
	global_store_dwordx4 v[50:51], v[36:39], off offset:256 sc0 sc1
	s_and_saveexec_b64 s[0:1], s[42:43]
	s_cbranch_execz .LBB0_142
	s_waitcnt lgkmcnt(0)
	v_add_f32_e32 v34, v34, v35
	s_andn2_b64 vcc, exec, s[80:81]
	s_mov_b64 s[10:11], -1
	s_cbranch_vccnz .LBB0_140
	v_readlane_b32 s4, v251, 57
	v_lshlrev_b64 v[36:37], 5, v[168:169]
	v_readlane_b32 s5, v251, 58
	s_lshl_b32 s76, s90, 2
	s_mov_b64 s[10:11], 0
	v_lshl_add_u64 v[36:37], s[4:5], 0, v[36:37]
	v_lshl_add_u64 v[36:37], s[82:83], 2, v[36:37]
	v_lshl_add_u64 v[36:37], v[36:37], 0, s[76:77]
	global_store_dword v[36:37], v34, off

.LBB0_147:
	s_andn2_b64 vcc, exec, s[0:1]
	s_cbranch_vccnz .LBB0_154
	v_lshlrev_b64 v[34:35], 10, v[164:165]
	v_lshlrev_b64 v[36:37], 9, v[164:165]
	v_lshl_add_u64 v[34:35], s[20:21], 0, v[34:35]
	v_pk_mul_f32 v[38:39], v[28:29], v[50:51] op_sel_hi:[1,0]
	v_pk_mul_f32 v[28:29], v[26:27], v[50:51] op_sel_hi:[1,0]
	v_lshl_add_u64 v[26:27], s[52:53], 0, v[36:37]
	v_lshl_add_u64 v[34:35], s[84:85], 1, v[34:35]
	v_pk_mul_f32 v[30:31], v[30:31], v[50:51] op_sel_hi:[1,0]
	v_cndmask_b32_e64 v27, v35, v27, s[44:45]
	v_cndmask_b32_e64 v26, v34, v26, s[44:45]
	v_pk_mul_f32 v[32:33], v[32:33], v[50:51] op_sel_hi:[1,0]
	v_lshl_add_u64 v[34:35], v[130:131], 1, v[26:27]
	v_cvt_pk_bf16_f32 v26, v30, v31
	v_mul_f32_e32 v31, v31, v31
	v_fmac_f32_e32 v31, v30, v30
	v_mul_f32_e32 v30, v33, v33
	v_fmac_f32_e32 v30, v32, v32
	v_cvt_pk_bf16_f32 v27, v32, v33
	v_add_f32_e32 v30, v31, v30
	v_mul_f32_e32 v31, v29, v29
	v_mul_f32_e32 v32, v39, v39
	v_fmac_f32_e32 v31, v28, v28
	v_fmac_f32_e32 v32, v38, v38
	v_pk_mul_f32 v[24:25], v[24:25], v[50:51] op_sel_hi:[1,0]
	v_pk_mul_f32 v[22:23], v[22:23], v[50:51] op_sel_hi:[1,0]
	v_add_f32_e32 v31, v31, v32
	v_pk_mul_f32 v[32:33], v[18:19], v[50:51] op_sel_hi:[1,0]
	v_mul_f32_e32 v18, v23, v23
	v_mul_f32_e32 v19, v25, v25
	v_add_f32_e32 v36, v30, v31
	v_pk_mul_f32 v[30:31], v[20:21], v[50:51] op_sel_hi:[1,0]
	v_fmac_f32_e32 v18, v22, v22
	v_fmac_f32_e32 v19, v24, v24
	v_add_f32_e32 v18, v18, v19
	v_mul_f32_e32 v19, v33, v33
	v_mul_f32_e32 v20, v31, v31
	v_fmac_f32_e32 v19, v32, v32
	v_fmac_f32_e32 v20, v30, v30
	v_add_f32_e32 v19, v19, v20
	v_add_f32_e32 v18, v18, v19
	v_add_f32_e32 v18, v36, v18
	ds_bpermute_b32 v19, v232, v18
	v_cvt_pk_bf16_f32 v28, v28, v29
	v_cvt_pk_bf16_f32 v29, v38, v39
	v_cvt_pk_bf16_f32 v20, v22, v23
	v_cvt_pk_bf16_f32 v21, v24, v25
	s_waitcnt lgkmcnt(0)
	v_add_f32_e32 v18, v18, v19
	ds_bpermute_b32 v19, v231, v18
	v_cvt_pk_bf16_f32 v22, v32, v33
	v_cvt_pk_bf16_f32 v23, v30, v31
	global_store_dwordx4 v[34:35], v[26:29], off sc0 sc1
	global_store_dwordx4 v[34:35], v[20:23], off offset:256 sc0 sc1
	s_and_saveexec_b64 s[0:1], s[42:43]
	s_cbranch_execz .LBB0_153
	s_waitcnt lgkmcnt(0)
	v_add_f32_e32 v18, v18, v19
	s_andn2_b64 vcc, exec, s[80:81]
	s_mov_b64 s[10:11], -1
	s_cbranch_vccnz .LBB0_151
	v_readlane_b32 s4, v251, 57
	v_lshlrev_b64 v[20:21], 5, v[164:165]
	v_readlane_b32 s5, v251, 58
	s_lshl_b32 s76, s90, 2
	s_mov_b64 s[10:11], 0
	v_lshl_add_u64 v[20:21], s[4:5], 0, v[20:21]
	v_lshl_add_u64 v[20:21], s[82:83], 2, v[20:21]
	v_lshl_add_u64 v[20:21], v[20:21], 0, s[76:77]
	global_store_dword v[20:21], v18, off

.LBB0_158:
	s_andn2_b64 vcc, exec, s[0:1]
	s_cbranch_vccnz .LBB0_165
	v_lshlrev_b64 v[18:19], 10, v[158:159]
	v_lshlrev_b64 v[20:21], 9, v[158:159]
	v_lshl_add_u64 v[18:19], s[20:21], 0, v[18:19]
	v_pk_mul_f32 v[22:23], v[12:13], v[34:35] op_sel_hi:[1,0]
	v_pk_mul_f32 v[12:13], v[10:11], v[34:35] op_sel_hi:[1,0]
	v_lshl_add_u64 v[10:11], s[52:53], 0, v[20:21]
	v_lshl_add_u64 v[18:19], s[84:85], 1, v[18:19]
	v_pk_mul_f32 v[14:15], v[14:15], v[34:35] op_sel_hi:[1,0]
	v_cndmask_b32_e64 v11, v19, v11, s[44:45]
	v_cndmask_b32_e64 v10, v18, v10, s[44:45]
	v_pk_mul_f32 v[16:17], v[16:17], v[34:35] op_sel_hi:[1,0]
	v_lshl_add_u64 v[18:19], v[130:131], 1, v[10:11]
	v_cvt_pk_bf16_f32 v10, v14, v15
	v_mul_f32_e32 v15, v15, v15
	v_fmac_f32_e32 v15, v14, v14
	v_mul_f32_e32 v14, v17, v17
	v_fmac_f32_e32 v14, v16, v16
	v_cvt_pk_bf16_f32 v11, v16, v17
	v_add_f32_e32 v14, v15, v14
	v_mul_f32_e32 v15, v13, v13
	v_mul_f32_e32 v16, v23, v23
	v_fmac_f32_e32 v15, v12, v12
	v_fmac_f32_e32 v16, v22, v22
	v_pk_mul_f32 v[8:9], v[8:9], v[34:35] op_sel_hi:[1,0]
	v_pk_mul_f32 v[6:7], v[6:7], v[34:35] op_sel_hi:[1,0]
	v_add_f32_e32 v15, v15, v16
	v_pk_mul_f32 v[16:17], v[2:3], v[34:35] op_sel_hi:[1,0]
	v_mul_f32_e32 v2, v7, v7
	v_mul_f32_e32 v3, v9, v9
	v_add_f32_e32 v20, v14, v15
	v_pk_mul_f32 v[14:15], v[4:5], v[34:35] op_sel_hi:[1,0]
	v_fmac_f32_e32 v2, v6, v6
	v_fmac_f32_e32 v3, v8, v8
	v_add_f32_e32 v2, v2, v3
	v_mul_f32_e32 v3, v17, v17
	v_mul_f32_e32 v4, v15, v15
	v_fmac_f32_e32 v3, v16, v16
	v_fmac_f32_e32 v4, v14, v14
	v_add_f32_e32 v3, v3, v4
	v_add_f32_e32 v2, v2, v3
	v_add_f32_e32 v2, v20, v2
	ds_bpermute_b32 v3, v232, v2
	v_cvt_pk_bf16_f32 v12, v12, v13
	v_cvt_pk_bf16_f32 v13, v22, v23
	v_cvt_pk_bf16_f32 v4, v6, v7
	v_cvt_pk_bf16_f32 v5, v8, v9
	s_waitcnt lgkmcnt(0)
	v_add_f32_e32 v2, v2, v3
	ds_bpermute_b32 v3, v231, v2
	v_cvt_pk_bf16_f32 v6, v16, v17
	v_cvt_pk_bf16_f32 v7, v14, v15
	global_store_dwordx4 v[18:19], v[10:13], off sc0 sc1
	global_store_dwordx4 v[18:19], v[4:7], off offset:256 sc0 sc1
	s_and_saveexec_b64 s[0:1], s[42:43]
	s_cbranch_execz .LBB0_164
	s_waitcnt lgkmcnt(0)
	v_add_f32_e32 v2, v2, v3
	s_andn2_b64 vcc, exec, s[80:81]
	s_mov_b64 s[10:11], -1
	s_cbranch_vccnz .LBB0_162
	v_readlane_b32 s4, v251, 57
	v_lshlrev_b64 v[4:5], 5, v[158:159]
	v_readlane_b32 s5, v251, 58
	s_lshl_b32 s76, s90, 2
	s_mov_b64 s[10:11], 0
	v_lshl_add_u64 v[4:5], s[4:5], 0, v[4:5]
	v_lshl_add_u64 v[4:5], s[82:83], 2, v[4:5]
	v_lshl_add_u64 v[4:5], v[4:5], 0, s[76:77]
	global_store_dword v[4:5], v2, off

.LBB0_276:
	s_or_b64 exec, exec, s[0:1]
	s_add_i32 s4, 0, 0x20000
	s_waitcnt lgkmcnt(0)
	s_barrier
	v_add_u32_e32 v2, s4, v177
	ds_read_b128 v[6:9], v2
	s_waitcnt lgkmcnt(1)
	ds_read_b128 v[2:5], v2 offset:16
	v_lshl_add_u32 v38, v185, 3, s73
	v_ashrrev_i32_e32 v39, 31, v38
	s_lshl_b64 s[10:11], s[68:69], 20
	s_waitcnt lgkmcnt(1)
	v_mov_b32_e32 v18, v7
	v_mov_b32_e32 v19, v8
	v_mov_b32_e32 v7, v9
	v_pk_add_f32 v[6:7], v[18:19], v[6:7]
	s_lshl_b32 s0, s83, 8
	v_add_f32_e32 v6, v6, v7
	v_fmamk_f32 v6, v6, 0x3c000000, v243
	v_lshlrev_b64 v[168:169], 12, v[168:169]
	s_nop 1
	v_readlane_b32 s6, v251, 45
	v_readlane_b32 s7, v251, 46
	s_add_u32 s44, s6, s10
	v_rsq_f32_e32 v6, v6
	s_nop 0
	v_lshl_add_u64 v[18:19], v[38:39], 2, s[56:57]
	v_mul_f32_e32 v186, 0x3dd53b94, v6
	global_load_dwordx4 v[212:215], v[18:19], off
	global_load_dwordx4 v[216:219], v[18:19], off offset:16
	s_addc_u32 s45, s7, s11
	s_ashr_i32 s1, s0, 31
	s_lshl_b64 s[68:69], s[0:1], 1
	v_lshlrev_b64 v[38:39], 1, v[38:39]
	s_waitcnt vmcnt(0)
	v_pk_mul_f32 v[8:9], v[164:165], v[218:219]
	v_pk_mul_f32 v[160:161], v[160:161], v[214:215]
	v_pk_mul_f32 v[6:7], v[166:167], v[216:217]
	v_pk_mul_f32 v[160:161], v[160:161], v[186:187] op_sel_hi:[1,0]
	v_pk_mul_f32 v[162:163], v[162:163], v[212:213]
	v_pk_mul_f32 v[164:165], v[8:9], v[186:187] op_sel_hi:[1,0]
	v_pk_mul_f32 v[8:9], v[6:7], v[186:187] op_sel_hi:[1,0]
	v_cvt_pk_bf16_f32 v7, v160, v161
	v_lshl_add_u64 v[160:161], s[44:45], 0, v[168:169]
	v_pk_mul_f32 v[162:163], v[162:163], v[186:187] op_sel_hi:[1,0]
	v_lshl_add_u64 v[160:161], v[160:161], 0, s[68:69]
	v_cvt_pk_bf16_f32 v6, v162, v163
	v_cvt_pk_bf16_f32 v8, v8, v9
	v_cvt_pk_bf16_f32 v9, v164, v165
	v_lshl_add_u64 v[160:161], v[160:161], 0, v[38:39]
	global_store_dwordx4 v[160:161], v[6:9], off sc0 sc1
	s_nop 1
	s_waitcnt lgkmcnt(0)
	s_nop 0
	v_mov_b32_e32 v6, v3
	v_mov_b32_e32 v7, v4
	v_mov_b32_e32 v3, v5
	v_pk_add_f32 v[2:3], v[6:7], v[2:3]
	s_nop 0
	v_add_f32_e32 v2, v2, v3
	v_fmamk_f32 v2, v2, 0x3c000000, v243
	v_rsq_f32_e32 v2, v2
	s_nop 0
	v_mul_f32_e32 v6, 0x3dd53b94, v2
	v_pk_mul_f32 v[4:5], v[150:151], v[218:219]
	v_pk_mul_f32 v[8:9], v[156:157], v[214:215]
	v_pk_mul_f32 v[156:157], v[158:159], v[212:213]
	v_pk_mul_f32 v[2:3], v[152:153], v[216:217]
	v_pk_mul_f32 v[8:9], v[8:9], v[6:7] op_sel_hi:[1,0]
	v_pk_mul_f32 v[156:157], v[156:157], v[6:7] op_sel_hi:[1,0]
	v_pk_mul_f32 v[150:151], v[4:5], v[6:7] op_sel_hi:[1,0]
	v_pk_mul_f32 v[4:5], v[2:3], v[6:7] op_sel_hi:[1,0]
	v_cvt_pk_bf16_f32 v2, v156, v157
	v_cvt_pk_bf16_f32 v3, v8, v9
	v_cvt_pk_bf16_f32 v4, v4, v5
	v_cvt_pk_bf16_f32 v5, v150, v151
	global_store_dwordx4 v[160:161], v[2:5], off offset:256 sc0 sc1
	s_nop 1
	v_lshlrev_b64 v[150:151], 12, v[154:155]
	s_nop 0
	v_add_u32_e32 v2, s4, v176
	ds_read_b128 v[6:9], v2
	ds_read_b128 v[2:5], v2 offset:16
	s_waitcnt lgkmcnt(1)
	v_mov_b32_e32 v152, v7
	v_mov_b32_e32 v153, v8
	v_mov_b32_e32 v7, v9
	v_pk_add_f32 v[6:7], v[152:153], v[6:7]
	s_nop 0
	v_add_f32_e32 v6, v6, v7
	v_fmamk_f32 v6, v6, 0x3c000000, v243
	v_rsq_f32_e32 v6, v6
	s_nop 0
	v_mul_f32_e32 v156, 0x3dd53b94, v6
	v_pk_mul_f32 v[8:9], v[134:135], v[218:219]
	v_pk_mul_f32 v[130:131], v[130:131], v[214:215]
	v_pk_mul_f32 v[6:7], v[136:137], v[216:217]
	v_pk_mul_f32 v[130:131], v[130:131], v[156:157] op_sel_hi:[1,0]
	v_pk_mul_f32 v[132:133], v[132:133], v[212:213]
	v_pk_mul_f32 v[134:135], v[8:9], v[156:157] op_sel_hi:[1,0]
	v_pk_mul_f32 v[8:9], v[6:7], v[156:157] op_sel_hi:[1,0]
	v_cvt_pk_bf16_f32 v7, v130, v131
	v_lshl_add_u64 v[130:131], s[44:45], 0, v[150:151]
	v_pk_mul_f32 v[132:133], v[132:133], v[156:157] op_sel_hi:[1,0]
	v_lshl_add_u64 v[130:131], v[130:131], 0, s[68:69]
	v_cvt_pk_bf16_f32 v6, v132, v133
	v_cvt_pk_bf16_f32 v8, v8, v9
	v_cvt_pk_bf16_f32 v9, v134, v135
	v_lshl_add_u64 v[130:131], v[130:131], 0, v[38:39]
	global_store_dwordx4 v[130:131], v[6:9], off sc0 sc1
	s_nop 1
	s_waitcnt lgkmcnt(0)
	s_nop 0
	v_mov_b32_e32 v6, v3
	v_mov_b32_e32 v7, v4
	v_mov_b32_e32 v3, v5
	v_pk_add_f32 v[2:3], v[6:7], v[2:3]
	s_nop 0
	v_add_f32_e32 v2, v2, v3
	v_fmamk_f32 v2, v2, 0x3c000000, v243
	v_rsq_f32_e32 v2, v2
	s_nop 0
	v_mul_f32_e32 v6, 0x3dd53b94, v2
	v_pk_mul_f32 v[4:5], v[120:121], v[218:219]
	v_pk_mul_f32 v[8:9], v[126:127], v[214:215]
	v_pk_mul_f32 v[126:127], v[128:129], v[212:213]
	v_pk_mul_f32 v[2:3], v[122:123], v[216:217]
	v_pk_mul_f32 v[8:9], v[8:9], v[6:7] op_sel_hi:[1,0]
	v_pk_mul_f32 v[126:127], v[126:127], v[6:7] op_sel_hi:[1,0]
	v_pk_mul_f32 v[120:121], v[4:5], v[6:7] op_sel_hi:[1,0]
	v_pk_mul_f32 v[4:5], v[2:3], v[6:7] op_sel_hi:[1,0]
	v_cvt_pk_bf16_f32 v2, v126, v127
	v_cvt_pk_bf16_f32 v3, v8, v9
	v_cvt_pk_bf16_f32 v4, v4, v5
	v_cvt_pk_bf16_f32 v5, v120, v121
	v_add_u32_e32 v123, s4, v175
	global_store_dwordx4 v[130:131], v[2:5], off offset:256 sc0 sc1
	s_nop 1
	ds_read_b128 v[2:5], v123
	v_lshlrev_b64 v[120:121], 12, v[124:125]
	s_waitcnt lgkmcnt(0)
	v_mov_b32_e32 v6, v3
	v_mov_b32_e32 v7, v4
	v_mov_b32_e32 v3, v5
	v_pk_add_f32 v[2:3], v[6:7], v[2:3]
	s_nop 0
	v_add_f32_e32 v2, v2, v3
	v_fmamk_f32 v2, v2, 0x3c000000, v243
	v_rsq_f32_e32 v2, v2
	s_nop 0
	v_mul_f32_e32 v122, 0x3dd53b94, v2
	v_pk_mul_f32 v[4:5], v[116:117], v[218:219]
	v_pk_mul_f32 v[6:7], v[114:115], v[212:213]
	v_pk_mul_f32 v[2:3], v[118:119], v[216:217]
	v_pk_mul_f32 v[6:7], v[6:7], v[122:123] op_sel_hi:[1,0]
	v_pk_mul_f32 v[8:9], v[112:113], v[214:215]
	v_pk_mul_f32 v[112:113], v[4:5], v[122:123] op_sel_hi:[1,0]
	v_pk_mul_f32 v[4:5], v[2:3], v[122:123] op_sel_hi:[1,0]
	v_cvt_pk_bf16_f32 v2, v6, v7
	v_lshl_add_u64 v[6:7], s[44:45], 0, v[120:121]
	v_pk_mul_f32 v[8:9], v[8:9], v[122:123] op_sel_hi:[1,0]
	v_lshl_add_u64 v[6:7], v[6:7], 0, s[68:69]
	v_cvt_pk_bf16_f32 v3, v8, v9
	v_cvt_pk_bf16_f32 v4, v4, v5
	v_cvt_pk_bf16_f32 v5, v112, v113
	v_lshl_add_u64 v[6:7], v[6:7], 0, v[38:39]
	global_store_dwordx4 v[6:7], v[2:5], off sc0 sc1
	s_nop 1
	ds_read_b128 v[2:5], v123 offset:16
	s_waitcnt lgkmcnt(0)
	v_mov_b32_e32 v8, v3
	v_mov_b32_e32 v9, v4
	v_mov_b32_e32 v3, v5
	v_pk_add_f32 v[2:3], v[8:9], v[2:3]
	s_nop 0
	v_add_f32_e32 v2, v2, v3
	v_fmamk_f32 v2, v2, 0x3c000000, v243
	v_rsq_f32_e32 v2, v2
	s_nop 0
	v_mul_f32_e32 v8, 0x3dd53b94, v2
	v_pk_mul_f32 v[4:5], v[102:103], v[218:219]
	v_pk_mul_f32 v[108:109], v[108:109], v[214:215]
	v_pk_mul_f32 v[110:111], v[110:111], v[212:213]
	v_pk_mul_f32 v[2:3], v[104:105], v[216:217]
	v_pk_mul_f32 v[108:109], v[108:109], v[8:9] op_sel_hi:[1,0]
	v_pk_mul_f32 v[110:111], v[110:111], v[8:9] op_sel_hi:[1,0]
	v_pk_mul_f32 v[102:103], v[4:5], v[8:9] op_sel_hi:[1,0]
	v_pk_mul_f32 v[4:5], v[2:3], v[8:9] op_sel_hi:[1,0]
	v_cvt_pk_bf16_f32 v2, v110, v111
	v_cvt_pk_bf16_f32 v3, v108, v109
	v_cvt_pk_bf16_f32 v4, v4, v5
	v_cvt_pk_bf16_f32 v5, v102, v103
	v_add_u32_e32 v105, s4, v174
	global_store_dwordx4 v[6:7], v[2:5], off offset:256 sc0 sc1
	s_nop 1
	ds_read_b128 v[2:5], v105
	v_lshlrev_b64 v[102:103], 12, v[106:107]
	s_waitcnt lgkmcnt(0)
	v_mov_b32_e32 v6, v3
	v_mov_b32_e32 v7, v4
	v_mov_b32_e32 v3, v5
	v_pk_add_f32 v[2:3], v[6:7], v[2:3]
	s_nop 0
	v_add_f32_e32 v2, v2, v3
	v_fmamk_f32 v2, v2, 0x3c000000, v243
	v_rsq_f32_e32 v2, v2
	s_nop 0
	v_mul_f32_e32 v104, 0x3dd53b94, v2
	v_pk_mul_f32 v[4:5], v[98:99], v[218:219]
	v_pk_mul_f32 v[6:7], v[96:97], v[212:213]
	v_pk_mul_f32 v[2:3], v[100:101], v[216:217]
	v_pk_mul_f32 v[6:7], v[6:7], v[104:105] op_sel_hi:[1,0]
	v_pk_mul_f32 v[8:9], v[94:95], v[214:215]
	v_pk_mul_f32 v[94:95], v[4:5], v[104:105] op_sel_hi:[1,0]
	v_pk_mul_f32 v[4:5], v[2:3], v[104:105] op_sel_hi:[1,0]
	v_cvt_pk_bf16_f32 v2, v6, v7
	v_lshl_add_u64 v[6:7], s[44:45], 0, v[102:103]
	v_pk_mul_f32 v[8:9], v[8:9], v[104:105] op_sel_hi:[1,0]
	v_lshl_add_u64 v[6:7], v[6:7], 0, s[68:69]
	v_cvt_pk_bf16_f32 v3, v8, v9
	v_cvt_pk_bf16_f32 v4, v4, v5
	v_cvt_pk_bf16_f32 v5, v94, v95
	v_lshl_add_u64 v[6:7], v[6:7], 0, v[38:39]
	global_store_dwordx4 v[6:7], v[2:5], off sc0 sc1
	s_nop 1
	ds_read_b128 v[2:5], v105 offset:16
	s_waitcnt lgkmcnt(0)
	v_mov_b32_e32 v8, v3
	v_mov_b32_e32 v9, v4
	v_mov_b32_e32 v3, v5
	v_pk_add_f32 v[2:3], v[8:9], v[2:3]
	s_nop 0
	v_add_f32_e32 v2, v2, v3
	v_fmamk_f32 v2, v2, 0x3c000000, v243
	v_rsq_f32_e32 v2, v2
	s_nop 0
	v_mul_f32_e32 v8, 0x3dd53b94, v2
	v_pk_mul_f32 v[4:5], v[84:85], v[218:219]
	v_pk_mul_f32 v[90:91], v[90:91], v[214:215]
	v_pk_mul_f32 v[92:93], v[92:93], v[212:213]
	v_pk_mul_f32 v[2:3], v[86:87], v[216:217]
	v_pk_mul_f32 v[90:91], v[90:91], v[8:9] op_sel_hi:[1,0]
	v_pk_mul_f32 v[92:93], v[92:93], v[8:9] op_sel_hi:[1,0]
	v_pk_mul_f32 v[84:85], v[4:5], v[8:9] op_sel_hi:[1,0]
	v_pk_mul_f32 v[4:5], v[2:3], v[8:9] op_sel_hi:[1,0]
	v_cvt_pk_bf16_f32 v2, v92, v93
	v_cvt_pk_bf16_f32 v3, v90, v91
	v_cvt_pk_bf16_f32 v4, v4, v5
	v_cvt_pk_bf16_f32 v5, v84, v85
	v_add_u32_e32 v87, s4, v173
	global_store_dwordx4 v[6:7], v[2:5], off offset:256 sc0 sc1
	s_nop 1
	ds_read_b128 v[2:5], v87
	v_lshlrev_b64 v[84:85], 12, v[88:89]
	s_waitcnt lgkmcnt(0)
	v_mov_b32_e32 v6, v3
	v_mov_b32_e32 v7, v4
	v_mov_b32_e32 v3, v5
	v_pk_add_f32 v[2:3], v[6:7], v[2:3]
	s_nop 0
	v_add_f32_e32 v2, v2, v3
	v_fmamk_f32 v2, v2, 0x3c000000, v243
	v_rsq_f32_e32 v2, v2
	s_nop 0
	v_mul_f32_e32 v86, 0x3dd53b94, v2
	v_pk_mul_f32 v[4:5], v[80:81], v[218:219]
	v_pk_mul_f32 v[6:7], v[78:79], v[212:213]
	v_pk_mul_f32 v[2:3], v[82:83], v[216:217]
	v_pk_mul_f32 v[6:7], v[6:7], v[86:87] op_sel_hi:[1,0]
	v_pk_mul_f32 v[8:9], v[76:77], v[214:215]
	v_pk_mul_f32 v[76:77], v[4:5], v[86:87] op_sel_hi:[1,0]
	v_pk_mul_f32 v[4:5], v[2:3], v[86:87] op_sel_hi:[1,0]
	v_cvt_pk_bf16_f32 v2, v6, v7
	v_lshl_add_u64 v[6:7], s[44:45], 0, v[84:85]
	v_pk_mul_f32 v[8:9], v[8:9], v[86:87] op_sel_hi:[1,0]
	v_lshl_add_u64 v[6:7], v[6:7], 0, s[68:69]
	v_cvt_pk_bf16_f32 v3, v8, v9
	v_cvt_pk_bf16_f32 v4, v4, v5
	v_cvt_pk_bf16_f32 v5, v76, v77
	v_lshl_add_u64 v[6:7], v[6:7], 0, v[38:39]
	global_store_dwordx4 v[6:7], v[2:5], off sc0 sc1
	s_nop 1
	ds_read_b128 v[2:5], v87 offset:16
	s_waitcnt lgkmcnt(0)
	v_mov_b32_e32 v8, v3
	v_mov_b32_e32 v9, v4
	v_mov_b32_e32 v3, v5
	v_pk_add_f32 v[2:3], v[8:9], v[2:3]
	s_nop 0
	v_add_f32_e32 v2, v2, v3
	v_fmamk_f32 v2, v2, 0x3c000000, v243
	v_rsq_f32_e32 v2, v2
	s_nop 0
	v_mul_f32_e32 v8, 0x3dd53b94, v2
	v_pk_mul_f32 v[4:5], v[66:67], v[218:219]
	v_pk_mul_f32 v[72:73], v[72:73], v[214:215]
	v_pk_mul_f32 v[74:75], v[74:75], v[212:213]
	v_pk_mul_f32 v[2:3], v[68:69], v[216:217]
	v_pk_mul_f32 v[72:73], v[72:73], v[8:9] op_sel_hi:[1,0]
	v_pk_mul_f32 v[74:75], v[74:75], v[8:9] op_sel_hi:[1,0]
	v_pk_mul_f32 v[66:67], v[4:5], v[8:9] op_sel_hi:[1,0]
	v_pk_mul_f32 v[4:5], v[2:3], v[8:9] op_sel_hi:[1,0]
	v_cvt_pk_bf16_f32 v2, v74, v75
	v_cvt_pk_bf16_f32 v3, v72, v73
	v_cvt_pk_bf16_f32 v4, v4, v5
	v_cvt_pk_bf16_f32 v5, v66, v67
	v_add_u32_e32 v69, s4, v172
	global_store_dwordx4 v[6:7], v[2:5], off offset:256 sc0 sc1
	s_nop 1
	ds_read_b128 v[2:5], v69
	v_lshlrev_b64 v[66:67], 12, v[70:71]
	s_waitcnt lgkmcnt(0)
	v_mov_b32_e32 v6, v3
	v_mov_b32_e32 v7, v4
	v_mov_b32_e32 v3, v5
	v_pk_add_f32 v[2:3], v[6:7], v[2:3]
	s_nop 0
	v_add_f32_e32 v2, v2, v3
	v_fmamk_f32 v2, v2, 0x3c000000, v243
	v_rsq_f32_e32 v2, v2
	s_nop 0
	v_mul_f32_e32 v68, 0x3dd53b94, v2
	v_pk_mul_f32 v[4:5], v[62:63], v[218:219]
	v_pk_mul_f32 v[6:7], v[60:61], v[212:213]
	v_pk_mul_f32 v[2:3], v[64:65], v[216:217]
	v_pk_mul_f32 v[6:7], v[6:7], v[68:69] op_sel_hi:[1,0]
	v_pk_mul_f32 v[8:9], v[58:59], v[214:215]
	v_pk_mul_f32 v[58:59], v[4:5], v[68:69] op_sel_hi:[1,0]
	v_pk_mul_f32 v[4:5], v[2:3], v[68:69] op_sel_hi:[1,0]
	v_cvt_pk_bf16_f32 v2, v6, v7
	v_lshl_add_u64 v[6:7], s[44:45], 0, v[66:67]
	v_pk_mul_f32 v[8:9], v[8:9], v[68:69] op_sel_hi:[1,0]
	v_lshl_add_u64 v[6:7], v[6:7], 0, s[68:69]
	v_cvt_pk_bf16_f32 v3, v8, v9
	v_cvt_pk_bf16_f32 v4, v4, v5
	v_cvt_pk_bf16_f32 v5, v58, v59
	v_lshl_add_u64 v[6:7], v[6:7], 0, v[38:39]
	global_store_dwordx4 v[6:7], v[2:5], off sc0 sc1
	s_nop 1
	ds_read_b128 v[2:5], v69 offset:16
	s_waitcnt lgkmcnt(0)
	v_mov_b32_e32 v8, v3
	v_mov_b32_e32 v9, v4
	v_mov_b32_e32 v3, v5
	v_pk_add_f32 v[2:3], v[8:9], v[2:3]
	s_nop 0
	v_add_f32_e32 v2, v2, v3
	v_fmamk_f32 v2, v2, 0x3c000000, v243
	v_rsq_f32_e32 v2, v2
	s_nop 0
	v_mul_f32_e32 v8, 0x3dd53b94, v2
	v_pk_mul_f32 v[4:5], v[48:49], v[218:219]
	v_pk_mul_f32 v[54:55], v[54:55], v[214:215]
	v_pk_mul_f32 v[56:57], v[56:57], v[212:213]
	v_pk_mul_f32 v[2:3], v[50:51], v[216:217]
	v_pk_mul_f32 v[54:55], v[54:55], v[8:9] op_sel_hi:[1,0]
	v_pk_mul_f32 v[56:57], v[56:57], v[8:9] op_sel_hi:[1,0]
	v_pk_mul_f32 v[48:49], v[4:5], v[8:9] op_sel_hi:[1,0]
	v_pk_mul_f32 v[4:5], v[2:3], v[8:9] op_sel_hi:[1,0]
	v_cvt_pk_bf16_f32 v2, v56, v57
	v_cvt_pk_bf16_f32 v3, v54, v55
	v_cvt_pk_bf16_f32 v4, v4, v5
	v_cvt_pk_bf16_f32 v5, v48, v49
	v_add_u32_e32 v51, s4, v171
	global_store_dwordx4 v[6:7], v[2:5], off offset:256 sc0 sc1
	s_nop 1
	ds_read_b128 v[2:5], v51
	v_lshlrev_b64 v[48:49], 12, v[52:53]
	s_waitcnt lgkmcnt(0)
	v_mov_b32_e32 v6, v3
	v_mov_b32_e32 v7, v4
	v_mov_b32_e32 v3, v5
	v_pk_add_f32 v[2:3], v[6:7], v[2:3]
	s_nop 0
	v_add_f32_e32 v2, v2, v3
	v_fmamk_f32 v2, v2, 0x3c000000, v243
	v_rsq_f32_e32 v2, v2
	s_nop 0
	v_mul_f32_e32 v50, 0x3dd53b94, v2
	v_pk_mul_f32 v[4:5], v[44:45], v[218:219]
	v_pk_mul_f32 v[6:7], v[42:43], v[212:213]
	v_pk_mul_f32 v[2:3], v[46:47], v[216:217]
	v_pk_mul_f32 v[6:7], v[6:7], v[50:51] op_sel_hi:[1,0]
	v_pk_mul_f32 v[8:9], v[40:41], v[214:215]
	v_pk_mul_f32 v[40:41], v[4:5], v[50:51] op_sel_hi:[1,0]
	v_pk_mul_f32 v[4:5], v[2:3], v[50:51] op_sel_hi:[1,0]
	v_cvt_pk_bf16_f32 v2, v6, v7
	v_lshl_add_u64 v[6:7], s[44:45], 0, v[48:49]
	v_pk_mul_f32 v[8:9], v[8:9], v[50:51] op_sel_hi:[1,0]
	v_lshl_add_u64 v[6:7], v[6:7], 0, s[68:69]
	v_cvt_pk_bf16_f32 v3, v8, v9
	v_cvt_pk_bf16_f32 v4, v4, v5
	v_cvt_pk_bf16_f32 v5, v40, v41
	v_lshl_add_u64 v[6:7], v[6:7], 0, v[38:39]
	global_store_dwordx4 v[6:7], v[2:5], off sc0 sc1
	s_nop 1
	ds_read_b128 v[2:5], v51 offset:16
	s_waitcnt lgkmcnt(0)
	v_mov_b32_e32 v8, v3
	v_mov_b32_e32 v9, v4
	v_mov_b32_e32 v3, v5
	v_pk_add_f32 v[2:3], v[8:9], v[2:3]
	s_nop 0
	v_add_f32_e32 v2, v2, v3
	v_fmamk_f32 v2, v2, 0x3c000000, v243
	v_rsq_f32_e32 v2, v2
	s_nop 0
	v_mul_f32_e32 v8, 0x3dd53b94, v2
	v_pk_mul_f32 v[4:5], v[28:29], v[218:219]
	v_pk_mul_f32 v[34:35], v[34:35], v[214:215]
	v_pk_mul_f32 v[36:37], v[36:37], v[212:213]
	v_pk_mul_f32 v[2:3], v[30:31], v[216:217]
	v_pk_mul_f32 v[34:35], v[34:35], v[8:9] op_sel_hi:[1,0]
	v_pk_mul_f32 v[36:37], v[36:37], v[8:9] op_sel_hi:[1,0]
	v_pk_mul_f32 v[28:29], v[4:5], v[8:9] op_sel_hi:[1,0]
	v_pk_mul_f32 v[4:5], v[2:3], v[8:9] op_sel_hi:[1,0]
	v_cvt_pk_bf16_f32 v2, v36, v37
	v_cvt_pk_bf16_f32 v3, v34, v35
	v_cvt_pk_bf16_f32 v4, v4, v5
	v_cvt_pk_bf16_f32 v5, v28, v29
	v_add_u32_e32 v31, s4, v170
	global_store_dwordx4 v[6:7], v[2:5], off offset:256 sc0 sc1
	s_nop 1
	ds_read_b128 v[2:5], v31
	v_lshlrev_b64 v[28:29], 12, v[32:33]
	s_waitcnt lgkmcnt(0)
	v_mov_b32_e32 v6, v3
	v_mov_b32_e32 v7, v4
	v_mov_b32_e32 v3, v5
	v_pk_add_f32 v[2:3], v[6:7], v[2:3]
	s_nop 0
	v_add_f32_e32 v2, v2, v3
	v_fmamk_f32 v2, v2, 0x3c000000, v243
	v_rsq_f32_e32 v2, v2
	s_nop 0
	v_mul_f32_e32 v30, 0x3dd53b94, v2
	v_pk_mul_f32 v[4:5], v[24:25], v[218:219]
	v_pk_mul_f32 v[6:7], v[22:23], v[212:213]
	v_pk_mul_f32 v[2:3], v[26:27], v[216:217]
	v_pk_mul_f32 v[6:7], v[6:7], v[30:31] op_sel_hi:[1,0]
	v_pk_mul_f32 v[8:9], v[20:21], v[214:215]
	v_pk_mul_f32 v[20:21], v[4:5], v[30:31] op_sel_hi:[1,0]
	v_pk_mul_f32 v[4:5], v[2:3], v[30:31] op_sel_hi:[1,0]
	v_cvt_pk_bf16_f32 v2, v6, v7
	v_lshl_add_u64 v[6:7], s[44:45], 0, v[28:29]
	v_pk_mul_f32 v[8:9], v[8:9], v[30:31] op_sel_hi:[1,0]
	v_lshl_add_u64 v[6:7], v[6:7], 0, s[68:69]
	v_cvt_pk_bf16_f32 v3, v8, v9
	v_cvt_pk_bf16_f32 v4, v4, v5
	v_cvt_pk_bf16_f32 v5, v20, v21
	v_lshl_add_u64 v[6:7], v[6:7], 0, v[38:39]
	global_store_dwordx4 v[6:7], v[2:5], off sc0 sc1
	s_nop 1
	ds_read_b128 v[2:5], v31 offset:16
	s_waitcnt lgkmcnt(0)
	v_mov_b32_e32 v8, v3
	v_mov_b32_e32 v9, v4
	v_mov_b32_e32 v3, v5
	v_pk_add_f32 v[2:3], v[8:9], v[2:3]
	s_nop 0
	v_add_f32_e32 v2, v2, v3
	v_fmamk_f32 v2, v2, 0x3c000000, v243
	v_rsq_f32_e32 v2, v2
	s_nop 0
	v_mul_f32_e32 v8, 0x3dd53b94, v2
	v_pk_mul_f32 v[4:5], v[10:11], v[218:219]
	v_pk_mul_f32 v[14:15], v[14:15], v[214:215]
	v_pk_mul_f32 v[16:17], v[16:17], v[212:213]
	v_pk_mul_f32 v[2:3], v[12:13], v[216:217]
	v_pk_mul_f32 v[14:15], v[14:15], v[8:9] op_sel_hi:[1,0]
	v_pk_mul_f32 v[16:17], v[16:17], v[8:9] op_sel_hi:[1,0]
	v_pk_mul_f32 v[10:11], v[4:5], v[8:9] op_sel_hi:[1,0]
	v_pk_mul_f32 v[4:5], v[2:3], v[8:9] op_sel_hi:[1,0]
	v_cvt_pk_bf16_f32 v2, v16, v17
	v_cvt_pk_bf16_f32 v3, v14, v15
	v_cvt_pk_bf16_f32 v4, v4, v5
	v_cvt_pk_bf16_f32 v5, v10, v11
	global_store_dwordx4 v[6:7], v[2:5], off offset:256 sc0 sc1
	s_nop 1
	s_and_b64 vcc, exec, s[40:41]
	s_mov_b64 s[0:1], -1
	s_cbranch_vccnz .LBB0_228

.LBB0_318:
	s_or_b64 exec, exec, s[0:1]
	v_mov_b32_e32 v66, v80
	s_waitcnt lgkmcnt(0)
	v_mov_b32_e32 v67, v80
	v_pk_mul_f32 v[64:65], v[64:65], v[66:67]
	v_pk_mul_f32 v[56:57], v[56:57], v[66:67]
	v_mov_b32_e32 v66, v178
	v_mov_b32_e32 v67, v178
	v_pk_mul_f32 v[60:61], v[60:61], v[66:67]
	v_pk_mul_f32 v[52:53], v[52:53], v[66:67]
	v_mov_b32_e32 v66, v176
	v_mov_b32_e32 v67, v176
	v_pk_mul_f32 v[48:49], v[48:49], v[66:67]
	v_pk_mul_f32 v[44:45], v[44:45], v[66:67]
	v_mov_b32_e32 v66, v174
	v_mov_b32_e32 v67, v174
	v_pk_mul_f32 v[40:41], v[40:41], v[66:67]
	v_pk_mul_f32 v[32:33], v[32:33], v[66:67]
	v_mov_b32_e32 v66, v112
	v_mov_b32_e32 v67, v112
	v_mov_b32_e32 v81, v80
	v_pk_mul_f32 v[36:37], v[36:37], v[66:67]
	v_pk_mul_f32 v[28:29], v[28:29], v[66:67]
	v_mov_b32_e32 v66, v114
	v_mov_b32_e32 v67, v114
	v_mov_b32_e32 v171, v170
	v_pk_mul_f32 v[62:63], v[62:63], v[80:81]
	v_pk_mul_f32 v[54:55], v[54:55], v[80:81]
	v_pk_mul_f32 v[24:25], v[24:25], v[66:67]
	v_pk_mul_f32 v[20:21], v[20:21], v[66:67]
	v_mov_b32_e32 v66, v172
	v_mov_b32_e32 v67, v172
	v_mov_b32_e32 v80, v170
	v_mov_b32_e32 v81, v170
	s_add_i32 s5, 0, 0x20000
	v_pk_mul_f32 v[16:17], v[16:17], v[66:67]
	v_pk_mul_f32 v[12:13], v[12:13], v[66:67]
	v_pk_mul_f32 v[66:67], v[8:9], v[80:81]
	v_pk_mul_f32 v[8:9], v[2:3], v[170:171]
	s_waitcnt lgkmcnt(0)
	s_barrier
	v_lshl_add_u32 v2, v160, 4, s5
	v_pk_mul_f32 v[68:69], v[6:7], v[170:171]
	v_pk_mul_f32 v[6:7], v[4:5], v[80:81]
	ds_read_b128 v[2:5], v2
	v_mov_b32_e32 v115, v114
	v_pk_mul_f32 v[22:23], v[22:23], v[114:115]
	v_pk_mul_f32 v[18:19], v[18:19], v[114:115]
	v_mov_b32_e32 v113, v112
	s_waitcnt lgkmcnt(0)
	v_mov_b32_e32 v114, v3
	v_mov_b32_e32 v115, v4
	v_mov_b32_e32 v3, v5
	v_pk_add_f32 v[2:3], v[114:115], v[2:3]
	v_lshlrev_b32_e32 v80, 3, v183
	v_add_f32_e32 v2, v2, v3
	v_fmamk_f32 v2, v2, 0x3c000000, v243
	v_cmp_gt_f32_e32 vcc, s37, v2
	v_mul_f32_e32 v3, 0x4f800000, v2
	v_pk_mul_f32 v[34:35], v[34:35], v[112:113]
	v_cndmask_b32_e32 v2, v2, v3, vcc
	v_sqrt_f32_e32 v3, v2
	v_pk_mul_f32 v[26:27], v[26:27], v[112:113]
	v_add_u32_e32 v112, s76, v80
	v_ashrrev_i32_e32 v113, 31, v112
	v_add_u32_e32 v4, -1, v3
	v_fma_f32 v5, -v4, v3, v2
	v_cmp_ge_f32_e64 s[42:43], 0, v5
	v_add_u32_e32 v5, 1, v3
	v_mov_b32_e32 v173, v172
	v_cndmask_b32_e64 v4, v3, v4, s[42:43]
	v_fma_f32 v3, -v5, v3, v2
	v_cmp_lt_f32_e64 s[42:43], 0, v3
	v_mov_b32_e32 v175, v174
	v_pk_mul_f32 v[38:39], v[38:39], v[174:175]
	v_cndmask_b32_e64 v3, v4, v5, s[42:43]
	v_mul_f32_e32 v4, 0x37800000, v3
	v_cndmask_b32_e32 v3, v3, v4, vcc
	v_cmp_class_f32_e32 vcc, v2, v241
	v_pk_mul_f32 v[30:31], v[30:31], v[174:175]
	v_pk_mul_f32 v[14:15], v[14:15], v[172:173]
	v_cndmask_b32_e32 v2, v3, v2, vcc
	v_div_scale_f32 v3, s[6:7], v2, v2, 1.0
	v_rcp_f32_e32 v4, v3
	v_pk_mul_f32 v[10:11], v[10:11], v[172:173]
	s_lshl_b32 s10, s4, 7
	s_lshl_b64 s[0:1], s[64:65], 20
	v_fma_f32 v5, -v3, v4, 1.0
	v_fmac_f32_e32 v4, v5, v4
	v_div_scale_f32 v5, vcc, 1.0, v2, 1.0
	v_mul_f32_e32 v81, v5, v4
	v_fma_f32 v114, -v3, v81, v5
	v_fmac_f32_e32 v81, v114, v4
	v_fma_f32 v3, -v3, v81, v5
	v_div_fmas_f32 v3, v3, v4, v81
	v_lshl_add_u64 v[114:115], v[112:113], 2, s[46:47]
	v_div_fixup_f32 v174, v3, v2, 1.0
	global_load_dwordx4 v[212:215], v[114:115], off
	global_load_dwordx4 v[216:219], v[114:115], off offset:16
	s_ashr_i32 s11, s10, 31
	v_readlane_b32 s6, v251, 43
	v_readlane_b32 s7, v251, 44
	s_add_u32 s0, s6, s0
	s_addc_u32 s1, s7, s1
	v_lshlrev_b64 v[160:161], 12, v[160:161]
	v_lshl_add_u64 v[160:161], s[0:1], 0, v[160:161]
	s_lshl_b64 s[10:11], s[10:11], 1
	v_lshl_add_u64 v[160:161], v[160:161], 0, s[10:11]
	v_lshlrev_b64 v[112:113], 1, v[112:113]
	v_lshl_add_u64 v[160:161], v[160:161], 0, v[112:113]
	v_cvt_pk_bf16_f32 v8, v8, v9
	v_cvt_pk_bf16_f32 v14, v14, v15
	v_cvt_pk_bf16_f32 v10, v10, v11
	v_cvt_pk_bf16_f32 v15, v16, v17
	v_cvt_pk_bf16_f32 v11, v12, v13
	v_mov_b32_e32 v177, v176
	v_pk_mul_f32 v[46:47], v[46:47], v[176:177]
	v_mov_b32_e32 v179, v178
	v_pk_mul_f32 v[42:43], v[42:43], v[176:177]
	v_pk_mul_f32 v[58:59], v[58:59], v[178:179]
	v_pk_mul_f32 v[50:51], v[50:51], v[178:179]
	s_waitcnt vmcnt(0)
	v_pk_mul_f32 v[4:5], v[166:167], v[218:219]
	v_pk_mul_f32 v[162:163], v[162:163], v[214:215]
	v_pk_mul_f32 v[164:165], v[164:165], v[212:213]
	v_pk_mul_f32 v[2:3], v[168:169], v[216:217]
	v_pk_mul_f32 v[162:163], v[162:163], v[174:175] op_sel_hi:[1,0]
	v_pk_mul_f32 v[164:165], v[164:165], v[174:175] op_sel_hi:[1,0]
	v_pk_mul_f32 v[166:167], v[4:5], v[174:175] op_sel_hi:[1,0]
	v_pk_mul_f32 v[4:5], v[2:3], v[174:175] op_sel_hi:[1,0]
	v_cvt_pk_bf16_f32 v2, v164, v165
	v_cvt_pk_bf16_f32 v3, v162, v163
	v_cvt_pk_bf16_f32 v4, v4, v5
	v_cvt_pk_bf16_f32 v5, v166, v167
	global_store_dwordx4 v[160:161], v[2:5], off sc0 sc1
	s_nop 1
	s_nop 1
	v_lshl_add_u32 v2, v150, 4, s5
	ds_read_b128 v[2:5], v2
	v_lshlrev_b64 v[150:151], 12, v[150:151]
	v_lshl_add_u64 v[150:151], s[0:1], 0, v[150:151]
	v_lshl_add_u64 v[150:151], v[150:151], 0, s[10:11]
	v_lshl_add_u64 v[150:151], v[150:151], 0, v[112:113]
	s_waitcnt lgkmcnt(0)
	v_mov_b32_e32 v160, v3
	v_mov_b32_e32 v161, v4
	v_mov_b32_e32 v3, v5
	v_pk_add_f32 v[2:3], v[160:161], v[2:3]
	s_nop 0
	v_add_f32_e32 v2, v2, v3
	v_fmamk_f32 v2, v2, 0x3c000000, v243
	v_rsq_f32_e32 v164, v2
	s_nop 0
	v_pk_mul_f32 v[4:5], v[156:157], v[218:219]
	v_pk_mul_f32 v[152:153], v[152:153], v[214:215]
	v_pk_mul_f32 v[154:155], v[154:155], v[212:213]
	v_pk_mul_f32 v[2:3], v[158:159], v[216:217]
	v_pk_mul_f32 v[152:153], v[152:153], v[164:165] op_sel_hi:[1,0]
	v_pk_mul_f32 v[154:155], v[154:155], v[164:165] op_sel_hi:[1,0]
	v_pk_mul_f32 v[156:157], v[4:5], v[164:165] op_sel_hi:[1,0]
	v_pk_mul_f32 v[4:5], v[2:3], v[164:165] op_sel_hi:[1,0]
	v_cvt_pk_bf16_f32 v2, v154, v155
	v_cvt_pk_bf16_f32 v3, v152, v153
	v_cvt_pk_bf16_f32 v4, v4, v5
	v_cvt_pk_bf16_f32 v5, v156, v157
	global_store_dwordx4 v[150:151], v[2:5], off sc0 sc1
	s_nop 1
	s_nop 1
	v_lshl_add_u32 v2, v126, 4, s5
	ds_read_b128 v[2:5], v2
	v_lshlrev_b64 v[126:127], 12, v[126:127]
	v_lshl_add_u64 v[126:127], s[0:1], 0, v[126:127]
	v_lshl_add_u64 v[126:127], v[126:127], 0, s[10:11]
	v_lshl_add_u64 v[126:127], v[126:127], 0, v[112:113]
	s_waitcnt lgkmcnt(0)
	v_mov_b32_e32 v150, v3
	v_mov_b32_e32 v151, v4
	v_mov_b32_e32 v3, v5
	v_pk_add_f32 v[2:3], v[150:151], v[2:3]
	s_nop 0
	v_add_f32_e32 v2, v2, v3
	v_fmamk_f32 v2, v2, 0x3c000000, v243
	v_rsq_f32_e32 v150, v2
	s_nop 0
	v_pk_mul_f32 v[4:5], v[146:147], v[218:219]
	v_pk_mul_f32 v[128:129], v[128:129], v[214:215]
	v_pk_mul_f32 v[144:145], v[144:145], v[212:213]
	v_pk_mul_f32 v[2:3], v[148:149], v[216:217]
	v_pk_mul_f32 v[128:129], v[128:129], v[150:151] op_sel_hi:[1,0]
	v_pk_mul_f32 v[144:145], v[144:145], v[150:151] op_sel_hi:[1,0]
	v_pk_mul_f32 v[146:147], v[4:5], v[150:151] op_sel_hi:[1,0]
	v_pk_mul_f32 v[4:5], v[2:3], v[150:151] op_sel_hi:[1,0]
	v_cvt_pk_bf16_f32 v2, v144, v145
	v_cvt_pk_bf16_f32 v3, v128, v129
	v_cvt_pk_bf16_f32 v4, v4, v5
	v_cvt_pk_bf16_f32 v5, v146, v147
	global_store_dwordx4 v[126:127], v[2:5], off sc0 sc1
	s_nop 1
	s_nop 1
	v_lshl_add_u32 v2, v116, 4, s5
	ds_read_b128 v[2:5], v2
	v_lshlrev_b64 v[116:117], 12, v[116:117]
	v_lshl_add_u64 v[116:117], s[0:1], 0, v[116:117]
	v_lshl_add_u64 v[116:117], v[116:117], 0, s[10:11]
	v_lshl_add_u64 v[116:117], v[116:117], 0, v[112:113]
	s_waitcnt lgkmcnt(0)
	v_mov_b32_e32 v126, v3
	v_mov_b32_e32 v127, v4
	v_mov_b32_e32 v3, v5
	v_pk_add_f32 v[2:3], v[126:127], v[2:3]
	s_nop 0
	v_add_f32_e32 v2, v2, v3
	v_fmamk_f32 v2, v2, 0x3c000000, v243
	v_rsq_f32_e32 v144, v2
	s_nop 0
	v_pk_mul_f32 v[4:5], v[122:123], v[218:219]
	v_pk_mul_f32 v[118:119], v[118:119], v[214:215]
	v_pk_mul_f32 v[120:121], v[120:121], v[212:213]
	v_pk_mul_f32 v[2:3], v[124:125], v[216:217]
	v_pk_mul_f32 v[118:119], v[118:119], v[144:145] op_sel_hi:[1,0]
	v_pk_mul_f32 v[120:121], v[120:121], v[144:145] op_sel_hi:[1,0]
	v_pk_mul_f32 v[122:123], v[4:5], v[144:145] op_sel_hi:[1,0]
	v_pk_mul_f32 v[4:5], v[2:3], v[144:145] op_sel_hi:[1,0]
	v_cvt_pk_bf16_f32 v2, v120, v121
	v_cvt_pk_bf16_f32 v3, v118, v119
	v_cvt_pk_bf16_f32 v4, v4, v5
	v_cvt_pk_bf16_f32 v5, v122, v123
	global_store_dwordx4 v[116:117], v[2:5], off sc0 sc1
	s_nop 1
	s_nop 1
	v_lshl_add_u32 v2, v98, 4, s5
	ds_read_b128 v[2:5], v2
	v_lshlrev_b64 v[98:99], 12, v[98:99]
	v_lshl_add_u64 v[98:99], s[0:1], 0, v[98:99]
	v_lshl_add_u64 v[98:99], v[98:99], 0, s[10:11]
	v_lshl_add_u64 v[98:99], v[98:99], 0, v[112:113]
	s_waitcnt lgkmcnt(0)
	v_mov_b32_e32 v116, v3
	v_mov_b32_e32 v117, v4
	v_mov_b32_e32 v3, v5
	v_pk_add_f32 v[2:3], v[116:117], v[2:3]
	s_nop 0
	v_add_f32_e32 v2, v2, v3
	v_fmamk_f32 v2, v2, 0x3c000000, v243
	v_rsq_f32_e32 v116, v2
	s_nop 0
	v_pk_mul_f32 v[4:5], v[108:109], v[218:219]
	v_pk_mul_f32 v[104:105], v[104:105], v[214:215]
	v_pk_mul_f32 v[106:107], v[106:107], v[212:213]
	v_pk_mul_f32 v[2:3], v[110:111], v[216:217]
	v_pk_mul_f32 v[104:105], v[104:105], v[116:117] op_sel_hi:[1,0]
	v_pk_mul_f32 v[106:107], v[106:107], v[116:117] op_sel_hi:[1,0]
	v_pk_mul_f32 v[108:109], v[4:5], v[116:117] op_sel_hi:[1,0]
	v_pk_mul_f32 v[4:5], v[2:3], v[116:117] op_sel_hi:[1,0]
	v_cvt_pk_bf16_f32 v2, v106, v107
	v_cvt_pk_bf16_f32 v3, v104, v105
	v_cvt_pk_bf16_f32 v4, v4, v5
	v_cvt_pk_bf16_f32 v5, v108, v109
	global_store_dwordx4 v[98:99], v[2:5], off sc0 sc1
	s_nop 1
	s_nop 1
	v_lshl_add_u32 v2, v90, 4, s5
	ds_read_b128 v[2:5], v2
	v_lshlrev_b64 v[90:91], 12, v[90:91]
	v_lshl_add_u64 v[90:91], s[0:1], 0, v[90:91]
	v_lshl_add_u64 v[90:91], v[90:91], 0, s[10:11]
	v_lshl_add_u64 v[90:91], v[90:91], 0, v[112:113]
	s_waitcnt lgkmcnt(0)
	v_mov_b32_e32 v98, v3
	v_mov_b32_e32 v99, v4
	v_mov_b32_e32 v3, v5
	v_pk_add_f32 v[2:3], v[98:99], v[2:3]
	s_nop 0
	v_add_f32_e32 v2, v2, v3
	v_fmamk_f32 v2, v2, 0x3c000000, v243
	v_rsq_f32_e32 v98, v2
	s_nop 0
	v_pk_mul_f32 v[4:5], v[100:101], v[218:219]
	v_pk_mul_f32 v[94:95], v[94:95], v[214:215]
	v_pk_mul_f32 v[96:97], v[96:97], v[212:213]
	v_pk_mul_f32 v[2:3], v[102:103], v[216:217]
	v_pk_mul_f32 v[94:95], v[94:95], v[98:99] op_sel_hi:[1,0]
	v_pk_mul_f32 v[96:97], v[96:97], v[98:99] op_sel_hi:[1,0]
	v_pk_mul_f32 v[100:101], v[4:5], v[98:99] op_sel_hi:[1,0]
	v_pk_mul_f32 v[4:5], v[2:3], v[98:99] op_sel_hi:[1,0]
	v_cvt_pk_bf16_f32 v2, v96, v97
	v_cvt_pk_bf16_f32 v3, v94, v95
	v_cvt_pk_bf16_f32 v4, v4, v5
	v_cvt_pk_bf16_f32 v5, v100, v101
	global_store_dwordx4 v[90:91], v[2:5], off sc0 sc1
	s_nop 1
	s_nop 1
	v_lshl_add_u32 v2, v82, 4, s5
	ds_read_b128 v[2:5], v2
	v_lshlrev_b64 v[82:83], 12, v[82:83]
	v_lshl_add_u64 v[82:83], s[0:1], 0, v[82:83]
	v_lshl_add_u64 v[82:83], v[82:83], 0, s[10:11]
	v_lshl_add_u64 v[82:83], v[82:83], 0, v[112:113]
	s_waitcnt lgkmcnt(0)
	v_mov_b32_e32 v90, v3
	v_mov_b32_e32 v91, v4
	v_mov_b32_e32 v3, v5
	v_pk_add_f32 v[2:3], v[90:91], v[2:3]
	s_nop 0
	v_add_f32_e32 v2, v2, v3
	v_fmamk_f32 v2, v2, 0x3c000000, v243
	v_rsq_f32_e32 v90, v2
	s_nop 0
	v_pk_mul_f32 v[4:5], v[88:89], v[218:219]
	v_pk_mul_f32 v[84:85], v[84:85], v[214:215]
	v_pk_mul_f32 v[86:87], v[86:87], v[212:213]
	v_pk_mul_f32 v[2:3], v[92:93], v[216:217]
	v_pk_mul_f32 v[84:85], v[84:85], v[90:91] op_sel_hi:[1,0]
	v_pk_mul_f32 v[86:87], v[86:87], v[90:91] op_sel_hi:[1,0]
	v_pk_mul_f32 v[88:89], v[4:5], v[90:91] op_sel_hi:[1,0]
	v_pk_mul_f32 v[4:5], v[2:3], v[90:91] op_sel_hi:[1,0]
	v_cvt_pk_bf16_f32 v2, v86, v87
	v_cvt_pk_bf16_f32 v3, v84, v85
	v_cvt_pk_bf16_f32 v4, v4, v5
	v_cvt_pk_bf16_f32 v5, v88, v89
	global_store_dwordx4 v[82:83], v[2:5], off sc0 sc1
	s_nop 1
	s_nop 1
	v_add_u32_e32 v2, s5, v143
	ds_read_b128 v[2:5], v2
	v_ashrrev_i32_e32 v143, 31, v142
	s_waitcnt lgkmcnt(0)
	v_mov_b32_e32 v82, v3
	v_mov_b32_e32 v83, v4
	v_mov_b32_e32 v3, v5
	v_pk_add_f32 v[2:3], v[82:83], v[2:3]
	s_nop 0
	v_add_f32_e32 v2, v2, v3
	v_fmamk_f32 v2, v2, 0x3c000000, v243
	v_rsq_f32_e32 v86, v2
	s_nop 0
	v_ashrrev_i32_e32 v81, 31, v80
	v_pk_mul_f32 v[4:5], v[76:77], v[218:219]
	v_pk_mul_f32 v[70:71], v[70:71], v[212:213]
	v_pk_mul_f32 v[2:3], v[78:79], v[216:217]
	v_pk_mul_f32 v[70:71], v[70:71], v[86:87] op_sel_hi:[1,0]
	v_pk_mul_f32 v[76:77], v[4:5], v[86:87] op_sel_hi:[1,0]
	v_pk_mul_f32 v[4:5], v[2:3], v[86:87] op_sel_hi:[1,0]
	v_cvt_pk_bf16_f32 v2, v70, v71
	v_lshlrev_b64 v[70:71], 12, v[74:75]
	v_pk_mul_f32 v[72:73], v[72:73], v[214:215]
	v_lshl_add_u64 v[70:71], s[0:1], 0, v[70:71]
	s_lshl_b64 s[0:1], s[64:65], 8
	v_pk_mul_f32 v[72:73], v[72:73], v[86:87] op_sel_hi:[1,0]
	v_lshl_add_u64 v[70:71], v[70:71], 0, s[10:11]
	s_add_u32 s0, s0, s68
	v_cvt_pk_bf16_f32 v3, v72, v73
	v_cvt_pk_bf16_f32 v4, v4, v5
	v_cvt_pk_bf16_f32 v5, v76, v77
	v_lshl_add_u64 v[70:71], v[70:71], 0, v[112:113]
	s_addc_u32 s1, s1, s70
	global_store_dwordx4 v[70:71], v[2:5], off sc0 sc1
	s_nop 1
	v_lshl_add_u64 v[70:71], v[80:81], 0, s[76:77]
	v_lshlrev_b64 v[70:71], 13, v[70:71]
	v_lshl_add_u64 v[2:3], s[0:1], 0, v[142:143]
	v_alignbit_b32 v3, v3, v2, 8
	v_and_b32_e32 v3, -16, v3
	v_add_u32_e32 v4, s4, v3
	v_ashrrev_i32_e32 v5, 31, v4
	v_readlane_b32 s0, v251, 51
	v_lshlrev_b64 v[4:5], 20, v[4:5]
	v_readlane_b32 s1, v251, 52
	v_and_b32_e32 v72, 0xff0, v2
	v_and_b32_e32 v73, 3, v142
	v_lshl_add_u64 v[4:5], s[0:1], 0, v[4:5]
	v_lshl_add_u64 v[4:5], v[4:5], 0, v[70:71]
	v_lshlrev_b32_e32 v70, 1, v72
	v_mov_b32_e32 v71, v0
	v_lshl_add_u64 v[4:5], v[4:5], 0, v[70:71]
	v_and_b32_e32 v70, 8, v142
	v_lshl_add_u64 v[4:5], v[4:5], 0, v[70:71]
	v_lshlrev_b32_e32 v70, 1, v73
	v_lshlrev_b32_e32 v2, 2, v2
	v_lshl_add_u64 v[4:5], v[4:5], 0, v[70:71]
	v_and_b32_e32 v2, 16, v2
	v_mov_b32_e32 v3, v0
	v_lshl_add_u64 v[70:71], v[4:5], 0, v[2:3]
	s_movk_i32 s0, 0x2000
	v_cvt_pk_bf16_f32 v3, v66, v67
	v_add_co_u32_e32 v66, vcc, s0, v70
	s_movk_i32 s0, 0x4000
	s_nop 0
	v_addc_co_u32_e32 v67, vcc, 0, v71, vcc
	v_cvt_pk_bf16_f32 v2, v68, v69
	v_add_co_u32_e32 v68, vcc, s0, v70
	s_movk_i32 s0, 0x6000
	s_nop 0
	v_addc_co_u32_e32 v69, vcc, 0, v71, vcc
	v_add_co_u32_e32 v72, vcc, s0, v70
	s_mov_b32 s0, 0x8000
	s_nop 0
	v_addc_co_u32_e32 v73, vcc, 0, v71, vcc
	global_store_short v[70:71], v2, off
	global_store_short_d16_hi v[66:67], v2, off
	v_add_co_u32_e32 v2, vcc, s0, v70
	global_store_short v[68:69], v3, off
	global_store_short_d16_hi v[72:73], v3, off
	v_addc_co_u32_e32 v3, vcc, 0, v71, vcc
	s_mov_b32 s0, 0xa000
	v_add_co_u32_e32 v4, vcc, s0, v70
	s_mov_b32 s0, 0xc000
	s_nop 0
	v_addc_co_u32_e32 v5, vcc, 0, v71, vcc
	v_cvt_pk_bf16_f32 v74, v6, v7
	v_add_co_u32_e32 v6, vcc, s0, v70
	s_mov_b32 s0, 0xe000
	s_nop 0
	v_addc_co_u32_e32 v7, vcc, 0, v71, vcc
	global_store_short v[2:3], v8, off
	global_store_short_d16_hi v[4:5], v8, off
	v_add_co_u32_e32 v8, vcc, s0, v70
	global_store_short v[6:7], v74, off
	s_nop 0
	v_addc_co_u32_e32 v9, vcc, 0, v71, vcc
	global_store_short_d16_hi v[8:9], v74, off
	global_store_short v[70:71], v14, off offset:32
	global_store_short_d16_hi v[66:67], v14, off offset:32
	global_store_short v[68:69], v15, off offset:32
	global_store_short_d16_hi v[72:73], v15, off offset:32
	global_store_short v[2:3], v10, off offset:32
	global_store_short_d16_hi v[4:5], v10, off offset:32
	global_store_short v[6:7], v11, off offset:32
	global_store_short_d16_hi v[8:9], v11, off offset:32
	v_cvt_pk_bf16_f32 v10, v22, v23
	v_cvt_pk_bf16_f32 v11, v24, v25
	global_store_short v[70:71], v10, off offset:64
	global_store_short_d16_hi v[66:67], v10, off offset:64
	global_store_short v[68:69], v11, off offset:64
	global_store_short_d16_hi v[72:73], v11, off offset:64
	v_cvt_pk_bf16_f32 v10, v18, v19
	v_cvt_pk_bf16_f32 v11, v20, v21
	global_store_short v[2:3], v10, off offset:64
	global_store_short_d16_hi v[4:5], v10, off offset:64
	global_store_short v[6:7], v11, off offset:64
	global_store_short_d16_hi v[8:9], v11, off offset:64
	v_cvt_pk_bf16_f32 v10, v34, v35
	v_cvt_pk_bf16_f32 v11, v36, v37
	global_store_short v[70:71], v10, off offset:96
	global_store_short_d16_hi v[66:67], v10, off offset:96
	global_store_short v[68:69], v11, off offset:96
	global_store_short_d16_hi v[72:73], v11, off offset:96
	v_cvt_pk_bf16_f32 v10, v26, v27
	v_cvt_pk_bf16_f32 v11, v28, v29
	global_store_short v[2:3], v10, off offset:96
	global_store_short_d16_hi v[4:5], v10, off offset:96
	global_store_short v[6:7], v11, off offset:96
	global_store_short_d16_hi v[8:9], v11, off offset:96
	v_cvt_pk_bf16_f32 v10, v38, v39
	v_cvt_pk_bf16_f32 v11, v40, v41
	global_store_short v[70:71], v10, off offset:256
	global_store_short_d16_hi v[66:67], v10, off offset:256
	global_store_short v[68:69], v11, off offset:256
	global_store_short_d16_hi v[72:73], v11, off offset:256
	v_cvt_pk_bf16_f32 v10, v30, v31
	v_cvt_pk_bf16_f32 v11, v32, v33
	global_store_short v[2:3], v10, off offset:256
	global_store_short_d16_hi v[4:5], v10, off offset:256
	global_store_short v[6:7], v11, off offset:256
	global_store_short_d16_hi v[8:9], v11, off offset:256
	v_cvt_pk_bf16_f32 v10, v46, v47
	v_cvt_pk_bf16_f32 v11, v48, v49
	global_store_short v[70:71], v10, off offset:288
	global_store_short_d16_hi v[66:67], v10, off offset:288
	global_store_short v[68:69], v11, off offset:288
	global_store_short_d16_hi v[72:73], v11, off offset:288
	v_cvt_pk_bf16_f32 v10, v42, v43
	v_cvt_pk_bf16_f32 v11, v44, v45
	global_store_short v[2:3], v10, off offset:288
	global_store_short_d16_hi v[4:5], v10, off offset:288
	global_store_short v[6:7], v11, off offset:288
	global_store_short_d16_hi v[8:9], v11, off offset:288
	v_cvt_pk_bf16_f32 v10, v58, v59
	v_cvt_pk_bf16_f32 v11, v60, v61
	global_store_short v[70:71], v10, off offset:320
	global_store_short_d16_hi v[66:67], v10, off offset:320
	global_store_short v[68:69], v11, off offset:320
	global_store_short_d16_hi v[72:73], v11, off offset:320
	v_cvt_pk_bf16_f32 v10, v50, v51
	v_cvt_pk_bf16_f32 v11, v52, v53
	global_store_short v[2:3], v10, off offset:320
	global_store_short_d16_hi v[4:5], v10, off offset:320
	global_store_short v[6:7], v11, off offset:320
	global_store_short_d16_hi v[8:9], v11, off offset:320
	v_cvt_pk_bf16_f32 v10, v62, v63
	v_cvt_pk_bf16_f32 v11, v64, v65
	global_store_short v[70:71], v10, off offset:352
	global_store_short_d16_hi v[66:67], v10, off offset:352
	global_store_short v[68:69], v11, off offset:352
	global_store_short_d16_hi v[72:73], v11, off offset:352
	v_cvt_pk_bf16_f32 v10, v54, v55
	s_mov_b64 s[0:1], -1
	s_and_b64 vcc, exec, s[40:41]
	v_cvt_pk_bf16_f32 v11, v56, v57
	global_store_short v[2:3], v10, off offset:352
	global_store_short_d16_hi v[4:5], v10, off offset:352
	global_store_short v[6:7], v11, off offset:352
	global_store_short_d16_hi v[8:9], v11, off offset:352
	s_cbranch_vccnz .LBB0_286
	s_andn2_b64 vcc, exec, s[54:55]
	s_cbranch_vccnz .LBB0_285
	s_barrier
	s_branch .LBB0_285

.LBB0_378:
	s_waitcnt vmcnt(30)
	ds_write2_b32 v37, v4, v5 offset1:65
	s_waitcnt vmcnt(28)
	ds_write2_b32 v37, v6, v7 offset0:130 offset1:195
	v_add_u32_e32 v4, 0x400, v37
	s_waitcnt vmcnt(26)
	ds_write2_b32 v4, v8, v9 offset0:4 offset1:69
	s_waitcnt vmcnt(24)
	ds_write2_b32 v4, v10, v11 offset0:134 offset1:199
	v_add_u32_e32 v4, 0x800, v37
	s_waitcnt vmcnt(22)
	ds_write2_b32 v4, v12, v13 offset0:8 offset1:73
	s_waitcnt vmcnt(20)
	ds_write2_b32 v4, v14, v15 offset0:138 offset1:203
	v_add_u32_e32 v4, 0xc00, v37
	s_waitcnt vmcnt(18)
	ds_write2_b32 v4, v16, v17 offset0:12 offset1:77
	s_waitcnt vmcnt(16)
	ds_write2_b32 v4, v18, v19 offset0:142 offset1:207
	v_add_u32_e32 v4, 0x1000, v37
	s_waitcnt vmcnt(14)
	ds_write2_b32 v4, v20, v21 offset0:16 offset1:81
	s_waitcnt vmcnt(12)
	ds_write2_b32 v4, v22, v23 offset0:146 offset1:211
	v_add_u32_e32 v4, 0x1400, v37
	s_waitcnt vmcnt(10)
	ds_write2_b32 v4, v24, v25 offset0:20 offset1:85
	s_waitcnt vmcnt(8)
	ds_write2_b32 v4, v26, v27 offset0:150 offset1:215
	v_add_u32_e32 v4, 0x1800, v37
	s_waitcnt vmcnt(6)
	ds_write2_b32 v4, v28, v29 offset0:24 offset1:89
	s_waitcnt vmcnt(4)
	ds_write2_b32 v4, v30, v31 offset0:154 offset1:219
	v_add_u32_e32 v4, 0x1c00, v37
	s_waitcnt vmcnt(2)
	ds_write2_b32 v4, v32, v33 offset0:28 offset1:93
	s_waitcnt vmcnt(0)
	ds_write2_b32 v4, v34, v35 offset0:158 offset1:223
	s_waitcnt lgkmcnt(0)
	v_add_u32_e32 v30, 0x400, v39
	ds_read2_b32 v[8:9], v39 offset1:16
	ds_read2_b32 v[10:11], v39 offset0:65 offset1:81
	ds_read2_b32 v[12:13], v39 offset0:130 offset1:146
	ds_read2_b32 v[14:15], v39 offset0:195 offset1:211
	ds_read2_b32 v[16:17], v30 offset0:4 offset1:20
	ds_read2_b32 v[18:19], v30 offset0:69 offset1:85
	ds_read2_b32 v[20:21], v30 offset0:134 offset1:150
	ds_read2_b32 v[22:23], v30 offset0:199 offset1:215
	v_add_u32_e32 v26, s15, v38
	v_ashrrev_i32_e32 v27, 31, v26
	v_lshl_add_u64 v[24:25], s[12:13], 1, v[2:3]
	v_lshlrev_b64 v[28:29], 11, v[26:27]
	s_waitcnt lgkmcnt(6)
	v_cvt_pk_bf16_f32 v4, v8, v10
	s_waitcnt lgkmcnt(4)
	v_cvt_pk_bf16_f32 v5, v12, v14
	s_waitcnt lgkmcnt(2)
	v_cvt_pk_bf16_f32 v6, v16, v18
	s_waitcnt lgkmcnt(0)
	v_cvt_pk_bf16_f32 v7, v20, v22
	v_lshl_add_u64 v[28:29], v[24:25], 0, v[28:29]
	v_add_u32_e32 v8, 16, v26
	global_store_dwordx4 v[28:29], v[4:7], off sc0 sc1
	s_add_i32 s14, s14, s89
	s_add_i32 s6, s6, s7
	v_cvt_pk_bf16_f32 v4, v9, v11
	v_ashrrev_i32_e32 v9, 31, v8
	v_cvt_pk_bf16_f32 v5, v13, v15
	v_cvt_pk_bf16_f32 v6, v17, v19
	v_cvt_pk_bf16_f32 v7, v21, v23
	v_lshlrev_b64 v[8:9], 11, v[8:9]
	ds_read2_b32 v[10:11], v39 offset0:32 offset1:48
	ds_read2_b32 v[12:13], v39 offset0:97 offset1:113
	ds_read2_b32 v[14:15], v39 offset0:162 offset1:178
	ds_read2_b32 v[16:17], v39 offset0:227 offset1:243
	ds_read2_b32 v[18:19], v30 offset0:36 offset1:52
	ds_read2_b32 v[20:21], v30 offset0:101 offset1:117
	ds_read2_b32 v[22:23], v30 offset0:166 offset1:182
	ds_read2_b32 v[28:29], v30 offset0:231 offset1:247
	v_lshl_add_u64 v[8:9], v[24:25], 0, v[8:9]
	global_store_dwordx4 v[8:9], v[4:7], off sc0 sc1
	v_add_u32_e32 v8, 32, v26
	v_ashrrev_i32_e32 v9, 31, v8
	v_lshlrev_b64 v[8:9], 11, v[8:9]
	s_waitcnt lgkmcnt(6)
	v_cvt_pk_bf16_f32 v4, v10, v12
	s_waitcnt lgkmcnt(4)
	v_cvt_pk_bf16_f32 v5, v14, v16
	s_waitcnt lgkmcnt(2)
	v_cvt_pk_bf16_f32 v6, v18, v20
	s_waitcnt lgkmcnt(0)
	v_cvt_pk_bf16_f32 v7, v22, v28
	v_lshl_add_u64 v[8:9], v[24:25], 0, v[8:9]
	global_store_dwordx4 v[8:9], v[4:7], off sc0 sc1
	v_add_u32_e32 v8, 48, v26
	v_ashrrev_i32_e32 v9, 31, v8
	v_lshlrev_b64 v[8:9], 11, v[8:9]
	v_cvt_pk_bf16_f32 v4, v11, v13
	v_cvt_pk_bf16_f32 v5, v15, v17
	v_cvt_pk_bf16_f32 v6, v19, v21
	v_cvt_pk_bf16_f32 v7, v23, v29
	v_lshl_add_u64 v[8:9], v[24:25], 0, v[8:9]
	global_store_dwordx4 v[8:9], v[4:7], off sc0 sc1
	s_waitcnt lgkmcnt(0)
	s_add_i32 s8, s8, s9
	s_cmpk_lt_i32 s14, 0xb00
	s_cbranch_scc0 .LBB0_381

.LBB0_384:
	s_ashr_i32 s7, s6, 31
	s_lshr_b32 s7, s7, 28
	s_add_i32 s7, s6, s7
	s_ashr_i32 s7, s7, 4
	s_lshl_b32 s10, s7, 5
	s_lshl_b32 s7, s7, 10
	s_sub_i32 s7, s4, s7
	v_add_u32_e32 v4, s7, v8
	v_ashrrev_i32_e32 v5, 31, v4
	s_ashr_i32 s11, s10, 31
	v_lshl_add_u64 v[4:5], v[4:5], 2, s[0:1]
	s_lshl_b64 s[8:9], s[10:11], 12
	v_lshl_add_u64 v[10:11], v[4:5], 0, s[8:9]
	s_or_b32 s8, s10, 1
	s_ashr_i32 s9, s8, 31
	s_lshl_b64 s[8:9], s[8:9], 12
	global_load_dword v9, v[10:11], off
	v_lshl_add_u64 v[10:11], v[4:5], 0, s[8:9]
	s_or_b32 s8, s10, 2
	s_ashr_i32 s9, s8, 31
	s_lshl_b64 s[8:9], s[8:9], 12
	v_lshl_add_u64 v[12:13], v[4:5], 0, s[8:9]
	s_or_b32 s8, s10, 3
	s_ashr_i32 s9, s8, 31
	s_lshl_b64 s[8:9], s[8:9], 12
	global_load_dword v10, v[10:11], off
	s_or_b32 s12, s10, 31
	global_load_dword v11, v[12:13], off
	v_lshl_add_u64 v[12:13], v[4:5], 0, s[8:9]
	s_or_b32 s8, s10, 4
	s_ashr_i32 s9, s8, 31
	s_lshl_b64 s[8:9], s[8:9], 12
	v_lshl_add_u64 v[14:15], v[4:5], 0, s[8:9]
	s_or_b32 s8, s10, 5
	s_ashr_i32 s9, s8, 31
	s_lshl_b64 s[8:9], s[8:9], 12
	global_load_dword v12, v[12:13], off
	s_ashr_i32 s13, s12, 31
	global_load_dword v13, v[14:15], off
	v_lshl_add_u64 v[14:15], v[4:5], 0, s[8:9]
	s_or_b32 s8, s10, 6
	s_ashr_i32 s9, s8, 31
	s_lshl_b64 s[8:9], s[8:9], 12
	v_lshl_add_u64 v[16:17], v[4:5], 0, s[8:9]
	s_or_b32 s8, s10, 7
	s_ashr_i32 s9, s8, 31
	s_lshl_b64 s[8:9], s[8:9], 12
	global_load_dword v14, v[14:15], off
	s_lshl_b64 s[12:13], s[12:13], 12
	global_load_dword v15, v[16:17], off
	v_lshl_add_u64 v[16:17], v[4:5], 0, s[8:9]
	s_or_b32 s8, s10, 8
	s_ashr_i32 s9, s8, 31
	s_lshl_b64 s[8:9], s[8:9], 12
	v_lshl_add_u64 v[18:19], v[4:5], 0, s[8:9]
	s_or_b32 s8, s10, 9
	s_ashr_i32 s9, s8, 31
	s_lshl_b64 s[8:9], s[8:9], 12
	global_load_dword v16, v[16:17], off
	s_add_i32 s6, s6, s89
	global_load_dword v17, v[18:19], off
	v_lshl_add_u64 v[18:19], v[4:5], 0, s[8:9]
	s_or_b32 s8, s10, 10
	s_ashr_i32 s9, s8, 31
	s_lshl_b64 s[8:9], s[8:9], 12
	v_lshl_add_u64 v[20:21], v[4:5], 0, s[8:9]
	s_or_b32 s8, s10, 11
	s_ashr_i32 s9, s8, 31
	s_lshl_b64 s[8:9], s[8:9], 12
	global_load_dword v18, v[18:19], off
	s_add_i32 s4, s4, s5
	global_load_dword v19, v[20:21], off
	v_lshl_add_u64 v[20:21], v[4:5], 0, s[8:9]
	s_or_b32 s8, s10, 12
	s_ashr_i32 s9, s8, 31
	s_lshl_b64 s[8:9], s[8:9], 12
	v_lshl_add_u64 v[22:23], v[4:5], 0, s[8:9]
	s_or_b32 s8, s10, 13
	s_ashr_i32 s9, s8, 31
	s_lshl_b64 s[8:9], s[8:9], 12
	global_load_dword v20, v[20:21], off
	s_nop 0
	global_load_dword v21, v[22:23], off
	v_lshl_add_u64 v[22:23], v[4:5], 0, s[8:9]
	s_or_b32 s8, s10, 14
	s_ashr_i32 s9, s8, 31
	s_lshl_b64 s[8:9], s[8:9], 12
	v_lshl_add_u64 v[24:25], v[4:5], 0, s[8:9]
	s_or_b32 s8, s10, 15
	s_ashr_i32 s9, s8, 31
	s_lshl_b64 s[8:9], s[8:9], 12
	global_load_dword v22, v[22:23], off
	s_nop 0
	global_load_dword v23, v[24:25], off
	v_lshl_add_u64 v[24:25], v[4:5], 0, s[8:9]
	s_or_b32 s8, s10, 16
	s_ashr_i32 s9, s8, 31
	s_lshl_b64 s[8:9], s[8:9], 12
	v_lshl_add_u64 v[26:27], v[4:5], 0, s[8:9]
	s_or_b32 s8, s10, 17
	s_ashr_i32 s9, s8, 31
	s_lshl_b64 s[8:9], s[8:9], 12
	global_load_dword v24, v[24:25], off
	s_nop 0
	global_load_dword v25, v[26:27], off
	v_lshl_add_u64 v[26:27], v[4:5], 0, s[8:9]
	s_or_b32 s8, s10, 18
	s_ashr_i32 s9, s8, 31
	s_lshl_b64 s[8:9], s[8:9], 12
	v_lshl_add_u64 v[28:29], v[4:5], 0, s[8:9]
	s_or_b32 s8, s10, 19
	s_ashr_i32 s9, s8, 31
	s_lshl_b64 s[8:9], s[8:9], 12
	global_load_dword v26, v[26:27], off
	s_nop 0
	global_load_dword v27, v[28:29], off
	v_lshl_add_u64 v[28:29], v[4:5], 0, s[8:9]
	s_or_b32 s8, s10, 20
	s_ashr_i32 s9, s8, 31
	s_lshl_b64 s[8:9], s[8:9], 12
	v_lshl_add_u64 v[30:31], v[4:5], 0, s[8:9]
	s_or_b32 s8, s10, 21
	s_ashr_i32 s9, s8, 31
	s_lshl_b64 s[8:9], s[8:9], 12
	global_load_dword v28, v[28:29], off
	s_nop 0
	global_load_dword v29, v[30:31], off
	v_lshl_add_u64 v[30:31], v[4:5], 0, s[8:9]
	s_or_b32 s8, s10, 22
	s_ashr_i32 s9, s8, 31
	s_lshl_b64 s[8:9], s[8:9], 12
	v_lshl_add_u64 v[32:33], v[4:5], 0, s[8:9]
	s_or_b32 s8, s10, 23
	s_ashr_i32 s9, s8, 31
	s_lshl_b64 s[8:9], s[8:9], 12
	global_load_dword v30, v[30:31], off
	s_nop 0
	global_load_dword v31, v[32:33], off
	v_lshl_add_u64 v[32:33], v[4:5], 0, s[8:9]
	s_or_b32 s8, s10, 24
	s_ashr_i32 s9, s8, 31
	s_lshl_b64 s[8:9], s[8:9], 12
	v_lshl_add_u64 v[34:35], v[4:5], 0, s[8:9]
	s_or_b32 s8, s10, 25
	s_ashr_i32 s9, s8, 31
	s_lshl_b64 s[8:9], s[8:9], 12
	global_load_dword v32, v[32:33], off
	s_nop 0
	global_load_dword v33, v[34:35], off
	v_lshl_add_u64 v[34:35], v[4:5], 0, s[8:9]
	s_or_b32 s8, s10, 26
	s_ashr_i32 s9, s8, 31
	s_lshl_b64 s[8:9], s[8:9], 12
	v_lshl_add_u64 v[36:37], v[4:5], 0, s[8:9]
	s_or_b32 s8, s10, 27
	s_ashr_i32 s9, s8, 31
	s_lshl_b64 s[8:9], s[8:9], 12
	global_load_dword v34, v[34:35], off
	s_nop 0
	global_load_dword v35, v[36:37], off
	v_lshl_add_u64 v[36:37], v[4:5], 0, s[8:9]
	s_or_b32 s8, s10, 28
	s_ashr_i32 s9, s8, 31
	s_lshl_b64 s[8:9], s[8:9], 12
	v_lshl_add_u64 v[38:39], v[4:5], 0, s[8:9]
	s_or_b32 s8, s10, 29
	s_ashr_i32 s9, s8, 31
	s_lshl_b64 s[8:9], s[8:9], 12
	global_load_dword v36, v[36:37], off
	s_nop 0
	global_load_dword v37, v[38:39], off
	v_lshl_add_u64 v[38:39], v[4:5], 0, s[8:9]
	s_or_b32 s8, s10, 30
	s_ashr_i32 s9, s8, 31
	s_lshl_b64 s[8:9], s[8:9], 12
	global_load_dword v38, v[38:39], off
	v_lshl_add_u64 v[40:41], v[4:5], 0, s[8:9]
	v_lshl_add_u64 v[4:5], v[4:5], 0, s[12:13]
	global_load_dword v4, v[4:5], off
	v_add_u32_e32 v5, 0x400, v1
	global_load_dword v39, v[40:41], off
	s_waitcnt vmcnt(30)
	ds_write2_b32 v1, v9, v10 offset1:65
	s_waitcnt vmcnt(28)
	ds_write2_b32 v1, v11, v12 offset0:130 offset1:195
	s_waitcnt vmcnt(26)
	ds_write2_b32 v5, v13, v14 offset0:4 offset1:69
	s_waitcnt vmcnt(24)
	ds_write2_b32 v5, v15, v16 offset0:134 offset1:199
	v_add_u32_e32 v5, 0x800, v1
	s_waitcnt vmcnt(22)
	ds_write2_b32 v5, v17, v18 offset0:8 offset1:73
	s_waitcnt vmcnt(20)
	ds_write2_b32 v5, v19, v20 offset0:138 offset1:203
	v_add_u32_e32 v5, 0xc00, v1
	s_waitcnt vmcnt(18)
	ds_write2_b32 v5, v21, v22 offset0:12 offset1:77
	s_waitcnt vmcnt(16)
	ds_write2_b32 v5, v23, v24 offset0:142 offset1:207
	v_add_u32_e32 v5, 0x1000, v1
	s_waitcnt vmcnt(14)
	ds_write2_b32 v5, v25, v26 offset0:16 offset1:81
	s_waitcnt vmcnt(12)
	ds_write2_b32 v5, v27, v28 offset0:146 offset1:211
	v_add_u32_e32 v5, 0x1400, v1
	s_waitcnt vmcnt(10)
	ds_write2_b32 v5, v29, v30 offset0:20 offset1:85
	s_waitcnt vmcnt(8)
	ds_write2_b32 v5, v31, v32 offset0:150 offset1:215
	v_add_u32_e32 v5, 0x1800, v1
	s_waitcnt vmcnt(6)
	ds_write2_b32 v5, v33, v34 offset0:24 offset1:89
	s_waitcnt vmcnt(4)
	ds_write2_b32 v5, v35, v36 offset0:154 offset1:219
	v_add_u32_e32 v5, 0x1c00, v1
	s_waitcnt vmcnt(2)
	ds_write2_b32 v5, v37, v38 offset0:28 offset1:93
	s_waitcnt vmcnt(0)
	ds_write2_b32 v5, v39, v4 offset0:158 offset1:223
	s_waitcnt lgkmcnt(0)
	v_add_u32_e32 v9, 0x400, v7
	ds_read2_b32 v[14:15], v7 offset1:16
	ds_read2_b32 v[16:17], v7 offset0:65 offset1:81
	ds_read2_b32 v[18:19], v7 offset0:130 offset1:146
	ds_read2_b32 v[20:21], v7 offset0:195 offset1:211
	ds_read2_b32 v[22:23], v9 offset0:4 offset1:20
	ds_read2_b32 v[24:25], v9 offset0:69 offset1:85
	ds_read2_b32 v[26:27], v9 offset0:134 offset1:150
	ds_read2_b32 v[28:29], v9 offset0:199 offset1:215
	v_lshl_add_u64 v[4:5], s[10:11], 1, v[2:3]
	v_add_u32_e32 v32, s7, v6
	s_waitcnt lgkmcnt(6)
	v_cvt_pk_bf16_f32 v10, v14, v16
	s_waitcnt lgkmcnt(4)
	v_cvt_pk_bf16_f32 v11, v18, v20
	s_waitcnt lgkmcnt(2)
	v_cvt_pk_bf16_f32 v12, v22, v24
	s_waitcnt lgkmcnt(0)
	v_cvt_pk_bf16_f32 v13, v26, v28
	v_mad_i64_i32 v[30:31], s[8:9], v32, s54, v[4:5]
	v_add_u32_e32 v14, 16, v32
	global_store_dwordx4 v[30:31], v[10:13], off sc0 sc1
	s_cmpk_lt_i32 s6, 0x580
	s_nop 0
	v_cvt_pk_bf16_f32 v10, v15, v17
	v_cvt_pk_bf16_f32 v11, v19, v21
	v_cvt_pk_bf16_f32 v12, v23, v25
	v_cvt_pk_bf16_f32 v13, v27, v29
	v_mad_i64_i32 v[14:15], s[8:9], v14, s54, v[4:5]
	global_store_dwordx4 v[14:15], v[10:13], off sc0 sc1
	ds_read2_b32 v[14:15], v7 offset0:32 offset1:48
	ds_read2_b32 v[16:17], v7 offset0:97 offset1:113
	ds_read2_b32 v[18:19], v7 offset0:162 offset1:178
	ds_read2_b32 v[20:21], v7 offset0:227 offset1:243
	ds_read2_b32 v[22:23], v9 offset0:36 offset1:52
	ds_read2_b32 v[24:25], v9 offset0:101 offset1:117
	ds_read2_b32 v[26:27], v9 offset0:166 offset1:182
	ds_read2_b32 v[28:29], v9 offset0:231 offset1:247
	v_add_u32_e32 v9, 32, v32
	s_waitcnt lgkmcnt(6)
	v_cvt_pk_bf16_f32 v10, v14, v16
	s_waitcnt lgkmcnt(4)
	v_cvt_pk_bf16_f32 v11, v18, v20
	s_waitcnt lgkmcnt(2)
	v_cvt_pk_bf16_f32 v12, v22, v24
	s_waitcnt lgkmcnt(0)
	v_cvt_pk_bf16_f32 v13, v26, v28
	v_mad_i64_i32 v[30:31], s[8:9], v9, s54, v[4:5]
	v_add_u32_e32 v9, 48, v32
	global_store_dwordx4 v[30:31], v[10:13], off sc0 sc1
	v_mad_i64_i32 v[4:5], s[8:9], v9, s54, v[4:5]
	s_nop 0
	v_cvt_pk_bf16_f32 v10, v15, v17
	v_cvt_pk_bf16_f32 v11, v19, v21
	v_cvt_pk_bf16_f32 v12, v23, v25
	v_cvt_pk_bf16_f32 v13, v27, v29
	global_store_dwordx4 v[4:5], v[10:13], off sc0 sc1
	s_waitcnt lgkmcnt(0)
	s_cbranch_scc1 .LBB0_384

.LBB0_387:
	s_waitcnt vmcnt(30)
	ds_write2_b32 v1, v4, v5 offset1:65
	s_waitcnt vmcnt(28)
	ds_write2_b32 v1, v6, v7 offset0:130 offset1:195
	v_add_u32_e32 v4, 0x400, v1
	s_waitcnt vmcnt(26)
	ds_write2_b32 v4, v8, v9 offset0:4 offset1:69
	s_waitcnt vmcnt(24)
	ds_write2_b32 v4, v10, v11 offset0:134 offset1:199
	v_add_u32_e32 v4, 0x800, v1
	s_waitcnt vmcnt(22)
	ds_write2_b32 v4, v12, v13 offset0:8 offset1:73
	s_waitcnt vmcnt(20)
	ds_write2_b32 v4, v14, v15 offset0:138 offset1:203
	v_add_u32_e32 v4, 0xc00, v1
	s_waitcnt vmcnt(18)
	ds_write2_b32 v4, v16, v17 offset0:12 offset1:77
	s_waitcnt vmcnt(16)
	ds_write2_b32 v4, v18, v19 offset0:142 offset1:207
	v_add_u32_e32 v4, 0x1000, v1
	s_waitcnt vmcnt(14)
	ds_write2_b32 v4, v20, v21 offset0:16 offset1:81
	s_waitcnt vmcnt(12)
	ds_write2_b32 v4, v22, v23 offset0:146 offset1:211
	v_add_u32_e32 v4, 0x1400, v1
	s_waitcnt vmcnt(10)
	ds_write2_b32 v4, v24, v25 offset0:20 offset1:85
	s_waitcnt vmcnt(8)
	ds_write2_b32 v4, v28, v29 offset0:150 offset1:215
	v_add_u32_e32 v4, 0x1800, v1
	s_waitcnt vmcnt(6)
	ds_write2_b32 v4, v30, v31 offset0:24 offset1:89
	s_waitcnt vmcnt(4)
	ds_write2_b32 v4, v32, v33 offset0:154 offset1:219
	v_add_u32_e32 v4, 0x1c00, v1
	s_waitcnt vmcnt(2)
	ds_write2_b32 v4, v34, v35 offset0:28 offset1:93
	s_waitcnt vmcnt(0)
	ds_write2_b32 v4, v36, v37 offset0:158 offset1:223
	s_waitcnt lgkmcnt(0)
	v_add_u32_e32 v30, 0x400, v39
	s_sub_i32 s9, 0, s9
	ds_read2_b32 v[8:9], v39 offset1:16
	ds_read2_b32 v[10:11], v39 offset0:65 offset1:81
	ds_read2_b32 v[12:13], v39 offset0:130 offset1:146
	ds_read2_b32 v[14:15], v39 offset0:195 offset1:211
	ds_read2_b32 v[16:17], v30 offset0:4 offset1:20
	ds_read2_b32 v[18:19], v30 offset0:69 offset1:85
	ds_read2_b32 v[20:21], v30 offset0:134 offset1:150
	ds_read2_b32 v[22:23], v30 offset0:199 offset1:215
	s_add_i32 s9, s9, s6
	v_add_u32_e32 v26, s9, v38
	v_ashrrev_i32_e32 v27, 31, v26
	v_lshl_add_u64 v[24:25], s[12:13], 1, v[2:3]
	v_lshlrev_b64 v[28:29], 11, v[26:27]
	s_waitcnt lgkmcnt(6)
	v_cvt_pk_bf16_f32 v4, v8, v10
	s_waitcnt lgkmcnt(4)
	v_cvt_pk_bf16_f32 v5, v12, v14
	s_waitcnt lgkmcnt(2)
	v_cvt_pk_bf16_f32 v6, v16, v18
	s_waitcnt lgkmcnt(0)
	v_cvt_pk_bf16_f32 v7, v20, v22
	v_lshl_add_u64 v[28:29], v[24:25], 0, v[28:29]
	v_add_u32_e32 v8, 16, v26
	global_store_dwordx4 v[28:29], v[4:7], off sc0 sc1
	s_add_i32 s8, s8, s89
	s_add_i32 s6, s6, s7
	v_cvt_pk_bf16_f32 v4, v9, v11
	v_ashrrev_i32_e32 v9, 31, v8
	v_cvt_pk_bf16_f32 v5, v13, v15
	v_cvt_pk_bf16_f32 v6, v17, v19
	v_cvt_pk_bf16_f32 v7, v21, v23
	v_lshlrev_b64 v[8:9], 11, v[8:9]
	ds_read2_b32 v[10:11], v39 offset0:32 offset1:48
	ds_read2_b32 v[12:13], v39 offset0:97 offset1:113
	ds_read2_b32 v[14:15], v39 offset0:162 offset1:178
	ds_read2_b32 v[16:17], v39 offset0:227 offset1:243
	ds_read2_b32 v[18:19], v30 offset0:36 offset1:52
	ds_read2_b32 v[20:21], v30 offset0:101 offset1:117
	ds_read2_b32 v[22:23], v30 offset0:166 offset1:182
	ds_read2_b32 v[28:29], v30 offset0:231 offset1:247
	v_lshl_add_u64 v[8:9], v[24:25], 0, v[8:9]
	global_store_dwordx4 v[8:9], v[4:7], off sc0 sc1
	v_add_u32_e32 v8, 32, v26
	v_ashrrev_i32_e32 v9, 31, v8
	v_lshlrev_b64 v[8:9], 11, v[8:9]
	s_waitcnt lgkmcnt(6)
	v_cvt_pk_bf16_f32 v4, v10, v12
	s_waitcnt lgkmcnt(4)
	v_cvt_pk_bf16_f32 v5, v14, v16
	s_waitcnt lgkmcnt(2)
	v_cvt_pk_bf16_f32 v6, v18, v20
	s_waitcnt lgkmcnt(0)
	v_cvt_pk_bf16_f32 v7, v22, v28
	v_lshl_add_u64 v[8:9], v[24:25], 0, v[8:9]
	global_store_dwordx4 v[8:9], v[4:7], off sc0 sc1
	v_add_u32_e32 v8, 48, v26
	v_ashrrev_i32_e32 v9, 31, v8
	v_lshlrev_b64 v[8:9], 11, v[8:9]
	v_cvt_pk_bf16_f32 v4, v11, v13
	v_cvt_pk_bf16_f32 v5, v15, v17
	v_cvt_pk_bf16_f32 v6, v19, v21
	v_cvt_pk_bf16_f32 v7, v23, v29
	v_lshl_add_u64 v[8:9], v[24:25], 0, v[8:9]
	global_store_dwordx4 v[8:9], v[4:7], off sc0 sc1
	s_waitcnt lgkmcnt(0)
	s_cmpk_lt_i32 s8, 0x200
	s_cbranch_scc0 .LBB0_390

.LBB0_392:
	s_ashr_i32 s7, s6, 31
	s_lshr_b32 s7, s7, 28
	s_add_i32 s7, s6, s7
	s_ashr_i32 s7, s7, 4
	s_lshl_b32 s10, s7, 5
	s_lshl_b32 s7, s7, 10
	s_sub_i32 s7, s4, s7
	v_add_u32_e32 v4, s7, v8
	v_ashrrev_i32_e32 v5, 31, v4
	s_ashr_i32 s11, s10, 31
	v_lshl_add_u64 v[4:5], v[4:5], 2, s[0:1]
	s_lshl_b64 s[8:9], s[10:11], 12
	v_lshl_add_u64 v[10:11], v[4:5], 0, s[8:9]
	s_or_b32 s8, s10, 1
	s_ashr_i32 s9, s8, 31
	s_lshl_b64 s[8:9], s[8:9], 12
	global_load_dword v9, v[10:11], off
	v_lshl_add_u64 v[10:11], v[4:5], 0, s[8:9]
	s_or_b32 s8, s10, 2
	s_ashr_i32 s9, s8, 31
	s_lshl_b64 s[8:9], s[8:9], 12
	v_lshl_add_u64 v[12:13], v[4:5], 0, s[8:9]
	s_or_b32 s8, s10, 3
	s_ashr_i32 s9, s8, 31
	s_lshl_b64 s[8:9], s[8:9], 12
	global_load_dword v10, v[10:11], off
	s_or_b32 s12, s10, 31
	global_load_dword v11, v[12:13], off
	v_lshl_add_u64 v[12:13], v[4:5], 0, s[8:9]
	s_or_b32 s8, s10, 4
	s_ashr_i32 s9, s8, 31
	s_lshl_b64 s[8:9], s[8:9], 12
	v_lshl_add_u64 v[14:15], v[4:5], 0, s[8:9]
	s_or_b32 s8, s10, 5
	s_ashr_i32 s9, s8, 31
	s_lshl_b64 s[8:9], s[8:9], 12
	global_load_dword v12, v[12:13], off
	s_ashr_i32 s13, s12, 31
	global_load_dword v13, v[14:15], off
	v_lshl_add_u64 v[14:15], v[4:5], 0, s[8:9]
	s_or_b32 s8, s10, 6
	s_ashr_i32 s9, s8, 31
	s_lshl_b64 s[8:9], s[8:9], 12
	v_lshl_add_u64 v[16:17], v[4:5], 0, s[8:9]
	s_or_b32 s8, s10, 7
	s_ashr_i32 s9, s8, 31
	s_lshl_b64 s[8:9], s[8:9], 12
	global_load_dword v14, v[14:15], off
	s_lshl_b64 s[12:13], s[12:13], 12
	global_load_dword v15, v[16:17], off
	v_lshl_add_u64 v[16:17], v[4:5], 0, s[8:9]
	s_or_b32 s8, s10, 8
	s_ashr_i32 s9, s8, 31
	s_lshl_b64 s[8:9], s[8:9], 12
	v_lshl_add_u64 v[18:19], v[4:5], 0, s[8:9]
	s_or_b32 s8, s10, 9
	s_ashr_i32 s9, s8, 31
	s_lshl_b64 s[8:9], s[8:9], 12
	global_load_dword v16, v[16:17], off
	s_add_i32 s6, s6, s89
	global_load_dword v17, v[18:19], off
	v_lshl_add_u64 v[18:19], v[4:5], 0, s[8:9]
	s_or_b32 s8, s10, 10
	s_ashr_i32 s9, s8, 31
	s_lshl_b64 s[8:9], s[8:9], 12
	v_lshl_add_u64 v[20:21], v[4:5], 0, s[8:9]
	s_or_b32 s8, s10, 11
	s_ashr_i32 s9, s8, 31
	s_lshl_b64 s[8:9], s[8:9], 12
	global_load_dword v18, v[18:19], off
	s_add_i32 s4, s4, s5
	global_load_dword v19, v[20:21], off
	v_lshl_add_u64 v[20:21], v[4:5], 0, s[8:9]
	s_or_b32 s8, s10, 12
	s_ashr_i32 s9, s8, 31
	s_lshl_b64 s[8:9], s[8:9], 12
	v_lshl_add_u64 v[22:23], v[4:5], 0, s[8:9]
	s_or_b32 s8, s10, 13
	s_ashr_i32 s9, s8, 31
	s_lshl_b64 s[8:9], s[8:9], 12
	global_load_dword v20, v[20:21], off
	s_nop 0
	global_load_dword v21, v[22:23], off
	v_lshl_add_u64 v[22:23], v[4:5], 0, s[8:9]
	s_or_b32 s8, s10, 14
	s_ashr_i32 s9, s8, 31
	s_lshl_b64 s[8:9], s[8:9], 12
	v_lshl_add_u64 v[24:25], v[4:5], 0, s[8:9]
	s_or_b32 s8, s10, 15
	s_ashr_i32 s9, s8, 31
	s_lshl_b64 s[8:9], s[8:9], 12
	global_load_dword v22, v[22:23], off
	s_nop 0
	global_load_dword v23, v[24:25], off
	v_lshl_add_u64 v[24:25], v[4:5], 0, s[8:9]
	s_or_b32 s8, s10, 16
	s_ashr_i32 s9, s8, 31
	s_lshl_b64 s[8:9], s[8:9], 12
	v_lshl_add_u64 v[26:27], v[4:5], 0, s[8:9]
	s_or_b32 s8, s10, 17
	s_ashr_i32 s9, s8, 31
	s_lshl_b64 s[8:9], s[8:9], 12
	global_load_dword v24, v[24:25], off
	s_nop 0
	global_load_dword v25, v[26:27], off
	v_lshl_add_u64 v[26:27], v[4:5], 0, s[8:9]
	s_or_b32 s8, s10, 18
	s_ashr_i32 s9, s8, 31
	s_lshl_b64 s[8:9], s[8:9], 12
	v_lshl_add_u64 v[28:29], v[4:5], 0, s[8:9]
	s_or_b32 s8, s10, 19
	s_ashr_i32 s9, s8, 31
	s_lshl_b64 s[8:9], s[8:9], 12
	global_load_dword v26, v[26:27], off
	s_nop 0
	global_load_dword v27, v[28:29], off
	v_lshl_add_u64 v[28:29], v[4:5], 0, s[8:9]
	s_or_b32 s8, s10, 20
	s_ashr_i32 s9, s8, 31
	s_lshl_b64 s[8:9], s[8:9], 12
	v_lshl_add_u64 v[30:31], v[4:5], 0, s[8:9]
	s_or_b32 s8, s10, 21
	s_ashr_i32 s9, s8, 31
	s_lshl_b64 s[8:9], s[8:9], 12
	global_load_dword v28, v[28:29], off
	s_nop 0
	global_load_dword v29, v[30:31], off
	v_lshl_add_u64 v[30:31], v[4:5], 0, s[8:9]
	s_or_b32 s8, s10, 22
	s_ashr_i32 s9, s8, 31
	s_lshl_b64 s[8:9], s[8:9], 12
	v_lshl_add_u64 v[32:33], v[4:5], 0, s[8:9]
	s_or_b32 s8, s10, 23
	s_ashr_i32 s9, s8, 31
	s_lshl_b64 s[8:9], s[8:9], 12
	global_load_dword v30, v[30:31], off
	s_nop 0
	global_load_dword v31, v[32:33], off
	v_lshl_add_u64 v[32:33], v[4:5], 0, s[8:9]
	s_or_b32 s8, s10, 24
	s_ashr_i32 s9, s8, 31
	s_lshl_b64 s[8:9], s[8:9], 12
	v_lshl_add_u64 v[34:35], v[4:5], 0, s[8:9]
	s_or_b32 s8, s10, 25
	s_ashr_i32 s9, s8, 31
	s_lshl_b64 s[8:9], s[8:9], 12
	global_load_dword v32, v[32:33], off
	s_nop 0
	global_load_dword v33, v[34:35], off
	v_lshl_add_u64 v[34:35], v[4:5], 0, s[8:9]
	s_or_b32 s8, s10, 26
	s_ashr_i32 s9, s8, 31
	s_lshl_b64 s[8:9], s[8:9], 12
	v_lshl_add_u64 v[36:37], v[4:5], 0, s[8:9]
	s_or_b32 s8, s10, 27
	s_ashr_i32 s9, s8, 31
	s_lshl_b64 s[8:9], s[8:9], 12
	global_load_dword v34, v[34:35], off
	s_nop 0
	global_load_dword v35, v[36:37], off
	v_lshl_add_u64 v[36:37], v[4:5], 0, s[8:9]
	s_or_b32 s8, s10, 28
	s_ashr_i32 s9, s8, 31
	s_lshl_b64 s[8:9], s[8:9], 12
	v_lshl_add_u64 v[38:39], v[4:5], 0, s[8:9]
	s_or_b32 s8, s10, 29
	s_ashr_i32 s9, s8, 31
	s_lshl_b64 s[8:9], s[8:9], 12
	global_load_dword v36, v[36:37], off
	s_nop 0
	global_load_dword v37, v[38:39], off
	v_lshl_add_u64 v[38:39], v[4:5], 0, s[8:9]
	s_or_b32 s8, s10, 30
	s_ashr_i32 s9, s8, 31
	s_lshl_b64 s[8:9], s[8:9], 12
	global_load_dword v38, v[38:39], off
	v_lshl_add_u64 v[40:41], v[4:5], 0, s[8:9]
	v_lshl_add_u64 v[4:5], v[4:5], 0, s[12:13]
	global_load_dword v4, v[4:5], off
	v_add_u32_e32 v5, 0x400, v1
	global_load_dword v39, v[40:41], off
	s_waitcnt vmcnt(30)
	ds_write2_b32 v1, v9, v10 offset1:65
	s_waitcnt vmcnt(28)
	ds_write2_b32 v1, v11, v12 offset0:130 offset1:195
	s_waitcnt vmcnt(26)
	ds_write2_b32 v5, v13, v14 offset0:4 offset1:69
	s_waitcnt vmcnt(24)
	ds_write2_b32 v5, v15, v16 offset0:134 offset1:199
	v_add_u32_e32 v5, 0x800, v1
	s_waitcnt vmcnt(22)
	ds_write2_b32 v5, v17, v18 offset0:8 offset1:73
	s_waitcnt vmcnt(20)
	ds_write2_b32 v5, v19, v20 offset0:138 offset1:203
	v_add_u32_e32 v5, 0xc00, v1
	s_waitcnt vmcnt(18)
	ds_write2_b32 v5, v21, v22 offset0:12 offset1:77
	s_waitcnt vmcnt(16)
	ds_write2_b32 v5, v23, v24 offset0:142 offset1:207
	v_add_u32_e32 v5, 0x1000, v1
	s_waitcnt vmcnt(14)
	ds_write2_b32 v5, v25, v26 offset0:16 offset1:81
	s_waitcnt vmcnt(12)
	ds_write2_b32 v5, v27, v28 offset0:146 offset1:211
	v_add_u32_e32 v5, 0x1400, v1
	s_waitcnt vmcnt(10)
	ds_write2_b32 v5, v29, v30 offset0:20 offset1:85
	s_waitcnt vmcnt(8)
	ds_write2_b32 v5, v31, v32 offset0:150 offset1:215
	v_add_u32_e32 v5, 0x1800, v1
	s_waitcnt vmcnt(6)
	ds_write2_b32 v5, v33, v34 offset0:24 offset1:89
	s_waitcnt vmcnt(4)
	ds_write2_b32 v5, v35, v36 offset0:154 offset1:219
	v_add_u32_e32 v5, 0x1c00, v1
	s_waitcnt vmcnt(2)
	ds_write2_b32 v5, v37, v38 offset0:28 offset1:93
	s_waitcnt vmcnt(0)
	ds_write2_b32 v5, v39, v4 offset0:158 offset1:223
	s_waitcnt lgkmcnt(0)
	v_add_u32_e32 v9, 0x400, v7
	ds_read2_b32 v[14:15], v7 offset1:16
	ds_read2_b32 v[16:17], v7 offset0:65 offset1:81
	ds_read2_b32 v[18:19], v7 offset0:130 offset1:146
	ds_read2_b32 v[20:21], v7 offset0:195 offset1:211
	ds_read2_b32 v[22:23], v9 offset0:4 offset1:20
	ds_read2_b32 v[24:25], v9 offset0:69 offset1:85
	ds_read2_b32 v[26:27], v9 offset0:134 offset1:150
	ds_read2_b32 v[28:29], v9 offset0:199 offset1:215
	v_add_u32_e32 v30, s7, v6
	v_ashrrev_i32_e32 v31, 31, v30
	v_lshl_add_u64 v[4:5], s[10:11], 1, v[2:3]
	v_lshlrev_b64 v[32:33], 9, v[30:31]
	s_waitcnt lgkmcnt(6)
	v_cvt_pk_bf16_f32 v10, v14, v16
	s_waitcnt lgkmcnt(4)
	v_cvt_pk_bf16_f32 v11, v18, v20
	s_waitcnt lgkmcnt(2)
	v_cvt_pk_bf16_f32 v12, v22, v24
	s_waitcnt lgkmcnt(0)
	v_cvt_pk_bf16_f32 v13, v26, v28
	v_lshl_add_u64 v[32:33], v[4:5], 0, v[32:33]
	v_add_u32_e32 v14, 16, v30
	global_store_dwordx4 v[32:33], v[10:13], off sc0 sc1
	v_add_u32_e32 v32, 32, v30
	v_ashrrev_i32_e32 v33, 31, v32
	v_cvt_pk_bf16_f32 v10, v15, v17
	v_ashrrev_i32_e32 v15, 31, v14
	v_lshlrev_b64 v[14:15], 9, v[14:15]
	v_cvt_pk_bf16_f32 v11, v19, v21
	v_cvt_pk_bf16_f32 v12, v23, v25
	v_cvt_pk_bf16_f32 v13, v27, v29
	v_lshl_add_u64 v[14:15], v[4:5], 0, v[14:15]
	global_store_dwordx4 v[14:15], v[10:13], off sc0 sc1
	ds_read2_b32 v[14:15], v7 offset0:32 offset1:48
	ds_read2_b32 v[16:17], v7 offset0:97 offset1:113
	ds_read2_b32 v[18:19], v7 offset0:162 offset1:178
	ds_read2_b32 v[20:21], v7 offset0:227 offset1:243
	ds_read2_b32 v[22:23], v9 offset0:36 offset1:52
	ds_read2_b32 v[24:25], v9 offset0:101 offset1:117
	ds_read2_b32 v[26:27], v9 offset0:166 offset1:182
	ds_read2_b32 v[28:29], v9 offset0:231 offset1:247
	v_lshlrev_b64 v[32:33], 9, v[32:33]
	s_waitcnt lgkmcnt(6)
	v_cvt_pk_bf16_f32 v10, v14, v16
	s_waitcnt lgkmcnt(4)
	v_cvt_pk_bf16_f32 v11, v18, v20
	s_waitcnt lgkmcnt(2)
	v_cvt_pk_bf16_f32 v12, v22, v24
	s_waitcnt lgkmcnt(0)
	v_cvt_pk_bf16_f32 v13, v26, v28
	v_lshl_add_u64 v[32:33], v[4:5], 0, v[32:33]
	v_add_u32_e32 v14, 48, v30
	global_store_dwordx4 v[32:33], v[10:13], off sc0 sc1
	s_cmpk_lt_i32 s6, 0x80
	s_nop 0
	v_cvt_pk_bf16_f32 v10, v15, v17
	v_ashrrev_i32_e32 v15, 31, v14
	v_lshlrev_b64 v[14:15], 9, v[14:15]
	v_cvt_pk_bf16_f32 v11, v19, v21
	v_cvt_pk_bf16_f32 v12, v23, v25
	v_cvt_pk_bf16_f32 v13, v27, v29
	v_lshl_add_u64 v[4:5], v[4:5], 0, v[14:15]
	global_store_dwordx4 v[4:5], v[10:13], off sc0 sc1
	s_waitcnt lgkmcnt(0)
	s_cbranch_scc1 .LBB0_392

.LBB0_402:
	s_or_b64 exec, exec, s[26:27]
	s_waitcnt vmcnt(0)
	v_cvt_pk_bf16_f32 v30, v30, v31
	v_cvt_pk_bf16_f32 v31, v32, v33
	v_cvt_pk_bf16_f32 v32, v26, v27
	v_cvt_pk_bf16_f32 v33, v28, v29
	v_lshl_add_u64 v[26:27], s[24:25], 0, v[34:35]
	global_store_dwordx4 v[26:27], v[30:33], off sc0 sc1
	s_and_saveexec_b64 s[26:27], vcc
	s_cbranch_execnz .LBB0_405
	s_or_b64 exec, exec, s[26:27]
	s_and_saveexec_b64 s[26:27], s[40:41]
	s_cbranch_execnz .LBB0_406

.LBB0_405:
	v_cvt_pk_bf16_f32 v26, v10, v11
	v_cvt_pk_bf16_f32 v27, v12, v13
	v_cvt_pk_bf16_f32 v28, v22, v23
	v_cvt_pk_bf16_f32 v29, v24, v25
	v_lshl_add_u64 v[30:31], s[24:25], 0, v[46:47]
	global_store_dwordx4 v[30:31], v[26:29], off sc0 sc1
	s_or_b64 exec, exec, s[26:27]
	s_and_saveexec_b64 s[26:27], s[40:41]
	s_cbranch_execz .LBB0_404
.LBB0_406:
	v_cvt_pk_bf16_f32 v26, v6, v7
	v_cvt_pk_bf16_f32 v27, v8, v9
	v_cvt_pk_bf16_f32 v28, v18, v19
	v_cvt_pk_bf16_f32 v29, v20, v21
	v_lshl_add_u64 v[30:31], s[24:25], 0, v[40:41]
	global_store_dwordx4 v[30:31], v[26:29], off sc0 sc1
	s_or_b64 exec, exec, s[26:27]
	s_and_saveexec_b64 s[26:27], s[42:43]
	s_cbranch_execz .LBB0_395
.LBB0_407:
	v_cvt_pk_bf16_f32 v26, v2, v3
	v_cvt_pk_bf16_f32 v27, v4, v5
	v_cvt_pk_bf16_f32 v28, v14, v15
	v_cvt_pk_bf16_f32 v29, v16, v17
	v_lshl_add_u64 v[30:31], s[24:25], 0, v[44:45]
	global_store_dwordx4 v[30:31], v[26:29], off sc0 sc1
	s_branch .LBB0_395

.LBB0_447:
	ds_bpermute_b32 v1, v178, v183
	s_mulk_i32 s5, 0x2200
	s_add_i32 s5, s5, 0
	v_readlane_b32 s8, v251, 45
	v_readlane_b32 s9, v251, 46
	s_waitcnt lgkmcnt(0)
	v_add_f32_e32 v1, v183, v1
	v_div_scale_f32 v2, s[6:7], v1, v1, 1.0
	v_rcp_f32_e32 v3, v2
	v_div_scale_f32 v4, vcc, 1.0, v1, 1.0
	s_mov_b64 s[18:19], 0x80000
	v_fma_f32 v5, -v2, v3, 1.0
	v_fmac_f32_e32 v3, v5, v3
	v_mul_f32_e32 v5, v4, v3
	v_fma_f32 v6, -v2, v5, v4
	v_fmac_f32_e32 v5, v6, v3
	v_fma_f32 v2, -v2, v5, v4
	v_div_fmas_f32 v2, v2, v3, v5
	v_div_fixup_f32 v2, v2, v1, 1.0
	v_pk_mul_f32 v[4:5], v[18:19], v[2:3] op_sel_hi:[1,0]
	v_pk_mul_f32 v[6:7], v[20:21], v[2:3] op_sel_hi:[1,0]
	v_pk_mul_f32 v[10:11], v[24:25], v[2:3] op_sel_hi:[1,0]
	v_pk_mul_f32 v[24:25], v[38:39], v[2:3] op_sel_hi:[1,0]
	v_pk_mul_f32 v[38:39], v[52:53], v[2:3] op_sel_hi:[1,0]
	v_pk_mul_f32 v[52:53], v[66:67], v[2:3] op_sel_hi:[1,0]
	v_mbcnt_lo_u32_b32 v1, -1, 0
	v_mbcnt_hi_u32_b32 v1, -1, v1
	v_cvt_pk_bf16_f32 v4, v4, v5
	v_and_b32_e32 v66, 31, v1
	v_cvt_pk_bf16_f32 v5, v6, v7
	v_ashrrev_i32_e32 v6, 2, v1
	v_pk_mul_f32 v[8:9], v[22:23], v[2:3] op_sel_hi:[1,0]
	v_mul_u32_u24_e32 v66, 0x110, v66
	v_and_b32_e32 v6, -8, v6
	v_pk_mul_f32 v[12:13], v[26:27], v[2:3] op_sel_hi:[1,0]
	v_pk_mul_f32 v[14:15], v[28:29], v[2:3] op_sel_hi:[1,0]
	v_pk_mul_f32 v[16:17], v[30:31], v[2:3] op_sel_hi:[1,0]
	v_pk_mul_f32 v[18:19], v[32:33], v[2:3] op_sel_hi:[1,0]
	v_add3_u32 v66, s5, v66, v6
	v_cvt_pk_bf16_f32 v6, v8, v9
	v_cvt_pk_bf16_f32 v7, v10, v11
	v_pk_mul_f32 v[20:21], v[34:35], v[2:3] op_sel_hi:[1,0]
	v_pk_mul_f32 v[22:23], v[36:37], v[2:3] op_sel_hi:[1,0]
	v_pk_mul_f32 v[26:27], v[40:41], v[2:3] op_sel_hi:[1,0]
	ds_write2_b64 v66, v[4:5], v[6:7] offset1:2
	v_cvt_pk_bf16_f32 v4, v12, v13
	v_cvt_pk_bf16_f32 v5, v14, v15
	v_cvt_pk_bf16_f32 v6, v16, v17
	v_cvt_pk_bf16_f32 v7, v18, v19
	v_pk_mul_f32 v[28:29], v[42:43], v[2:3] op_sel_hi:[1,0]
	v_pk_mul_f32 v[30:31], v[44:45], v[2:3] op_sel_hi:[1,0]
	v_pk_mul_f32 v[32:33], v[46:47], v[2:3] op_sel_hi:[1,0]
	v_pk_mul_f32 v[34:35], v[48:49], v[2:3] op_sel_hi:[1,0]
	ds_write2_b64 v66, v[4:5], v[6:7] offset0:4 offset1:6
	v_cvt_pk_bf16_f32 v4, v20, v21
	v_cvt_pk_bf16_f32 v5, v22, v23
	v_cvt_pk_bf16_f32 v6, v24, v25
	v_cvt_pk_bf16_f32 v7, v26, v27
	v_pk_mul_f32 v[36:37], v[50:51], v[2:3] op_sel_hi:[1,0]
	v_pk_mul_f32 v[40:41], v[54:55], v[2:3] op_sel_hi:[1,0]
	v_pk_mul_f32 v[42:43], v[56:57], v[2:3] op_sel_hi:[1,0]
	ds_write2_b64 v66, v[4:5], v[6:7] offset0:8 offset1:10
	v_cvt_pk_bf16_f32 v4, v28, v29
	v_cvt_pk_bf16_f32 v5, v30, v31
	v_cvt_pk_bf16_f32 v6, v32, v33
	v_cvt_pk_bf16_f32 v7, v34, v35
	v_pk_mul_f32 v[44:45], v[58:59], v[2:3] op_sel_hi:[1,0]
	v_pk_mul_f32 v[46:47], v[60:61], v[2:3] op_sel_hi:[1,0]
	v_pk_mul_f32 v[48:49], v[62:63], v[2:3] op_sel_hi:[1,0]
	v_pk_mul_f32 v[50:51], v[64:65], v[2:3] op_sel_hi:[1,0]
	ds_write2_b64 v66, v[4:5], v[6:7] offset0:12 offset1:14
	v_cvt_pk_bf16_f32 v4, v36, v37
	v_cvt_pk_bf16_f32 v5, v38, v39
	v_cvt_pk_bf16_f32 v6, v40, v41
	v_cvt_pk_bf16_f32 v7, v42, v43
	v_pk_mul_f32 v[54:55], v[68:69], v[2:3] op_sel_hi:[1,0]
	v_pk_mul_f32 v[56:57], v[70:71], v[2:3] op_sel_hi:[1,0]
	v_pk_mul_f32 v[58:59], v[72:73], v[2:3] op_sel_hi:[1,0]
	ds_write2_b64 v66, v[4:5], v[6:7] offset0:16 offset1:18
	v_cvt_pk_bf16_f32 v4, v44, v45
	v_cvt_pk_bf16_f32 v5, v46, v47
	v_cvt_pk_bf16_f32 v6, v48, v49
	v_cvt_pk_bf16_f32 v7, v50, v51
	v_pk_mul_f32 v[60:61], v[74:75], v[2:3] op_sel_hi:[1,0]
	v_pk_mul_f32 v[62:63], v[76:77], v[2:3] op_sel_hi:[1,0]
	v_pk_mul_f32 v[64:65], v[78:79], v[2:3] op_sel_hi:[1,0]
	v_pk_mul_f32 v[2:3], v[80:81], v[2:3] op_sel_hi:[1,0]
	ds_write2_b64 v66, v[4:5], v[6:7] offset0:20 offset1:22
	v_cvt_pk_bf16_f32 v4, v52, v53
	v_cvt_pk_bf16_f32 v5, v54, v55
	v_cvt_pk_bf16_f32 v6, v56, v57
	v_cvt_pk_bf16_f32 v7, v58, v59
	ds_write2_b64 v66, v[4:5], v[6:7] offset0:24 offset1:26
	v_cvt_pk_bf16_f32 v4, v60, v61
	v_cvt_pk_bf16_f32 v5, v62, v63
	v_cvt_pk_bf16_f32 v6, v64, v65
	v_cvt_pk_bf16_f32 v7, v2, v3
	v_lshlrev_b32_e32 v2, 4, v1
	ds_write2_b64 v66, v[4:5], v[6:7] offset0:28 offset1:30
	v_and_b32_e32 v10, 0xf0, v2
	v_ashrrev_i32_e32 v6, 4, v1
	v_add_u32_e32 v12, s5, v10
	s_movk_i32 s5, 0x110
	v_ashrrev_i32_e32 v7, 31, v6
	v_mad_u64_u32 v[2:3], s[6:7], v6, s5, v[12:13]
	v_lshl_add_u64 v[6:7], s[0:1], 0, v[6:7]
	s_waitcnt lgkmcnt(0)
	v_lshlrev_b64 v[6:7], 12, v[6:7]
	ds_read_b128 v[2:5], v2
	v_lshl_add_u64 v[6:7], s[8:9], 0, v[6:7]
	v_lshl_add_u64 v[6:7], v[6:7], 0, s[10:11]
	v_mov_b32_e32 v11, v0
	v_lshl_add_u64 v[14:15], v[6:7], 0, v[10:11]
	v_add_u32_e32 v6, 64, v1
	v_ashrrev_i32_e32 v16, 4, v6
	v_mad_u64_u32 v[6:7], s[6:7], v16, s5, v[12:13]
	v_ashrrev_i32_e32 v17, 31, v16
	ds_read_b128 v[6:9], v6
	s_waitcnt lgkmcnt(1)
	global_store_dwordx4 v[14:15], v[2:5], off sc0 sc1
	s_nop 1
	v_lshl_add_u64 v[2:3], s[0:1], 0, v[16:17]
	v_lshlrev_b64 v[2:3], 12, v[2:3]
	v_lshl_add_u64 v[2:3], s[8:9], 0, v[2:3]
	v_lshl_add_u64 v[2:3], v[2:3], 0, s[10:11]
	v_lshl_add_u64 v[2:3], v[2:3], 0, v[10:11]
	s_waitcnt lgkmcnt(0)
	global_store_dwordx4 v[2:3], v[6:9], off sc0 sc1
	v_add_u32_e32 v2, 0x80, v1
	s_nop 0
	v_ashrrev_i32_e32 v6, 4, v2
	v_ashrrev_i32_e32 v7, 31, v6
	v_mad_u64_u32 v[2:3], s[6:7], v6, s5, v[12:13]
	v_lshl_add_u64 v[6:7], s[0:1], 0, v[6:7]
	v_lshlrev_b64 v[6:7], 12, v[6:7]
	ds_read_b128 v[2:5], v2
	v_lshl_add_u64 v[6:7], s[8:9], 0, v[6:7]
	v_lshl_add_u64 v[6:7], v[6:7], 0, s[10:11]
	v_lshl_add_u64 v[14:15], v[6:7], 0, v[10:11]
	v_add_u32_e32 v6, 0xc0, v1
	v_ashrrev_i32_e32 v16, 4, v6
	v_mad_u64_u32 v[6:7], s[6:7], v16, s5, v[12:13]
	v_ashrrev_i32_e32 v17, 31, v16
	ds_read_b128 v[6:9], v6
	s_waitcnt lgkmcnt(1)
	global_store_dwordx4 v[14:15], v[2:5], off sc0 sc1
	s_nop 1
	v_lshl_add_u64 v[2:3], s[0:1], 0, v[16:17]
	v_lshlrev_b64 v[2:3], 12, v[2:3]
	v_lshl_add_u64 v[2:3], s[8:9], 0, v[2:3]
	v_lshl_add_u64 v[2:3], v[2:3], 0, s[10:11]
	v_lshl_add_u64 v[2:3], v[2:3], 0, v[10:11]
	s_waitcnt lgkmcnt(0)
	global_store_dwordx4 v[2:3], v[6:9], off sc0 sc1
	v_add_u32_e32 v2, 0x100, v1
	s_nop 0
	v_ashrrev_i32_e32 v6, 4, v2
	v_ashrrev_i32_e32 v7, 31, v6
	v_mad_u64_u32 v[2:3], s[6:7], v6, s5, v[12:13]
	v_lshl_add_u64 v[6:7], s[0:1], 0, v[6:7]
	v_lshlrev_b64 v[6:7], 12, v[6:7]
	ds_read_b128 v[2:5], v2
	v_lshl_add_u64 v[6:7], s[8:9], 0, v[6:7]
	v_lshl_add_u64 v[6:7], v[6:7], 0, s[10:11]
	v_lshl_add_u64 v[14:15], v[6:7], 0, v[10:11]
	v_add_u32_e32 v6, 0x140, v1
	v_ashrrev_i32_e32 v16, 4, v6
	v_mad_u64_u32 v[6:7], s[6:7], v16, s5, v[12:13]
	v_ashrrev_i32_e32 v17, 31, v16
	ds_read_b128 v[6:9], v6
	s_waitcnt lgkmcnt(1)
	global_store_dwordx4 v[14:15], v[2:5], off sc0 sc1
	s_nop 1
	v_lshl_add_u64 v[2:3], s[0:1], 0, v[16:17]
	v_lshlrev_b64 v[2:3], 12, v[2:3]
	v_lshl_add_u64 v[2:3], s[8:9], 0, v[2:3]
	v_lshl_add_u64 v[2:3], v[2:3], 0, s[10:11]
	v_lshl_add_u64 v[2:3], v[2:3], 0, v[10:11]
	s_waitcnt lgkmcnt(0)
	global_store_dwordx4 v[2:3], v[6:9], off sc0 sc1
	v_add_u32_e32 v2, 0x180, v1
	v_add_u32_e32 v1, 0x1c0, v1
	v_ashrrev_i32_e32 v6, 4, v2
	v_mad_u64_u32 v[2:3], s[6:7], v6, s5, v[12:13]
	v_ashrrev_i32_e32 v7, 31, v6
	ds_read_b128 v[2:5], v2
	v_lshl_add_u64 v[6:7], s[0:1], 0, v[6:7]
	v_lshlrev_b64 v[6:7], 12, v[6:7]
	v_lshl_add_u64 v[6:7], s[8:9], 0, v[6:7]
	v_lshl_add_u64 v[6:7], v[6:7], 0, s[10:11]
	v_ashrrev_i32_e32 v16, 4, v1
	v_lshl_add_u64 v[14:15], v[6:7], 0, v[10:11]
	v_mad_u64_u32 v[6:7], s[6:7], v16, s5, v[12:13]
	v_ashrrev_i32_e32 v17, 31, v16
	ds_read_b128 v[6:9], v6
	s_waitcnt lgkmcnt(1)
	global_store_dwordx4 v[14:15], v[2:5], off sc0 sc1
	s_mov_b32 s5, 0
	s_nop 0
	v_lshl_add_u64 v[2:3], s[0:1], 0, v[16:17]
	v_lshlrev_b64 v[2:3], 12, v[2:3]
	v_lshl_add_u64 v[2:3], s[8:9], 0, v[2:3]
	v_lshl_add_u64 v[2:3], v[2:3], 0, s[10:11]
	v_lshl_add_u64 v[2:3], v[2:3], 0, v[10:11]
	s_waitcnt lgkmcnt(0)
	global_store_dwordx4 v[2:3], v[6:9], off sc0 sc1

.LBB0_528:
	s_ashr_i32 s65, s76, 31
	s_mov_b32 s64, s76
	s_andn2_b64 vcc, exec, s[10:11]
	v_ashrrev_i32_e32 v145, 31, v144
	s_cbranch_vccnz .LBB0_530
	v_pk_mul_f32 v[172:173], v[128:129], v[170:171] op_sel_hi:[1,0]
	v_pk_mul_f32 v[174:175], v[126:127], v[170:171] op_sel_hi:[1,0]
	v_pk_mul_f32 v[126:127], v[172:173], v[172:173]
	v_pk_mul_f32 v[128:129], v[174:175], v[174:175]
	v_pk_mul_f32 v[178:179], v[122:123], v[170:171] op_sel_hi:[1,0]
	v_pk_mov_b32 v[176:177], v[128:129], v[126:127] op_sel:[1,0]
	v_mov_b32_e32 v129, v127
	v_pk_add_f32 v[126:127], v[176:177], v[128:129]
	v_pk_mul_f32 v[176:177], v[124:125], v[170:171] op_sel_hi:[1,0]
	v_pk_mul_f32 v[124:125], v[178:179], v[178:179]
	v_pk_mul_f32 v[122:123], v[176:177], v[176:177]
	v_pk_mul_f32 v[128:129], v[118:119], v[170:171] op_sel_hi:[1,0]
	v_pk_add_f32 v[180:181], v[126:127], v[126:127] op_sel_hi:[0,1]
	v_pk_mov_b32 v[126:127], v[124:125], v[122:123] op_sel:[1,0]
	v_mov_b32_e32 v125, v123
	v_mul_f32_e32 v118, v128, v128
	v_pk_add_f32 v[122:123], v[126:127], v[124:125]
	v_pk_mul_f32 v[126:127], v[120:121], v[170:171] op_sel_hi:[1,0]
	v_pk_fma_f32 v[118:119], v[128:129], v[128:129], v[118:119] op_sel_hi:[1,1,0]
	v_pk_add_f32 v[202:203], v[122:123], v[122:123] op_sel_hi:[0,1]
	v_mul_f32_e32 v118, v126, v126
	v_pk_fma_f32 v[120:121], v[126:127], v[126:127], v[118:119] op_sel_hi:[1,1,0]
	v_pk_mul_f32 v[122:123], v[116:117], v[170:171] op_sel_hi:[1,0]
	v_pk_mul_f32 v[124:125], v[114:115], v[170:171] op_sel_hi:[1,0]
	v_mul_f32_e32 v180, v122, v122
	v_mul_f32_e32 v118, v124, v124
	v_mul_f32_e32 v120, v125, v125
	v_mul_f32_e32 v202, v123, v123
	v_pk_add_f32 v[114:115], v[118:119], v[120:121]
	v_pk_add_f32 v[116:117], v[180:181], v[202:203]
	s_and_b64 s[4:5], s[42:43], exec
	v_pk_add_f32 v[114:115], v[114:115], v[116:117]
	s_nop 0
	v_add_f32_e32 v114, v114, v115
	ds_bpermute_b32 v115, v185, v114
	s_waitcnt lgkmcnt(0)
	v_add_f32_e32 v114, v114, v115
	ds_bpermute_b32 v115, v184, v114
	s_waitcnt lgkmcnt(0)
	v_add_f32_e32 v114, v114, v115
	v_fmamk_f32 v114, v114, 0x3c800000, v243
	s_nop 1
	s_cselect_b32 s4, s27, s39
	s_cselect_b32 s5, s26, s38
	v_rsq_f32_e32 v116, v114
	s_nop 0
	v_mov_b32_e32 v114, s5
	v_mov_b32_e32 v115, s4
	v_mul_f32_e32 v117, 0x3e38aa3b, v116
	v_readlane_b32 s4, v251, 43
	v_cndmask_b32_e64 v170, v116, v117, s[42:43]
	v_lshlrev_b64 v[116:117], 11, v[168:169]
	v_readlane_b32 s5, v251, 44
	v_lshl_add_u64 v[180:181], v[144:145], 2, v[114:115]
	s_nop 0
	v_lshl_add_u64 v[118:119], s[4:5], 0, v[116:117]
	v_readlane_b32 s4, v253, 16
	v_readlane_b32 s5, v253, 17
	v_lshl_add_u64 v[118:119], s[64:65], 1, v[118:119]
	s_nop 0
	v_lshl_add_u64 v[116:117], s[4:5], 0, v[116:117]
	s_movk_i32 s4, 0xf800
	v_lshl_add_u64 v[116:117], s[76:77], 1, v[116:117]
	s_mov_b32 s5, -1
	v_lshl_add_u64 v[116:117], v[116:117], 0, s[4:5]
	v_cndmask_b32_e64 v169, v117, v119, s[42:43]
	v_cndmask_b32_e64 v168, v116, v118, s[42:43]
	global_load_dwordx4 v[216:219], v[180:181], off offset:16
	global_load_dwordx4 v[212:215], v[180:181], off
	global_load_dwordx4 v[204:207], v[180:181], off offset:144
	global_load_dwordx4 v[220:223], v[180:181], off offset:128
	s_waitcnt vmcnt(0)
	v_lshl_add_u64 v[168:169], v[144:145], 1, v[168:169]
	v_pk_mul_f32 v[116:117], v[176:177], v[218:219]
	v_pk_mul_f32 v[120:121], v[172:173], v[214:215]
	v_pk_mul_f32 v[118:119], v[174:175], v[212:213]
	v_pk_mul_f32 v[114:115], v[178:179], v[216:217]
	v_pk_mul_f32 v[120:121], v[170:171], v[120:121] op_sel_hi:[0,1]
	v_pk_mul_f32 v[118:119], v[170:171], v[118:119] op_sel_hi:[0,1]
	v_pk_mul_f32 v[172:173], v[170:171], v[116:117] op_sel_hi:[0,1]
	v_pk_mul_f32 v[116:117], v[170:171], v[114:115] op_sel_hi:[0,1]
	v_cvt_pk_bf16_f32 v114, v118, v119
	v_cvt_pk_bf16_f32 v115, v120, v121
	v_cvt_pk_bf16_f32 v116, v116, v117
	v_cvt_pk_bf16_f32 v117, v172, v173
	global_store_dwordx4 v[168:169], v[114:117], off sc0 sc1
	s_nop 1
	v_pk_mul_f32 v[116:117], v[122:123], v[206:207]
	v_pk_mul_f32 v[120:121], v[126:127], v[222:223]
	v_pk_mul_f32 v[118:119], v[128:129], v[220:221]
	v_pk_mul_f32 v[114:115], v[124:125], v[204:205]
	v_pk_mul_f32 v[120:121], v[170:171], v[120:121] op_sel_hi:[0,1]
	v_pk_mul_f32 v[118:119], v[170:171], v[118:119] op_sel_hi:[0,1]
	v_pk_mul_f32 v[122:123], v[170:171], v[116:117] op_sel_hi:[0,1]
	v_pk_mul_f32 v[116:117], v[170:171], v[114:115] op_sel_hi:[0,1]
	v_cvt_pk_bf16_f32 v114, v118, v119
	v_cvt_pk_bf16_f32 v115, v120, v121
	v_cvt_pk_bf16_f32 v116, v116, v117
	v_cvt_pk_bf16_f32 v117, v122, v123
	global_store_dwordx4 v[168:169], v[114:117], off offset:64 sc0 sc1
	s_nop 1

.LBB0_532:
	v_readlane_b32 s4, v253, 16
	s_andn2_b64 vcc, exec, s[0:1]
	v_readlane_b32 s5, v253, 17
	s_cbranch_vccnz .LBB0_534
	v_pk_mul_f32 v[114:115], v[112:113], v[122:123] op_sel_hi:[1,0]
	v_pk_mul_f32 v[116:117], v[110:111], v[122:123] op_sel_hi:[1,0]
	v_pk_mul_f32 v[110:111], v[114:115], v[114:115]
	v_pk_mul_f32 v[112:113], v[116:117], v[116:117]
	v_pk_mul_f32 v[120:121], v[106:107], v[122:123] op_sel_hi:[1,0]
	v_pk_mov_b32 v[118:119], v[112:113], v[110:111] op_sel:[1,0]
	v_mov_b32_e32 v113, v111
	v_pk_add_f32 v[110:111], v[118:119], v[112:113]
	v_pk_mul_f32 v[118:119], v[108:109], v[122:123] op_sel_hi:[1,0]
	v_pk_mul_f32 v[108:109], v[120:121], v[120:121]
	v_pk_mul_f32 v[106:107], v[118:119], v[118:119]
	v_pk_mul_f32 v[112:113], v[102:103], v[122:123] op_sel_hi:[1,0]
	v_pk_add_f32 v[124:125], v[110:111], v[110:111] op_sel_hi:[0,1]
	v_pk_mov_b32 v[110:111], v[108:109], v[106:107] op_sel:[1,0]
	v_mov_b32_e32 v109, v107
	v_mul_f32_e32 v102, v112, v112
	v_pk_add_f32 v[106:107], v[110:111], v[108:109]
	v_pk_mul_f32 v[110:111], v[104:105], v[122:123] op_sel_hi:[1,0]
	v_pk_fma_f32 v[102:103], v[112:113], v[112:113], v[102:103] op_sel_hi:[1,1,0]
	v_pk_add_f32 v[126:127], v[106:107], v[106:107] op_sel_hi:[0,1]
	v_mul_f32_e32 v102, v110, v110
	v_pk_fma_f32 v[104:105], v[110:111], v[110:111], v[102:103] op_sel_hi:[1,1,0]
	v_pk_mul_f32 v[106:107], v[100:101], v[122:123] op_sel_hi:[1,0]
	v_pk_mul_f32 v[108:109], v[98:99], v[122:123] op_sel_hi:[1,0]
	v_mul_f32_e32 v124, v106, v106
	v_mul_f32_e32 v102, v108, v108
	v_mul_f32_e32 v104, v109, v109
	v_mul_f32_e32 v126, v107, v107
	v_pk_add_f32 v[98:99], v[102:103], v[104:105]
	v_pk_add_f32 v[100:101], v[124:125], v[126:127]
	s_and_b64 s[0:1], s[42:43], exec
	v_pk_add_f32 v[98:99], v[98:99], v[100:101]
	s_nop 0
	v_add_f32_e32 v98, v98, v99
	ds_bpermute_b32 v99, v185, v98
	s_waitcnt lgkmcnt(0)
	v_add_f32_e32 v98, v98, v99
	ds_bpermute_b32 v99, v184, v98
	s_waitcnt lgkmcnt(0)
	v_add_f32_e32 v98, v98, v99
	v_fmamk_f32 v98, v98, 0x3c800000, v243
	s_nop 1
	s_cselect_b32 s0, s27, s39
	s_cselect_b32 s1, s26, s38
	v_rsq_f32_e32 v100, v98
	s_nop 0
	v_mov_b32_e32 v98, s1
	v_mov_b32_e32 v99, s0
	v_mul_f32_e32 v101, 0x3e38aa3b, v100
	v_readlane_b32 s0, v251, 43
	v_cndmask_b32_e64 v122, v100, v101, s[42:43]
	v_lshlrev_b64 v[100:101], 11, v[166:167]
	v_readlane_b32 s1, v251, 44
	v_lshl_add_u64 v[126:127], v[144:145], 2, v[98:99]
	s_nop 0
	v_lshl_add_u64 v[102:103], s[0:1], 0, v[100:101]
	v_lshl_add_u64 v[100:101], s[4:5], 0, v[100:101]
	s_movk_i32 s0, 0xf800
	v_lshl_add_u64 v[100:101], s[76:77], 1, v[100:101]
	s_mov_b32 s1, -1
	v_lshl_add_u64 v[102:103], s[64:65], 1, v[102:103]
	v_lshl_add_u64 v[100:101], v[100:101], 0, s[0:1]
	v_cndmask_b32_e64 v125, v101, v103, s[42:43]
	v_cndmask_b32_e64 v124, v100, v102, s[42:43]
	v_pk_mul_f32 v[100:101], v[118:119], v[218:219]
	v_pk_mul_f32 v[104:105], v[114:115], v[214:215]
	v_pk_mul_f32 v[102:103], v[116:117], v[212:213]
	v_pk_mul_f32 v[98:99], v[120:121], v[216:217]
	v_pk_mul_f32 v[104:105], v[122:123], v[104:105] op_sel_hi:[0,1]
	v_pk_mul_f32 v[102:103], v[122:123], v[102:103] op_sel_hi:[0,1]
	v_pk_mul_f32 v[114:115], v[122:123], v[100:101] op_sel_hi:[0,1]
	v_pk_mul_f32 v[100:101], v[122:123], v[98:99] op_sel_hi:[0,1]
	v_cvt_pk_bf16_f32 v98, v102, v103
	v_cvt_pk_bf16_f32 v99, v104, v105
	v_cvt_pk_bf16_f32 v100, v100, v101
	v_cvt_pk_bf16_f32 v101, v114, v115
	v_lshl_add_u64 v[114:115], v[144:145], 1, v[124:125]
	global_store_dwordx4 v[114:115], v[98:101], off sc0 sc1
	s_nop 1
	v_pk_mul_f32 v[100:101], v[106:107], v[206:207]
	v_pk_mul_f32 v[104:105], v[110:111], v[222:223]
	v_pk_mul_f32 v[102:103], v[112:113], v[220:221]
	v_pk_mul_f32 v[98:99], v[108:109], v[204:205]
	v_pk_mul_f32 v[104:105], v[122:123], v[104:105] op_sel_hi:[0,1]
	v_pk_mul_f32 v[102:103], v[122:123], v[102:103] op_sel_hi:[0,1]
	v_pk_mul_f32 v[106:107], v[122:123], v[100:101] op_sel_hi:[0,1]
	v_pk_mul_f32 v[100:101], v[122:123], v[98:99] op_sel_hi:[0,1]
	v_cvt_pk_bf16_f32 v98, v102, v103
	v_cvt_pk_bf16_f32 v99, v104, v105
	v_cvt_pk_bf16_f32 v100, v100, v101
	v_cvt_pk_bf16_f32 v101, v106, v107
	global_store_dwordx4 v[114:115], v[98:101], off offset:64 sc0 sc1
	s_nop 1

.LBB0_536:
	s_andn2_b64 vcc, exec, s[0:1]
	s_cbranch_vccnz .LBB0_538
	v_pk_mul_f32 v[98:99], v[96:97], v[106:107] op_sel_hi:[1,0]
	v_pk_mul_f32 v[100:101], v[94:95], v[106:107] op_sel_hi:[1,0]
	v_pk_mul_f32 v[94:95], v[98:99], v[98:99]
	v_pk_mul_f32 v[96:97], v[100:101], v[100:101]
	v_pk_mul_f32 v[104:105], v[90:91], v[106:107] op_sel_hi:[1,0]
	v_pk_mov_b32 v[102:103], v[96:97], v[94:95] op_sel:[1,0]
	v_mov_b32_e32 v97, v95
	v_pk_add_f32 v[94:95], v[102:103], v[96:97]
	v_pk_mul_f32 v[102:103], v[92:93], v[106:107] op_sel_hi:[1,0]
	v_pk_mul_f32 v[92:93], v[104:105], v[104:105]
	v_pk_mul_f32 v[90:91], v[102:103], v[102:103]
	v_pk_mul_f32 v[96:97], v[86:87], v[106:107] op_sel_hi:[1,0]
	v_pk_add_f32 v[108:109], v[94:95], v[94:95] op_sel_hi:[0,1]
	v_pk_mov_b32 v[94:95], v[92:93], v[90:91] op_sel:[1,0]
	v_mov_b32_e32 v93, v91
	v_mul_f32_e32 v86, v96, v96
	v_pk_add_f32 v[90:91], v[94:95], v[92:93]
	v_pk_mul_f32 v[94:95], v[88:89], v[106:107] op_sel_hi:[1,0]
	v_pk_fma_f32 v[86:87], v[96:97], v[96:97], v[86:87] op_sel_hi:[1,1,0]
	v_pk_add_f32 v[110:111], v[90:91], v[90:91] op_sel_hi:[0,1]
	v_mul_f32_e32 v86, v94, v94
	v_pk_fma_f32 v[88:89], v[94:95], v[94:95], v[86:87] op_sel_hi:[1,1,0]
	v_pk_mul_f32 v[90:91], v[84:85], v[106:107] op_sel_hi:[1,0]
	v_pk_mul_f32 v[92:93], v[82:83], v[106:107] op_sel_hi:[1,0]
	v_mul_f32_e32 v108, v90, v90
	v_mul_f32_e32 v86, v92, v92
	v_mul_f32_e32 v88, v93, v93
	v_mul_f32_e32 v110, v91, v91
	v_pk_add_f32 v[82:83], v[86:87], v[88:89]
	v_pk_add_f32 v[84:85], v[108:109], v[110:111]
	s_and_b64 s[0:1], s[42:43], exec
	v_pk_add_f32 v[82:83], v[82:83], v[84:85]
	s_nop 0
	v_add_f32_e32 v82, v82, v83
	ds_bpermute_b32 v83, v185, v82
	s_waitcnt lgkmcnt(0)
	v_add_f32_e32 v82, v82, v83
	ds_bpermute_b32 v83, v184, v82
	s_waitcnt lgkmcnt(0)
	v_add_f32_e32 v82, v82, v83
	v_fmamk_f32 v82, v82, 0x3c800000, v243
	s_nop 1
	s_cselect_b32 s0, s27, s39
	s_cselect_b32 s1, s26, s38
	v_rsq_f32_e32 v84, v82
	s_nop 0
	v_mov_b32_e32 v82, s1
	v_mov_b32_e32 v83, s0
	v_mul_f32_e32 v85, 0x3e38aa3b, v84
	v_readlane_b32 s0, v251, 43
	v_cndmask_b32_e64 v106, v84, v85, s[42:43]
	v_lshlrev_b64 v[84:85], 11, v[164:165]
	v_readlane_b32 s1, v251, 44
	v_lshl_add_u64 v[110:111], v[144:145], 2, v[82:83]
	s_nop 0
	v_lshl_add_u64 v[86:87], s[0:1], 0, v[84:85]
	v_lshl_add_u64 v[84:85], s[4:5], 0, v[84:85]
	s_movk_i32 s0, 0xf800
	v_lshl_add_u64 v[84:85], s[76:77], 1, v[84:85]
	s_mov_b32 s1, -1
	v_lshl_add_u64 v[86:87], s[64:65], 1, v[86:87]
	v_lshl_add_u64 v[84:85], v[84:85], 0, s[0:1]
	v_cndmask_b32_e64 v109, v85, v87, s[42:43]
	v_cndmask_b32_e64 v108, v84, v86, s[42:43]
	v_pk_mul_f32 v[84:85], v[102:103], v[218:219]
	v_pk_mul_f32 v[88:89], v[98:99], v[214:215]
	v_pk_mul_f32 v[86:87], v[100:101], v[212:213]
	v_pk_mul_f32 v[82:83], v[104:105], v[216:217]
	v_pk_mul_f32 v[88:89], v[106:107], v[88:89] op_sel_hi:[0,1]
	v_pk_mul_f32 v[86:87], v[106:107], v[86:87] op_sel_hi:[0,1]
	v_pk_mul_f32 v[98:99], v[106:107], v[84:85] op_sel_hi:[0,1]
	v_pk_mul_f32 v[84:85], v[106:107], v[82:83] op_sel_hi:[0,1]
	v_cvt_pk_bf16_f32 v82, v86, v87
	v_cvt_pk_bf16_f32 v83, v88, v89
	v_cvt_pk_bf16_f32 v84, v84, v85
	v_cvt_pk_bf16_f32 v85, v98, v99
	v_lshl_add_u64 v[98:99], v[144:145], 1, v[108:109]
	global_store_dwordx4 v[98:99], v[82:85], off sc0 sc1
	s_nop 1
	v_pk_mul_f32 v[84:85], v[90:91], v[206:207]
	v_pk_mul_f32 v[88:89], v[94:95], v[222:223]
	v_pk_mul_f32 v[86:87], v[96:97], v[220:221]
	v_pk_mul_f32 v[82:83], v[92:93], v[204:205]
	v_pk_mul_f32 v[88:89], v[106:107], v[88:89] op_sel_hi:[0,1]
	v_pk_mul_f32 v[86:87], v[106:107], v[86:87] op_sel_hi:[0,1]
	v_pk_mul_f32 v[90:91], v[106:107], v[84:85] op_sel_hi:[0,1]
	v_pk_mul_f32 v[84:85], v[106:107], v[82:83] op_sel_hi:[0,1]
	v_cvt_pk_bf16_f32 v82, v86, v87
	v_cvt_pk_bf16_f32 v83, v88, v89
	v_cvt_pk_bf16_f32 v84, v84, v85
	v_cvt_pk_bf16_f32 v85, v90, v91
	global_store_dwordx4 v[98:99], v[82:85], off offset:64 sc0 sc1
	s_nop 1

.LBB0_540:
	s_andn2_b64 vcc, exec, s[0:1]
	s_cbranch_vccnz .LBB0_542
	v_pk_mul_f32 v[82:83], v[80:81], v[90:91] op_sel_hi:[1,0]
	v_pk_mul_f32 v[84:85], v[78:79], v[90:91] op_sel_hi:[1,0]
	v_pk_mul_f32 v[78:79], v[82:83], v[82:83]
	v_pk_mul_f32 v[80:81], v[84:85], v[84:85]
	v_pk_mul_f32 v[88:89], v[74:75], v[90:91] op_sel_hi:[1,0]
	v_pk_mov_b32 v[86:87], v[80:81], v[78:79] op_sel:[1,0]
	v_mov_b32_e32 v81, v79
	v_pk_add_f32 v[78:79], v[86:87], v[80:81]
	v_pk_mul_f32 v[86:87], v[76:77], v[90:91] op_sel_hi:[1,0]
	v_pk_mul_f32 v[76:77], v[88:89], v[88:89]
	v_pk_mul_f32 v[74:75], v[86:87], v[86:87]
	v_pk_mul_f32 v[80:81], v[70:71], v[90:91] op_sel_hi:[1,0]
	v_pk_add_f32 v[92:93], v[78:79], v[78:79] op_sel_hi:[0,1]
	v_pk_mov_b32 v[78:79], v[76:77], v[74:75] op_sel:[1,0]
	v_mov_b32_e32 v77, v75
	v_mul_f32_e32 v70, v80, v80
	v_pk_add_f32 v[74:75], v[78:79], v[76:77]
	v_pk_mul_f32 v[78:79], v[72:73], v[90:91] op_sel_hi:[1,0]
	v_pk_fma_f32 v[70:71], v[80:81], v[80:81], v[70:71] op_sel_hi:[1,1,0]
	v_pk_add_f32 v[94:95], v[74:75], v[74:75] op_sel_hi:[0,1]
	v_mul_f32_e32 v70, v78, v78
	v_pk_fma_f32 v[72:73], v[78:79], v[78:79], v[70:71] op_sel_hi:[1,1,0]
	v_pk_mul_f32 v[74:75], v[68:69], v[90:91] op_sel_hi:[1,0]
	v_pk_mul_f32 v[76:77], v[66:67], v[90:91] op_sel_hi:[1,0]
	v_mul_f32_e32 v92, v74, v74
	v_mul_f32_e32 v70, v76, v76
	v_mul_f32_e32 v72, v77, v77
	v_mul_f32_e32 v94, v75, v75
	v_pk_add_f32 v[66:67], v[70:71], v[72:73]
	v_pk_add_f32 v[68:69], v[92:93], v[94:95]
	s_and_b64 s[0:1], s[42:43], exec
	v_pk_add_f32 v[66:67], v[66:67], v[68:69]
	s_nop 0
	v_add_f32_e32 v66, v66, v67
	ds_bpermute_b32 v67, v185, v66
	s_waitcnt lgkmcnt(0)
	v_add_f32_e32 v66, v66, v67
	ds_bpermute_b32 v67, v184, v66
	s_waitcnt lgkmcnt(0)
	v_add_f32_e32 v66, v66, v67
	v_fmamk_f32 v66, v66, 0x3c800000, v243
	s_nop 1
	s_cselect_b32 s0, s27, s39
	s_cselect_b32 s1, s26, s38
	v_rsq_f32_e32 v68, v66
	s_nop 0
	v_mov_b32_e32 v66, s1
	v_mov_b32_e32 v67, s0
	v_mul_f32_e32 v69, 0x3e38aa3b, v68
	v_readlane_b32 s0, v251, 43
	v_cndmask_b32_e64 v90, v68, v69, s[42:43]
	v_lshlrev_b64 v[68:69], 11, v[162:163]
	v_readlane_b32 s1, v251, 44
	v_lshl_add_u64 v[94:95], v[144:145], 2, v[66:67]
	s_nop 0
	v_lshl_add_u64 v[70:71], s[0:1], 0, v[68:69]
	v_lshl_add_u64 v[68:69], s[4:5], 0, v[68:69]
	s_movk_i32 s0, 0xf800
	v_lshl_add_u64 v[68:69], s[76:77], 1, v[68:69]
	s_mov_b32 s1, -1
	v_lshl_add_u64 v[70:71], s[64:65], 1, v[70:71]
	v_lshl_add_u64 v[68:69], v[68:69], 0, s[0:1]
	v_cndmask_b32_e64 v93, v69, v71, s[42:43]
	v_cndmask_b32_e64 v92, v68, v70, s[42:43]
	v_pk_mul_f32 v[68:69], v[86:87], v[218:219]
	v_pk_mul_f32 v[72:73], v[82:83], v[214:215]
	v_pk_mul_f32 v[70:71], v[84:85], v[212:213]
	v_pk_mul_f32 v[66:67], v[88:89], v[216:217]
	v_pk_mul_f32 v[72:73], v[90:91], v[72:73] op_sel_hi:[0,1]
	v_pk_mul_f32 v[70:71], v[90:91], v[70:71] op_sel_hi:[0,1]
	v_pk_mul_f32 v[82:83], v[90:91], v[68:69] op_sel_hi:[0,1]
	v_pk_mul_f32 v[68:69], v[90:91], v[66:67] op_sel_hi:[0,1]
	v_cvt_pk_bf16_f32 v66, v70, v71
	v_cvt_pk_bf16_f32 v67, v72, v73
	v_cvt_pk_bf16_f32 v68, v68, v69
	v_cvt_pk_bf16_f32 v69, v82, v83
	v_lshl_add_u64 v[82:83], v[144:145], 1, v[92:93]
	global_store_dwordx4 v[82:83], v[66:69], off sc0 sc1
	s_nop 1
	v_pk_mul_f32 v[68:69], v[74:75], v[206:207]
	v_pk_mul_f32 v[72:73], v[78:79], v[222:223]
	v_pk_mul_f32 v[70:71], v[80:81], v[220:221]
	v_pk_mul_f32 v[66:67], v[76:77], v[204:205]
	v_pk_mul_f32 v[72:73], v[90:91], v[72:73] op_sel_hi:[0,1]
	v_pk_mul_f32 v[70:71], v[90:91], v[70:71] op_sel_hi:[0,1]
	v_pk_mul_f32 v[74:75], v[90:91], v[68:69] op_sel_hi:[0,1]
	v_pk_mul_f32 v[68:69], v[90:91], v[66:67] op_sel_hi:[0,1]
	v_cvt_pk_bf16_f32 v66, v70, v71
	v_cvt_pk_bf16_f32 v67, v72, v73
	v_cvt_pk_bf16_f32 v68, v68, v69
	v_cvt_pk_bf16_f32 v69, v74, v75
	global_store_dwordx4 v[82:83], v[66:69], off offset:64 sc0 sc1
	s_nop 1

.LBB0_544:
	s_andn2_b64 vcc, exec, s[0:1]
	s_cbranch_vccnz .LBB0_546
	v_pk_mul_f32 v[66:67], v[64:65], v[74:75] op_sel_hi:[1,0]
	v_pk_mul_f32 v[68:69], v[62:63], v[74:75] op_sel_hi:[1,0]
	v_pk_mul_f32 v[62:63], v[66:67], v[66:67]
	v_pk_mul_f32 v[64:65], v[68:69], v[68:69]
	v_pk_mul_f32 v[72:73], v[58:59], v[74:75] op_sel_hi:[1,0]
	v_pk_mov_b32 v[70:71], v[64:65], v[62:63] op_sel:[1,0]
	v_mov_b32_e32 v65, v63
	v_pk_add_f32 v[62:63], v[70:71], v[64:65]
	v_pk_mul_f32 v[70:71], v[60:61], v[74:75] op_sel_hi:[1,0]
	v_pk_mul_f32 v[60:61], v[72:73], v[72:73]
	v_pk_mul_f32 v[58:59], v[70:71], v[70:71]
	v_pk_mul_f32 v[64:65], v[54:55], v[74:75] op_sel_hi:[1,0]
	v_pk_add_f32 v[76:77], v[62:63], v[62:63] op_sel_hi:[0,1]
	v_pk_mov_b32 v[62:63], v[60:61], v[58:59] op_sel:[1,0]
	v_mov_b32_e32 v61, v59
	v_mul_f32_e32 v54, v64, v64
	v_pk_add_f32 v[58:59], v[62:63], v[60:61]
	v_pk_mul_f32 v[62:63], v[56:57], v[74:75] op_sel_hi:[1,0]
	v_pk_fma_f32 v[54:55], v[64:65], v[64:65], v[54:55] op_sel_hi:[1,1,0]
	v_pk_add_f32 v[78:79], v[58:59], v[58:59] op_sel_hi:[0,1]
	v_mul_f32_e32 v54, v62, v62
	v_pk_fma_f32 v[56:57], v[62:63], v[62:63], v[54:55] op_sel_hi:[1,1,0]
	v_pk_mul_f32 v[58:59], v[52:53], v[74:75] op_sel_hi:[1,0]
	v_pk_mul_f32 v[60:61], v[50:51], v[74:75] op_sel_hi:[1,0]
	v_mul_f32_e32 v76, v58, v58
	v_mul_f32_e32 v54, v60, v60
	v_mul_f32_e32 v56, v61, v61
	v_mul_f32_e32 v78, v59, v59
	v_pk_add_f32 v[50:51], v[54:55], v[56:57]
	v_pk_add_f32 v[52:53], v[76:77], v[78:79]
	s_and_b64 s[0:1], s[42:43], exec
	v_pk_add_f32 v[50:51], v[50:51], v[52:53]
	s_nop 0
	v_add_f32_e32 v50, v50, v51
	ds_bpermute_b32 v51, v185, v50
	s_waitcnt lgkmcnt(0)
	v_add_f32_e32 v50, v50, v51
	ds_bpermute_b32 v51, v184, v50
	s_waitcnt lgkmcnt(0)
	v_add_f32_e32 v50, v50, v51
	v_fmamk_f32 v50, v50, 0x3c800000, v243
	s_nop 1
	s_cselect_b32 s0, s27, s39
	s_cselect_b32 s1, s26, s38
	v_rsq_f32_e32 v52, v50
	s_nop 0
	v_mov_b32_e32 v50, s1
	v_mov_b32_e32 v51, s0
	v_mul_f32_e32 v53, 0x3e38aa3b, v52
	v_readlane_b32 s0, v251, 43
	v_cndmask_b32_e64 v74, v52, v53, s[42:43]
	v_lshlrev_b64 v[52:53], 11, v[160:161]
	v_readlane_b32 s1, v251, 44
	v_lshl_add_u64 v[78:79], v[144:145], 2, v[50:51]
	s_nop 0
	v_lshl_add_u64 v[54:55], s[0:1], 0, v[52:53]
	v_lshl_add_u64 v[52:53], s[4:5], 0, v[52:53]
	s_movk_i32 s0, 0xf800
	v_lshl_add_u64 v[52:53], s[76:77], 1, v[52:53]
	s_mov_b32 s1, -1
	v_lshl_add_u64 v[54:55], s[64:65], 1, v[54:55]
	v_lshl_add_u64 v[52:53], v[52:53], 0, s[0:1]
	v_cndmask_b32_e64 v77, v53, v55, s[42:43]
	v_cndmask_b32_e64 v76, v52, v54, s[42:43]
	v_pk_mul_f32 v[52:53], v[70:71], v[218:219]
	v_pk_mul_f32 v[56:57], v[66:67], v[214:215]
	v_pk_mul_f32 v[54:55], v[68:69], v[212:213]
	v_pk_mul_f32 v[50:51], v[72:73], v[216:217]
	v_pk_mul_f32 v[56:57], v[74:75], v[56:57] op_sel_hi:[0,1]
	v_pk_mul_f32 v[54:55], v[74:75], v[54:55] op_sel_hi:[0,1]
	v_pk_mul_f32 v[66:67], v[74:75], v[52:53] op_sel_hi:[0,1]
	v_pk_mul_f32 v[52:53], v[74:75], v[50:51] op_sel_hi:[0,1]
	v_cvt_pk_bf16_f32 v50, v54, v55
	v_cvt_pk_bf16_f32 v51, v56, v57
	v_cvt_pk_bf16_f32 v52, v52, v53
	v_cvt_pk_bf16_f32 v53, v66, v67
	v_lshl_add_u64 v[66:67], v[144:145], 1, v[76:77]
	global_store_dwordx4 v[66:67], v[50:53], off sc0 sc1
	s_nop 1
	v_pk_mul_f32 v[52:53], v[58:59], v[206:207]
	v_pk_mul_f32 v[56:57], v[62:63], v[222:223]
	v_pk_mul_f32 v[54:55], v[64:65], v[220:221]
	v_pk_mul_f32 v[50:51], v[60:61], v[204:205]
	v_pk_mul_f32 v[56:57], v[74:75], v[56:57] op_sel_hi:[0,1]
	v_pk_mul_f32 v[54:55], v[74:75], v[54:55] op_sel_hi:[0,1]
	v_pk_mul_f32 v[58:59], v[74:75], v[52:53] op_sel_hi:[0,1]
	v_pk_mul_f32 v[52:53], v[74:75], v[50:51] op_sel_hi:[0,1]
	v_cvt_pk_bf16_f32 v50, v54, v55
	v_cvt_pk_bf16_f32 v51, v56, v57
	v_cvt_pk_bf16_f32 v52, v52, v53
	v_cvt_pk_bf16_f32 v53, v58, v59
	global_store_dwordx4 v[66:67], v[50:53], off offset:64 sc0 sc1
	s_nop 1

.LBB0_548:
	s_andn2_b64 vcc, exec, s[0:1]
	s_cbranch_vccnz .LBB0_550
	v_pk_mul_f32 v[50:51], v[48:49], v[58:59] op_sel_hi:[1,0]
	v_pk_mul_f32 v[52:53], v[46:47], v[58:59] op_sel_hi:[1,0]
	v_pk_mul_f32 v[46:47], v[50:51], v[50:51]
	v_pk_mul_f32 v[48:49], v[52:53], v[52:53]
	v_pk_mul_f32 v[56:57], v[42:43], v[58:59] op_sel_hi:[1,0]
	v_pk_mov_b32 v[54:55], v[48:49], v[46:47] op_sel:[1,0]
	v_mov_b32_e32 v49, v47
	v_pk_add_f32 v[46:47], v[54:55], v[48:49]
	v_pk_mul_f32 v[54:55], v[44:45], v[58:59] op_sel_hi:[1,0]
	v_pk_mul_f32 v[44:45], v[56:57], v[56:57]
	v_pk_mul_f32 v[42:43], v[54:55], v[54:55]
	v_pk_mul_f32 v[48:49], v[38:39], v[58:59] op_sel_hi:[1,0]
	v_pk_add_f32 v[60:61], v[46:47], v[46:47] op_sel_hi:[0,1]
	v_pk_mov_b32 v[46:47], v[44:45], v[42:43] op_sel:[1,0]
	v_mov_b32_e32 v45, v43
	v_mul_f32_e32 v38, v48, v48
	v_pk_add_f32 v[42:43], v[46:47], v[44:45]
	v_pk_mul_f32 v[46:47], v[40:41], v[58:59] op_sel_hi:[1,0]
	v_pk_fma_f32 v[38:39], v[48:49], v[48:49], v[38:39] op_sel_hi:[1,1,0]
	v_pk_add_f32 v[62:63], v[42:43], v[42:43] op_sel_hi:[0,1]
	v_mul_f32_e32 v38, v46, v46
	v_pk_fma_f32 v[40:41], v[46:47], v[46:47], v[38:39] op_sel_hi:[1,1,0]
	v_pk_mul_f32 v[42:43], v[36:37], v[58:59] op_sel_hi:[1,0]
	v_pk_mul_f32 v[44:45], v[34:35], v[58:59] op_sel_hi:[1,0]
	v_mul_f32_e32 v60, v42, v42
	v_mul_f32_e32 v38, v44, v44
	v_mul_f32_e32 v40, v45, v45
	v_mul_f32_e32 v62, v43, v43
	v_pk_add_f32 v[34:35], v[38:39], v[40:41]
	v_pk_add_f32 v[36:37], v[60:61], v[62:63]
	s_and_b64 s[0:1], s[42:43], exec
	v_pk_add_f32 v[34:35], v[34:35], v[36:37]
	s_nop 0
	v_add_f32_e32 v34, v34, v35
	ds_bpermute_b32 v35, v185, v34
	s_waitcnt lgkmcnt(0)
	v_add_f32_e32 v34, v34, v35
	ds_bpermute_b32 v35, v184, v34
	s_waitcnt lgkmcnt(0)
	v_add_f32_e32 v34, v34, v35
	v_fmamk_f32 v34, v34, 0x3c800000, v243
	s_nop 1
	s_cselect_b32 s0, s27, s39
	s_cselect_b32 s1, s26, s38
	v_rsq_f32_e32 v36, v34
	s_nop 0
	v_mov_b32_e32 v34, s1
	v_mov_b32_e32 v35, s0
	v_mul_f32_e32 v37, 0x3e38aa3b, v36
	v_readlane_b32 s0, v251, 43
	v_cndmask_b32_e64 v58, v36, v37, s[42:43]
	v_lshlrev_b64 v[36:37], 11, v[158:159]
	v_readlane_b32 s1, v251, 44
	v_lshl_add_u64 v[62:63], v[144:145], 2, v[34:35]
	s_nop 0
	v_lshl_add_u64 v[38:39], s[0:1], 0, v[36:37]
	v_lshl_add_u64 v[36:37], s[4:5], 0, v[36:37]
	s_movk_i32 s0, 0xf800
	v_lshl_add_u64 v[36:37], s[76:77], 1, v[36:37]
	s_mov_b32 s1, -1
	v_lshl_add_u64 v[38:39], s[64:65], 1, v[38:39]
	v_lshl_add_u64 v[36:37], v[36:37], 0, s[0:1]
	v_cndmask_b32_e64 v61, v37, v39, s[42:43]
	v_cndmask_b32_e64 v60, v36, v38, s[42:43]
	v_pk_mul_f32 v[36:37], v[54:55], v[218:219]
	v_pk_mul_f32 v[40:41], v[50:51], v[214:215]
	v_pk_mul_f32 v[38:39], v[52:53], v[212:213]
	v_pk_mul_f32 v[34:35], v[56:57], v[216:217]
	v_pk_mul_f32 v[40:41], v[58:59], v[40:41] op_sel_hi:[0,1]
	v_pk_mul_f32 v[38:39], v[58:59], v[38:39] op_sel_hi:[0,1]
	v_pk_mul_f32 v[50:51], v[58:59], v[36:37] op_sel_hi:[0,1]
	v_pk_mul_f32 v[36:37], v[58:59], v[34:35] op_sel_hi:[0,1]
	v_cvt_pk_bf16_f32 v34, v38, v39
	v_cvt_pk_bf16_f32 v35, v40, v41
	v_cvt_pk_bf16_f32 v36, v36, v37
	v_cvt_pk_bf16_f32 v37, v50, v51
	v_lshl_add_u64 v[50:51], v[144:145], 1, v[60:61]
	global_store_dwordx4 v[50:51], v[34:37], off sc0 sc1
	s_nop 1
	v_pk_mul_f32 v[36:37], v[42:43], v[206:207]
	v_pk_mul_f32 v[40:41], v[46:47], v[222:223]
	v_pk_mul_f32 v[38:39], v[48:49], v[220:221]
	v_pk_mul_f32 v[34:35], v[44:45], v[204:205]
	v_pk_mul_f32 v[40:41], v[58:59], v[40:41] op_sel_hi:[0,1]
	v_pk_mul_f32 v[38:39], v[58:59], v[38:39] op_sel_hi:[0,1]
	v_pk_mul_f32 v[42:43], v[58:59], v[36:37] op_sel_hi:[0,1]
	v_pk_mul_f32 v[36:37], v[58:59], v[34:35] op_sel_hi:[0,1]
	v_cvt_pk_bf16_f32 v34, v38, v39
	v_cvt_pk_bf16_f32 v35, v40, v41
	v_cvt_pk_bf16_f32 v36, v36, v37
	v_cvt_pk_bf16_f32 v37, v42, v43
	global_store_dwordx4 v[50:51], v[34:37], off offset:64 sc0 sc1
	s_nop 1

.LBB0_552:
	s_andn2_b64 vcc, exec, s[0:1]
	s_cbranch_vccnz .LBB0_554
	v_pk_mul_f32 v[34:35], v[32:33], v[42:43] op_sel_hi:[1,0]
	v_pk_mul_f32 v[36:37], v[30:31], v[42:43] op_sel_hi:[1,0]
	v_pk_mul_f32 v[30:31], v[34:35], v[34:35]
	v_pk_mul_f32 v[32:33], v[36:37], v[36:37]
	v_pk_mul_f32 v[40:41], v[26:27], v[42:43] op_sel_hi:[1,0]
	v_pk_mov_b32 v[38:39], v[32:33], v[30:31] op_sel:[1,0]
	v_mov_b32_e32 v33, v31
	v_pk_add_f32 v[30:31], v[38:39], v[32:33]
	v_pk_mul_f32 v[38:39], v[28:29], v[42:43] op_sel_hi:[1,0]
	v_pk_mul_f32 v[28:29], v[40:41], v[40:41]
	v_pk_mul_f32 v[26:27], v[38:39], v[38:39]
	v_pk_mul_f32 v[32:33], v[22:23], v[42:43] op_sel_hi:[1,0]
	v_pk_add_f32 v[44:45], v[30:31], v[30:31] op_sel_hi:[0,1]
	v_pk_mov_b32 v[30:31], v[28:29], v[26:27] op_sel:[1,0]
	v_mov_b32_e32 v29, v27
	v_mul_f32_e32 v22, v32, v32
	v_pk_add_f32 v[26:27], v[30:31], v[28:29]
	v_pk_mul_f32 v[30:31], v[24:25], v[42:43] op_sel_hi:[1,0]
	v_pk_fma_f32 v[22:23], v[32:33], v[32:33], v[22:23] op_sel_hi:[1,1,0]
	v_pk_add_f32 v[46:47], v[26:27], v[26:27] op_sel_hi:[0,1]
	v_mul_f32_e32 v22, v30, v30
	v_pk_fma_f32 v[24:25], v[30:31], v[30:31], v[22:23] op_sel_hi:[1,1,0]
	v_pk_mul_f32 v[26:27], v[20:21], v[42:43] op_sel_hi:[1,0]
	v_pk_mul_f32 v[28:29], v[18:19], v[42:43] op_sel_hi:[1,0]
	v_mul_f32_e32 v44, v26, v26
	v_mul_f32_e32 v22, v28, v28
	v_mul_f32_e32 v24, v29, v29
	v_mul_f32_e32 v46, v27, v27
	v_pk_add_f32 v[18:19], v[22:23], v[24:25]
	v_pk_add_f32 v[20:21], v[44:45], v[46:47]
	s_and_b64 s[0:1], s[42:43], exec
	v_pk_add_f32 v[18:19], v[18:19], v[20:21]
	s_nop 0
	v_add_f32_e32 v18, v18, v19
	ds_bpermute_b32 v19, v185, v18
	s_waitcnt lgkmcnt(0)
	v_add_f32_e32 v18, v18, v19
	ds_bpermute_b32 v19, v184, v18
	s_waitcnt lgkmcnt(0)
	v_add_f32_e32 v18, v18, v19
	v_fmamk_f32 v18, v18, 0x3c800000, v243
	s_nop 1
	s_cselect_b32 s0, s27, s39
	s_cselect_b32 s1, s26, s38
	v_rsq_f32_e32 v20, v18
	s_nop 0
	v_mov_b32_e32 v18, s1
	v_mov_b32_e32 v19, s0
	v_mul_f32_e32 v21, 0x3e38aa3b, v20
	v_readlane_b32 s0, v251, 43
	v_cndmask_b32_e64 v42, v20, v21, s[42:43]
	v_lshlrev_b64 v[20:21], 11, v[156:157]
	v_readlane_b32 s1, v251, 44
	v_lshl_add_u64 v[46:47], v[144:145], 2, v[18:19]
	s_nop 0
	v_lshl_add_u64 v[22:23], s[0:1], 0, v[20:21]
	v_lshl_add_u64 v[20:21], s[4:5], 0, v[20:21]
	s_movk_i32 s0, 0xf800
	v_lshl_add_u64 v[20:21], s[76:77], 1, v[20:21]
	s_mov_b32 s1, -1
	v_lshl_add_u64 v[22:23], s[64:65], 1, v[22:23]
	v_lshl_add_u64 v[20:21], v[20:21], 0, s[0:1]
	v_cndmask_b32_e64 v45, v21, v23, s[42:43]
	v_cndmask_b32_e64 v44, v20, v22, s[42:43]
	v_pk_mul_f32 v[20:21], v[38:39], v[218:219]
	v_pk_mul_f32 v[24:25], v[34:35], v[214:215]
	v_pk_mul_f32 v[22:23], v[36:37], v[212:213]
	v_pk_mul_f32 v[18:19], v[40:41], v[216:217]
	v_pk_mul_f32 v[24:25], v[42:43], v[24:25] op_sel_hi:[0,1]
	v_pk_mul_f32 v[22:23], v[42:43], v[22:23] op_sel_hi:[0,1]
	v_pk_mul_f32 v[34:35], v[42:43], v[20:21] op_sel_hi:[0,1]
	v_pk_mul_f32 v[20:21], v[42:43], v[18:19] op_sel_hi:[0,1]
	v_cvt_pk_bf16_f32 v18, v22, v23
	v_cvt_pk_bf16_f32 v19, v24, v25
	v_cvt_pk_bf16_f32 v20, v20, v21
	v_cvt_pk_bf16_f32 v21, v34, v35
	v_lshl_add_u64 v[34:35], v[144:145], 1, v[44:45]
	global_store_dwordx4 v[34:35], v[18:21], off sc0 sc1
	s_nop 1
	v_pk_mul_f32 v[20:21], v[26:27], v[206:207]
	v_pk_mul_f32 v[24:25], v[30:31], v[222:223]
	v_pk_mul_f32 v[22:23], v[32:33], v[220:221]
	v_pk_mul_f32 v[18:19], v[28:29], v[204:205]
	v_pk_mul_f32 v[24:25], v[42:43], v[24:25] op_sel_hi:[0,1]
	v_pk_mul_f32 v[22:23], v[42:43], v[22:23] op_sel_hi:[0,1]
	v_pk_mul_f32 v[26:27], v[42:43], v[20:21] op_sel_hi:[0,1]
	v_pk_mul_f32 v[20:21], v[42:43], v[18:19] op_sel_hi:[0,1]
	v_cvt_pk_bf16_f32 v18, v22, v23
	v_cvt_pk_bf16_f32 v19, v24, v25
	v_cvt_pk_bf16_f32 v20, v20, v21
	v_cvt_pk_bf16_f32 v21, v26, v27
	global_store_dwordx4 v[34:35], v[18:21], off offset:64 sc0 sc1
	s_nop 1

.LBB0_556:
	s_andn2_b64 vcc, exec, s[0:1]
	s_cbranch_vccnz .LBB0_558
	v_pk_mul_f32 v[18:19], v[16:17], v[26:27] op_sel_hi:[1,0]
	v_pk_mul_f32 v[20:21], v[14:15], v[26:27] op_sel_hi:[1,0]
	v_pk_mul_f32 v[14:15], v[18:19], v[18:19]
	v_pk_mul_f32 v[16:17], v[20:21], v[20:21]
	v_pk_mul_f32 v[24:25], v[10:11], v[26:27] op_sel_hi:[1,0]
	v_pk_mov_b32 v[22:23], v[16:17], v[14:15] op_sel:[1,0]
	v_mov_b32_e32 v17, v15
	v_pk_add_f32 v[14:15], v[22:23], v[16:17]
	v_pk_mul_f32 v[22:23], v[12:13], v[26:27] op_sel_hi:[1,0]
	v_pk_mul_f32 v[12:13], v[24:25], v[24:25]
	v_pk_mul_f32 v[10:11], v[22:23], v[22:23]
	v_pk_mul_f32 v[16:17], v[6:7], v[26:27] op_sel_hi:[1,0]
	v_pk_add_f32 v[28:29], v[14:15], v[14:15] op_sel_hi:[0,1]
	v_pk_mov_b32 v[14:15], v[12:13], v[10:11] op_sel:[1,0]
	v_mov_b32_e32 v13, v11
	v_mul_f32_e32 v6, v16, v16
	v_pk_add_f32 v[10:11], v[14:15], v[12:13]
	v_pk_mul_f32 v[14:15], v[8:9], v[26:27] op_sel_hi:[1,0]
	v_pk_fma_f32 v[6:7], v[16:17], v[16:17], v[6:7] op_sel_hi:[1,1,0]
	v_pk_add_f32 v[30:31], v[10:11], v[10:11] op_sel_hi:[0,1]
	v_mul_f32_e32 v6, v14, v14
	v_pk_fma_f32 v[8:9], v[14:15], v[14:15], v[6:7] op_sel_hi:[1,1,0]
	v_pk_mul_f32 v[10:11], v[4:5], v[26:27] op_sel_hi:[1,0]
	v_pk_mul_f32 v[12:13], v[2:3], v[26:27] op_sel_hi:[1,0]
	v_mul_f32_e32 v28, v10, v10
	v_mul_f32_e32 v6, v12, v12
	v_mul_f32_e32 v8, v13, v13
	v_mul_f32_e32 v30, v11, v11
	v_pk_add_f32 v[2:3], v[6:7], v[8:9]
	v_pk_add_f32 v[4:5], v[28:29], v[30:31]
	s_and_b64 s[0:1], s[42:43], exec
	v_pk_add_f32 v[2:3], v[2:3], v[4:5]
	s_nop 0
	v_add_f32_e32 v2, v2, v3
	ds_bpermute_b32 v3, v185, v2
	s_waitcnt lgkmcnt(0)
	v_add_f32_e32 v2, v2, v3
	ds_bpermute_b32 v3, v184, v2
	s_waitcnt lgkmcnt(0)
	v_add_f32_e32 v2, v2, v3
	v_fmamk_f32 v2, v2, 0x3c800000, v243
	s_nop 1
	s_cselect_b32 s0, s27, s39
	s_cselect_b32 s1, s26, s38
	v_rsq_f32_e32 v4, v2
	s_nop 0
	v_mov_b32_e32 v2, s1
	v_mov_b32_e32 v3, s0
	v_mul_f32_e32 v5, 0x3e38aa3b, v4
	v_readlane_b32 s0, v251, 43
	v_cndmask_b32_e64 v26, v4, v5, s[42:43]
	v_lshlrev_b64 v[4:5], 11, v[142:143]
	v_readlane_b32 s1, v251, 44
	v_lshl_add_u64 v[30:31], v[144:145], 2, v[2:3]
	s_nop 0
	v_lshl_add_u64 v[6:7], s[0:1], 0, v[4:5]
	v_lshl_add_u64 v[4:5], s[4:5], 0, v[4:5]
	s_movk_i32 s0, 0xf800
	v_lshl_add_u64 v[4:5], s[76:77], 1, v[4:5]
	s_mov_b32 s1, -1
	v_lshl_add_u64 v[6:7], s[64:65], 1, v[6:7]
	v_lshl_add_u64 v[4:5], v[4:5], 0, s[0:1]
	v_cndmask_b32_e64 v29, v5, v7, s[42:43]
	v_cndmask_b32_e64 v28, v4, v6, s[42:43]
	v_pk_mul_f32 v[4:5], v[22:23], v[218:219]
	v_pk_mul_f32 v[8:9], v[18:19], v[214:215]
	v_pk_mul_f32 v[6:7], v[20:21], v[212:213]
	v_pk_mul_f32 v[2:3], v[24:25], v[216:217]
	v_pk_mul_f32 v[8:9], v[26:27], v[8:9] op_sel_hi:[0,1]
	v_pk_mul_f32 v[6:7], v[26:27], v[6:7] op_sel_hi:[0,1]
	v_pk_mul_f32 v[18:19], v[26:27], v[4:5] op_sel_hi:[0,1]
	v_pk_mul_f32 v[4:5], v[26:27], v[2:3] op_sel_hi:[0,1]
	v_cvt_pk_bf16_f32 v2, v6, v7
	v_cvt_pk_bf16_f32 v3, v8, v9
	v_cvt_pk_bf16_f32 v4, v4, v5
	v_cvt_pk_bf16_f32 v5, v18, v19
	v_lshl_add_u64 v[18:19], v[144:145], 1, v[28:29]
	global_store_dwordx4 v[18:19], v[2:5], off sc0 sc1
	s_nop 1
	v_pk_mul_f32 v[4:5], v[10:11], v[206:207]
	v_pk_mul_f32 v[8:9], v[14:15], v[222:223]
	v_pk_mul_f32 v[6:7], v[16:17], v[220:221]
	v_pk_mul_f32 v[2:3], v[12:13], v[204:205]
	v_pk_mul_f32 v[8:9], v[26:27], v[8:9] op_sel_hi:[0,1]
	v_pk_mul_f32 v[6:7], v[26:27], v[6:7] op_sel_hi:[0,1]
	v_pk_mul_f32 v[10:11], v[26:27], v[4:5] op_sel_hi:[0,1]
	v_pk_mul_f32 v[4:5], v[26:27], v[2:3] op_sel_hi:[0,1]
	v_cvt_pk_bf16_f32 v2, v6, v7
	v_cvt_pk_bf16_f32 v3, v8, v9
	v_cvt_pk_bf16_f32 v4, v4, v5
	v_cvt_pk_bf16_f32 v5, v10, v11
	global_store_dwordx4 v[18:19], v[2:5], off offset:64 sc0 sc1
	s_nop 1

.LBB0_709:
	v_mbcnt_lo_u32_b32 v1, -1, 0
	v_mbcnt_hi_u32_b32 v1, -1, v1
	s_mulk_i32 s5, 0x2200
	v_and_b32_e32 v2, 31, v1
	v_ashrrev_i32_e32 v5, 2, v1
	s_add_i32 s5, s5, 0
	v_mul_u32_u24_e32 v4, 0x110, v2
	v_and_b32_e32 v5, -8, v5
	v_cvt_pk_bf16_f32 v2, v96, v97
	v_cvt_pk_bf16_f32 v3, v98, v99
	v_add3_u32 v6, s5, v4, v5
	v_cvt_pk_bf16_f32 v4, v100, v101
	v_cvt_pk_bf16_f32 v5, v102, v103
	ds_write2_b64 v6, v[2:3], v[4:5] offset1:2
	v_cvt_pk_bf16_f32 v2, v104, v105
	v_cvt_pk_bf16_f32 v3, v106, v107
	v_cvt_pk_bf16_f32 v4, v108, v109
	v_cvt_pk_bf16_f32 v5, v110, v111
	ds_write2_b64 v6, v[2:3], v[4:5] offset0:4 offset1:6
	v_cvt_pk_bf16_f32 v2, v112, v113
	v_cvt_pk_bf16_f32 v3, v114, v115
	v_cvt_pk_bf16_f32 v4, v116, v117
	v_cvt_pk_bf16_f32 v5, v118, v119
	ds_write2_b64 v6, v[2:3], v[4:5] offset0:8 offset1:10
	v_cvt_pk_bf16_f32 v2, v120, v121
	v_cvt_pk_bf16_f32 v3, v122, v123
	v_cvt_pk_bf16_f32 v4, v124, v125
	v_cvt_pk_bf16_f32 v5, v126, v127
	ds_write2_b64 v6, v[2:3], v[4:5] offset0:12 offset1:14
	v_cvt_pk_bf16_f32 v2, v128, v129
	v_cvt_pk_bf16_f32 v3, v130, v131
	v_cvt_pk_bf16_f32 v4, v132, v133
	v_cvt_pk_bf16_f32 v5, v134, v135
	ds_write2_b64 v6, v[2:3], v[4:5] offset0:16 offset1:18
	v_cvt_pk_bf16_f32 v2, v136, v137
	v_cvt_pk_bf16_f32 v3, v138, v139
	v_cvt_pk_bf16_f32 v4, v140, v141
	v_cvt_pk_bf16_f32 v5, v142, v143
	ds_write2_b64 v6, v[2:3], v[4:5] offset0:20 offset1:22
	v_cvt_pk_bf16_f32 v2, v144, v145
	v_cvt_pk_bf16_f32 v3, v146, v147
	v_cvt_pk_bf16_f32 v4, v148, v149
	v_cvt_pk_bf16_f32 v5, v150, v151
	ds_write2_b64 v6, v[2:3], v[4:5] offset0:24 offset1:26
	v_cvt_pk_bf16_f32 v2, v152, v153
	v_cvt_pk_bf16_f32 v3, v154, v155
	v_cvt_pk_bf16_f32 v4, v156, v157
	v_cvt_pk_bf16_f32 v5, v158, v159
	ds_write2_b64 v6, v[2:3], v[4:5] offset0:28 offset1:30
	v_lshlrev_b32_e32 v2, 4, v1
	v_and_b32_e32 v10, 0xf0, v2
	v_ashrrev_i32_e32 v6, 4, v1
	v_add_u32_e32 v12, s5, v10
	s_movk_i32 s5, 0x110
	v_ashrrev_i32_e32 v7, 31, v6
	v_mad_u64_u32 v[2:3], s[6:7], v6, s5, v[12:13]
	v_lshl_add_u64 v[6:7], s[12:13], 0, v[6:7]
	v_readlane_b32 s8, v251, 43
	s_waitcnt lgkmcnt(0)
	v_lshlrev_b64 v[6:7], 11, v[6:7]
	v_readlane_b32 s9, v251, 44
	ds_read_b128 v[2:5], v2
	v_mov_b32_e32 v11, v0
	v_lshl_add_u64 v[6:7], s[8:9], 0, v[6:7]
	v_lshl_add_u64 v[6:7], v[6:7], 0, s[0:1]
	v_lshl_add_u64 v[14:15], v[6:7], 0, v[10:11]
	v_add_u32_e32 v6, 64, v1
	v_ashrrev_i32_e32 v16, 4, v6
	v_mad_u64_u32 v[6:7], s[6:7], v16, s5, v[12:13]
	v_ashrrev_i32_e32 v17, 31, v16
	ds_read_b128 v[6:9], v6
	s_waitcnt lgkmcnt(1)
	global_store_dwordx4 v[14:15], v[2:5], off sc0 sc1
	s_movk_i32 s54, 0x1600
	s_mov_b64 s[18:19], 0x80000
	v_lshl_add_u64 v[2:3], s[12:13], 0, v[16:17]
	v_lshlrev_b64 v[2:3], 11, v[2:3]
	v_lshl_add_u64 v[2:3], s[8:9], 0, v[2:3]
	v_lshl_add_u64 v[2:3], v[2:3], 0, s[0:1]
	v_lshl_add_u64 v[2:3], v[2:3], 0, v[10:11]
	s_waitcnt lgkmcnt(0)
	global_store_dwordx4 v[2:3], v[6:9], off sc0 sc1
	v_add_u32_e32 v2, 0x80, v1
	v_mov_b64_e32 v[226:227], 0x300
	v_ashrrev_i32_e32 v6, 4, v2
	v_ashrrev_i32_e32 v7, 31, v6
	v_mad_u64_u32 v[2:3], s[6:7], v6, s5, v[12:13]
	v_lshl_add_u64 v[6:7], s[12:13], 0, v[6:7]
	v_lshlrev_b64 v[6:7], 11, v[6:7]
	ds_read_b128 v[2:5], v2
	v_lshl_add_u64 v[6:7], s[8:9], 0, v[6:7]
	v_lshl_add_u64 v[6:7], v[6:7], 0, s[0:1]
	v_lshl_add_u64 v[14:15], v[6:7], 0, v[10:11]
	v_add_u32_e32 v6, 0xc0, v1
	v_ashrrev_i32_e32 v16, 4, v6
	v_mad_u64_u32 v[6:7], s[6:7], v16, s5, v[12:13]
	v_ashrrev_i32_e32 v17, 31, v16
	ds_read_b128 v[6:9], v6
	s_waitcnt lgkmcnt(1)
	global_store_dwordx4 v[14:15], v[2:5], off sc0 sc1
	v_mov_b64_e32 v[228:229], 0x2ff
	v_mov_b64_e32 v[230:231], 0x3ff
	v_lshl_add_u64 v[2:3], s[12:13], 0, v[16:17]
	v_lshlrev_b64 v[2:3], 11, v[2:3]
	v_lshl_add_u64 v[2:3], s[8:9], 0, v[2:3]
	v_lshl_add_u64 v[2:3], v[2:3], 0, s[0:1]
	v_lshl_add_u64 v[2:3], v[2:3], 0, v[10:11]
	s_waitcnt lgkmcnt(0)
	global_store_dwordx4 v[2:3], v[6:9], off sc0 sc1
	v_add_u32_e32 v2, 0x100, v1
	v_mov_b64_e32 v[224:225], 0x1ff
	v_ashrrev_i32_e32 v6, 4, v2
	v_ashrrev_i32_e32 v7, 31, v6
	v_mad_u64_u32 v[2:3], s[6:7], v6, s5, v[12:13]
	v_lshl_add_u64 v[6:7], s[12:13], 0, v[6:7]
	v_lshlrev_b64 v[6:7], 11, v[6:7]
	ds_read_b128 v[2:5], v2
	v_lshl_add_u64 v[6:7], s[8:9], 0, v[6:7]
	v_lshl_add_u64 v[6:7], v[6:7], 0, s[0:1]
	v_lshl_add_u64 v[14:15], v[6:7], 0, v[10:11]
	v_add_u32_e32 v6, 0x140, v1
	v_ashrrev_i32_e32 v16, 4, v6
	v_mad_u64_u32 v[6:7], s[6:7], v16, s5, v[12:13]
	v_ashrrev_i32_e32 v17, 31, v16
	ds_read_b128 v[6:9], v6
	s_waitcnt lgkmcnt(1)
	global_store_dwordx4 v[14:15], v[2:5], off sc0 sc1
	v_mov_b64_e32 v[232:233], 0x100
	v_mov_b64_e32 v[234:235], 0xff
	v_lshl_add_u64 v[2:3], s[12:13], 0, v[16:17]
	v_lshlrev_b64 v[2:3], 11, v[2:3]
	v_lshl_add_u64 v[2:3], s[8:9], 0, v[2:3]
	v_lshl_add_u64 v[2:3], v[2:3], 0, s[0:1]
	v_lshl_add_u64 v[2:3], v[2:3], 0, v[10:11]
	s_waitcnt lgkmcnt(0)
	global_store_dwordx4 v[2:3], v[6:9], off sc0 sc1
	v_add_u32_e32 v2, 0x180, v1
	v_add_u32_e32 v1, 0x1c0, v1
	v_ashrrev_i32_e32 v6, 4, v2
	v_mad_u64_u32 v[2:3], s[6:7], v6, s5, v[12:13]
	v_ashrrev_i32_e32 v7, 31, v6
	ds_read_b128 v[2:5], v2
	v_lshl_add_u64 v[6:7], s[12:13], 0, v[6:7]
	v_lshlrev_b64 v[6:7], 11, v[6:7]
	v_lshl_add_u64 v[6:7], s[8:9], 0, v[6:7]
	v_lshl_add_u64 v[6:7], v[6:7], 0, s[0:1]
	v_ashrrev_i32_e32 v16, 4, v1
	v_lshl_add_u64 v[14:15], v[6:7], 0, v[10:11]
	v_mad_u64_u32 v[6:7], s[6:7], v16, s5, v[12:13]
	v_ashrrev_i32_e32 v17, 31, v16
	ds_read_b128 v[6:9], v6
	s_waitcnt lgkmcnt(1)
	global_store_dwordx4 v[14:15], v[2:5], off sc0 sc1
	s_mov_b32 s5, 0
	s_nop 0
	v_lshl_add_u64 v[2:3], s[12:13], 0, v[16:17]
	v_lshlrev_b64 v[2:3], 11, v[2:3]
	v_lshl_add_u64 v[2:3], s[8:9], 0, v[2:3]
	v_lshl_add_u64 v[2:3], v[2:3], 0, s[0:1]
	v_lshl_add_u64 v[2:3], v[2:3], 0, v[10:11]
	s_waitcnt lgkmcnt(0)
	global_store_dwordx4 v[2:3], v[6:9], off sc0 sc1

.LBB0_790:
	s_ashr_i32 s1, s0, 31
	s_lshl_b64 s[0:1], s[0:1], 8
	v_mov_b32_e32 v146, v1
	v_mov_b32_e32 v153, v148
	s_add_u32 s0, s0, s19
	s_addc_u32 s1, s1, s21
	v_ashrrev_i32_e32 v147, 31, v146
	v_lshl_add_u64 v[142:143], s[0:1], 0, v[146:147]
	v_lshlrev_b32_e32 v146, 2, v146
	v_lshl_add_u32 v146, v153, 6, v146
	s_lshl_b32 s10, s31, 8
	v_xor_b32_e32 v152, 64, v146
	v_xor_b32_e32 v151, 0x80, v146
	v_lshlrev_b64 v[146:147], 11, v[142:143]
	s_ashr_i32 s11, s10, 31
	v_lshl_add_u64 v[146:147], s[22:23], 0, v[146:147]
	v_lshlrev_b32_e32 v144, 3, v153
	v_lshl_add_u64 v[146:147], s[10:11], 1, v[146:147]
	v_ashrrev_i32_e32 v145, 31, v144
	v_lshl_add_u64 v[146:147], v[146:147], 0, s[76:77]
	v_lshl_add_u64 v[146:147], v[144:145], 1, v[146:147]
	global_load_dwordx4 v[160:163], v[146:147], off
	global_load_dwordx4 v[164:167], v[146:147], off offset:256
	s_mov_b64 s[12:13], 0x8000
	v_lshl_add_u64 v[154:155], v[146:147], 0, s[12:13]
	global_load_dwordx4 v[168:171], v[154:155], off
	global_load_dwordx4 v[172:175], v[154:155], off offset:256
	s_mov_b64 s[12:13], 0x8000
	v_lshl_add_u64 v[154:155], v[154:155], 0, s[12:13]
	global_load_dwordx4 v[176:179], v[154:155], off
	global_load_dwordx4 v[180:183], v[154:155], off offset:256
	s_mov_b64 s[12:13], 0x8000
	v_lshl_add_u64 v[154:155], v[154:155], 0, s[12:13]
	global_load_dwordx4 v[184:187], v[154:155], off
	global_load_dwordx4 v[188:191], v[154:155], off offset:256
	s_mov_b64 s[12:13], 0x28000
	v_lshl_add_u64 v[154:155], v[154:155], 0, s[12:13]
	global_load_dwordx4 v[192:195], v[154:155], off
	global_load_dwordx4 v[196:199], v[154:155], off offset:256
	s_mov_b64 s[12:13], 0x8000
	v_lshl_add_u64 v[154:155], v[154:155], 0, s[12:13]
	global_load_dwordx4 v[200:203], v[154:155], off
	global_load_dwordx4 v[204:207], v[154:155], off offset:256
	s_mov_b64 s[12:13], 0x8000
	v_lshl_add_u64 v[154:155], v[154:155], 0, s[12:13]
	global_load_dwordx4 v[208:211], v[154:155], off
	global_load_dwordx4 v[212:215], v[154:155], off offset:256
	s_mov_b64 s[12:13], 0x8000
	v_lshl_add_u64 v[154:155], v[154:155], 0, s[12:13]
	global_load_dwordx4 v[216:219], v[154:155], off
	global_load_dwordx4 v[220:223], v[154:155], off offset:256
	s_lshl_b32 s0, s31, 2
	v_cmp_eq_u32_e32 vcc, 0, v153
	s_ashr_i32 s1, s0, 31
	s_waitcnt vmcnt(15)
	v_mov_b64_e32 v[154:155], v[160:161]
	v_mov_b64_e32 v[156:157], v[162:163]
	v_lshlrev_b32_e32 v158, 16, v154
	v_and_b32_e32 v159, 0xffff0000, v154
	v_lshlrev_b32_e32 v154, 16, v155
	v_and_b32_e32 v155, 0xffff0000, v155
	v_pk_add_f32 v[128:129], v[128:129], v[154:155]
	v_lshlrev_b32_e32 v154, 16, v156
	v_and_b32_e32 v155, 0xffff0000, v156
	v_lshlrev_b32_e32 v156, 16, v157
	v_and_b32_e32 v157, 0xffff0000, v157
	v_pk_add_f32 v[126:127], v[126:127], v[158:159]
	v_pk_add_f32 v[156:157], v[124:125], v[156:157]
	v_pk_add_f32 v[154:155], v[122:123], v[154:155]
	v_cvt_pk_bf16_f32 v122, v126, v127
	v_cvt_pk_bf16_f32 v123, v128, v129
	v_cvt_pk_bf16_f32 v124, v154, v155
	v_cvt_pk_bf16_f32 v125, v156, v157
	global_store_dwordx4 v[146:147], v[122:125], off sc0 sc1
	s_nop 1
	v_mul_f32_e32 v122, v127, v127
	v_mul_f32_e32 v123, v129, v129
	v_fmac_f32_e32 v122, v126, v126
	v_fmac_f32_e32 v123, v128, v128
	v_add_f32_e32 v122, v122, v123
	v_mul_f32_e32 v123, v155, v155
	v_mul_f32_e32 v124, v157, v157
	v_fmac_f32_e32 v123, v154, v154
	v_fmac_f32_e32 v124, v156, v156
	v_add_f32_e32 v123, v123, v124
	v_add_f32_e32 v128, v122, v123
	s_waitcnt vmcnt(15)
	v_mov_b64_e32 v[122:123], v[164:165]
	v_mov_b64_e32 v[124:125], v[166:167]
	v_lshlrev_b32_e32 v126, 16, v122
	v_and_b32_e32 v127, 0xffff0000, v122
	v_lshlrev_b32_e32 v122, 16, v123
	v_and_b32_e32 v123, 0xffff0000, v123
	v_pk_add_f32 v[120:121], v[120:121], v[122:123]
	v_lshlrev_b32_e32 v122, 16, v124
	v_and_b32_e32 v123, 0xffff0000, v124
	v_lshlrev_b32_e32 v124, 16, v125
	v_and_b32_e32 v125, 0xffff0000, v125
	v_pk_add_f32 v[118:119], v[118:119], v[126:127]
	v_pk_add_f32 v[124:125], v[116:117], v[124:125]
	v_pk_add_f32 v[122:123], v[114:115], v[122:123]
	v_cvt_pk_bf16_f32 v114, v118, v119
	v_cvt_pk_bf16_f32 v115, v120, v121
	v_cvt_pk_bf16_f32 v116, v122, v123
	v_cvt_pk_bf16_f32 v117, v124, v125
	global_store_dwordx4 v[146:147], v[114:117], off offset:256 sc0 sc1
	s_nop 1
	v_mul_f32_e32 v114, v119, v119
	v_mul_f32_e32 v115, v121, v121
	v_fmac_f32_e32 v114, v118, v118
	v_fmac_f32_e32 v115, v120, v120
	v_add_f32_e32 v114, v114, v115
	v_mul_f32_e32 v115, v123, v123
	v_mul_f32_e32 v116, v125, v125
	v_fmac_f32_e32 v115, v122, v122
	v_fmac_f32_e32 v116, v124, v124
	v_add_f32_e32 v115, v115, v116
	v_add_f32_e32 v114, v114, v115
	v_add_f32_e32 v114, v128, v114
	ds_bpermute_b32 v115, v152, v114
	s_waitcnt lgkmcnt(0)
	v_add_f32_e32 v114, v114, v115
	ds_bpermute_b32 v115, v151, v114
	s_and_saveexec_b64 s[12:13], vcc
	s_cbranch_execz .LBB0_792
	s_waitcnt lgkmcnt(0)
	v_add_f32_e32 v116, v114, v115
	v_lshlrev_b64 v[114:115], 6, v[142:143]
	v_lshl_add_u64 v[114:115], s[80:81], 0, v[114:115]
	v_lshl_add_u64 v[114:115], s[0:1], 2, v[114:115]
	s_lshl_b32 s24, s15, 2
	s_mov_b32 s25, s77
	v_lshl_add_u64 v[114:115], v[114:115], 0, s[24:25]
	global_store_dword v[114:115], v116, off
.LBB0_792:
	s_or_b64 exec, exec, s[12:13]
	s_waitcnt lgkmcnt(0)
	v_lshl_add_u64 v[114:115], v[142:143], 0, 16
	v_lshlrev_b64 v[116:117], 11, v[114:115]
	v_lshl_add_u64 v[116:117], s[22:23], 0, v[116:117]
	v_lshl_add_u64 v[116:117], s[10:11], 1, v[116:117]
	v_lshl_add_u64 v[116:117], v[116:117], 0, s[76:77]
	v_lshl_add_u64 v[116:117], v[144:145], 1, v[116:117]
	s_waitcnt vmcnt(15)
	v_mov_b64_e32 v[118:119], v[168:169]
	v_mov_b64_e32 v[120:121], v[170:171]
	v_lshlrev_b32_e32 v122, 16, v118
	v_and_b32_e32 v123, 0xffff0000, v118
	v_lshlrev_b32_e32 v118, 16, v119
	v_and_b32_e32 v119, 0xffff0000, v119
	v_pk_add_f32 v[112:113], v[112:113], v[118:119]
	v_lshlrev_b32_e32 v118, 16, v120
	v_and_b32_e32 v119, 0xffff0000, v120
	v_lshlrev_b32_e32 v120, 16, v121
	v_and_b32_e32 v121, 0xffff0000, v121
	v_pk_add_f32 v[110:111], v[110:111], v[122:123]
	v_pk_add_f32 v[120:121], v[108:109], v[120:121]
	v_pk_add_f32 v[118:119], v[106:107], v[118:119]
	v_cvt_pk_bf16_f32 v106, v110, v111
	v_cvt_pk_bf16_f32 v107, v112, v113
	v_cvt_pk_bf16_f32 v108, v118, v119
	v_cvt_pk_bf16_f32 v109, v120, v121
	global_store_dwordx4 v[116:117], v[106:109], off sc0 sc1
	s_nop 1
	v_mul_f32_e32 v106, v111, v111
	v_mul_f32_e32 v107, v113, v113
	v_fmac_f32_e32 v106, v110, v110
	v_fmac_f32_e32 v107, v112, v112
	v_add_f32_e32 v106, v106, v107
	v_mul_f32_e32 v107, v119, v119
	v_mul_f32_e32 v108, v121, v121
	v_fmac_f32_e32 v107, v118, v118
	v_fmac_f32_e32 v108, v120, v120
	v_add_f32_e32 v107, v107, v108
	v_add_f32_e32 v112, v106, v107
	s_waitcnt vmcnt(15)
	v_mov_b64_e32 v[106:107], v[172:173]
	v_mov_b64_e32 v[108:109], v[174:175]
	v_lshlrev_b32_e32 v110, 16, v106
	v_and_b32_e32 v111, 0xffff0000, v106
	v_lshlrev_b32_e32 v106, 16, v107
	v_and_b32_e32 v107, 0xffff0000, v107
	v_pk_add_f32 v[104:105], v[104:105], v[106:107]
	v_lshlrev_b32_e32 v106, 16, v108
	v_and_b32_e32 v107, 0xffff0000, v108
	v_lshlrev_b32_e32 v108, 16, v109
	v_and_b32_e32 v109, 0xffff0000, v109
	v_pk_add_f32 v[102:103], v[102:103], v[110:111]
	v_pk_add_f32 v[108:109], v[100:101], v[108:109]
	v_pk_add_f32 v[106:107], v[98:99], v[106:107]
	v_cvt_pk_bf16_f32 v98, v102, v103
	v_cvt_pk_bf16_f32 v99, v104, v105
	v_cvt_pk_bf16_f32 v100, v106, v107
	v_cvt_pk_bf16_f32 v101, v108, v109
	global_store_dwordx4 v[116:117], v[98:101], off offset:256 sc0 sc1
	s_nop 1
	v_mul_f32_e32 v98, v103, v103
	v_mul_f32_e32 v99, v105, v105
	v_fmac_f32_e32 v98, v102, v102
	v_fmac_f32_e32 v99, v104, v104
	v_add_f32_e32 v98, v98, v99
	v_mul_f32_e32 v99, v107, v107
	v_mul_f32_e32 v100, v109, v109
	v_fmac_f32_e32 v99, v106, v106
	v_fmac_f32_e32 v100, v108, v108
	v_add_f32_e32 v99, v99, v100
	v_add_f32_e32 v98, v98, v99
	v_add_f32_e32 v98, v112, v98
	ds_bpermute_b32 v99, v152, v98
	s_waitcnt lgkmcnt(0)
	v_add_f32_e32 v98, v98, v99
	ds_bpermute_b32 v99, v151, v98
	s_and_saveexec_b64 s[12:13], vcc
	s_cbranch_execz .LBB0_794
	s_waitcnt lgkmcnt(0)
	v_add_f32_e32 v100, v98, v99
	v_lshlrev_b64 v[98:99], 6, v[114:115]
	v_lshl_add_u64 v[98:99], s[80:81], 0, v[98:99]
	v_lshl_add_u64 v[98:99], s[0:1], 2, v[98:99]
	s_lshl_b32 s24, s15, 2
	s_mov_b32 s25, s77
	v_lshl_add_u64 v[98:99], v[98:99], 0, s[24:25]
	global_store_dword v[98:99], v100, off
.LBB0_794:
	s_or_b64 exec, exec, s[12:13]
	s_waitcnt lgkmcnt(0)
	v_lshl_add_u64 v[98:99], v[142:143], 0, 32
	v_lshlrev_b64 v[100:101], 11, v[98:99]
	v_lshl_add_u64 v[100:101], s[22:23], 0, v[100:101]
	v_lshl_add_u64 v[100:101], s[10:11], 1, v[100:101]
	v_lshl_add_u64 v[100:101], v[100:101], 0, s[76:77]
	v_lshl_add_u64 v[100:101], v[144:145], 1, v[100:101]
	s_waitcnt vmcnt(15)
	v_mov_b64_e32 v[102:103], v[176:177]
	v_mov_b64_e32 v[104:105], v[178:179]
	v_lshlrev_b32_e32 v106, 16, v102
	v_and_b32_e32 v107, 0xffff0000, v102
	v_lshlrev_b32_e32 v102, 16, v103
	v_and_b32_e32 v103, 0xffff0000, v103
	v_pk_add_f32 v[96:97], v[96:97], v[102:103]
	v_lshlrev_b32_e32 v102, 16, v104
	v_and_b32_e32 v103, 0xffff0000, v104
	v_lshlrev_b32_e32 v104, 16, v105
	v_and_b32_e32 v105, 0xffff0000, v105
	v_pk_add_f32 v[94:95], v[94:95], v[106:107]
	v_pk_add_f32 v[104:105], v[92:93], v[104:105]
	v_pk_add_f32 v[102:103], v[90:91], v[102:103]
	v_cvt_pk_bf16_f32 v90, v94, v95
	v_cvt_pk_bf16_f32 v91, v96, v97
	v_cvt_pk_bf16_f32 v92, v102, v103
	v_cvt_pk_bf16_f32 v93, v104, v105
	global_store_dwordx4 v[100:101], v[90:93], off sc0 sc1
	s_nop 1
	v_mul_f32_e32 v90, v95, v95
	v_mul_f32_e32 v91, v97, v97
	v_fmac_f32_e32 v90, v94, v94
	v_fmac_f32_e32 v91, v96, v96
	v_add_f32_e32 v90, v90, v91
	v_mul_f32_e32 v91, v103, v103
	v_mul_f32_e32 v92, v105, v105
	v_fmac_f32_e32 v91, v102, v102
	v_fmac_f32_e32 v92, v104, v104
	v_add_f32_e32 v91, v91, v92
	v_add_f32_e32 v96, v90, v91
	s_waitcnt vmcnt(15)
	v_mov_b64_e32 v[90:91], v[180:181]
	v_mov_b64_e32 v[92:93], v[182:183]
	v_lshlrev_b32_e32 v94, 16, v90
	v_and_b32_e32 v95, 0xffff0000, v90
	v_lshlrev_b32_e32 v90, 16, v91
	v_and_b32_e32 v91, 0xffff0000, v91
	v_pk_add_f32 v[88:89], v[88:89], v[90:91]
	v_lshlrev_b32_e32 v90, 16, v92
	v_and_b32_e32 v91, 0xffff0000, v92
	v_lshlrev_b32_e32 v92, 16, v93
	v_and_b32_e32 v93, 0xffff0000, v93
	v_pk_add_f32 v[86:87], v[86:87], v[94:95]
	v_pk_add_f32 v[92:93], v[84:85], v[92:93]
	v_pk_add_f32 v[90:91], v[82:83], v[90:91]
	v_cvt_pk_bf16_f32 v82, v86, v87
	v_cvt_pk_bf16_f32 v83, v88, v89
	v_cvt_pk_bf16_f32 v84, v90, v91
	v_cvt_pk_bf16_f32 v85, v92, v93
	global_store_dwordx4 v[100:101], v[82:85], off offset:256 sc0 sc1
	s_nop 1
	v_mul_f32_e32 v82, v87, v87
	v_mul_f32_e32 v83, v89, v89
	v_fmac_f32_e32 v82, v86, v86
	v_fmac_f32_e32 v83, v88, v88
	v_add_f32_e32 v82, v82, v83
	v_mul_f32_e32 v83, v91, v91
	v_mul_f32_e32 v84, v93, v93
	v_fmac_f32_e32 v83, v90, v90
	v_fmac_f32_e32 v84, v92, v92
	v_add_f32_e32 v83, v83, v84
	v_add_f32_e32 v82, v82, v83
	v_add_f32_e32 v82, v96, v82
	ds_bpermute_b32 v83, v152, v82
	s_waitcnt lgkmcnt(0)
	v_add_f32_e32 v82, v82, v83
	ds_bpermute_b32 v83, v151, v82
	s_and_saveexec_b64 s[12:13], vcc
	s_cbranch_execz .LBB0_796
	s_waitcnt lgkmcnt(0)
	v_add_f32_e32 v84, v82, v83
	v_lshlrev_b64 v[82:83], 6, v[98:99]
	v_lshl_add_u64 v[82:83], s[80:81], 0, v[82:83]
	v_lshl_add_u64 v[82:83], s[0:1], 2, v[82:83]
	s_lshl_b32 s24, s15, 2
	s_mov_b32 s25, s77
	v_lshl_add_u64 v[82:83], v[82:83], 0, s[24:25]
	global_store_dword v[82:83], v84, off
.LBB0_796:
	s_or_b64 exec, exec, s[12:13]
	s_waitcnt lgkmcnt(0)
	v_lshl_add_u64 v[82:83], v[142:143], 0, 48
	v_lshlrev_b64 v[84:85], 11, v[82:83]
	v_lshl_add_u64 v[84:85], s[22:23], 0, v[84:85]
	v_lshl_add_u64 v[84:85], s[10:11], 1, v[84:85]
	v_lshl_add_u64 v[84:85], v[84:85], 0, s[76:77]
	v_lshl_add_u64 v[84:85], v[144:145], 1, v[84:85]
	s_waitcnt vmcnt(15)
	v_mov_b64_e32 v[86:87], v[184:185]
	v_mov_b64_e32 v[88:89], v[186:187]
	v_lshlrev_b32_e32 v90, 16, v86
	v_and_b32_e32 v91, 0xffff0000, v86
	v_lshlrev_b32_e32 v86, 16, v87
	v_and_b32_e32 v87, 0xffff0000, v87
	v_pk_add_f32 v[80:81], v[80:81], v[86:87]
	v_lshlrev_b32_e32 v86, 16, v88
	v_and_b32_e32 v87, 0xffff0000, v88
	v_lshlrev_b32_e32 v88, 16, v89
	v_and_b32_e32 v89, 0xffff0000, v89
	v_pk_add_f32 v[78:79], v[78:79], v[90:91]
	v_pk_add_f32 v[88:89], v[76:77], v[88:89]
	v_pk_add_f32 v[86:87], v[74:75], v[86:87]
	v_cvt_pk_bf16_f32 v74, v78, v79
	v_cvt_pk_bf16_f32 v75, v80, v81
	v_cvt_pk_bf16_f32 v76, v86, v87
	v_cvt_pk_bf16_f32 v77, v88, v89
	global_store_dwordx4 v[84:85], v[74:77], off sc0 sc1
	s_nop 1
	v_mul_f32_e32 v74, v79, v79
	v_mul_f32_e32 v75, v81, v81
	v_fmac_f32_e32 v74, v78, v78
	v_fmac_f32_e32 v75, v80, v80
	v_add_f32_e32 v74, v74, v75
	v_mul_f32_e32 v75, v87, v87
	v_mul_f32_e32 v76, v89, v89
	v_fmac_f32_e32 v75, v86, v86
	v_fmac_f32_e32 v76, v88, v88
	v_add_f32_e32 v75, v75, v76
	v_add_f32_e32 v80, v74, v75
	s_waitcnt vmcnt(15)
	v_mov_b64_e32 v[74:75], v[188:189]
	v_mov_b64_e32 v[76:77], v[190:191]
	v_lshlrev_b32_e32 v78, 16, v74
	v_and_b32_e32 v79, 0xffff0000, v74
	v_lshlrev_b32_e32 v74, 16, v75
	v_and_b32_e32 v75, 0xffff0000, v75
	v_pk_add_f32 v[72:73], v[72:73], v[74:75]
	v_lshlrev_b32_e32 v74, 16, v76
	v_and_b32_e32 v75, 0xffff0000, v76
	v_lshlrev_b32_e32 v76, 16, v77
	v_and_b32_e32 v77, 0xffff0000, v77
	v_pk_add_f32 v[70:71], v[70:71], v[78:79]
	v_pk_add_f32 v[76:77], v[68:69], v[76:77]
	v_pk_add_f32 v[74:75], v[66:67], v[74:75]
	v_cvt_pk_bf16_f32 v66, v70, v71
	v_cvt_pk_bf16_f32 v67, v72, v73
	v_cvt_pk_bf16_f32 v68, v74, v75
	v_cvt_pk_bf16_f32 v69, v76, v77
	global_store_dwordx4 v[84:85], v[66:69], off offset:256 sc0 sc1
	s_nop 1
	v_mul_f32_e32 v66, v71, v71
	v_mul_f32_e32 v67, v73, v73
	v_fmac_f32_e32 v66, v70, v70
	v_fmac_f32_e32 v67, v72, v72
	v_add_f32_e32 v66, v66, v67
	v_mul_f32_e32 v67, v75, v75
	v_mul_f32_e32 v68, v77, v77
	v_fmac_f32_e32 v67, v74, v74
	v_fmac_f32_e32 v68, v76, v76
	v_add_f32_e32 v67, v67, v68
	v_add_f32_e32 v66, v66, v67
	v_add_f32_e32 v66, v80, v66
	ds_bpermute_b32 v67, v152, v66
	s_waitcnt lgkmcnt(0)
	v_add_f32_e32 v66, v66, v67
	ds_bpermute_b32 v67, v151, v66
	s_and_saveexec_b64 s[12:13], vcc
	s_cbranch_execz .LBB0_798
	s_waitcnt lgkmcnt(0)
	v_add_f32_e32 v68, v66, v67
	v_lshlrev_b64 v[66:67], 6, v[82:83]
	v_lshl_add_u64 v[66:67], s[80:81], 0, v[66:67]
	v_lshl_add_u64 v[66:67], s[0:1], 2, v[66:67]
	s_lshl_b32 s24, s15, 2
	s_mov_b32 s25, s77
	v_lshl_add_u64 v[66:67], v[66:67], 0, s[24:25]
	global_store_dword v[66:67], v68, off
.LBB0_798:
	s_or_b64 exec, exec, s[12:13]
	s_waitcnt lgkmcnt(0)
	v_lshl_add_u64 v[66:67], v[142:143], 0, s[28:29]
	v_lshlrev_b64 v[68:69], 11, v[66:67]
	v_lshl_add_u64 v[68:69], s[22:23], 0, v[68:69]
	v_lshl_add_u64 v[68:69], s[10:11], 1, v[68:69]
	v_lshl_add_u64 v[68:69], v[68:69], 0, s[76:77]
	v_lshl_add_u64 v[68:69], v[144:145], 1, v[68:69]
	s_waitcnt vmcnt(15)
	v_mov_b64_e32 v[70:71], v[192:193]
	v_mov_b64_e32 v[72:73], v[194:195]
	v_lshlrev_b32_e32 v74, 16, v70
	v_and_b32_e32 v75, 0xffff0000, v70
	v_lshlrev_b32_e32 v70, 16, v71
	v_and_b32_e32 v71, 0xffff0000, v71
	v_pk_add_f32 v[64:65], v[64:65], v[70:71]
	v_lshlrev_b32_e32 v70, 16, v72
	v_and_b32_e32 v71, 0xffff0000, v72
	v_lshlrev_b32_e32 v72, 16, v73
	v_and_b32_e32 v73, 0xffff0000, v73
	v_pk_add_f32 v[62:63], v[62:63], v[74:75]
	v_pk_add_f32 v[72:73], v[60:61], v[72:73]
	v_pk_add_f32 v[70:71], v[58:59], v[70:71]
	v_cvt_pk_bf16_f32 v58, v62, v63
	v_cvt_pk_bf16_f32 v59, v64, v65
	v_cvt_pk_bf16_f32 v60, v70, v71
	v_cvt_pk_bf16_f32 v61, v72, v73
	global_store_dwordx4 v[68:69], v[58:61], off sc0 sc1
	s_nop 1
	v_mul_f32_e32 v58, v63, v63
	v_mul_f32_e32 v59, v65, v65
	v_fmac_f32_e32 v58, v62, v62
	v_fmac_f32_e32 v59, v64, v64
	v_add_f32_e32 v58, v58, v59
	v_mul_f32_e32 v59, v71, v71
	v_mul_f32_e32 v60, v73, v73
	v_fmac_f32_e32 v59, v70, v70
	v_fmac_f32_e32 v60, v72, v72
	v_add_f32_e32 v59, v59, v60
	v_add_f32_e32 v64, v58, v59
	s_waitcnt vmcnt(15)
	v_mov_b64_e32 v[58:59], v[196:197]
	v_mov_b64_e32 v[60:61], v[198:199]
	v_lshlrev_b32_e32 v62, 16, v58
	v_and_b32_e32 v63, 0xffff0000, v58
	v_lshlrev_b32_e32 v58, 16, v59
	v_and_b32_e32 v59, 0xffff0000, v59
	v_pk_add_f32 v[56:57], v[56:57], v[58:59]
	v_lshlrev_b32_e32 v58, 16, v60
	v_and_b32_e32 v59, 0xffff0000, v60
	v_lshlrev_b32_e32 v60, 16, v61
	v_and_b32_e32 v61, 0xffff0000, v61
	v_pk_add_f32 v[54:55], v[54:55], v[62:63]
	v_pk_add_f32 v[60:61], v[52:53], v[60:61]
	v_pk_add_f32 v[58:59], v[50:51], v[58:59]
	v_cvt_pk_bf16_f32 v50, v54, v55
	v_cvt_pk_bf16_f32 v51, v56, v57
	v_cvt_pk_bf16_f32 v52, v58, v59
	v_cvt_pk_bf16_f32 v53, v60, v61
	global_store_dwordx4 v[68:69], v[50:53], off offset:256 sc0 sc1
	s_nop 1
	v_mul_f32_e32 v50, v55, v55
	v_mul_f32_e32 v51, v57, v57
	v_fmac_f32_e32 v50, v54, v54
	v_fmac_f32_e32 v51, v56, v56
	v_add_f32_e32 v50, v50, v51
	v_mul_f32_e32 v51, v59, v59
	v_mul_f32_e32 v52, v61, v61
	v_fmac_f32_e32 v51, v58, v58
	v_fmac_f32_e32 v52, v60, v60
	v_add_f32_e32 v51, v51, v52
	v_add_f32_e32 v50, v50, v51
	v_add_f32_e32 v50, v64, v50
	ds_bpermute_b32 v51, v152, v50
	s_waitcnt lgkmcnt(0)
	v_add_f32_e32 v50, v50, v51
	ds_bpermute_b32 v51, v151, v50
	s_and_saveexec_b64 s[12:13], vcc
	s_cbranch_execz .LBB0_800
	s_waitcnt lgkmcnt(0)
	v_add_f32_e32 v52, v50, v51
	v_lshlrev_b64 v[50:51], 6, v[66:67]
	v_lshl_add_u64 v[50:51], s[80:81], 0, v[50:51]
	v_lshl_add_u64 v[50:51], s[0:1], 2, v[50:51]
	s_lshl_b32 s24, s15, 2
	s_mov_b32 s25, s77
	v_lshl_add_u64 v[50:51], v[50:51], 0, s[24:25]
	global_store_dword v[50:51], v52, off
.LBB0_800:
	s_or_b64 exec, exec, s[12:13]
	s_mov_b64 s[12:13], 0x90
	s_waitcnt lgkmcnt(0)
	v_lshl_add_u64 v[50:51], v[142:143], 0, s[12:13]
	v_lshlrev_b64 v[52:53], 11, v[50:51]
	v_lshl_add_u64 v[52:53], s[22:23], 0, v[52:53]
	v_lshl_add_u64 v[52:53], s[10:11], 1, v[52:53]
	v_lshl_add_u64 v[52:53], v[52:53], 0, s[76:77]
	v_lshl_add_u64 v[52:53], v[144:145], 1, v[52:53]
	s_waitcnt vmcnt(15)
	v_mov_b64_e32 v[54:55], v[200:201]
	v_mov_b64_e32 v[56:57], v[202:203]
	v_lshlrev_b32_e32 v58, 16, v54
	v_and_b32_e32 v59, 0xffff0000, v54
	v_lshlrev_b32_e32 v54, 16, v55
	v_and_b32_e32 v55, 0xffff0000, v55
	v_pk_add_f32 v[48:49], v[48:49], v[54:55]
	v_lshlrev_b32_e32 v54, 16, v56
	v_and_b32_e32 v55, 0xffff0000, v56
	v_lshlrev_b32_e32 v56, 16, v57
	v_and_b32_e32 v57, 0xffff0000, v57
	v_pk_add_f32 v[46:47], v[46:47], v[58:59]
	v_pk_add_f32 v[56:57], v[44:45], v[56:57]
	v_pk_add_f32 v[54:55], v[42:43], v[54:55]
	v_cvt_pk_bf16_f32 v42, v46, v47
	v_cvt_pk_bf16_f32 v43, v48, v49
	v_cvt_pk_bf16_f32 v44, v54, v55
	v_cvt_pk_bf16_f32 v45, v56, v57
	global_store_dwordx4 v[52:53], v[42:45], off sc0 sc1
	s_nop 1
	v_mul_f32_e32 v42, v47, v47
	v_mul_f32_e32 v43, v49, v49
	v_fmac_f32_e32 v42, v46, v46
	v_fmac_f32_e32 v43, v48, v48
	v_add_f32_e32 v42, v42, v43
	v_mul_f32_e32 v43, v55, v55
	v_mul_f32_e32 v44, v57, v57
	v_fmac_f32_e32 v43, v54, v54
	v_fmac_f32_e32 v44, v56, v56
	v_add_f32_e32 v43, v43, v44
	v_add_f32_e32 v48, v42, v43
	s_waitcnt vmcnt(15)
	v_mov_b64_e32 v[42:43], v[204:205]
	v_mov_b64_e32 v[44:45], v[206:207]
	v_lshlrev_b32_e32 v46, 16, v42
	v_and_b32_e32 v47, 0xffff0000, v42
	v_lshlrev_b32_e32 v42, 16, v43
	v_and_b32_e32 v43, 0xffff0000, v43
	v_pk_add_f32 v[40:41], v[40:41], v[42:43]
	v_lshlrev_b32_e32 v42, 16, v44
	v_and_b32_e32 v43, 0xffff0000, v44
	v_lshlrev_b32_e32 v44, 16, v45
	v_and_b32_e32 v45, 0xffff0000, v45
	v_pk_add_f32 v[38:39], v[38:39], v[46:47]
	v_pk_add_f32 v[44:45], v[36:37], v[44:45]
	v_pk_add_f32 v[42:43], v[34:35], v[42:43]
	v_cvt_pk_bf16_f32 v34, v38, v39
	v_cvt_pk_bf16_f32 v35, v40, v41
	v_cvt_pk_bf16_f32 v36, v42, v43
	v_cvt_pk_bf16_f32 v37, v44, v45
	global_store_dwordx4 v[52:53], v[34:37], off offset:256 sc0 sc1
	s_nop 1
	v_mul_f32_e32 v34, v39, v39
	v_mul_f32_e32 v35, v41, v41
	v_fmac_f32_e32 v34, v38, v38
	v_fmac_f32_e32 v35, v40, v40
	v_add_f32_e32 v34, v34, v35
	v_mul_f32_e32 v35, v43, v43
	v_mul_f32_e32 v36, v45, v45
	v_fmac_f32_e32 v35, v42, v42
	v_fmac_f32_e32 v36, v44, v44
	v_add_f32_e32 v35, v35, v36
	v_add_f32_e32 v34, v34, v35
	v_add_f32_e32 v34, v48, v34
	ds_bpermute_b32 v35, v152, v34
	s_waitcnt lgkmcnt(0)
	v_add_f32_e32 v34, v34, v35
	ds_bpermute_b32 v35, v151, v34
	s_and_saveexec_b64 s[12:13], vcc
	s_cbranch_execz .LBB0_802
	s_waitcnt lgkmcnt(0)
	v_add_f32_e32 v36, v34, v35
	v_lshlrev_b64 v[34:35], 6, v[50:51]
	v_lshl_add_u64 v[34:35], s[80:81], 0, v[34:35]
	v_lshl_add_u64 v[34:35], s[0:1], 2, v[34:35]
	s_lshl_b32 s24, s15, 2
	s_mov_b32 s25, s77
	v_lshl_add_u64 v[34:35], v[34:35], 0, s[24:25]
	global_store_dword v[34:35], v36, off
.LBB0_802:
	s_or_b64 exec, exec, s[12:13]
	s_mov_b64 s[12:13], 0xa0
	s_waitcnt lgkmcnt(0)
	v_lshl_add_u64 v[34:35], v[142:143], 0, s[12:13]
	v_lshlrev_b64 v[36:37], 11, v[34:35]
	v_lshl_add_u64 v[36:37], s[22:23], 0, v[36:37]
	v_lshl_add_u64 v[36:37], s[10:11], 1, v[36:37]
	v_lshl_add_u64 v[36:37], v[36:37], 0, s[76:77]
	v_lshl_add_u64 v[36:37], v[144:145], 1, v[36:37]
	s_waitcnt vmcnt(15)
	v_mov_b64_e32 v[38:39], v[208:209]
	v_mov_b64_e32 v[40:41], v[210:211]
	v_lshlrev_b32_e32 v42, 16, v38
	v_and_b32_e32 v43, 0xffff0000, v38
	v_lshlrev_b32_e32 v38, 16, v39
	v_and_b32_e32 v39, 0xffff0000, v39
	v_pk_add_f32 v[32:33], v[32:33], v[38:39]
	v_lshlrev_b32_e32 v38, 16, v40
	v_and_b32_e32 v39, 0xffff0000, v40
	v_lshlrev_b32_e32 v40, 16, v41
	v_and_b32_e32 v41, 0xffff0000, v41
	v_pk_add_f32 v[30:31], v[30:31], v[42:43]
	v_pk_add_f32 v[40:41], v[28:29], v[40:41]
	v_pk_add_f32 v[38:39], v[26:27], v[38:39]
	v_cvt_pk_bf16_f32 v26, v30, v31
	v_cvt_pk_bf16_f32 v27, v32, v33
	v_cvt_pk_bf16_f32 v28, v38, v39
	v_cvt_pk_bf16_f32 v29, v40, v41
	global_store_dwordx4 v[36:37], v[26:29], off sc0 sc1
	s_nop 1
	v_mul_f32_e32 v26, v31, v31
	v_mul_f32_e32 v27, v33, v33
	v_fmac_f32_e32 v26, v30, v30
	v_fmac_f32_e32 v27, v32, v32
	v_add_f32_e32 v26, v26, v27
	v_mul_f32_e32 v27, v39, v39
	v_mul_f32_e32 v28, v41, v41
	v_fmac_f32_e32 v27, v38, v38
	v_fmac_f32_e32 v28, v40, v40
	v_add_f32_e32 v27, v27, v28
	v_add_f32_e32 v32, v26, v27
	s_waitcnt vmcnt(15)
	v_mov_b64_e32 v[26:27], v[212:213]
	v_mov_b64_e32 v[28:29], v[214:215]
	v_lshlrev_b32_e32 v30, 16, v26
	v_and_b32_e32 v31, 0xffff0000, v26
	v_lshlrev_b32_e32 v26, 16, v27
	v_and_b32_e32 v27, 0xffff0000, v27
	v_pk_add_f32 v[24:25], v[24:25], v[26:27]
	v_lshlrev_b32_e32 v26, 16, v28
	v_and_b32_e32 v27, 0xffff0000, v28
	v_lshlrev_b32_e32 v28, 16, v29
	v_and_b32_e32 v29, 0xffff0000, v29
	v_pk_add_f32 v[22:23], v[22:23], v[30:31]
	v_pk_add_f32 v[28:29], v[20:21], v[28:29]
	v_pk_add_f32 v[26:27], v[18:19], v[26:27]
	v_cvt_pk_bf16_f32 v18, v22, v23
	v_cvt_pk_bf16_f32 v19, v24, v25
	v_cvt_pk_bf16_f32 v20, v26, v27
	v_cvt_pk_bf16_f32 v21, v28, v29
	global_store_dwordx4 v[36:37], v[18:21], off offset:256 sc0 sc1
	s_nop 1
	v_mul_f32_e32 v18, v23, v23
	v_mul_f32_e32 v19, v25, v25
	v_fmac_f32_e32 v18, v22, v22
	v_fmac_f32_e32 v19, v24, v24
	v_add_f32_e32 v18, v18, v19
	v_mul_f32_e32 v19, v27, v27
	v_mul_f32_e32 v20, v29, v29
	v_fmac_f32_e32 v19, v26, v26
	v_fmac_f32_e32 v20, v28, v28
	v_add_f32_e32 v19, v19, v20
	v_add_f32_e32 v18, v18, v19
	v_add_f32_e32 v18, v32, v18
	ds_bpermute_b32 v19, v152, v18
	s_waitcnt lgkmcnt(0)
	v_add_f32_e32 v18, v18, v19
	ds_bpermute_b32 v19, v151, v18
	s_and_saveexec_b64 s[12:13], vcc
	s_cbranch_execz .LBB0_804
	s_waitcnt lgkmcnt(0)
	v_add_f32_e32 v20, v18, v19
	v_lshlrev_b64 v[18:19], 6, v[34:35]
	v_lshl_add_u64 v[18:19], s[80:81], 0, v[18:19]
	v_lshl_add_u64 v[18:19], s[0:1], 2, v[18:19]
	s_lshl_b32 s24, s15, 2
	s_mov_b32 s25, s77
	v_lshl_add_u64 v[18:19], v[18:19], 0, s[24:25]
	global_store_dword v[18:19], v20, off
.LBB0_804:
	s_or_b64 exec, exec, s[12:13]
	s_mov_b64 s[12:13], 0xb0
	s_waitcnt lgkmcnt(0)
	v_lshl_add_u64 v[18:19], v[142:143], 0, s[12:13]
	v_lshlrev_b64 v[20:21], 11, v[18:19]
	v_lshl_add_u64 v[20:21], s[22:23], 0, v[20:21]
	v_lshl_add_u64 v[20:21], s[10:11], 1, v[20:21]
	v_lshl_add_u64 v[20:21], v[20:21], 0, s[76:77]
	v_lshl_add_u64 v[20:21], v[144:145], 1, v[20:21]
	s_waitcnt vmcnt(15)
	v_mov_b64_e32 v[22:23], v[216:217]
	v_mov_b64_e32 v[24:25], v[218:219]
	v_lshlrev_b32_e32 v26, 16, v22
	v_and_b32_e32 v27, 0xffff0000, v22
	v_lshlrev_b32_e32 v22, 16, v23
	v_and_b32_e32 v23, 0xffff0000, v23
	v_pk_add_f32 v[16:17], v[16:17], v[22:23]
	v_lshlrev_b32_e32 v22, 16, v24
	v_and_b32_e32 v23, 0xffff0000, v24
	v_lshlrev_b32_e32 v24, 16, v25
	v_and_b32_e32 v25, 0xffff0000, v25
	v_pk_add_f32 v[14:15], v[14:15], v[26:27]
	v_pk_add_f32 v[24:25], v[12:13], v[24:25]
	v_pk_add_f32 v[22:23], v[10:11], v[22:23]
	v_cvt_pk_bf16_f32 v10, v14, v15
	v_cvt_pk_bf16_f32 v11, v16, v17
	v_cvt_pk_bf16_f32 v12, v22, v23
	v_cvt_pk_bf16_f32 v13, v24, v25
	global_store_dwordx4 v[20:21], v[10:13], off sc0 sc1
	s_nop 1
	v_mul_f32_e32 v10, v15, v15
	v_mul_f32_e32 v11, v17, v17
	v_fmac_f32_e32 v10, v14, v14
	v_fmac_f32_e32 v11, v16, v16
	v_add_f32_e32 v10, v10, v11
	v_mul_f32_e32 v11, v23, v23
	v_mul_f32_e32 v12, v25, v25
	v_fmac_f32_e32 v11, v22, v22
	v_fmac_f32_e32 v12, v24, v24
	v_add_f32_e32 v11, v11, v12
	v_add_f32_e32 v16, v10, v11
	s_waitcnt vmcnt(15)
	v_mov_b64_e32 v[10:11], v[220:221]
	v_mov_b64_e32 v[12:13], v[222:223]
	v_lshlrev_b32_e32 v14, 16, v10
	v_and_b32_e32 v15, 0xffff0000, v10
	v_lshlrev_b32_e32 v10, 16, v11
	v_and_b32_e32 v11, 0xffff0000, v11
	v_pk_add_f32 v[8:9], v[8:9], v[10:11]
	v_lshlrev_b32_e32 v10, 16, v12
	v_and_b32_e32 v11, 0xffff0000, v12
	v_lshlrev_b32_e32 v12, 16, v13
	v_and_b32_e32 v13, 0xffff0000, v13
	v_pk_add_f32 v[6:7], v[6:7], v[14:15]
	v_pk_add_f32 v[12:13], v[4:5], v[12:13]
	v_pk_add_f32 v[10:11], v[2:3], v[10:11]
	v_cvt_pk_bf16_f32 v2, v6, v7
	v_cvt_pk_bf16_f32 v3, v8, v9
	v_cvt_pk_bf16_f32 v4, v10, v11
	v_cvt_pk_bf16_f32 v5, v12, v13
	global_store_dwordx4 v[20:21], v[2:5], off offset:256 sc0 sc1
	s_nop 1
	v_mul_f32_e32 v2, v7, v7
	v_mul_f32_e32 v3, v9, v9
	v_fmac_f32_e32 v2, v6, v6
	v_fmac_f32_e32 v3, v8, v8
	v_add_f32_e32 v2, v2, v3
	v_mul_f32_e32 v3, v11, v11
	v_mul_f32_e32 v4, v13, v13
	v_fmac_f32_e32 v3, v10, v10
	v_fmac_f32_e32 v4, v12, v12
	v_add_f32_e32 v3, v3, v4
	v_add_f32_e32 v2, v2, v3
	v_add_f32_e32 v2, v16, v2
	ds_bpermute_b32 v3, v152, v2
	s_waitcnt lgkmcnt(0)
	v_add_f32_e32 v2, v2, v3
	ds_bpermute_b32 v3, v151, v2
	s_and_saveexec_b64 s[10:11], vcc
	s_cbranch_execz .LBB0_806
	s_waitcnt lgkmcnt(0)
	v_add_f32_e32 v4, v2, v3
	v_lshlrev_b64 v[2:3], 6, v[18:19]
	v_lshl_add_u64 v[2:3], s[80:81], 0, v[2:3]
	v_lshl_add_u64 v[2:3], s[0:1], 2, v[2:3]
	s_lshl_b32 s0, s15, 2
	s_mov_b32 s1, s77
	v_lshl_add_u64 v[2:3], v[2:3], 0, s[0:1]
	global_store_dword v[2:3], v4, off

.LBB0_868:
	s_waitcnt vmcnt(30)
	ds_write2_b32 v1, v4, v5 offset1:65
	s_waitcnt vmcnt(28)
	ds_write2_b32 v1, v6, v7 offset0:130 offset1:195
	v_add_u32_e32 v4, 0x400, v1
	s_waitcnt vmcnt(26)
	ds_write2_b32 v4, v8, v9 offset0:4 offset1:69
	s_waitcnt vmcnt(24)
	ds_write2_b32 v4, v10, v11 offset0:134 offset1:199
	v_add_u32_e32 v4, 0x800, v1
	s_waitcnt vmcnt(22)
	ds_write2_b32 v4, v12, v13 offset0:8 offset1:73
	s_waitcnt vmcnt(20)
	ds_write2_b32 v4, v14, v15 offset0:138 offset1:203
	v_add_u32_e32 v4, 0xc00, v1
	s_waitcnt vmcnt(18)
	ds_write2_b32 v4, v16, v17 offset0:12 offset1:77
	s_waitcnt vmcnt(16)
	ds_write2_b32 v4, v18, v19 offset0:142 offset1:207
	v_add_u32_e32 v4, 0x1000, v1
	s_waitcnt vmcnt(14)
	ds_write2_b32 v4, v20, v21 offset0:16 offset1:81
	s_waitcnt vmcnt(12)
	ds_write2_b32 v4, v22, v23 offset0:146 offset1:211
	v_add_u32_e32 v4, 0x1400, v1
	s_waitcnt vmcnt(10)
	ds_write2_b32 v4, v24, v25 offset0:20 offset1:85
	s_waitcnt vmcnt(8)
	ds_write2_b32 v4, v28, v29 offset0:150 offset1:215
	v_add_u32_e32 v4, 0x1800, v1
	s_waitcnt vmcnt(6)
	ds_write2_b32 v4, v30, v31 offset0:24 offset1:89
	s_waitcnt vmcnt(4)
	ds_write2_b32 v4, v32, v33 offset0:154 offset1:219
	v_add_u32_e32 v4, 0x1c00, v1
	s_waitcnt vmcnt(2)
	ds_write2_b32 v4, v34, v35 offset0:28 offset1:93
	s_waitcnt vmcnt(0)
	ds_write2_b32 v4, v36, v37 offset0:158 offset1:223
	s_waitcnt lgkmcnt(0)
	v_add_u32_e32 v30, 0x400, v39
	s_sub_i32 s14, 0, s14
	ds_read2_b32 v[8:9], v39 offset1:16
	ds_read2_b32 v[10:11], v39 offset0:65 offset1:81
	ds_read2_b32 v[12:13], v39 offset0:130 offset1:146
	ds_read2_b32 v[14:15], v39 offset0:195 offset1:211
	ds_read2_b32 v[16:17], v30 offset0:4 offset1:20
	ds_read2_b32 v[18:19], v30 offset0:69 offset1:85
	ds_read2_b32 v[20:21], v30 offset0:134 offset1:150
	ds_read2_b32 v[22:23], v30 offset0:199 offset1:215
	s_add_i32 s14, s14, s7
	v_add_u32_e32 v26, s14, v38
	v_ashrrev_i32_e32 v27, 31, v26
	v_lshl_add_u64 v[24:25], s[12:13], 1, v[2:3]
	v_lshlrev_b64 v[28:29], 11, v[26:27]
	s_waitcnt lgkmcnt(6)
	v_cvt_pk_bf16_f32 v4, v8, v10
	s_waitcnt lgkmcnt(4)
	v_cvt_pk_bf16_f32 v5, v12, v14
	s_waitcnt lgkmcnt(2)
	v_cvt_pk_bf16_f32 v6, v16, v18
	s_waitcnt lgkmcnt(0)
	v_cvt_pk_bf16_f32 v7, v20, v22
	v_lshl_add_u64 v[28:29], v[24:25], 0, v[28:29]
	v_add_u32_e32 v8, 16, v26
	global_store_dwordx4 v[28:29], v[4:7], off sc0 sc1
	s_add_i32 s9, s9, s89
	s_add_i32 s7, s7, s8
	v_cvt_pk_bf16_f32 v4, v9, v11
	v_ashrrev_i32_e32 v9, 31, v8
	v_cvt_pk_bf16_f32 v5, v13, v15
	v_cvt_pk_bf16_f32 v6, v17, v19
	v_cvt_pk_bf16_f32 v7, v21, v23
	v_lshlrev_b64 v[8:9], 11, v[8:9]
	ds_read2_b32 v[10:11], v39 offset0:32 offset1:48
	ds_read2_b32 v[12:13], v39 offset0:97 offset1:113
	ds_read2_b32 v[14:15], v39 offset0:162 offset1:178
	ds_read2_b32 v[16:17], v39 offset0:227 offset1:243
	ds_read2_b32 v[18:19], v30 offset0:36 offset1:52
	ds_read2_b32 v[20:21], v30 offset0:101 offset1:117
	ds_read2_b32 v[22:23], v30 offset0:166 offset1:182
	ds_read2_b32 v[28:29], v30 offset0:231 offset1:247
	v_lshl_add_u64 v[8:9], v[24:25], 0, v[8:9]
	global_store_dwordx4 v[8:9], v[4:7], off sc0 sc1
	v_add_u32_e32 v8, 32, v26
	v_ashrrev_i32_e32 v9, 31, v8
	v_lshlrev_b64 v[8:9], 11, v[8:9]
	s_waitcnt lgkmcnt(6)
	v_cvt_pk_bf16_f32 v4, v10, v12
	s_waitcnt lgkmcnt(4)
	v_cvt_pk_bf16_f32 v5, v14, v16
	s_waitcnt lgkmcnt(2)
	v_cvt_pk_bf16_f32 v6, v18, v20
	s_waitcnt lgkmcnt(0)
	v_cvt_pk_bf16_f32 v7, v22, v28
	v_lshl_add_u64 v[8:9], v[24:25], 0, v[8:9]
	global_store_dwordx4 v[8:9], v[4:7], off sc0 sc1
	v_add_u32_e32 v8, 48, v26
	v_ashrrev_i32_e32 v9, 31, v8
	v_lshlrev_b64 v[8:9], 11, v[8:9]
	v_cvt_pk_bf16_f32 v4, v11, v13
	v_cvt_pk_bf16_f32 v5, v15, v17
	v_cvt_pk_bf16_f32 v6, v19, v21
	v_cvt_pk_bf16_f32 v7, v23, v29
	v_lshl_add_u64 v[8:9], v[24:25], 0, v[8:9]
	global_store_dwordx4 v[8:9], v[4:7], off sc0 sc1
	s_waitcnt lgkmcnt(0)
	s_cmpk_lt_i32 s9, 0x100
	s_cbranch_scc0 .LBB0_871

.LBB0_874:
	s_waitcnt vmcnt(30)
	ds_write2_b32 v1, v4, v5 offset1:65
	s_waitcnt vmcnt(28)
	ds_write2_b32 v1, v6, v7 offset0:130 offset1:195
	v_add_u32_e32 v4, 0x400, v1
	s_waitcnt vmcnt(26)
	ds_write2_b32 v4, v8, v9 offset0:4 offset1:69
	s_waitcnt vmcnt(24)
	ds_write2_b32 v4, v10, v11 offset0:134 offset1:199
	v_add_u32_e32 v4, 0x800, v1
	s_waitcnt vmcnt(22)
	ds_write2_b32 v4, v12, v13 offset0:8 offset1:73
	s_waitcnt vmcnt(20)
	ds_write2_b32 v4, v14, v15 offset0:138 offset1:203
	v_add_u32_e32 v4, 0xc00, v1
	s_waitcnt vmcnt(18)
	ds_write2_b32 v4, v16, v17 offset0:12 offset1:77
	s_waitcnt vmcnt(16)
	ds_write2_b32 v4, v18, v19 offset0:142 offset1:207
	v_add_u32_e32 v4, 0x1000, v1
	s_waitcnt vmcnt(14)
	ds_write2_b32 v4, v20, v21 offset0:16 offset1:81
	s_waitcnt vmcnt(12)
	ds_write2_b32 v4, v22, v23 offset0:146 offset1:211
	v_add_u32_e32 v4, 0x1400, v1
	s_waitcnt vmcnt(10)
	ds_write2_b32 v4, v24, v25 offset0:20 offset1:85
	s_waitcnt vmcnt(8)
	ds_write2_b32 v4, v26, v27 offset0:150 offset1:215
	v_add_u32_e32 v4, 0x1800, v1
	s_waitcnt vmcnt(6)
	ds_write2_b32 v4, v28, v29 offset0:24 offset1:89
	s_waitcnt vmcnt(4)
	ds_write2_b32 v4, v30, v31 offset0:154 offset1:219
	v_add_u32_e32 v4, 0x1c00, v1
	s_waitcnt vmcnt(2)
	ds_write2_b32 v4, v32, v33 offset0:28 offset1:93
	s_waitcnt vmcnt(0)
	ds_write2_b32 v4, v34, v35 offset0:158 offset1:223
	s_waitcnt lgkmcnt(0)
	v_add_u32_e32 v30, 0x400, v37
	s_sub_i32 s8, 0, s8
	ds_read2_b32 v[8:9], v37 offset1:16
	ds_read2_b32 v[10:11], v37 offset0:65 offset1:81
	ds_read2_b32 v[12:13], v37 offset0:130 offset1:146
	ds_read2_b32 v[14:15], v37 offset0:195 offset1:211
	ds_read2_b32 v[16:17], v30 offset0:4 offset1:20
	ds_read2_b32 v[18:19], v30 offset0:69 offset1:85
	ds_read2_b32 v[20:21], v30 offset0:134 offset1:150
	ds_read2_b32 v[22:23], v30 offset0:199 offset1:215
	s_add_i32 s8, s8, s5
	v_add_u32_e32 v26, s8, v36
	v_ashrrev_i32_e32 v27, 31, v26
	v_lshl_add_u64 v[24:25], s[24:25], 1, v[2:3]
	v_lshlrev_b64 v[28:29], 11, v[26:27]
	s_waitcnt lgkmcnt(6)
	v_cvt_pk_bf16_f32 v4, v8, v10
	s_waitcnt lgkmcnt(4)
	v_cvt_pk_bf16_f32 v5, v12, v14
	s_waitcnt lgkmcnt(2)
	v_cvt_pk_bf16_f32 v6, v16, v18
	s_waitcnt lgkmcnt(0)
	v_cvt_pk_bf16_f32 v7, v20, v22
	v_lshl_add_u64 v[28:29], v[24:25], 0, v[28:29]
	v_add_u32_e32 v8, 16, v26
	global_store_dwordx4 v[28:29], v[4:7], off sc0 sc1
	s_add_i32 s7, s7, s89
	s_add_i32 s5, s5, s6
	v_cvt_pk_bf16_f32 v4, v9, v11
	v_ashrrev_i32_e32 v9, 31, v8
	v_cvt_pk_bf16_f32 v5, v13, v15
	v_cvt_pk_bf16_f32 v6, v17, v19
	v_cvt_pk_bf16_f32 v7, v21, v23
	v_lshlrev_b64 v[8:9], 11, v[8:9]
	ds_read2_b32 v[10:11], v37 offset0:32 offset1:48
	ds_read2_b32 v[12:13], v37 offset0:97 offset1:113
	ds_read2_b32 v[14:15], v37 offset0:162 offset1:178
	ds_read2_b32 v[16:17], v37 offset0:227 offset1:243
	ds_read2_b32 v[18:19], v30 offset0:36 offset1:52
	ds_read2_b32 v[20:21], v30 offset0:101 offset1:117
	ds_read2_b32 v[22:23], v30 offset0:166 offset1:182
	ds_read2_b32 v[28:29], v30 offset0:231 offset1:247
	v_lshl_add_u64 v[8:9], v[24:25], 0, v[8:9]
	global_store_dwordx4 v[8:9], v[4:7], off sc0 sc1
	v_add_u32_e32 v8, 32, v26
	v_ashrrev_i32_e32 v9, 31, v8
	v_lshlrev_b64 v[8:9], 11, v[8:9]
	s_waitcnt lgkmcnt(6)
	v_cvt_pk_bf16_f32 v4, v10, v12
	s_waitcnt lgkmcnt(4)
	v_cvt_pk_bf16_f32 v5, v14, v16
	s_waitcnt lgkmcnt(2)
	v_cvt_pk_bf16_f32 v6, v18, v20
	s_waitcnt lgkmcnt(0)
	v_cvt_pk_bf16_f32 v7, v22, v28
	v_lshl_add_u64 v[8:9], v[24:25], 0, v[8:9]
	global_store_dwordx4 v[8:9], v[4:7], off sc0 sc1
	v_add_u32_e32 v8, 48, v26
	v_ashrrev_i32_e32 v9, 31, v8
	v_lshlrev_b64 v[8:9], 11, v[8:9]
	v_cvt_pk_bf16_f32 v4, v11, v13
	v_cvt_pk_bf16_f32 v5, v15, v17
	v_cvt_pk_bf16_f32 v6, v19, v21
	v_cvt_pk_bf16_f32 v7, v23, v29
	v_lshl_add_u64 v[8:9], v[24:25], 0, v[8:9]
	global_store_dwordx4 v[8:9], v[4:7], off sc0 sc1
	s_waitcnt lgkmcnt(0)
	s_cmpk_lt_i32 s7, 0x80
	s_cbranch_scc0 .LBB0_877

.LBB0_879:
	s_waitcnt vmcnt(30)
	ds_write2_b32 v49, v15, v14 offset1:66
	s_waitcnt vmcnt(28)
	ds_write2_b32 v49, v17, v16 offset0:132 offset1:198
	v_add_u32_e32 v14, 0x400, v49
	s_waitcnt vmcnt(26)
	ds_write2_b32 v14, v19, v18 offset0:8 offset1:74
	s_waitcnt vmcnt(24)
	ds_write2_b32 v14, v21, v20 offset0:140 offset1:206
	v_add_u32_e32 v14, 0x800, v49
	s_waitcnt vmcnt(22)
	ds_write2_b32 v14, v23, v22 offset0:16 offset1:82
	s_waitcnt vmcnt(20)
	ds_write2_b32 v14, v25, v24 offset0:148 offset1:214
	v_add_u32_e32 v14, 0xc00, v49
	s_waitcnt vmcnt(18)
	ds_write2_b32 v14, v27, v26 offset0:24 offset1:90
	s_waitcnt vmcnt(16)
	ds_write2_b32 v14, v29, v28 offset0:156 offset1:222
	v_add_u32_e32 v14, 0x1000, v49
	s_waitcnt vmcnt(14)
	ds_write2_b32 v14, v31, v30 offset0:32 offset1:98
	s_waitcnt vmcnt(12)
	ds_write2_b32 v14, v33, v32 offset0:164 offset1:230
	v_add_u32_e32 v14, 0x1400, v49
	s_waitcnt vmcnt(10)
	ds_write2_b32 v14, v35, v34 offset0:40 offset1:106
	s_waitcnt vmcnt(8)
	ds_write2_b32 v14, v37, v36 offset0:172 offset1:238
	v_add_u32_e32 v14, 0x1800, v49
	s_waitcnt vmcnt(6)
	ds_write2_b32 v14, v39, v38 offset0:48 offset1:114
	s_waitcnt vmcnt(4)
	ds_write2_b32 v14, v41, v40 offset0:180 offset1:246
	v_add_u32_e32 v14, 0x1c00, v49
	s_waitcnt vmcnt(2)
	ds_write2_b32 v14, v43, v42 offset0:56 offset1:122
	s_waitcnt vmcnt(0)
	ds_write2_b32 v14, v45, v44 offset0:188 offset1:254
	s_waitcnt lgkmcnt(0)
	ds_read2_b32 v[18:19], v48 offset0:33 offset1:41
	ds_read2_b32 v[20:21], v48 offset1:8
	ds_read2_b32 v[22:23], v48 offset0:66 offset1:74
	ds_read2_b32 v[24:25], v48 offset0:99 offset1:107
	ds_read2_b32 v[26:27], v48 offset0:132 offset1:140
	ds_read2_b32 v[28:29], v48 offset0:165 offset1:173
	ds_read2_b32 v[30:31], v48 offset0:198 offset1:206
	ds_read2_b32 v[32:33], v48 offset0:231 offset1:239
	s_ashr_i32 s13, s12, 31
	v_lshl_add_u64 v[34:35], s[12:13], 1, v[4:5]
	s_waitcnt lgkmcnt(6)
	v_cvt_pk_bf16_f32 v14, v20, v18
	s_waitcnt lgkmcnt(4)
	v_cvt_pk_bf16_f32 v15, v22, v24
	s_waitcnt lgkmcnt(2)
	v_cvt_pk_bf16_f32 v16, v26, v28
	s_waitcnt lgkmcnt(0)
	v_cvt_pk_bf16_f32 v17, v30, v32
	v_lshl_add_u64 v[36:37], v[34:35], 0, v[6:7]
	global_store_dwordx4 v[36:37], v[14:17], off sc0 sc1
	v_readlane_b32 s6, v254, 28
	s_add_i32 s5, s5, s89
	v_cvt_pk_bf16_f32 v14, v21, v19
	v_cvt_pk_bf16_f32 v15, v23, v25
	v_cvt_pk_bf16_f32 v16, v27, v29
	v_cvt_pk_bf16_f32 v17, v31, v33
	ds_read2_b32 v[20:21], v48 offset0:49 offset1:57
	ds_read2_b32 v[22:23], v48 offset0:16 offset1:24
	ds_read2_b32 v[24:25], v48 offset0:82 offset1:90
	ds_read2_b32 v[26:27], v48 offset0:115 offset1:123
	ds_read2_b32 v[28:29], v48 offset0:148 offset1:156
	ds_read2_b32 v[30:31], v48 offset0:181 offset1:189
	ds_read2_b32 v[32:33], v48 offset0:214 offset1:222
	ds_read2_b32 v[36:37], v48 offset0:247 offset1:255
	v_lshl_add_u64 v[18:19], v[34:35], 0, v[8:9]
	global_store_dwordx4 v[18:19], v[14:17], off sc0 sc1
	v_lshl_add_u64 v[18:19], v[34:35], 0, v[10:11]
	s_add_i32 s12, s12, s6
	s_waitcnt lgkmcnt(6)
	v_cvt_pk_bf16_f32 v14, v22, v20
	s_waitcnt lgkmcnt(4)
	v_cvt_pk_bf16_f32 v15, v24, v26
	s_waitcnt lgkmcnt(2)
	v_cvt_pk_bf16_f32 v16, v28, v30
	s_waitcnt lgkmcnt(0)
	v_cvt_pk_bf16_f32 v17, v32, v36
	global_store_dwordx4 v[18:19], v[14:17], off sc0 sc1
	v_lshl_add_u64 v[18:19], v[34:35], 0, v[12:13]
	s_cmp_lt_i32 s5, 16
	v_cvt_pk_bf16_f32 v14, v23, v21
	v_cvt_pk_bf16_f32 v15, v25, v27
	v_cvt_pk_bf16_f32 v16, v29, v31
	v_cvt_pk_bf16_f32 v17, v33, v37
	global_store_dwordx4 v[18:19], v[14:17], off sc0 sc1
	s_waitcnt lgkmcnt(0)
	s_cbranch_scc0 .LBB0_882

.LBB0_889:
	s_waitcnt vmcnt(30)
	ds_write2_b32 v1, v4, v5 offset1:65
	s_waitcnt vmcnt(28)
	ds_write2_b32 v1, v6, v7 offset0:130 offset1:195
	v_add_u32_e32 v4, 0x400, v1
	s_waitcnt vmcnt(26)
	ds_write2_b32 v4, v8, v9 offset0:4 offset1:69
	s_waitcnt vmcnt(24)
	ds_write2_b32 v4, v10, v11 offset0:134 offset1:199
	v_add_u32_e32 v4, 0x800, v1
	s_waitcnt vmcnt(22)
	ds_write2_b32 v4, v12, v13 offset0:8 offset1:73
	s_waitcnt vmcnt(20)
	ds_write2_b32 v4, v14, v15 offset0:138 offset1:203
	v_add_u32_e32 v4, 0xc00, v1
	s_waitcnt vmcnt(18)
	ds_write2_b32 v4, v16, v17 offset0:12 offset1:77
	s_waitcnt vmcnt(16)
	ds_write2_b32 v4, v18, v19 offset0:142 offset1:207
	v_add_u32_e32 v4, 0x1000, v1
	s_waitcnt vmcnt(14)
	ds_write2_b32 v4, v20, v21 offset0:16 offset1:81
	s_waitcnt vmcnt(12)
	ds_write2_b32 v4, v22, v23 offset0:146 offset1:211
	v_add_u32_e32 v4, 0x1400, v1
	s_waitcnt vmcnt(10)
	ds_write2_b32 v4, v24, v25 offset0:20 offset1:85
	s_waitcnt vmcnt(8)
	ds_write2_b32 v4, v28, v29 offset0:150 offset1:215
	v_add_u32_e32 v4, 0x1800, v1
	s_waitcnt vmcnt(6)
	ds_write2_b32 v4, v30, v31 offset0:24 offset1:89
	s_waitcnt vmcnt(4)
	ds_write2_b32 v4, v32, v33 offset0:154 offset1:219
	v_add_u32_e32 v4, 0x1c00, v1
	s_waitcnt vmcnt(2)
	ds_write2_b32 v4, v34, v35 offset0:28 offset1:93
	s_waitcnt vmcnt(0)
	ds_write2_b32 v4, v36, v37 offset0:158 offset1:223
	s_waitcnt lgkmcnt(0)
	v_add_u32_e32 v30, 0x400, v39
	s_sub_i32 s8, 0, s8
	ds_read2_b32 v[8:9], v39 offset1:16
	ds_read2_b32 v[10:11], v39 offset0:65 offset1:81
	ds_read2_b32 v[12:13], v39 offset0:130 offset1:146
	ds_read2_b32 v[14:15], v39 offset0:195 offset1:211
	ds_read2_b32 v[16:17], v30 offset0:4 offset1:20
	ds_read2_b32 v[18:19], v30 offset0:69 offset1:85
	ds_read2_b32 v[20:21], v30 offset0:134 offset1:150
	ds_read2_b32 v[22:23], v30 offset0:199 offset1:215
	s_add_i32 s8, s8, s5
	v_add_u32_e32 v26, s8, v38
	v_ashrrev_i32_e32 v27, 31, v26
	v_lshl_add_u64 v[24:25], s[24:25], 1, v[2:3]
	v_lshlrev_b64 v[28:29], 9, v[26:27]
	s_waitcnt lgkmcnt(6)
	v_cvt_pk_bf16_f32 v4, v8, v10
	s_waitcnt lgkmcnt(4)
	v_cvt_pk_bf16_f32 v5, v12, v14
	s_waitcnt lgkmcnt(2)
	v_cvt_pk_bf16_f32 v6, v16, v18
	s_waitcnt lgkmcnt(0)
	v_cvt_pk_bf16_f32 v7, v20, v22
	v_lshl_add_u64 v[28:29], v[24:25], 0, v[28:29]
	v_add_u32_e32 v8, 16, v26
	global_store_dwordx4 v[28:29], v[4:7], off sc0 sc1
	s_add_i32 s7, s7, s89
	s_add_i32 s5, s5, s6
	v_cvt_pk_bf16_f32 v4, v9, v11
	v_ashrrev_i32_e32 v9, 31, v8
	v_cvt_pk_bf16_f32 v5, v13, v15
	v_cvt_pk_bf16_f32 v6, v17, v19
	v_cvt_pk_bf16_f32 v7, v21, v23
	v_lshlrev_b64 v[8:9], 9, v[8:9]
	ds_read2_b32 v[10:11], v39 offset0:32 offset1:48
	ds_read2_b32 v[12:13], v39 offset0:97 offset1:113
	ds_read2_b32 v[14:15], v39 offset0:162 offset1:178
	ds_read2_b32 v[16:17], v39 offset0:227 offset1:243
	ds_read2_b32 v[18:19], v30 offset0:36 offset1:52
	ds_read2_b32 v[20:21], v30 offset0:101 offset1:117
	ds_read2_b32 v[22:23], v30 offset0:166 offset1:182
	ds_read2_b32 v[28:29], v30 offset0:231 offset1:247
	v_lshl_add_u64 v[8:9], v[24:25], 0, v[8:9]
	global_store_dwordx4 v[8:9], v[4:7], off sc0 sc1
	v_add_u32_e32 v8, 32, v26
	v_ashrrev_i32_e32 v9, 31, v8
	v_lshlrev_b64 v[8:9], 9, v[8:9]
	s_waitcnt lgkmcnt(6)
	v_cvt_pk_bf16_f32 v4, v10, v12
	s_waitcnt lgkmcnt(4)
	v_cvt_pk_bf16_f32 v5, v14, v16
	s_waitcnt lgkmcnt(2)
	v_cvt_pk_bf16_f32 v6, v18, v20
	s_waitcnt lgkmcnt(0)
	v_cvt_pk_bf16_f32 v7, v22, v28
	v_lshl_add_u64 v[8:9], v[24:25], 0, v[8:9]
	global_store_dwordx4 v[8:9], v[4:7], off sc0 sc1
	v_add_u32_e32 v8, 48, v26
	v_ashrrev_i32_e32 v9, 31, v8
	v_lshlrev_b64 v[8:9], 9, v[8:9]
	v_cvt_pk_bf16_f32 v4, v11, v13
	v_cvt_pk_bf16_f32 v5, v15, v17
	v_cvt_pk_bf16_f32 v6, v19, v21
	v_cvt_pk_bf16_f32 v7, v23, v29
	v_lshl_add_u64 v[8:9], v[24:25], 0, v[8:9]
	global_store_dwordx4 v[8:9], v[4:7], off sc0 sc1
	s_waitcnt lgkmcnt(0)
	s_cmpk_lt_i32 s7, 0x200
	v_readlane_b32 s8, v254, 0
	s_cbranch_scc0 .LBB0_892

.LBB0_894:
	s_waitcnt vmcnt(30)
	ds_write2_b32 v37, v4, v5 offset1:65
	s_waitcnt vmcnt(28)
	ds_write2_b32 v37, v6, v7 offset0:130 offset1:195
	v_add_u32_e32 v4, 0x400, v37
	s_waitcnt vmcnt(26)
	ds_write2_b32 v4, v8, v9 offset0:4 offset1:69
	s_waitcnt vmcnt(24)
	ds_write2_b32 v4, v10, v11 offset0:134 offset1:199
	v_add_u32_e32 v4, 0x800, v37
	s_waitcnt vmcnt(22)
	ds_write2_b32 v4, v12, v13 offset0:8 offset1:73
	s_waitcnt vmcnt(20)
	ds_write2_b32 v4, v14, v15 offset0:138 offset1:203
	v_add_u32_e32 v4, 0xc00, v37
	s_waitcnt vmcnt(18)
	ds_write2_b32 v4, v16, v17 offset0:12 offset1:77
	s_waitcnt vmcnt(16)
	ds_write2_b32 v4, v18, v19 offset0:142 offset1:207
	v_add_u32_e32 v4, 0x1000, v37
	s_waitcnt vmcnt(14)
	ds_write2_b32 v4, v20, v21 offset0:16 offset1:81
	s_waitcnt vmcnt(12)
	ds_write2_b32 v4, v22, v23 offset0:146 offset1:211
	v_add_u32_e32 v4, 0x1400, v37
	s_waitcnt vmcnt(10)
	ds_write2_b32 v4, v24, v25 offset0:20 offset1:85
	s_waitcnt vmcnt(8)
	ds_write2_b32 v4, v26, v27 offset0:150 offset1:215
	v_add_u32_e32 v4, 0x1800, v37
	s_waitcnt vmcnt(6)
	ds_write2_b32 v4, v28, v29 offset0:24 offset1:89
	s_waitcnt vmcnt(4)
	ds_write2_b32 v4, v30, v31 offset0:154 offset1:219
	v_add_u32_e32 v4, 0x1c00, v37
	s_waitcnt vmcnt(2)
	ds_write2_b32 v4, v32, v33 offset0:28 offset1:93
	s_waitcnt vmcnt(0)
	ds_write2_b32 v4, v34, v35 offset0:158 offset1:223
	s_waitcnt lgkmcnt(0)
	v_add_u32_e32 v30, 0x400, v39
	ds_read2_b32 v[8:9], v39 offset1:16
	ds_read2_b32 v[10:11], v39 offset0:65 offset1:81
	ds_read2_b32 v[12:13], v39 offset0:130 offset1:146
	ds_read2_b32 v[14:15], v39 offset0:195 offset1:211
	ds_read2_b32 v[16:17], v30 offset0:4 offset1:20
	ds_read2_b32 v[18:19], v30 offset0:69 offset1:85
	ds_read2_b32 v[20:21], v30 offset0:134 offset1:150
	ds_read2_b32 v[22:23], v30 offset0:199 offset1:215
	v_add_u32_e32 v26, s15, v38
	v_ashrrev_i32_e32 v27, 31, v26
	v_lshl_add_u64 v[24:25], s[12:13], 1, v[2:3]
	v_lshlrev_b64 v[28:29], 10, v[26:27]
	s_waitcnt lgkmcnt(6)
	v_cvt_pk_bf16_f32 v4, v8, v10
	s_waitcnt lgkmcnt(4)
	v_cvt_pk_bf16_f32 v5, v12, v14
	s_waitcnt lgkmcnt(2)
	v_cvt_pk_bf16_f32 v6, v16, v18
	s_waitcnt lgkmcnt(0)
	v_cvt_pk_bf16_f32 v7, v20, v22
	v_lshl_add_u64 v[28:29], v[24:25], 0, v[28:29]
	v_add_u32_e32 v8, 16, v26
	global_store_dwordx4 v[28:29], v[4:7], off sc0 sc1
	s_add_i32 s5, s5, s89
	s_add_i32 s9, s9, s14
	v_cvt_pk_bf16_f32 v4, v9, v11
	v_ashrrev_i32_e32 v9, 31, v8
	v_cvt_pk_bf16_f32 v5, v13, v15
	v_cvt_pk_bf16_f32 v6, v17, v19
	v_cvt_pk_bf16_f32 v7, v21, v23
	v_lshlrev_b64 v[8:9], 10, v[8:9]
	ds_read2_b32 v[10:11], v39 offset0:32 offset1:48
	ds_read2_b32 v[12:13], v39 offset0:97 offset1:113
	ds_read2_b32 v[14:15], v39 offset0:162 offset1:178
	ds_read2_b32 v[16:17], v39 offset0:227 offset1:243
	ds_read2_b32 v[18:19], v30 offset0:36 offset1:52
	ds_read2_b32 v[20:21], v30 offset0:101 offset1:117
	ds_read2_b32 v[22:23], v30 offset0:166 offset1:182
	ds_read2_b32 v[28:29], v30 offset0:231 offset1:247
	v_lshl_add_u64 v[8:9], v[24:25], 0, v[8:9]
	global_store_dwordx4 v[8:9], v[4:7], off sc0 sc1
	v_add_u32_e32 v8, 32, v26
	v_ashrrev_i32_e32 v9, 31, v8
	v_lshlrev_b64 v[8:9], 10, v[8:9]
	s_waitcnt lgkmcnt(6)
	v_cvt_pk_bf16_f32 v4, v10, v12
	s_waitcnt lgkmcnt(4)
	v_cvt_pk_bf16_f32 v5, v14, v16
	s_waitcnt lgkmcnt(2)
	v_cvt_pk_bf16_f32 v6, v18, v20
	s_waitcnt lgkmcnt(0)
	v_cvt_pk_bf16_f32 v7, v22, v28
	v_lshl_add_u64 v[8:9], v[24:25], 0, v[8:9]
	global_store_dwordx4 v[8:9], v[4:7], off sc0 sc1
	v_add_u32_e32 v8, 48, v26
	v_ashrrev_i32_e32 v9, 31, v8
	v_lshlrev_b64 v[8:9], 10, v[8:9]
	v_cvt_pk_bf16_f32 v4, v11, v13
	v_cvt_pk_bf16_f32 v5, v15, v17
	v_cvt_pk_bf16_f32 v6, v19, v21
	v_cvt_pk_bf16_f32 v7, v23, v29
	v_lshl_add_u64 v[8:9], v[24:25], 0, v[8:9]
	global_store_dwordx4 v[8:9], v[4:7], off sc0 sc1
	s_waitcnt lgkmcnt(0)
	s_cmpk_lt_i32 s5, 0x300
	s_cbranch_scc0 .LBB0_901

.LBB0_903:
	s_ashr_i32 s8, s5, 31
	s_lshr_b32 s8, s8, 28
	s_add_i32 s8, s5, s8
	s_ashr_i32 s8, s8, 4
	s_lshl_b32 s10, s8, 5
	s_lshl_b32 s8, s8, 10
	s_sub_i32 s8, s6, s8
	v_add_u32_e32 v4, s8, v8
	v_ashrrev_i32_e32 v5, 31, v4
	s_ashr_i32 s11, s10, 31
	v_lshl_add_u64 v[4:5], v[4:5], 2, s[0:1]
	s_lshl_b64 s[12:13], s[10:11], 12
	v_lshl_add_u64 v[10:11], v[4:5], 0, s[12:13]
	s_or_b32 s12, s10, 1
	s_ashr_i32 s13, s12, 31
	s_lshl_b64 s[12:13], s[12:13], 12
	global_load_dword v9, v[10:11], off
	v_lshl_add_u64 v[10:11], v[4:5], 0, s[12:13]
	s_or_b32 s12, s10, 2
	s_ashr_i32 s13, s12, 31
	s_lshl_b64 s[12:13], s[12:13], 12
	v_lshl_add_u64 v[12:13], v[4:5], 0, s[12:13]
	s_or_b32 s12, s10, 3
	s_ashr_i32 s13, s12, 31
	s_lshl_b64 s[12:13], s[12:13], 12
	global_load_dword v10, v[10:11], off
	s_add_i32 s5, s5, s89
	global_load_dword v11, v[12:13], off
	v_lshl_add_u64 v[12:13], v[4:5], 0, s[12:13]
	s_or_b32 s12, s10, 4
	s_ashr_i32 s13, s12, 31
	s_lshl_b64 s[12:13], s[12:13], 12
	v_lshl_add_u64 v[14:15], v[4:5], 0, s[12:13]
	s_or_b32 s12, s10, 5
	s_ashr_i32 s13, s12, 31
	s_lshl_b64 s[12:13], s[12:13], 12
	global_load_dword v12, v[12:13], off
	s_add_i32 s6, s6, s7
	global_load_dword v13, v[14:15], off
	v_lshl_add_u64 v[14:15], v[4:5], 0, s[12:13]
	s_or_b32 s12, s10, 6
	s_ashr_i32 s13, s12, 31
	s_lshl_b64 s[12:13], s[12:13], 12
	v_lshl_add_u64 v[16:17], v[4:5], 0, s[12:13]
	s_or_b32 s12, s10, 7
	s_ashr_i32 s13, s12, 31
	s_lshl_b64 s[12:13], s[12:13], 12
	global_load_dword v14, v[14:15], off
	s_nop 0
	global_load_dword v15, v[16:17], off
	v_lshl_add_u64 v[16:17], v[4:5], 0, s[12:13]
	s_or_b32 s12, s10, 8
	s_ashr_i32 s13, s12, 31
	s_lshl_b64 s[12:13], s[12:13], 12
	v_lshl_add_u64 v[18:19], v[4:5], 0, s[12:13]
	s_or_b32 s12, s10, 9
	s_ashr_i32 s13, s12, 31
	s_lshl_b64 s[12:13], s[12:13], 12
	global_load_dword v16, v[16:17], off
	s_nop 0
	global_load_dword v17, v[18:19], off
	v_lshl_add_u64 v[18:19], v[4:5], 0, s[12:13]
	s_or_b32 s12, s10, 10
	s_ashr_i32 s13, s12, 31
	s_lshl_b64 s[12:13], s[12:13], 12
	v_lshl_add_u64 v[20:21], v[4:5], 0, s[12:13]
	s_or_b32 s12, s10, 11
	s_ashr_i32 s13, s12, 31
	s_lshl_b64 s[12:13], s[12:13], 12
	global_load_dword v18, v[18:19], off
	s_nop 0
	global_load_dword v19, v[20:21], off
	v_lshl_add_u64 v[20:21], v[4:5], 0, s[12:13]
	s_or_b32 s12, s10, 12
	s_ashr_i32 s13, s12, 31
	s_lshl_b64 s[12:13], s[12:13], 12
	v_lshl_add_u64 v[22:23], v[4:5], 0, s[12:13]
	s_or_b32 s12, s10, 13
	s_ashr_i32 s13, s12, 31
	s_lshl_b64 s[12:13], s[12:13], 12
	global_load_dword v20, v[20:21], off
	s_nop 0
	global_load_dword v21, v[22:23], off
	v_lshl_add_u64 v[22:23], v[4:5], 0, s[12:13]
	s_or_b32 s12, s10, 14
	s_ashr_i32 s13, s12, 31
	s_lshl_b64 s[12:13], s[12:13], 12
	v_lshl_add_u64 v[24:25], v[4:5], 0, s[12:13]
	s_or_b32 s12, s10, 15
	s_ashr_i32 s13, s12, 31
	s_lshl_b64 s[12:13], s[12:13], 12
	global_load_dword v22, v[22:23], off
	s_nop 0
	global_load_dword v23, v[24:25], off
	v_lshl_add_u64 v[24:25], v[4:5], 0, s[12:13]
	s_or_b32 s12, s10, 16
	s_ashr_i32 s13, s12, 31
	s_lshl_b64 s[12:13], s[12:13], 12
	v_lshl_add_u64 v[26:27], v[4:5], 0, s[12:13]
	s_or_b32 s12, s10, 17
	s_ashr_i32 s13, s12, 31
	s_lshl_b64 s[12:13], s[12:13], 12
	global_load_dword v24, v[24:25], off
	s_nop 0
	global_load_dword v25, v[26:27], off
	v_lshl_add_u64 v[26:27], v[4:5], 0, s[12:13]
	s_or_b32 s12, s10, 18
	s_ashr_i32 s13, s12, 31
	s_lshl_b64 s[12:13], s[12:13], 12
	v_lshl_add_u64 v[28:29], v[4:5], 0, s[12:13]
	s_or_b32 s12, s10, 19
	s_ashr_i32 s13, s12, 31
	s_lshl_b64 s[12:13], s[12:13], 12
	global_load_dword v26, v[26:27], off
	s_nop 0
	global_load_dword v27, v[28:29], off
	v_lshl_add_u64 v[28:29], v[4:5], 0, s[12:13]
	s_or_b32 s12, s10, 20
	s_ashr_i32 s13, s12, 31
	s_lshl_b64 s[12:13], s[12:13], 12
	v_lshl_add_u64 v[30:31], v[4:5], 0, s[12:13]
	s_or_b32 s12, s10, 21
	s_ashr_i32 s13, s12, 31
	s_lshl_b64 s[12:13], s[12:13], 12
	global_load_dword v28, v[28:29], off
	s_nop 0
	global_load_dword v29, v[30:31], off
	v_lshl_add_u64 v[30:31], v[4:5], 0, s[12:13]
	s_or_b32 s12, s10, 22
	s_ashr_i32 s13, s12, 31
	s_lshl_b64 s[12:13], s[12:13], 12
	v_lshl_add_u64 v[32:33], v[4:5], 0, s[12:13]
	s_or_b32 s12, s10, 23
	s_ashr_i32 s13, s12, 31
	s_lshl_b64 s[12:13], s[12:13], 12
	global_load_dword v30, v[30:31], off
	s_nop 0
	global_load_dword v31, v[32:33], off
	v_lshl_add_u64 v[32:33], v[4:5], 0, s[12:13]
	s_or_b32 s12, s10, 24
	s_ashr_i32 s13, s12, 31
	s_lshl_b64 s[12:13], s[12:13], 12
	v_lshl_add_u64 v[34:35], v[4:5], 0, s[12:13]
	s_or_b32 s12, s10, 25
	s_ashr_i32 s13, s12, 31
	s_lshl_b64 s[12:13], s[12:13], 12
	global_load_dword v32, v[32:33], off
	s_nop 0
	global_load_dword v33, v[34:35], off
	v_lshl_add_u64 v[34:35], v[4:5], 0, s[12:13]
	s_or_b32 s12, s10, 26
	s_ashr_i32 s13, s12, 31
	s_lshl_b64 s[12:13], s[12:13], 12
	v_lshl_add_u64 v[36:37], v[4:5], 0, s[12:13]
	s_or_b32 s12, s10, 27
	s_ashr_i32 s13, s12, 31
	s_lshl_b64 s[12:13], s[12:13], 12
	global_load_dword v34, v[34:35], off
	s_nop 0
	global_load_dword v35, v[36:37], off
	v_lshl_add_u64 v[36:37], v[4:5], 0, s[12:13]
	s_or_b32 s12, s10, 28
	s_ashr_i32 s13, s12, 31
	s_lshl_b64 s[12:13], s[12:13], 12
	v_lshl_add_u64 v[38:39], v[4:5], 0, s[12:13]
	s_or_b32 s12, s10, 29
	s_ashr_i32 s13, s12, 31
	s_lshl_b64 s[12:13], s[12:13], 12
	global_load_dword v36, v[36:37], off
	s_nop 0
	global_load_dword v37, v[38:39], off
	v_lshl_add_u64 v[38:39], v[4:5], 0, s[12:13]
	s_or_b32 s12, s10, 30
	s_ashr_i32 s13, s12, 31
	s_lshl_b64 s[12:13], s[12:13], 12
	v_lshl_add_u64 v[40:41], v[4:5], 0, s[12:13]
	s_or_b32 s12, s10, 31
	s_ashr_i32 s13, s12, 31
	s_lshl_b64 s[12:13], s[12:13], 12
	global_load_dword v38, v[38:39], off
	v_lshl_add_u64 v[4:5], v[4:5], 0, s[12:13]
	global_load_dword v4, v[4:5], off
	v_add_u32_e32 v5, 0x400, v1
	global_load_dword v39, v[40:41], off
	s_waitcnt vmcnt(30)
	ds_write2_b32 v1, v9, v10 offset1:65
	s_waitcnt vmcnt(28)
	ds_write2_b32 v1, v11, v12 offset0:130 offset1:195
	s_waitcnt vmcnt(26)
	ds_write2_b32 v5, v13, v14 offset0:4 offset1:69
	s_waitcnt vmcnt(24)
	ds_write2_b32 v5, v15, v16 offset0:134 offset1:199
	v_add_u32_e32 v5, 0x800, v1
	s_waitcnt vmcnt(22)
	ds_write2_b32 v5, v17, v18 offset0:8 offset1:73
	s_waitcnt vmcnt(20)
	ds_write2_b32 v5, v19, v20 offset0:138 offset1:203
	v_add_u32_e32 v5, 0xc00, v1
	s_waitcnt vmcnt(18)
	ds_write2_b32 v5, v21, v22 offset0:12 offset1:77
	s_waitcnt vmcnt(16)
	ds_write2_b32 v5, v23, v24 offset0:142 offset1:207
	v_add_u32_e32 v5, 0x1000, v1
	s_waitcnt vmcnt(14)
	ds_write2_b32 v5, v25, v26 offset0:16 offset1:81
	s_waitcnt vmcnt(12)
	ds_write2_b32 v5, v27, v28 offset0:146 offset1:211
	v_add_u32_e32 v5, 0x1400, v1
	s_waitcnt vmcnt(10)
	ds_write2_b32 v5, v29, v30 offset0:20 offset1:85
	s_waitcnt vmcnt(8)
	ds_write2_b32 v5, v31, v32 offset0:150 offset1:215
	v_add_u32_e32 v5, 0x1800, v1
	s_waitcnt vmcnt(6)
	ds_write2_b32 v5, v33, v34 offset0:24 offset1:89
	s_waitcnt vmcnt(4)
	ds_write2_b32 v5, v35, v36 offset0:154 offset1:219
	v_add_u32_e32 v5, 0x1c00, v1
	s_waitcnt vmcnt(2)
	ds_write2_b32 v5, v37, v38 offset0:28 offset1:93
	s_waitcnt vmcnt(0)
	ds_write2_b32 v5, v39, v4 offset0:158 offset1:223
	s_waitcnt lgkmcnt(0)
	v_add_u32_e32 v9, 0x400, v7
	ds_read2_b32 v[14:15], v7 offset1:16
	ds_read2_b32 v[16:17], v7 offset0:65 offset1:81
	ds_read2_b32 v[18:19], v7 offset0:130 offset1:146
	ds_read2_b32 v[20:21], v7 offset0:195 offset1:211
	ds_read2_b32 v[22:23], v9 offset0:4 offset1:20
	ds_read2_b32 v[24:25], v9 offset0:69 offset1:85
	ds_read2_b32 v[26:27], v9 offset0:134 offset1:150
	ds_read2_b32 v[28:29], v9 offset0:199 offset1:215
	v_add_u32_e32 v30, s8, v6
	v_ashrrev_i32_e32 v31, 31, v30
	v_lshl_add_u64 v[4:5], s[10:11], 1, v[2:3]
	v_lshlrev_b64 v[32:33], 12, v[30:31]
	s_waitcnt lgkmcnt(6)
	v_cvt_pk_bf16_f32 v10, v14, v16
	s_waitcnt lgkmcnt(4)
	v_cvt_pk_bf16_f32 v11, v18, v20
	s_waitcnt lgkmcnt(2)
	v_cvt_pk_bf16_f32 v12, v22, v24
	s_waitcnt lgkmcnt(0)
	v_cvt_pk_bf16_f32 v13, v26, v28
	v_lshl_add_u64 v[32:33], v[4:5], 0, v[32:33]
	v_add_u32_e32 v14, 16, v30
	global_store_dwordx4 v[32:33], v[10:13], off sc0 sc1
	v_add_u32_e32 v32, 32, v30
	v_ashrrev_i32_e32 v33, 31, v32
	v_cvt_pk_bf16_f32 v10, v15, v17
	v_ashrrev_i32_e32 v15, 31, v14
	v_lshlrev_b64 v[14:15], 12, v[14:15]
	v_cvt_pk_bf16_f32 v11, v19, v21
	v_cvt_pk_bf16_f32 v12, v23, v25
	v_cvt_pk_bf16_f32 v13, v27, v29
	v_lshl_add_u64 v[14:15], v[4:5], 0, v[14:15]
	global_store_dwordx4 v[14:15], v[10:13], off sc0 sc1
	ds_read2_b32 v[14:15], v7 offset0:32 offset1:48
	ds_read2_b32 v[16:17], v7 offset0:97 offset1:113
	ds_read2_b32 v[18:19], v7 offset0:162 offset1:178
	ds_read2_b32 v[20:21], v7 offset0:227 offset1:243
	ds_read2_b32 v[22:23], v9 offset0:36 offset1:52
	ds_read2_b32 v[24:25], v9 offset0:101 offset1:117
	ds_read2_b32 v[26:27], v9 offset0:166 offset1:182
	ds_read2_b32 v[28:29], v9 offset0:231 offset1:247
	v_lshlrev_b64 v[32:33], 12, v[32:33]
	s_waitcnt lgkmcnt(6)
	v_cvt_pk_bf16_f32 v10, v14, v16
	s_waitcnt lgkmcnt(4)
	v_cvt_pk_bf16_f32 v11, v18, v20
	s_waitcnt lgkmcnt(2)
	v_cvt_pk_bf16_f32 v12, v22, v24
	s_waitcnt lgkmcnt(0)
	v_cvt_pk_bf16_f32 v13, v26, v28
	v_lshl_add_u64 v[32:33], v[4:5], 0, v[32:33]
	v_add_u32_e32 v14, 48, v30
	global_store_dwordx4 v[32:33], v[10:13], off sc0 sc1
	s_cmpk_lt_i32 s5, 0x400
	s_nop 0
	v_cvt_pk_bf16_f32 v10, v15, v17
	v_ashrrev_i32_e32 v15, 31, v14
	v_lshlrev_b64 v[14:15], 12, v[14:15]
	v_cvt_pk_bf16_f32 v11, v19, v21
	v_cvt_pk_bf16_f32 v12, v23, v25
	v_cvt_pk_bf16_f32 v13, v27, v29
	v_lshl_add_u64 v[4:5], v[4:5], 0, v[14:15]
	global_store_dwordx4 v[4:5], v[10:13], off sc0 sc1
	s_waitcnt lgkmcnt(0)
	s_cbranch_scc1 .LBB0_903

.LBB0_908:
	s_waitcnt vmcnt(30)
	ds_write2_b32 v36, v4, v5 offset1:65
	s_waitcnt vmcnt(28)
	ds_write2_b32 v36, v6, v7 offset0:130 offset1:195
	v_add_u32_e32 v4, 0x400, v36
	s_waitcnt vmcnt(26)
	ds_write2_b32 v4, v8, v9 offset0:4 offset1:69
	s_waitcnt vmcnt(24)
	ds_write2_b32 v4, v10, v11 offset0:134 offset1:199
	v_add_u32_e32 v4, 0x800, v36
	s_waitcnt vmcnt(22)
	ds_write2_b32 v4, v12, v13 offset0:8 offset1:73
	s_waitcnt vmcnt(20)
	ds_write2_b32 v4, v14, v15 offset0:138 offset1:203
	v_add_u32_e32 v4, 0xc00, v36
	s_waitcnt vmcnt(18)
	ds_write2_b32 v4, v16, v17 offset0:12 offset1:77
	s_waitcnt vmcnt(16)
	ds_write2_b32 v4, v18, v19 offset0:142 offset1:207
	v_add_u32_e32 v4, 0x1000, v36
	s_waitcnt vmcnt(14)
	ds_write2_b32 v4, v20, v21 offset0:16 offset1:81
	s_waitcnt vmcnt(12)
	ds_write2_b32 v4, v22, v23 offset0:146 offset1:211
	v_add_u32_e32 v4, 0x1400, v36
	s_waitcnt vmcnt(10)
	ds_write2_b32 v4, v24, v25 offset0:20 offset1:85
	s_waitcnt vmcnt(8)
	ds_write2_b32 v4, v26, v27 offset0:150 offset1:215
	v_add_u32_e32 v4, 0x1800, v36
	s_waitcnt vmcnt(6)
	ds_write2_b32 v4, v28, v29 offset0:24 offset1:89
	s_waitcnt vmcnt(4)
	ds_write2_b32 v4, v30, v31 offset0:154 offset1:219
	v_add_u32_e32 v4, 0x1c00, v36
	s_waitcnt vmcnt(2)
	ds_write2_b32 v4, v32, v33 offset0:28 offset1:93
	s_waitcnt vmcnt(0)
	ds_write2_b32 v4, v34, v35 offset0:158 offset1:223
	s_waitcnt lgkmcnt(0)
	v_add_u32_e32 v30, 0x400, v38
	ds_read2_b32 v[8:9], v38 offset1:16
	ds_read2_b32 v[10:11], v38 offset0:65 offset1:81
	ds_read2_b32 v[12:13], v38 offset0:130 offset1:146
	ds_read2_b32 v[14:15], v38 offset0:195 offset1:211
	ds_read2_b32 v[16:17], v30 offset0:4 offset1:20
	ds_read2_b32 v[18:19], v30 offset0:69 offset1:85
	ds_read2_b32 v[20:21], v30 offset0:134 offset1:150
	ds_read2_b32 v[22:23], v30 offset0:199 offset1:215
	v_add_u32_e32 v26, s14, v37
	v_ashrrev_i32_e32 v27, 31, v26
	v_lshl_add_u64 v[24:25], s[12:13], 1, v[2:3]
	v_lshlrev_b64 v[28:29], 11, v[26:27]
	s_waitcnt lgkmcnt(6)
	v_cvt_pk_bf16_f32 v4, v8, v10
	s_waitcnt lgkmcnt(4)
	v_cvt_pk_bf16_f32 v5, v12, v14
	s_waitcnt lgkmcnt(2)
	v_cvt_pk_bf16_f32 v6, v16, v18
	s_waitcnt lgkmcnt(0)
	v_cvt_pk_bf16_f32 v7, v20, v22
	v_lshl_add_u64 v[28:29], v[24:25], 0, v[28:29]
	v_add_u32_e32 v8, 16, v26
	global_store_dwordx4 v[28:29], v[4:7], off sc0 sc1
	s_add_i32 s9, s9, s89
	s_add_i32 s7, s7, s8
	v_cvt_pk_bf16_f32 v4, v9, v11
	v_ashrrev_i32_e32 v9, 31, v8
	v_cvt_pk_bf16_f32 v5, v13, v15
	v_cvt_pk_bf16_f32 v6, v17, v19
	v_cvt_pk_bf16_f32 v7, v21, v23
	v_lshlrev_b64 v[8:9], 11, v[8:9]
	ds_read2_b32 v[10:11], v38 offset0:32 offset1:48
	ds_read2_b32 v[12:13], v38 offset0:97 offset1:113
	ds_read2_b32 v[14:15], v38 offset0:162 offset1:178
	ds_read2_b32 v[16:17], v38 offset0:227 offset1:243
	ds_read2_b32 v[18:19], v30 offset0:36 offset1:52
	ds_read2_b32 v[20:21], v30 offset0:101 offset1:117
	ds_read2_b32 v[22:23], v30 offset0:166 offset1:182
	ds_read2_b32 v[28:29], v30 offset0:231 offset1:247
	v_lshl_add_u64 v[8:9], v[24:25], 0, v[8:9]
	global_store_dwordx4 v[8:9], v[4:7], off sc0 sc1
	v_add_u32_e32 v8, 32, v26
	v_ashrrev_i32_e32 v9, 31, v8
	v_lshlrev_b64 v[8:9], 11, v[8:9]
	s_waitcnt lgkmcnt(6)
	v_cvt_pk_bf16_f32 v4, v10, v12
	s_waitcnt lgkmcnt(4)
	v_cvt_pk_bf16_f32 v5, v14, v16
	s_waitcnt lgkmcnt(2)
	v_cvt_pk_bf16_f32 v6, v18, v20
	s_waitcnt lgkmcnt(0)
	v_cvt_pk_bf16_f32 v7, v22, v28
	v_lshl_add_u64 v[8:9], v[24:25], 0, v[8:9]
	global_store_dwordx4 v[8:9], v[4:7], off sc0 sc1
	v_add_u32_e32 v8, 48, v26
	v_ashrrev_i32_e32 v9, 31, v8
	v_lshlrev_b64 v[8:9], 11, v[8:9]
	v_cvt_pk_bf16_f32 v4, v11, v13
	v_cvt_pk_bf16_f32 v5, v15, v17
	v_cvt_pk_bf16_f32 v6, v19, v21
	v_cvt_pk_bf16_f32 v7, v23, v29
	v_lshl_add_u64 v[8:9], v[24:25], 0, v[8:9]
	global_store_dwordx4 v[8:9], v[4:7], off sc0 sc1
	s_waitcnt lgkmcnt(0)
	s_cmpk_lt_i32 s9, 0x600
	v_add_u32_e32 v39, s6, v39
	s_cbranch_scc0 .LBB0_911

.LBB0_913:
	s_ashr_i32 s7, s6, 31
	s_lshr_b32 s7, s7, 28
	s_add_i32 s7, s6, s7
	s_ashr_i32 s7, s7, 4
	s_lshl_b32 s10, s7, 5
	s_lshl_b32 s7, s7, 10
	s_sub_i32 s7, s4, s7
	v_add_u32_e32 v4, s7, v8
	v_ashrrev_i32_e32 v5, 31, v4
	s_ashr_i32 s11, s10, 31
	v_lshl_add_u64 v[4:5], v[4:5], 2, s[0:1]
	s_lshl_b64 s[8:9], s[10:11], 12
	v_lshl_add_u64 v[10:11], v[4:5], 0, s[8:9]
	s_or_b32 s8, s10, 1
	s_ashr_i32 s9, s8, 31
	s_lshl_b64 s[8:9], s[8:9], 12
	global_load_dword v9, v[10:11], off
	v_lshl_add_u64 v[10:11], v[4:5], 0, s[8:9]
	s_or_b32 s8, s10, 2
	s_ashr_i32 s9, s8, 31
	s_lshl_b64 s[8:9], s[8:9], 12
	v_lshl_add_u64 v[12:13], v[4:5], 0, s[8:9]
	s_or_b32 s8, s10, 3
	s_ashr_i32 s9, s8, 31
	s_lshl_b64 s[8:9], s[8:9], 12
	global_load_dword v10, v[10:11], off
	s_or_b32 s12, s10, 31
	global_load_dword v11, v[12:13], off
	v_lshl_add_u64 v[12:13], v[4:5], 0, s[8:9]
	s_or_b32 s8, s10, 4
	s_ashr_i32 s9, s8, 31
	s_lshl_b64 s[8:9], s[8:9], 12
	v_lshl_add_u64 v[14:15], v[4:5], 0, s[8:9]
	s_or_b32 s8, s10, 5
	s_ashr_i32 s9, s8, 31
	s_lshl_b64 s[8:9], s[8:9], 12
	global_load_dword v12, v[12:13], off
	s_ashr_i32 s13, s12, 31
	global_load_dword v13, v[14:15], off
	v_lshl_add_u64 v[14:15], v[4:5], 0, s[8:9]
	s_or_b32 s8, s10, 6
	s_ashr_i32 s9, s8, 31
	s_lshl_b64 s[8:9], s[8:9], 12
	v_lshl_add_u64 v[16:17], v[4:5], 0, s[8:9]
	s_or_b32 s8, s10, 7
	s_ashr_i32 s9, s8, 31
	s_lshl_b64 s[8:9], s[8:9], 12
	global_load_dword v14, v[14:15], off
	s_lshl_b64 s[12:13], s[12:13], 12
	global_load_dword v15, v[16:17], off
	v_lshl_add_u64 v[16:17], v[4:5], 0, s[8:9]
	s_or_b32 s8, s10, 8
	s_ashr_i32 s9, s8, 31
	s_lshl_b64 s[8:9], s[8:9], 12
	v_lshl_add_u64 v[18:19], v[4:5], 0, s[8:9]
	s_or_b32 s8, s10, 9
	s_ashr_i32 s9, s8, 31
	s_lshl_b64 s[8:9], s[8:9], 12
	global_load_dword v16, v[16:17], off
	s_add_i32 s6, s6, s89
	global_load_dword v17, v[18:19], off
	v_lshl_add_u64 v[18:19], v[4:5], 0, s[8:9]
	s_or_b32 s8, s10, 10
	s_ashr_i32 s9, s8, 31
	s_lshl_b64 s[8:9], s[8:9], 12
	v_lshl_add_u64 v[20:21], v[4:5], 0, s[8:9]
	s_or_b32 s8, s10, 11
	s_ashr_i32 s9, s8, 31
	s_lshl_b64 s[8:9], s[8:9], 12
	global_load_dword v18, v[18:19], off
	s_add_i32 s4, s4, s5
	global_load_dword v19, v[20:21], off
	v_lshl_add_u64 v[20:21], v[4:5], 0, s[8:9]
	s_or_b32 s8, s10, 12
	s_ashr_i32 s9, s8, 31
	s_lshl_b64 s[8:9], s[8:9], 12
	v_lshl_add_u64 v[22:23], v[4:5], 0, s[8:9]
	s_or_b32 s8, s10, 13
	s_ashr_i32 s9, s8, 31
	s_lshl_b64 s[8:9], s[8:9], 12
	global_load_dword v20, v[20:21], off
	s_nop 0
	global_load_dword v21, v[22:23], off
	v_lshl_add_u64 v[22:23], v[4:5], 0, s[8:9]
	s_or_b32 s8, s10, 14
	s_ashr_i32 s9, s8, 31
	s_lshl_b64 s[8:9], s[8:9], 12
	v_lshl_add_u64 v[24:25], v[4:5], 0, s[8:9]
	s_or_b32 s8, s10, 15
	s_ashr_i32 s9, s8, 31
	s_lshl_b64 s[8:9], s[8:9], 12
	global_load_dword v22, v[22:23], off
	s_nop 0
	global_load_dword v23, v[24:25], off
	v_lshl_add_u64 v[24:25], v[4:5], 0, s[8:9]
	s_or_b32 s8, s10, 16
	s_ashr_i32 s9, s8, 31
	s_lshl_b64 s[8:9], s[8:9], 12
	v_lshl_add_u64 v[26:27], v[4:5], 0, s[8:9]
	s_or_b32 s8, s10, 17
	s_ashr_i32 s9, s8, 31
	s_lshl_b64 s[8:9], s[8:9], 12
	global_load_dword v24, v[24:25], off
	s_nop 0
	global_load_dword v25, v[26:27], off
	v_lshl_add_u64 v[26:27], v[4:5], 0, s[8:9]
	s_or_b32 s8, s10, 18
	s_ashr_i32 s9, s8, 31
	s_lshl_b64 s[8:9], s[8:9], 12
	v_lshl_add_u64 v[28:29], v[4:5], 0, s[8:9]
	s_or_b32 s8, s10, 19
	s_ashr_i32 s9, s8, 31
	s_lshl_b64 s[8:9], s[8:9], 12
	global_load_dword v26, v[26:27], off
	s_nop 0
	global_load_dword v27, v[28:29], off
	v_lshl_add_u64 v[28:29], v[4:5], 0, s[8:9]
	s_or_b32 s8, s10, 20
	s_ashr_i32 s9, s8, 31
	s_lshl_b64 s[8:9], s[8:9], 12
	v_lshl_add_u64 v[30:31], v[4:5], 0, s[8:9]
	s_or_b32 s8, s10, 21
	s_ashr_i32 s9, s8, 31
	s_lshl_b64 s[8:9], s[8:9], 12
	global_load_dword v28, v[28:29], off
	s_nop 0
	global_load_dword v29, v[30:31], off
	v_lshl_add_u64 v[30:31], v[4:5], 0, s[8:9]
	s_or_b32 s8, s10, 22
	s_ashr_i32 s9, s8, 31
	s_lshl_b64 s[8:9], s[8:9], 12
	v_lshl_add_u64 v[32:33], v[4:5], 0, s[8:9]
	s_or_b32 s8, s10, 23
	s_ashr_i32 s9, s8, 31
	s_lshl_b64 s[8:9], s[8:9], 12
	global_load_dword v30, v[30:31], off
	s_nop 0
	global_load_dword v31, v[32:33], off
	v_lshl_add_u64 v[32:33], v[4:5], 0, s[8:9]
	s_or_b32 s8, s10, 24
	s_ashr_i32 s9, s8, 31
	s_lshl_b64 s[8:9], s[8:9], 12
	v_lshl_add_u64 v[34:35], v[4:5], 0, s[8:9]
	s_or_b32 s8, s10, 25
	s_ashr_i32 s9, s8, 31
	s_lshl_b64 s[8:9], s[8:9], 12
	global_load_dword v32, v[32:33], off
	s_nop 0
	global_load_dword v33, v[34:35], off
	v_lshl_add_u64 v[34:35], v[4:5], 0, s[8:9]
	s_or_b32 s8, s10, 26
	s_ashr_i32 s9, s8, 31
	s_lshl_b64 s[8:9], s[8:9], 12
	v_lshl_add_u64 v[36:37], v[4:5], 0, s[8:9]
	s_or_b32 s8, s10, 27
	s_ashr_i32 s9, s8, 31
	s_lshl_b64 s[8:9], s[8:9], 12
	global_load_dword v34, v[34:35], off
	s_nop 0
	global_load_dword v35, v[36:37], off
	v_lshl_add_u64 v[36:37], v[4:5], 0, s[8:9]
	s_or_b32 s8, s10, 28
	s_ashr_i32 s9, s8, 31
	s_lshl_b64 s[8:9], s[8:9], 12
	v_lshl_add_u64 v[38:39], v[4:5], 0, s[8:9]
	s_or_b32 s8, s10, 29
	s_ashr_i32 s9, s8, 31
	s_lshl_b64 s[8:9], s[8:9], 12
	global_load_dword v36, v[36:37], off
	s_nop 0
	global_load_dword v37, v[38:39], off
	v_lshl_add_u64 v[38:39], v[4:5], 0, s[8:9]
	s_or_b32 s8, s10, 30
	s_ashr_i32 s9, s8, 31
	s_lshl_b64 s[8:9], s[8:9], 12
	global_load_dword v38, v[38:39], off
	v_lshl_add_u64 v[40:41], v[4:5], 0, s[8:9]
	v_lshl_add_u64 v[4:5], v[4:5], 0, s[12:13]
	global_load_dword v4, v[4:5], off
	v_add_u32_e32 v5, 0x400, v1
	global_load_dword v39, v[40:41], off
	s_waitcnt vmcnt(30)
	ds_write2_b32 v1, v9, v10 offset1:65
	s_waitcnt vmcnt(28)
	ds_write2_b32 v1, v11, v12 offset0:130 offset1:195
	s_waitcnt vmcnt(26)
	ds_write2_b32 v5, v13, v14 offset0:4 offset1:69
	s_waitcnt vmcnt(24)
	ds_write2_b32 v5, v15, v16 offset0:134 offset1:199
	v_add_u32_e32 v5, 0x800, v1
	s_waitcnt vmcnt(22)
	ds_write2_b32 v5, v17, v18 offset0:8 offset1:73
	s_waitcnt vmcnt(20)
	ds_write2_b32 v5, v19, v20 offset0:138 offset1:203
	v_add_u32_e32 v5, 0xc00, v1
	s_waitcnt vmcnt(18)
	ds_write2_b32 v5, v21, v22 offset0:12 offset1:77
	s_waitcnt vmcnt(16)
	ds_write2_b32 v5, v23, v24 offset0:142 offset1:207
	v_add_u32_e32 v5, 0x1000, v1
	s_waitcnt vmcnt(14)
	ds_write2_b32 v5, v25, v26 offset0:16 offset1:81
	s_waitcnt vmcnt(12)
	ds_write2_b32 v5, v27, v28 offset0:146 offset1:211
	v_add_u32_e32 v5, 0x1400, v1
	s_waitcnt vmcnt(10)
	ds_write2_b32 v5, v29, v30 offset0:20 offset1:85
	s_waitcnt vmcnt(8)
	ds_write2_b32 v5, v31, v32 offset0:150 offset1:215
	v_add_u32_e32 v5, 0x1800, v1
	s_waitcnt vmcnt(6)
	ds_write2_b32 v5, v33, v34 offset0:24 offset1:89
	s_waitcnt vmcnt(4)
	ds_write2_b32 v5, v35, v36 offset0:154 offset1:219
	v_add_u32_e32 v5, 0x1c00, v1
	s_waitcnt vmcnt(2)
	ds_write2_b32 v5, v37, v38 offset0:28 offset1:93
	s_waitcnt vmcnt(0)
	ds_write2_b32 v5, v39, v4 offset0:158 offset1:223
	s_waitcnt lgkmcnt(0)
	v_add_u32_e32 v9, 0x400, v7
	ds_read2_b32 v[14:15], v7 offset1:16
	ds_read2_b32 v[16:17], v7 offset0:65 offset1:81
	ds_read2_b32 v[18:19], v7 offset0:130 offset1:146
	ds_read2_b32 v[20:21], v7 offset0:195 offset1:211
	ds_read2_b32 v[22:23], v9 offset0:4 offset1:20
	ds_read2_b32 v[24:25], v9 offset0:69 offset1:85
	ds_read2_b32 v[26:27], v9 offset0:134 offset1:150
	ds_read2_b32 v[28:29], v9 offset0:199 offset1:215
	v_add_u32_e32 v30, s7, v6
	v_ashrrev_i32_e32 v31, 31, v30
	v_lshl_add_u64 v[4:5], s[10:11], 1, v[2:3]
	v_lshlrev_b64 v[32:33], 11, v[30:31]
	s_waitcnt lgkmcnt(6)
	v_cvt_pk_bf16_f32 v10, v14, v16
	s_waitcnt lgkmcnt(4)
	v_cvt_pk_bf16_f32 v11, v18, v20
	s_waitcnt lgkmcnt(2)
	v_cvt_pk_bf16_f32 v12, v22, v24
	s_waitcnt lgkmcnt(0)
	v_cvt_pk_bf16_f32 v13, v26, v28
	v_lshl_add_u64 v[32:33], v[4:5], 0, v[32:33]
	v_add_u32_e32 v14, 16, v30
	global_store_dwordx4 v[32:33], v[10:13], off sc0 sc1
	v_add_u32_e32 v32, 32, v30
	v_ashrrev_i32_e32 v33, 31, v32
	v_cvt_pk_bf16_f32 v10, v15, v17
	v_ashrrev_i32_e32 v15, 31, v14
	v_lshlrev_b64 v[14:15], 11, v[14:15]
	v_cvt_pk_bf16_f32 v11, v19, v21
	v_cvt_pk_bf16_f32 v12, v23, v25
	v_cvt_pk_bf16_f32 v13, v27, v29
	v_lshl_add_u64 v[14:15], v[4:5], 0, v[14:15]
	global_store_dwordx4 v[14:15], v[10:13], off sc0 sc1
	ds_read2_b32 v[14:15], v7 offset0:32 offset1:48
	ds_read2_b32 v[16:17], v7 offset0:97 offset1:113
	ds_read2_b32 v[18:19], v7 offset0:162 offset1:178
	ds_read2_b32 v[20:21], v7 offset0:227 offset1:243
	ds_read2_b32 v[22:23], v9 offset0:36 offset1:52
	ds_read2_b32 v[24:25], v9 offset0:101 offset1:117
	ds_read2_b32 v[26:27], v9 offset0:166 offset1:182
	ds_read2_b32 v[28:29], v9 offset0:231 offset1:247
	v_lshlrev_b64 v[32:33], 11, v[32:33]
	s_waitcnt lgkmcnt(6)
	v_cvt_pk_bf16_f32 v10, v14, v16
	s_waitcnt lgkmcnt(4)
	v_cvt_pk_bf16_f32 v11, v18, v20
	s_waitcnt lgkmcnt(2)
	v_cvt_pk_bf16_f32 v12, v22, v24
	s_waitcnt lgkmcnt(0)
	v_cvt_pk_bf16_f32 v13, v26, v28
	v_lshl_add_u64 v[32:33], v[4:5], 0, v[32:33]
	v_add_u32_e32 v14, 48, v30
	global_store_dwordx4 v[32:33], v[10:13], off sc0 sc1
	s_cmpk_gt_i32 s6, 0x1ff
	s_nop 0
	v_cvt_pk_bf16_f32 v10, v15, v17
	v_ashrrev_i32_e32 v15, 31, v14
	v_lshlrev_b64 v[14:15], 11, v[14:15]
	v_cvt_pk_bf16_f32 v11, v19, v21
	v_cvt_pk_bf16_f32 v12, v23, v25
	v_cvt_pk_bf16_f32 v13, v27, v29
	v_lshl_add_u64 v[4:5], v[4:5], 0, v[14:15]
	global_store_dwordx4 v[4:5], v[10:13], off sc0 sc1
	s_waitcnt lgkmcnt(0)
	s_cbranch_scc0 .LBB0_913

.LBB0_1065:
	s_ashr_i32 s1, s0, 31
	s_lshl_b64 s[0:1], s[0:1], 8
	v_mov_b32_e32 v153, v148
	v_mov_b32_e32 v146, v1
	s_add_u32 s0, s0, s19
	s_addc_u32 s1, s1, s21
	v_ashrrev_i32_e32 v147, 31, v146
	v_lshl_add_u64 v[142:143], s[0:1], 0, v[146:147]
	v_lshlrev_b32_e32 v146, 2, v146
	v_lshl_add_u32 v146, v153, 6, v146
	s_lshl_b32 s10, s31, 8
	v_xor_b32_e32 v152, 64, v146
	v_xor_b32_e32 v151, 0x80, v146
	v_lshlrev_b64 v[146:147], 11, v[142:143]
	s_ashr_i32 s11, s10, 31
	v_lshl_add_u64 v[146:147], s[22:23], 0, v[146:147]
	v_lshlrev_b32_e32 v144, 3, v153
	v_lshl_add_u64 v[146:147], s[10:11], 1, v[146:147]
	v_ashrrev_i32_e32 v145, 31, v144
	v_lshl_add_u64 v[146:147], v[146:147], 0, s[76:77]
	v_lshl_add_u64 v[146:147], v[144:145], 1, v[146:147]
	global_load_dwordx4 v[160:163], v[146:147], off
	global_load_dwordx4 v[164:167], v[146:147], off offset:256
	s_mov_b64 s[12:13], 0x8000
	v_lshl_add_u64 v[154:155], v[146:147], 0, s[12:13]
	global_load_dwordx4 v[168:171], v[154:155], off
	global_load_dwordx4 v[172:175], v[154:155], off offset:256
	s_mov_b64 s[12:13], 0x8000
	v_lshl_add_u64 v[154:155], v[154:155], 0, s[12:13]
	global_load_dwordx4 v[176:179], v[154:155], off
	global_load_dwordx4 v[180:183], v[154:155], off offset:256
	s_mov_b64 s[12:13], 0x8000
	v_lshl_add_u64 v[154:155], v[154:155], 0, s[12:13]
	global_load_dwordx4 v[184:187], v[154:155], off
	global_load_dwordx4 v[188:191], v[154:155], off offset:256
	s_mov_b64 s[12:13], 0x28000
	v_lshl_add_u64 v[154:155], v[154:155], 0, s[12:13]
	global_load_dwordx4 v[192:195], v[154:155], off
	global_load_dwordx4 v[196:199], v[154:155], off offset:256
	s_mov_b64 s[12:13], 0x8000
	v_lshl_add_u64 v[154:155], v[154:155], 0, s[12:13]
	global_load_dwordx4 v[200:203], v[154:155], off
	global_load_dwordx4 v[204:207], v[154:155], off offset:256
	s_mov_b64 s[12:13], 0x8000
	v_lshl_add_u64 v[154:155], v[154:155], 0, s[12:13]
	global_load_dwordx4 v[208:211], v[154:155], off
	global_load_dwordx4 v[212:215], v[154:155], off offset:256
	s_mov_b64 s[12:13], 0x8000
	v_lshl_add_u64 v[154:155], v[154:155], 0, s[12:13]
	global_load_dwordx4 v[216:219], v[154:155], off
	global_load_dwordx4 v[220:223], v[154:155], off offset:256
	s_lshl_b32 s0, s31, 2
	v_cmp_eq_u32_e32 vcc, 0, v153
	s_ashr_i32 s1, s0, 31
	s_waitcnt vmcnt(15)
	v_mov_b64_e32 v[154:155], v[160:161]
	v_mov_b64_e32 v[156:157], v[162:163]
	v_lshlrev_b32_e32 v158, 16, v154
	v_and_b32_e32 v159, 0xffff0000, v154
	v_lshlrev_b32_e32 v154, 16, v155
	v_and_b32_e32 v155, 0xffff0000, v155
	v_pk_add_f32 v[128:129], v[128:129], v[154:155]
	v_lshlrev_b32_e32 v154, 16, v156
	v_and_b32_e32 v155, 0xffff0000, v156
	v_lshlrev_b32_e32 v156, 16, v157
	v_and_b32_e32 v157, 0xffff0000, v157
	v_pk_add_f32 v[126:127], v[126:127], v[158:159]
	v_pk_add_f32 v[156:157], v[124:125], v[156:157]
	v_pk_add_f32 v[154:155], v[122:123], v[154:155]
	v_cvt_pk_bf16_f32 v122, v126, v127
	v_cvt_pk_bf16_f32 v123, v128, v129
	v_cvt_pk_bf16_f32 v124, v154, v155
	v_cvt_pk_bf16_f32 v125, v156, v157
	global_store_dwordx4 v[146:147], v[122:125], off sc0 sc1
	s_nop 1
	v_mul_f32_e32 v122, v127, v127
	v_mul_f32_e32 v123, v129, v129
	v_fmac_f32_e32 v122, v126, v126
	v_fmac_f32_e32 v123, v128, v128
	v_add_f32_e32 v122, v122, v123
	v_mul_f32_e32 v123, v155, v155
	v_mul_f32_e32 v124, v157, v157
	v_fmac_f32_e32 v123, v154, v154
	v_fmac_f32_e32 v124, v156, v156
	v_add_f32_e32 v123, v123, v124
	v_add_f32_e32 v128, v122, v123
	s_waitcnt vmcnt(15)
	v_mov_b64_e32 v[122:123], v[164:165]
	v_mov_b64_e32 v[124:125], v[166:167]
	v_lshlrev_b32_e32 v126, 16, v122
	v_and_b32_e32 v127, 0xffff0000, v122
	v_lshlrev_b32_e32 v122, 16, v123
	v_and_b32_e32 v123, 0xffff0000, v123
	v_pk_add_f32 v[120:121], v[120:121], v[122:123]
	v_lshlrev_b32_e32 v122, 16, v124
	v_and_b32_e32 v123, 0xffff0000, v124
	v_lshlrev_b32_e32 v124, 16, v125
	v_and_b32_e32 v125, 0xffff0000, v125
	v_pk_add_f32 v[118:119], v[118:119], v[126:127]
	v_pk_add_f32 v[124:125], v[116:117], v[124:125]
	v_pk_add_f32 v[122:123], v[114:115], v[122:123]
	v_cvt_pk_bf16_f32 v114, v118, v119
	v_cvt_pk_bf16_f32 v115, v120, v121
	v_cvt_pk_bf16_f32 v116, v122, v123
	v_cvt_pk_bf16_f32 v117, v124, v125
	global_store_dwordx4 v[146:147], v[114:117], off offset:256 sc0 sc1
	s_nop 1
	v_mul_f32_e32 v114, v119, v119
	v_mul_f32_e32 v115, v121, v121
	v_fmac_f32_e32 v114, v118, v118
	v_fmac_f32_e32 v115, v120, v120
	v_add_f32_e32 v114, v114, v115
	v_mul_f32_e32 v115, v123, v123
	v_mul_f32_e32 v116, v125, v125
	v_fmac_f32_e32 v115, v122, v122
	v_fmac_f32_e32 v116, v124, v124
	v_add_f32_e32 v115, v115, v116
	v_add_f32_e32 v114, v114, v115
	v_add_f32_e32 v114, v128, v114
	ds_bpermute_b32 v115, v152, v114
	s_waitcnt lgkmcnt(0)
	v_add_f32_e32 v114, v114, v115
	ds_bpermute_b32 v115, v151, v114
	s_and_saveexec_b64 s[12:13], vcc
	s_cbranch_execz .LBB0_1067
	s_waitcnt lgkmcnt(0)
	v_add_f32_e32 v116, v114, v115
	v_lshlrev_b64 v[114:115], 6, v[142:143]
	v_lshl_add_u64 v[114:115], s[78:79], 0, v[114:115]
	v_lshl_add_u64 v[114:115], s[0:1], 2, v[114:115]
	s_lshl_b32 s24, s15, 2
	s_mov_b32 s25, s77
	v_lshl_add_u64 v[114:115], v[114:115], 0, s[24:25]
	global_store_dword v[114:115], v116, off
.LBB0_1067:
	s_or_b64 exec, exec, s[12:13]
	s_waitcnt lgkmcnt(0)
	v_lshl_add_u64 v[114:115], v[142:143], 0, 16
	v_lshlrev_b64 v[116:117], 11, v[114:115]
	v_lshl_add_u64 v[116:117], s[22:23], 0, v[116:117]
	v_lshl_add_u64 v[116:117], s[10:11], 1, v[116:117]
	v_lshl_add_u64 v[116:117], v[116:117], 0, s[76:77]
	v_lshl_add_u64 v[116:117], v[144:145], 1, v[116:117]
	s_waitcnt vmcnt(15)
	v_mov_b64_e32 v[118:119], v[168:169]
	v_mov_b64_e32 v[120:121], v[170:171]
	v_lshlrev_b32_e32 v122, 16, v118
	v_and_b32_e32 v123, 0xffff0000, v118
	v_lshlrev_b32_e32 v118, 16, v119
	v_and_b32_e32 v119, 0xffff0000, v119
	v_pk_add_f32 v[112:113], v[112:113], v[118:119]
	v_lshlrev_b32_e32 v118, 16, v120
	v_and_b32_e32 v119, 0xffff0000, v120
	v_lshlrev_b32_e32 v120, 16, v121
	v_and_b32_e32 v121, 0xffff0000, v121
	v_pk_add_f32 v[110:111], v[110:111], v[122:123]
	v_pk_add_f32 v[120:121], v[108:109], v[120:121]
	v_pk_add_f32 v[118:119], v[106:107], v[118:119]
	v_cvt_pk_bf16_f32 v106, v110, v111
	v_cvt_pk_bf16_f32 v107, v112, v113
	v_cvt_pk_bf16_f32 v108, v118, v119
	v_cvt_pk_bf16_f32 v109, v120, v121
	global_store_dwordx4 v[116:117], v[106:109], off sc0 sc1
	s_nop 1
	v_mul_f32_e32 v106, v111, v111
	v_mul_f32_e32 v107, v113, v113
	v_fmac_f32_e32 v106, v110, v110
	v_fmac_f32_e32 v107, v112, v112
	v_add_f32_e32 v106, v106, v107
	v_mul_f32_e32 v107, v119, v119
	v_mul_f32_e32 v108, v121, v121
	v_fmac_f32_e32 v107, v118, v118
	v_fmac_f32_e32 v108, v120, v120
	v_add_f32_e32 v107, v107, v108
	v_add_f32_e32 v112, v106, v107
	s_waitcnt vmcnt(15)
	v_mov_b64_e32 v[106:107], v[172:173]
	v_mov_b64_e32 v[108:109], v[174:175]
	v_lshlrev_b32_e32 v110, 16, v106
	v_and_b32_e32 v111, 0xffff0000, v106
	v_lshlrev_b32_e32 v106, 16, v107
	v_and_b32_e32 v107, 0xffff0000, v107
	v_pk_add_f32 v[104:105], v[104:105], v[106:107]
	v_lshlrev_b32_e32 v106, 16, v108
	v_and_b32_e32 v107, 0xffff0000, v108
	v_lshlrev_b32_e32 v108, 16, v109
	v_and_b32_e32 v109, 0xffff0000, v109
	v_pk_add_f32 v[102:103], v[102:103], v[110:111]
	v_pk_add_f32 v[108:109], v[100:101], v[108:109]
	v_pk_add_f32 v[106:107], v[98:99], v[106:107]
	v_cvt_pk_bf16_f32 v98, v102, v103
	v_cvt_pk_bf16_f32 v99, v104, v105
	v_cvt_pk_bf16_f32 v100, v106, v107
	v_cvt_pk_bf16_f32 v101, v108, v109
	global_store_dwordx4 v[116:117], v[98:101], off offset:256 sc0 sc1
	s_nop 1
	v_mul_f32_e32 v98, v103, v103
	v_mul_f32_e32 v99, v105, v105
	v_fmac_f32_e32 v98, v102, v102
	v_fmac_f32_e32 v99, v104, v104
	v_add_f32_e32 v98, v98, v99
	v_mul_f32_e32 v99, v107, v107
	v_mul_f32_e32 v100, v109, v109
	v_fmac_f32_e32 v99, v106, v106
	v_fmac_f32_e32 v100, v108, v108
	v_add_f32_e32 v99, v99, v100
	v_add_f32_e32 v98, v98, v99
	v_add_f32_e32 v98, v112, v98
	ds_bpermute_b32 v99, v152, v98
	s_waitcnt lgkmcnt(0)
	v_add_f32_e32 v98, v98, v99
	ds_bpermute_b32 v99, v151, v98
	s_and_saveexec_b64 s[12:13], vcc
	s_cbranch_execz .LBB0_1069
	s_waitcnt lgkmcnt(0)
	v_add_f32_e32 v100, v98, v99
	v_lshlrev_b64 v[98:99], 6, v[114:115]
	v_lshl_add_u64 v[98:99], s[78:79], 0, v[98:99]
	v_lshl_add_u64 v[98:99], s[0:1], 2, v[98:99]
	s_lshl_b32 s24, s15, 2
	s_mov_b32 s25, s77
	v_lshl_add_u64 v[98:99], v[98:99], 0, s[24:25]
	global_store_dword v[98:99], v100, off
.LBB0_1069:
	s_or_b64 exec, exec, s[12:13]
	s_waitcnt lgkmcnt(0)
	v_lshl_add_u64 v[98:99], v[142:143], 0, 32
	v_lshlrev_b64 v[100:101], 11, v[98:99]
	v_lshl_add_u64 v[100:101], s[22:23], 0, v[100:101]
	v_lshl_add_u64 v[100:101], s[10:11], 1, v[100:101]
	v_lshl_add_u64 v[100:101], v[100:101], 0, s[76:77]
	v_lshl_add_u64 v[100:101], v[144:145], 1, v[100:101]
	s_waitcnt vmcnt(15)
	v_mov_b64_e32 v[102:103], v[176:177]
	v_mov_b64_e32 v[104:105], v[178:179]
	v_lshlrev_b32_e32 v106, 16, v102
	v_and_b32_e32 v107, 0xffff0000, v102
	v_lshlrev_b32_e32 v102, 16, v103
	v_and_b32_e32 v103, 0xffff0000, v103
	v_pk_add_f32 v[96:97], v[96:97], v[102:103]
	v_lshlrev_b32_e32 v102, 16, v104
	v_and_b32_e32 v103, 0xffff0000, v104
	v_lshlrev_b32_e32 v104, 16, v105
	v_and_b32_e32 v105, 0xffff0000, v105
	v_pk_add_f32 v[94:95], v[94:95], v[106:107]
	v_pk_add_f32 v[104:105], v[92:93], v[104:105]
	v_pk_add_f32 v[102:103], v[90:91], v[102:103]
	v_cvt_pk_bf16_f32 v90, v94, v95
	v_cvt_pk_bf16_f32 v91, v96, v97
	v_cvt_pk_bf16_f32 v92, v102, v103
	v_cvt_pk_bf16_f32 v93, v104, v105
	global_store_dwordx4 v[100:101], v[90:93], off sc0 sc1
	s_nop 1
	v_mul_f32_e32 v90, v95, v95
	v_mul_f32_e32 v91, v97, v97
	v_fmac_f32_e32 v90, v94, v94
	v_fmac_f32_e32 v91, v96, v96
	v_add_f32_e32 v90, v90, v91
	v_mul_f32_e32 v91, v103, v103
	v_mul_f32_e32 v92, v105, v105
	v_fmac_f32_e32 v91, v102, v102
	v_fmac_f32_e32 v92, v104, v104
	v_add_f32_e32 v91, v91, v92
	v_add_f32_e32 v96, v90, v91
	s_waitcnt vmcnt(15)
	v_mov_b64_e32 v[90:91], v[180:181]
	v_mov_b64_e32 v[92:93], v[182:183]
	v_lshlrev_b32_e32 v94, 16, v90
	v_and_b32_e32 v95, 0xffff0000, v90
	v_lshlrev_b32_e32 v90, 16, v91
	v_and_b32_e32 v91, 0xffff0000, v91
	v_pk_add_f32 v[88:89], v[88:89], v[90:91]
	v_lshlrev_b32_e32 v90, 16, v92
	v_and_b32_e32 v91, 0xffff0000, v92
	v_lshlrev_b32_e32 v92, 16, v93
	v_and_b32_e32 v93, 0xffff0000, v93
	v_pk_add_f32 v[86:87], v[86:87], v[94:95]
	v_pk_add_f32 v[92:93], v[84:85], v[92:93]
	v_pk_add_f32 v[90:91], v[82:83], v[90:91]
	v_cvt_pk_bf16_f32 v82, v86, v87
	v_cvt_pk_bf16_f32 v83, v88, v89
	v_cvt_pk_bf16_f32 v84, v90, v91
	v_cvt_pk_bf16_f32 v85, v92, v93
	global_store_dwordx4 v[100:101], v[82:85], off offset:256 sc0 sc1
	s_nop 1
	v_mul_f32_e32 v82, v87, v87
	v_mul_f32_e32 v83, v89, v89
	v_fmac_f32_e32 v82, v86, v86
	v_fmac_f32_e32 v83, v88, v88
	v_add_f32_e32 v82, v82, v83
	v_mul_f32_e32 v83, v91, v91
	v_mul_f32_e32 v84, v93, v93
	v_fmac_f32_e32 v83, v90, v90
	v_fmac_f32_e32 v84, v92, v92
	v_add_f32_e32 v83, v83, v84
	v_add_f32_e32 v82, v82, v83
	v_add_f32_e32 v82, v96, v82
	ds_bpermute_b32 v83, v152, v82
	s_waitcnt lgkmcnt(0)
	v_add_f32_e32 v82, v82, v83
	ds_bpermute_b32 v83, v151, v82
	s_and_saveexec_b64 s[12:13], vcc
	s_cbranch_execz .LBB0_1071
	s_waitcnt lgkmcnt(0)
	v_add_f32_e32 v84, v82, v83
	v_lshlrev_b64 v[82:83], 6, v[98:99]
	v_lshl_add_u64 v[82:83], s[78:79], 0, v[82:83]
	v_lshl_add_u64 v[82:83], s[0:1], 2, v[82:83]
	s_lshl_b32 s24, s15, 2
	s_mov_b32 s25, s77
	v_lshl_add_u64 v[82:83], v[82:83], 0, s[24:25]
	global_store_dword v[82:83], v84, off
.LBB0_1071:
	s_or_b64 exec, exec, s[12:13]
	s_waitcnt lgkmcnt(0)
	v_lshl_add_u64 v[82:83], v[142:143], 0, 48
	v_lshlrev_b64 v[84:85], 11, v[82:83]
	v_lshl_add_u64 v[84:85], s[22:23], 0, v[84:85]
	v_lshl_add_u64 v[84:85], s[10:11], 1, v[84:85]
	v_lshl_add_u64 v[84:85], v[84:85], 0, s[76:77]
	v_lshl_add_u64 v[84:85], v[144:145], 1, v[84:85]
	s_waitcnt vmcnt(15)
	v_mov_b64_e32 v[86:87], v[184:185]
	v_mov_b64_e32 v[88:89], v[186:187]
	v_lshlrev_b32_e32 v90, 16, v86
	v_and_b32_e32 v91, 0xffff0000, v86
	v_lshlrev_b32_e32 v86, 16, v87
	v_and_b32_e32 v87, 0xffff0000, v87
	v_pk_add_f32 v[80:81], v[80:81], v[86:87]
	v_lshlrev_b32_e32 v86, 16, v88
	v_and_b32_e32 v87, 0xffff0000, v88
	v_lshlrev_b32_e32 v88, 16, v89
	v_and_b32_e32 v89, 0xffff0000, v89
	v_pk_add_f32 v[78:79], v[78:79], v[90:91]
	v_pk_add_f32 v[88:89], v[76:77], v[88:89]
	v_pk_add_f32 v[86:87], v[74:75], v[86:87]
	v_cvt_pk_bf16_f32 v74, v78, v79
	v_cvt_pk_bf16_f32 v75, v80, v81
	v_cvt_pk_bf16_f32 v76, v86, v87
	v_cvt_pk_bf16_f32 v77, v88, v89
	global_store_dwordx4 v[84:85], v[74:77], off sc0 sc1
	s_nop 1
	v_mul_f32_e32 v74, v79, v79
	v_mul_f32_e32 v75, v81, v81
	v_fmac_f32_e32 v74, v78, v78
	v_fmac_f32_e32 v75, v80, v80
	v_add_f32_e32 v74, v74, v75
	v_mul_f32_e32 v75, v87, v87
	v_mul_f32_e32 v76, v89, v89
	v_fmac_f32_e32 v75, v86, v86
	v_fmac_f32_e32 v76, v88, v88
	v_add_f32_e32 v75, v75, v76
	v_add_f32_e32 v80, v74, v75
	s_waitcnt vmcnt(15)
	v_mov_b64_e32 v[74:75], v[188:189]
	v_mov_b64_e32 v[76:77], v[190:191]
	v_lshlrev_b32_e32 v78, 16, v74
	v_and_b32_e32 v79, 0xffff0000, v74
	v_lshlrev_b32_e32 v74, 16, v75
	v_and_b32_e32 v75, 0xffff0000, v75
	v_pk_add_f32 v[72:73], v[72:73], v[74:75]
	v_lshlrev_b32_e32 v74, 16, v76
	v_and_b32_e32 v75, 0xffff0000, v76
	v_lshlrev_b32_e32 v76, 16, v77
	v_and_b32_e32 v77, 0xffff0000, v77
	v_pk_add_f32 v[70:71], v[70:71], v[78:79]
	v_pk_add_f32 v[76:77], v[68:69], v[76:77]
	v_pk_add_f32 v[74:75], v[66:67], v[74:75]
	v_cvt_pk_bf16_f32 v66, v70, v71
	v_cvt_pk_bf16_f32 v67, v72, v73
	v_cvt_pk_bf16_f32 v68, v74, v75
	v_cvt_pk_bf16_f32 v69, v76, v77
	global_store_dwordx4 v[84:85], v[66:69], off offset:256 sc0 sc1
	s_nop 1
	v_mul_f32_e32 v66, v71, v71
	v_mul_f32_e32 v67, v73, v73
	v_fmac_f32_e32 v66, v70, v70
	v_fmac_f32_e32 v67, v72, v72
	v_add_f32_e32 v66, v66, v67
	v_mul_f32_e32 v67, v75, v75
	v_mul_f32_e32 v68, v77, v77
	v_fmac_f32_e32 v67, v74, v74
	v_fmac_f32_e32 v68, v76, v76
	v_add_f32_e32 v67, v67, v68
	v_add_f32_e32 v66, v66, v67
	v_add_f32_e32 v66, v80, v66
	ds_bpermute_b32 v67, v152, v66
	s_waitcnt lgkmcnt(0)
	v_add_f32_e32 v66, v66, v67
	ds_bpermute_b32 v67, v151, v66
	s_and_saveexec_b64 s[12:13], vcc
	s_cbranch_execz .LBB0_1073
	s_waitcnt lgkmcnt(0)
	v_add_f32_e32 v68, v66, v67
	v_lshlrev_b64 v[66:67], 6, v[82:83]
	v_lshl_add_u64 v[66:67], s[78:79], 0, v[66:67]
	v_lshl_add_u64 v[66:67], s[0:1], 2, v[66:67]
	s_lshl_b32 s24, s15, 2
	s_mov_b32 s25, s77
	v_lshl_add_u64 v[66:67], v[66:67], 0, s[24:25]
	global_store_dword v[66:67], v68, off
.LBB0_1073:
	s_or_b64 exec, exec, s[12:13]
	s_waitcnt lgkmcnt(0)
	v_lshl_add_u64 v[66:67], v[142:143], 0, s[28:29]
	v_lshlrev_b64 v[68:69], 11, v[66:67]
	v_lshl_add_u64 v[68:69], s[22:23], 0, v[68:69]
	v_lshl_add_u64 v[68:69], s[10:11], 1, v[68:69]
	v_lshl_add_u64 v[68:69], v[68:69], 0, s[76:77]
	v_lshl_add_u64 v[68:69], v[144:145], 1, v[68:69]
	s_waitcnt vmcnt(15)
	v_mov_b64_e32 v[70:71], v[192:193]
	v_mov_b64_e32 v[72:73], v[194:195]
	v_lshlrev_b32_e32 v74, 16, v70
	v_and_b32_e32 v75, 0xffff0000, v70
	v_lshlrev_b32_e32 v70, 16, v71
	v_and_b32_e32 v71, 0xffff0000, v71
	v_pk_add_f32 v[64:65], v[64:65], v[70:71]
	v_lshlrev_b32_e32 v70, 16, v72
	v_and_b32_e32 v71, 0xffff0000, v72
	v_lshlrev_b32_e32 v72, 16, v73
	v_and_b32_e32 v73, 0xffff0000, v73
	v_pk_add_f32 v[62:63], v[62:63], v[74:75]
	v_pk_add_f32 v[72:73], v[60:61], v[72:73]
	v_pk_add_f32 v[70:71], v[58:59], v[70:71]
	v_cvt_pk_bf16_f32 v58, v62, v63
	v_cvt_pk_bf16_f32 v59, v64, v65
	v_cvt_pk_bf16_f32 v60, v70, v71
	v_cvt_pk_bf16_f32 v61, v72, v73
	global_store_dwordx4 v[68:69], v[58:61], off sc0 sc1
	s_nop 1
	v_mul_f32_e32 v58, v63, v63
	v_mul_f32_e32 v59, v65, v65
	v_fmac_f32_e32 v58, v62, v62
	v_fmac_f32_e32 v59, v64, v64
	v_add_f32_e32 v58, v58, v59
	v_mul_f32_e32 v59, v71, v71
	v_mul_f32_e32 v60, v73, v73
	v_fmac_f32_e32 v59, v70, v70
	v_fmac_f32_e32 v60, v72, v72
	v_add_f32_e32 v59, v59, v60
	v_add_f32_e32 v64, v58, v59
	s_waitcnt vmcnt(15)
	v_mov_b64_e32 v[58:59], v[196:197]
	v_mov_b64_e32 v[60:61], v[198:199]
	v_lshlrev_b32_e32 v62, 16, v58
	v_and_b32_e32 v63, 0xffff0000, v58
	v_lshlrev_b32_e32 v58, 16, v59
	v_and_b32_e32 v59, 0xffff0000, v59
	v_pk_add_f32 v[56:57], v[56:57], v[58:59]
	v_lshlrev_b32_e32 v58, 16, v60
	v_and_b32_e32 v59, 0xffff0000, v60
	v_lshlrev_b32_e32 v60, 16, v61
	v_and_b32_e32 v61, 0xffff0000, v61
	v_pk_add_f32 v[54:55], v[54:55], v[62:63]
	v_pk_add_f32 v[60:61], v[52:53], v[60:61]
	v_pk_add_f32 v[58:59], v[50:51], v[58:59]
	v_cvt_pk_bf16_f32 v50, v54, v55
	v_cvt_pk_bf16_f32 v51, v56, v57
	v_cvt_pk_bf16_f32 v52, v58, v59
	v_cvt_pk_bf16_f32 v53, v60, v61
	global_store_dwordx4 v[68:69], v[50:53], off offset:256 sc0 sc1
	s_nop 1
	v_mul_f32_e32 v50, v55, v55
	v_mul_f32_e32 v51, v57, v57
	v_fmac_f32_e32 v50, v54, v54
	v_fmac_f32_e32 v51, v56, v56
	v_add_f32_e32 v50, v50, v51
	v_mul_f32_e32 v51, v59, v59
	v_mul_f32_e32 v52, v61, v61
	v_fmac_f32_e32 v51, v58, v58
	v_fmac_f32_e32 v52, v60, v60
	v_add_f32_e32 v51, v51, v52
	v_add_f32_e32 v50, v50, v51
	v_add_f32_e32 v50, v64, v50
	ds_bpermute_b32 v51, v152, v50
	s_waitcnt lgkmcnt(0)
	v_add_f32_e32 v50, v50, v51
	ds_bpermute_b32 v51, v151, v50
	s_and_saveexec_b64 s[12:13], vcc
	s_cbranch_execz .LBB0_1075
	s_waitcnt lgkmcnt(0)
	v_add_f32_e32 v52, v50, v51
	v_lshlrev_b64 v[50:51], 6, v[66:67]
	v_lshl_add_u64 v[50:51], s[78:79], 0, v[50:51]
	v_lshl_add_u64 v[50:51], s[0:1], 2, v[50:51]
	s_lshl_b32 s24, s15, 2
	s_mov_b32 s25, s77
	v_lshl_add_u64 v[50:51], v[50:51], 0, s[24:25]
	global_store_dword v[50:51], v52, off
.LBB0_1075:
	s_or_b64 exec, exec, s[12:13]
	s_mov_b64 s[12:13], 0x90
	s_waitcnt lgkmcnt(0)
	v_lshl_add_u64 v[50:51], v[142:143], 0, s[12:13]
	v_lshlrev_b64 v[52:53], 11, v[50:51]
	v_lshl_add_u64 v[52:53], s[22:23], 0, v[52:53]
	v_lshl_add_u64 v[52:53], s[10:11], 1, v[52:53]
	v_lshl_add_u64 v[52:53], v[52:53], 0, s[76:77]
	v_lshl_add_u64 v[52:53], v[144:145], 1, v[52:53]
	s_waitcnt vmcnt(15)
	v_mov_b64_e32 v[54:55], v[200:201]
	v_mov_b64_e32 v[56:57], v[202:203]
	v_lshlrev_b32_e32 v58, 16, v54
	v_and_b32_e32 v59, 0xffff0000, v54
	v_lshlrev_b32_e32 v54, 16, v55
	v_and_b32_e32 v55, 0xffff0000, v55
	v_pk_add_f32 v[48:49], v[48:49], v[54:55]
	v_lshlrev_b32_e32 v54, 16, v56
	v_and_b32_e32 v55, 0xffff0000, v56
	v_lshlrev_b32_e32 v56, 16, v57
	v_and_b32_e32 v57, 0xffff0000, v57
	v_pk_add_f32 v[46:47], v[46:47], v[58:59]
	v_pk_add_f32 v[56:57], v[44:45], v[56:57]
	v_pk_add_f32 v[54:55], v[42:43], v[54:55]
	v_cvt_pk_bf16_f32 v42, v46, v47
	v_cvt_pk_bf16_f32 v43, v48, v49
	v_cvt_pk_bf16_f32 v44, v54, v55
	v_cvt_pk_bf16_f32 v45, v56, v57
	global_store_dwordx4 v[52:53], v[42:45], off sc0 sc1
	s_nop 1
	v_mul_f32_e32 v42, v47, v47
	v_mul_f32_e32 v43, v49, v49
	v_fmac_f32_e32 v42, v46, v46
	v_fmac_f32_e32 v43, v48, v48
	v_add_f32_e32 v42, v42, v43
	v_mul_f32_e32 v43, v55, v55
	v_mul_f32_e32 v44, v57, v57
	v_fmac_f32_e32 v43, v54, v54
	v_fmac_f32_e32 v44, v56, v56
	v_add_f32_e32 v43, v43, v44
	v_add_f32_e32 v48, v42, v43
	s_waitcnt vmcnt(15)
	v_mov_b64_e32 v[42:43], v[204:205]
	v_mov_b64_e32 v[44:45], v[206:207]
	v_lshlrev_b32_e32 v46, 16, v42
	v_and_b32_e32 v47, 0xffff0000, v42
	v_lshlrev_b32_e32 v42, 16, v43
	v_and_b32_e32 v43, 0xffff0000, v43
	v_pk_add_f32 v[40:41], v[40:41], v[42:43]
	v_lshlrev_b32_e32 v42, 16, v44
	v_and_b32_e32 v43, 0xffff0000, v44
	v_lshlrev_b32_e32 v44, 16, v45
	v_and_b32_e32 v45, 0xffff0000, v45
	v_pk_add_f32 v[38:39], v[38:39], v[46:47]
	v_pk_add_f32 v[44:45], v[36:37], v[44:45]
	v_pk_add_f32 v[42:43], v[34:35], v[42:43]
	v_cvt_pk_bf16_f32 v34, v38, v39
	v_cvt_pk_bf16_f32 v35, v40, v41
	v_cvt_pk_bf16_f32 v36, v42, v43
	v_cvt_pk_bf16_f32 v37, v44, v45
	global_store_dwordx4 v[52:53], v[34:37], off offset:256 sc0 sc1
	s_nop 1
	v_mul_f32_e32 v34, v39, v39
	v_mul_f32_e32 v35, v41, v41
	v_fmac_f32_e32 v34, v38, v38
	v_fmac_f32_e32 v35, v40, v40
	v_add_f32_e32 v34, v34, v35
	v_mul_f32_e32 v35, v43, v43
	v_mul_f32_e32 v36, v45, v45
	v_fmac_f32_e32 v35, v42, v42
	v_fmac_f32_e32 v36, v44, v44
	v_add_f32_e32 v35, v35, v36
	v_add_f32_e32 v34, v34, v35
	v_add_f32_e32 v34, v48, v34
	ds_bpermute_b32 v35, v152, v34
	s_waitcnt lgkmcnt(0)
	v_add_f32_e32 v34, v34, v35
	ds_bpermute_b32 v35, v151, v34
	s_and_saveexec_b64 s[12:13], vcc
	s_cbranch_execz .LBB0_1077
	s_waitcnt lgkmcnt(0)
	v_add_f32_e32 v36, v34, v35
	v_lshlrev_b64 v[34:35], 6, v[50:51]
	v_lshl_add_u64 v[34:35], s[78:79], 0, v[34:35]
	v_lshl_add_u64 v[34:35], s[0:1], 2, v[34:35]
	s_lshl_b32 s24, s15, 2
	s_mov_b32 s25, s77
	v_lshl_add_u64 v[34:35], v[34:35], 0, s[24:25]
	global_store_dword v[34:35], v36, off
.LBB0_1077:
	s_or_b64 exec, exec, s[12:13]
	s_mov_b64 s[12:13], 0xa0
	s_waitcnt lgkmcnt(0)
	v_lshl_add_u64 v[34:35], v[142:143], 0, s[12:13]
	v_lshlrev_b64 v[36:37], 11, v[34:35]
	v_lshl_add_u64 v[36:37], s[22:23], 0, v[36:37]
	v_lshl_add_u64 v[36:37], s[10:11], 1, v[36:37]
	v_lshl_add_u64 v[36:37], v[36:37], 0, s[76:77]
	v_lshl_add_u64 v[36:37], v[144:145], 1, v[36:37]
	s_waitcnt vmcnt(15)
	v_mov_b64_e32 v[38:39], v[208:209]
	v_mov_b64_e32 v[40:41], v[210:211]
	v_lshlrev_b32_e32 v42, 16, v38
	v_and_b32_e32 v43, 0xffff0000, v38
	v_lshlrev_b32_e32 v38, 16, v39
	v_and_b32_e32 v39, 0xffff0000, v39
	v_pk_add_f32 v[32:33], v[32:33], v[38:39]
	v_lshlrev_b32_e32 v38, 16, v40
	v_and_b32_e32 v39, 0xffff0000, v40
	v_lshlrev_b32_e32 v40, 16, v41
	v_and_b32_e32 v41, 0xffff0000, v41
	v_pk_add_f32 v[30:31], v[30:31], v[42:43]
	v_pk_add_f32 v[40:41], v[28:29], v[40:41]
	v_pk_add_f32 v[38:39], v[26:27], v[38:39]
	v_cvt_pk_bf16_f32 v26, v30, v31
	v_cvt_pk_bf16_f32 v27, v32, v33
	v_cvt_pk_bf16_f32 v28, v38, v39
	v_cvt_pk_bf16_f32 v29, v40, v41
	global_store_dwordx4 v[36:37], v[26:29], off sc0 sc1
	s_nop 1
	v_mul_f32_e32 v26, v31, v31
	v_mul_f32_e32 v27, v33, v33
	v_fmac_f32_e32 v26, v30, v30
	v_fmac_f32_e32 v27, v32, v32
	v_add_f32_e32 v26, v26, v27
	v_mul_f32_e32 v27, v39, v39
	v_mul_f32_e32 v28, v41, v41
	v_fmac_f32_e32 v27, v38, v38
	v_fmac_f32_e32 v28, v40, v40
	v_add_f32_e32 v27, v27, v28
	v_add_f32_e32 v32, v26, v27
	s_waitcnt vmcnt(15)
	v_mov_b64_e32 v[26:27], v[212:213]
	v_mov_b64_e32 v[28:29], v[214:215]
	v_lshlrev_b32_e32 v30, 16, v26
	v_and_b32_e32 v31, 0xffff0000, v26
	v_lshlrev_b32_e32 v26, 16, v27
	v_and_b32_e32 v27, 0xffff0000, v27
	v_pk_add_f32 v[24:25], v[24:25], v[26:27]
	v_lshlrev_b32_e32 v26, 16, v28
	v_and_b32_e32 v27, 0xffff0000, v28
	v_lshlrev_b32_e32 v28, 16, v29
	v_and_b32_e32 v29, 0xffff0000, v29
	v_pk_add_f32 v[22:23], v[22:23], v[30:31]
	v_pk_add_f32 v[28:29], v[20:21], v[28:29]
	v_pk_add_f32 v[26:27], v[18:19], v[26:27]
	v_cvt_pk_bf16_f32 v18, v22, v23
	v_cvt_pk_bf16_f32 v19, v24, v25
	v_cvt_pk_bf16_f32 v20, v26, v27
	v_cvt_pk_bf16_f32 v21, v28, v29
	global_store_dwordx4 v[36:37], v[18:21], off offset:256 sc0 sc1
	s_nop 1
	v_mul_f32_e32 v18, v23, v23
	v_mul_f32_e32 v19, v25, v25
	v_fmac_f32_e32 v18, v22, v22
	v_fmac_f32_e32 v19, v24, v24
	v_add_f32_e32 v18, v18, v19
	v_mul_f32_e32 v19, v27, v27
	v_mul_f32_e32 v20, v29, v29
	v_fmac_f32_e32 v19, v26, v26
	v_fmac_f32_e32 v20, v28, v28
	v_add_f32_e32 v19, v19, v20
	v_add_f32_e32 v18, v18, v19
	v_add_f32_e32 v18, v32, v18
	ds_bpermute_b32 v19, v152, v18
	s_waitcnt lgkmcnt(0)
	v_add_f32_e32 v18, v18, v19
	ds_bpermute_b32 v19, v151, v18
	s_and_saveexec_b64 s[12:13], vcc
	s_cbranch_execz .LBB0_1079
	s_waitcnt lgkmcnt(0)
	v_add_f32_e32 v20, v18, v19
	v_lshlrev_b64 v[18:19], 6, v[34:35]
	v_lshl_add_u64 v[18:19], s[78:79], 0, v[18:19]
	v_lshl_add_u64 v[18:19], s[0:1], 2, v[18:19]
	s_lshl_b32 s24, s15, 2
	s_mov_b32 s25, s77
	v_lshl_add_u64 v[18:19], v[18:19], 0, s[24:25]
	global_store_dword v[18:19], v20, off
.LBB0_1079:
	s_or_b64 exec, exec, s[12:13]
	s_mov_b64 s[12:13], 0xb0
	s_waitcnt lgkmcnt(0)
	v_lshl_add_u64 v[18:19], v[142:143], 0, s[12:13]
	v_lshlrev_b64 v[20:21], 11, v[18:19]
	v_lshl_add_u64 v[20:21], s[22:23], 0, v[20:21]
	v_lshl_add_u64 v[20:21], s[10:11], 1, v[20:21]
	v_lshl_add_u64 v[20:21], v[20:21], 0, s[76:77]
	v_lshl_add_u64 v[20:21], v[144:145], 1, v[20:21]
	s_waitcnt vmcnt(15)
	v_mov_b64_e32 v[22:23], v[216:217]
	v_mov_b64_e32 v[24:25], v[218:219]
	v_lshlrev_b32_e32 v26, 16, v22
	v_and_b32_e32 v27, 0xffff0000, v22
	v_lshlrev_b32_e32 v22, 16, v23
	v_and_b32_e32 v23, 0xffff0000, v23
	v_pk_add_f32 v[16:17], v[16:17], v[22:23]
	v_lshlrev_b32_e32 v22, 16, v24
	v_and_b32_e32 v23, 0xffff0000, v24
	v_lshlrev_b32_e32 v24, 16, v25
	v_and_b32_e32 v25, 0xffff0000, v25
	v_pk_add_f32 v[14:15], v[14:15], v[26:27]
	v_pk_add_f32 v[24:25], v[12:13], v[24:25]
	v_pk_add_f32 v[22:23], v[10:11], v[22:23]
	v_cvt_pk_bf16_f32 v10, v14, v15
	v_cvt_pk_bf16_f32 v11, v16, v17
	v_cvt_pk_bf16_f32 v12, v22, v23
	v_cvt_pk_bf16_f32 v13, v24, v25
	global_store_dwordx4 v[20:21], v[10:13], off sc0 sc1
	s_nop 1
	v_mul_f32_e32 v10, v15, v15
	v_mul_f32_e32 v11, v17, v17
	v_fmac_f32_e32 v10, v14, v14
	v_fmac_f32_e32 v11, v16, v16
	v_add_f32_e32 v10, v10, v11
	v_mul_f32_e32 v11, v23, v23
	v_mul_f32_e32 v12, v25, v25
	v_fmac_f32_e32 v11, v22, v22
	v_fmac_f32_e32 v12, v24, v24
	v_add_f32_e32 v11, v11, v12
	v_add_f32_e32 v16, v10, v11
	s_waitcnt vmcnt(15)
	v_mov_b64_e32 v[10:11], v[220:221]
	v_mov_b64_e32 v[12:13], v[222:223]
	v_lshlrev_b32_e32 v14, 16, v10
	v_and_b32_e32 v15, 0xffff0000, v10
	v_lshlrev_b32_e32 v10, 16, v11
	v_and_b32_e32 v11, 0xffff0000, v11
	v_pk_add_f32 v[8:9], v[8:9], v[10:11]
	v_lshlrev_b32_e32 v10, 16, v12
	v_and_b32_e32 v11, 0xffff0000, v12
	v_lshlrev_b32_e32 v12, 16, v13
	v_and_b32_e32 v13, 0xffff0000, v13
	v_pk_add_f32 v[6:7], v[6:7], v[14:15]
	v_pk_add_f32 v[12:13], v[4:5], v[12:13]
	v_pk_add_f32 v[10:11], v[2:3], v[10:11]
	v_cvt_pk_bf16_f32 v2, v6, v7
	v_cvt_pk_bf16_f32 v3, v8, v9
	v_cvt_pk_bf16_f32 v4, v10, v11
	v_cvt_pk_bf16_f32 v5, v12, v13
	global_store_dwordx4 v[20:21], v[2:5], off offset:256 sc0 sc1
	s_nop 1
	v_mul_f32_e32 v2, v7, v7
	v_mul_f32_e32 v3, v9, v9
	v_fmac_f32_e32 v2, v6, v6
	v_fmac_f32_e32 v3, v8, v8
	v_add_f32_e32 v2, v2, v3
	v_mul_f32_e32 v3, v11, v11
	v_mul_f32_e32 v4, v13, v13
	v_fmac_f32_e32 v3, v10, v10
	v_fmac_f32_e32 v4, v12, v12
	v_add_f32_e32 v3, v3, v4
	v_add_f32_e32 v2, v2, v3
	v_add_f32_e32 v2, v16, v2
	ds_bpermute_b32 v3, v152, v2
	s_waitcnt lgkmcnt(0)
	v_add_f32_e32 v2, v2, v3
	ds_bpermute_b32 v3, v151, v2
	s_and_saveexec_b64 s[10:11], vcc
	s_cbranch_execz .LBB0_1081
	s_waitcnt lgkmcnt(0)
	v_add_f32_e32 v4, v2, v3
	v_lshlrev_b64 v[2:3], 6, v[18:19]
	v_lshl_add_u64 v[2:3], s[78:79], 0, v[2:3]
	v_lshl_add_u64 v[2:3], s[0:1], 2, v[2:3]
	s_lshl_b32 s0, s15, 2
	s_mov_b32 s1, s77
	v_lshl_add_u64 v[2:3], v[2:3], 0, s[0:1]
	global_store_dword v[2:3], v4, off

.LBB0_1106:
	s_ashr_i32 s47, s46, 31
	s_lshl_b64 s[34:35], s[46:47], 8
	v_mov_b32_e32 v146, v1
	v_mov_b32_e32 v145, v142
	s_add_u32 s34, s34, s18
	s_addc_u32 s35, s35, s20
	v_ashrrev_i32_e32 v147, 31, v146
	v_lshl_add_u64 v[146:147], s[34:35], 0, v[146:147]
	v_readlane_b32 s44, v254, 54
	s_lshl_b32 s34, s33, 8
	v_lshlrev_b64 v[146:147], 11, v[146:147]
	v_readlane_b32 s45, v254, 55
	s_ashr_i32 s35, s34, 31
	v_cvt_pk_bf16_f32 v122, v122, v123
	v_cvt_pk_bf16_f32 v123, v124, v125
	v_cvt_pk_bf16_f32 v124, v126, v127
	v_lshl_add_u64 v[126:127], s[44:45], 0, v[146:147]
	v_lshlrev_b32_e32 v148, 3, v145
	v_lshl_add_u64 v[126:127], s[34:35], 1, v[126:127]
	v_ashrrev_i32_e32 v149, 31, v148
	v_lshl_add_u64 v[126:127], v[126:127], 0, s[76:77]
	v_lshl_add_u64 v[126:127], v[148:149], 1, v[126:127]
	s_mov_b32 s33, 0x8000
	v_cvt_pk_bf16_f32 v110, v110, v111
	v_cvt_pk_bf16_f32 v111, v112, v113
	v_cvt_pk_bf16_f32 v113, v108, v109
	v_add_co_u32_e32 v108, vcc, s33, v126
	s_mov_b32 s33, 0x10000
	s_nop 0
	v_addc_co_u32_e32 v109, vcc, 0, v127, vcc
	v_cvt_pk_bf16_f32 v94, v94, v95
	v_cvt_pk_bf16_f32 v95, v96, v97
	v_cvt_pk_bf16_f32 v97, v92, v93
	v_add_co_u32_e32 v92, vcc, s33, v126
	s_mov_b32 s33, 0x18000
	s_nop 0
	v_addc_co_u32_e32 v93, vcc, 0, v127, vcc
	v_cvt_pk_bf16_f32 v78, v78, v79
	v_cvt_pk_bf16_f32 v79, v80, v81
	v_cvt_pk_bf16_f32 v81, v76, v77
	v_add_co_u32_e32 v76, vcc, s33, v126
	s_mov_b32 s33, 0x40000
	s_nop 0
	v_addc_co_u32_e32 v77, vcc, 0, v127, vcc
	v_cvt_pk_bf16_f32 v62, v62, v63
	v_cvt_pk_bf16_f32 v63, v64, v65
	v_cvt_pk_bf16_f32 v65, v60, v61
	v_add_co_u32_e32 v60, vcc, s33, v126
	s_mov_b64 s[34:35], 0x8000
	s_nop 0
	v_addc_co_u32_e32 v61, vcc, 0, v127, vcc
	s_mov_b32 s33, 0x48000
	v_cvt_pk_bf16_f32 v112, v106, v107
	v_lshl_add_u64 v[106:107], v[126:127], 0, s[34:35]
	s_mov_b64 s[34:35], 0x10000
	v_cvt_pk_bf16_f32 v46, v46, v47
	v_cvt_pk_bf16_f32 v47, v48, v49
	v_cvt_pk_bf16_f32 v49, v44, v45
	v_add_co_u32_e32 v44, vcc, s33, v126
	v_cvt_pk_bf16_f32 v96, v90, v91
	v_lshl_add_u64 v[90:91], v[126:127], 0, s[34:35]
	s_mov_b64 s[34:35], 0x18000
	v_addc_co_u32_e32 v45, vcc, 0, v127, vcc
	s_mov_b32 s33, 0x50000
	v_cvt_pk_bf16_f32 v80, v74, v75
	v_lshl_add_u64 v[74:75], v[126:127], 0, s[34:35]
	s_mov_b64 s[34:35], 0x40000
	v_cvt_pk_bf16_f32 v30, v30, v31
	v_cvt_pk_bf16_f32 v31, v32, v33
	v_cvt_pk_bf16_f32 v33, v28, v29
	v_add_co_u32_e32 v28, vcc, s33, v126
	v_cvt_pk_bf16_f32 v64, v58, v59
	v_lshl_add_u64 v[58:59], v[126:127], 0, s[34:35]
	s_mov_b64 s[34:35], 0x48000
	v_addc_co_u32_e32 v29, vcc, 0, v127, vcc
	s_mov_b32 s33, 0x58000
	v_cvt_pk_bf16_f32 v48, v42, v43
	v_lshl_add_u64 v[42:43], v[126:127], 0, s[34:35]
	s_mov_b64 s[34:35], 0x50000
	v_cvt_pk_bf16_f32 v14, v14, v15
	v_cvt_pk_bf16_f32 v15, v16, v17
	v_cvt_pk_bf16_f32 v17, v12, v13
	v_add_co_u32_e32 v12, vcc, s33, v126
	v_cvt_pk_bf16_f32 v32, v26, v27
	v_lshl_add_u64 v[26:27], v[126:127], 0, s[34:35]
	s_mov_b64 s[34:35], 0x58000
	v_addc_co_u32_e32 v13, vcc, 0, v127, vcc
	v_cvt_pk_bf16_f32 v125, v128, v129
	v_cvt_pk_bf16_f32 v118, v118, v119
	v_cvt_pk_bf16_f32 v119, v120, v121
	v_cvt_pk_bf16_f32 v120, v114, v115
	v_cvt_pk_bf16_f32 v121, v116, v117
	v_cvt_pk_bf16_f32 v102, v102, v103
	v_cvt_pk_bf16_f32 v103, v104, v105
	v_cvt_pk_bf16_f32 v104, v98, v99
	v_cvt_pk_bf16_f32 v105, v100, v101
	v_cvt_pk_bf16_f32 v86, v86, v87
	v_cvt_pk_bf16_f32 v87, v88, v89
	v_cvt_pk_bf16_f32 v88, v82, v83
	v_cvt_pk_bf16_f32 v89, v84, v85
	v_cvt_pk_bf16_f32 v70, v70, v71
	v_cvt_pk_bf16_f32 v71, v72, v73
	v_cvt_pk_bf16_f32 v72, v66, v67
	v_cvt_pk_bf16_f32 v73, v68, v69
	v_cvt_pk_bf16_f32 v54, v54, v55
	v_cvt_pk_bf16_f32 v55, v56, v57
	v_cvt_pk_bf16_f32 v56, v50, v51
	v_cvt_pk_bf16_f32 v57, v52, v53
	v_cvt_pk_bf16_f32 v38, v38, v39
	v_cvt_pk_bf16_f32 v39, v40, v41
	v_cvt_pk_bf16_f32 v40, v34, v35
	v_cvt_pk_bf16_f32 v41, v36, v37
	v_cvt_pk_bf16_f32 v22, v22, v23
	v_cvt_pk_bf16_f32 v23, v24, v25
	v_cvt_pk_bf16_f32 v24, v18, v19
	v_cvt_pk_bf16_f32 v25, v20, v21
	v_cvt_pk_bf16_f32 v16, v10, v11
	v_lshl_add_u64 v[10:11], v[126:127], 0, s[34:35]
	v_cvt_pk_bf16_f32 v6, v6, v7
	v_cvt_pk_bf16_f32 v7, v8, v9
	v_cvt_pk_bf16_f32 v8, v2, v3
	v_cvt_pk_bf16_f32 v9, v4, v5
	s_and_b64 vcc, exec, s[42:43]
	s_mov_b64 s[42:43], -1
	global_store_dwordx4 v[126:127], v[122:125], off sc0 sc1
	global_store_dwordx4 v[126:127], v[118:121], off offset:256 sc0 sc1
	global_store_dwordx4 v[108:109], v[110:113], off sc0 sc1
	global_store_dwordx4 v[106:107], v[102:105], off offset:256 sc0 sc1
	global_store_dwordx4 v[92:93], v[94:97], off sc0 sc1
	global_store_dwordx4 v[90:91], v[86:89], off offset:256 sc0 sc1
	global_store_dwordx4 v[76:77], v[78:81], off sc0 sc1
	global_store_dwordx4 v[74:75], v[70:73], off offset:256 sc0 sc1
	global_store_dwordx4 v[60:61], v[62:65], off sc0 sc1
	global_store_dwordx4 v[58:59], v[54:57], off offset:256 sc0 sc1
	global_store_dwordx4 v[44:45], v[46:49], off sc0 sc1
	global_store_dwordx4 v[42:43], v[38:41], off offset:256 sc0 sc1
	global_store_dwordx4 v[28:29], v[30:33], off sc0 sc1
	global_store_dwordx4 v[26:27], v[22:25], off offset:256 sc0 sc1
	global_store_dwordx4 v[12:13], v[14:17], off sc0 sc1
	global_store_dwordx4 v[10:11], v[6:9], off offset:256 sc0 sc1
	s_cbranch_vccnz .LBB0_1090
	s_andn2_b64 vcc, exec, s[12:13]
	s_cbranch_vccnz .LBB0_1089
	s_barrier
	s_branch .LBB0_1089

.LBB0_1185:
	s_ashr_i32 s1, s0, 31
	s_lshl_b64 s[0:1], s[0:1], 8
	v_mov_b32_e32 v205, v188
	v_mov_b32_e32 v134, v1
	s_add_u32 s0, s0, s84
	s_addc_u32 s1, s1, s86
	v_ashrrev_i32_e32 v135, 31, v134
	v_lshlrev_b32_e32 v132, 2, v205
	v_lshl_add_u64 v[130:131], s[0:1], 0, v[134:135]
	v_ashrrev_i32_e32 v133, 31, v132
	v_lshlrev_b32_e32 v134, 2, v134
	v_lshl_add_u64 v[132:133], v[132:133], 2, s[78:79]
	v_lshl_add_u32 v134, v205, 6, v134
	v_lshlrev_b64 v[178:179], 6, v[130:131]
	v_xor_b32_e32 v192, 64, v134
	v_xor_b32_e32 v191, 0x80, v134
	v_lshl_add_u64 v[134:135], v[132:133], 0, v[178:179]
	global_load_dwordx4 v[134:137], v[134:135], off
	v_lshl_add_u64 v[180:181], v[130:131], 0, 16
	v_lshlrev_b64 v[176:177], 6, v[180:181]
	v_lshl_add_u64 v[174:175], v[130:131], 0, 32
	v_lshlrev_b64 v[172:173], 6, v[174:175]
	v_lshl_add_u64 v[170:171], v[130:131], 0, 48
	v_lshlrev_b64 v[168:169], 6, v[170:171]
	v_lshl_add_u64 v[166:167], v[130:131], 0, s[28:29]
	v_lshlrev_b64 v[164:165], 6, v[166:167]
	s_waitcnt vmcnt(0)
	v_add_f32_e32 v134, v134, v135
	v_add_f32_e32 v135, v136, v137
	v_add_f32_e32 v134, v134, v135
	ds_bpermute_b32 v135, v192, v134
	s_waitcnt lgkmcnt(0)
	v_add_f32_e32 v134, v134, v135
	ds_bpermute_b32 v135, v191, v134
	s_waitcnt lgkmcnt(0)
	v_add_f32_e32 v134, v134, v135
	v_fmamk_f32 v134, v134, 0x3a800000, v243
	s_nop 1
	s_mov_b64 s[0:1], 0x90
	v_lshl_add_u64 v[162:163], v[130:131], 0, s[0:1]
	v_lshlrev_b64 v[160:161], 6, v[162:163]
	v_rsq_f32_e32 v208, v134
	s_nop 0
	v_lshl_add_u64 v[134:135], v[132:133], 0, v[176:177]
	global_load_dwordx4 v[134:137], v[134:135], off
	s_mov_b64 s[0:1], 0xa0
	v_lshl_add_u64 v[158:159], v[130:131], 0, s[0:1]
	v_lshlrev_b64 v[156:157], 6, v[158:159]
	s_mov_b64 s[0:1], 0xb0
	v_lshl_add_u64 v[152:153], v[130:131], 0, s[0:1]
	v_lshlrev_b64 v[150:151], 6, v[152:153]
	s_lshl_b32 s0, s4, 8
	s_ashr_i32 s1, s0, 31
	s_or_b64 s[0:1], s[0:1], s[62:63]
	v_lshlrev_b64 v[130:131], 10, v[130:131]
	v_mul_f32_e32 v126, v126, v208
	v_mul_f32_e32 v127, v127, v208
	v_mul_f32_e32 v128, v128, v208
	v_mul_f32_e32 v129, v129, v208
	v_mul_f32_e32 v126, 0xbfb8aa3b, v126
	v_mul_f32_e32 v127, 0xbfb8aa3b, v127
	v_mul_f32_e32 v128, 0xbfb8aa3b, v128
	v_mul_f32_e32 v124, v124, v208
	v_mul_f32_e32 v129, 0xbfb8aa3b, v129
	v_mul_f32_e32 v125, v125, v208
	v_exp_f32_e32 v126, v126
	v_mul_f32_e32 v122, v122, v208
	v_exp_f32_e32 v127, v127
	v_mul_f32_e32 v123, v123, v208
	v_exp_f32_e32 v128, v128
	v_mul_f32_e32 v124, 0xbfb8aa3b, v124
	v_exp_f32_e32 v129, v129
	v_mul_f32_e32 v125, 0xbfb8aa3b, v125
	v_mul_f32_e32 v122, 0xbfb8aa3b, v122
	v_mul_f32_e32 v123, 0xbfb8aa3b, v123
	v_exp_f32_e32 v124, v124
	v_exp_f32_e32 v125, v125
	v_exp_f32_e32 v122, v122
	v_exp_f32_e32 v123, v123
	v_add_f32_e32 v126, 1.0, v126
	v_add_f32_e32 v127, 1.0, v127
	v_add_f32_e32 v128, 1.0, v128
	v_add_f32_e32 v129, 1.0, v129
	v_rcp_f32_e32 v126, v126
	v_rcp_f32_e32 v127, v127
	v_rcp_f32_e32 v128, v128
	v_add_f32_e32 v124, 1.0, v124
	v_rcp_f32_e32 v129, v129
	v_add_f32_e32 v125, 1.0, v125
	v_add_f32_e32 v122, 1.0, v122
	v_add_f32_e32 v123, 1.0, v123
	v_rcp_f32_e32 v124, v124
	v_rcp_f32_e32 v125, v125
	v_rcp_f32_e32 v122, v122
	v_rcp_f32_e32 v123, v123
	s_andn2_b64 vcc, exec, s[68:69]
	s_waitcnt vmcnt(0)
	v_add_f32_e32 v134, v134, v135
	v_add_f32_e32 v135, v136, v137
	v_add_f32_e32 v134, v134, v135
	ds_bpermute_b32 v135, v192, v134
	s_waitcnt lgkmcnt(0)
	v_add_f32_e32 v206, v134, v135
	v_lshl_add_u64 v[134:135], v[132:133], 0, v[172:173]
	global_load_dwordx4 v[134:137], v[134:135], off
	ds_bpermute_b32 v207, v191, v206
	s_waitcnt vmcnt(0)
	v_add_f32_e32 v134, v134, v135
	v_add_f32_e32 v135, v136, v137
	v_add_f32_e32 v134, v134, v135
	ds_bpermute_b32 v135, v192, v134
	s_waitcnt lgkmcnt(0)
	v_add_f32_e32 v203, v134, v135
	v_lshl_add_u64 v[134:135], v[132:133], 0, v[168:169]
	global_load_dwordx4 v[134:137], v[134:135], off
	ds_bpermute_b32 v204, v191, v203
	s_waitcnt vmcnt(0)
	v_add_f32_e32 v134, v134, v135
	v_add_f32_e32 v135, v136, v137
	v_add_f32_e32 v134, v134, v135
	ds_bpermute_b32 v135, v192, v134
	s_waitcnt lgkmcnt(0)
	v_add_f32_e32 v201, v134, v135
	v_lshl_add_u64 v[134:135], v[132:133], 0, v[164:165]
	global_load_dwordx4 v[134:137], v[134:135], off
	ds_bpermute_b32 v202, v191, v201
	s_waitcnt vmcnt(0)
	v_add_f32_e32 v134, v134, v135
	v_add_f32_e32 v135, v136, v137
	v_add_f32_e32 v134, v134, v135
	ds_bpermute_b32 v135, v192, v134
	s_waitcnt lgkmcnt(0)
	v_add_f32_e32 v199, v134, v135
	v_lshl_add_u64 v[134:135], v[132:133], 0, v[160:161]
	global_load_dwordx4 v[134:137], v[134:135], off
	ds_bpermute_b32 v200, v191, v199
	s_waitcnt vmcnt(0)
	v_add_f32_e32 v134, v134, v135
	v_add_f32_e32 v135, v136, v137
	v_add_f32_e32 v134, v134, v135
	ds_bpermute_b32 v135, v192, v134
	s_waitcnt lgkmcnt(0)
	v_add_f32_e32 v197, v134, v135
	v_lshl_add_u64 v[134:135], v[132:133], 0, v[156:157]
	global_load_dwordx4 v[134:137], v[134:135], off
	v_lshl_add_u64 v[132:133], v[132:133], 0, v[150:151]
	ds_bpermute_b32 v198, v191, v197
	s_waitcnt vmcnt(0)
	v_add_f32_e32 v134, v134, v135
	v_add_f32_e32 v135, v136, v137
	v_add_f32_e32 v134, v134, v135
	ds_bpermute_b32 v135, v192, v134
	s_waitcnt lgkmcnt(0)
	v_add_f32_e32 v195, v134, v135
	global_load_dwordx4 v[132:135], v[132:133], off
	ds_bpermute_b32 v196, v191, v195
	s_waitcnt vmcnt(0)
	v_add_f32_e32 v132, v132, v133
	v_add_f32_e32 v133, v134, v135
	v_add_f32_e32 v132, v132, v133
	ds_bpermute_b32 v133, v192, v132
	s_waitcnt lgkmcnt(0)
	v_add_f32_e32 v193, v132, v133
	v_lshlrev_b32_e32 v132, 3, v205
	v_ashrrev_i32_e32 v133, 31, v132
	v_lshl_add_u64 v[154:155], s[0:1], 0, v[132:133]
	v_lshl_add_u64 v[186:187], v[154:155], 0, v[130:131]
	v_lshlrev_b64 v[134:135], 1, v[186:187]
	v_lshl_add_u64 v[182:183], s[20:21], 0, v[134:135]
	v_lshl_add_u64 v[184:185], s[22:23], 0, v[134:135]
	global_load_dwordx4 v[130:133], v[182:183], off
	global_load_dwordx4 v[134:137], v[184:185], off
	ds_bpermute_b32 v194, v191, v193
	s_waitcnt vmcnt(1)
	v_lshlrev_b32_e32 v210, 16, v130
	v_and_b32_e32 v211, 0xffff0000, v130
	s_waitcnt vmcnt(0)
	v_lshlrev_b32_e32 v212, 16, v134
	v_and_b32_e32 v213, 0xffff0000, v134
	v_lshlrev_b32_e32 v130, 16, v131
	v_and_b32_e32 v131, 0xffff0000, v131
	v_lshlrev_b32_e32 v134, 16, v135
	v_and_b32_e32 v135, 0xffff0000, v135
	v_pk_fma_f32 v[126:127], v[126:127], v[210:211], v[212:213]
	v_lshlrev_b32_e32 v210, 16, v132
	v_and_b32_e32 v211, 0xffff0000, v132
	v_pk_fma_f32 v[128:129], v[128:129], v[130:131], v[134:135]
	v_lshlrev_b32_e32 v130, 16, v133
	v_and_b32_e32 v131, 0xffff0000, v133
	v_lshlrev_b32_e32 v132, 16, v137
	v_and_b32_e32 v133, 0xffff0000, v137
	v_lshlrev_b32_e32 v212, 16, v136
	v_and_b32_e32 v213, 0xffff0000, v136
	v_pk_fma_f32 v[124:125], v[124:125], v[130:131], v[132:133]
	v_cndmask_b32_e64 v130, 0, 1, s[68:69]
	v_pk_fma_f32 v[122:123], v[122:123], v[210:211], v[212:213]
	v_cmp_ne_u32_e64 s[42:43], 1, v130
	v_lshl_add_u64 v[134:135], v[186:187], 2, s[54:55]
	s_cbranch_vccnz .LBB0_1268
	global_store_dwordx4 v[134:135], v[126:129], off sc0 sc1
	global_store_dwordx4 v[134:135], v[122:125], off offset:16 sc0 sc1
	s_cbranch_execnz .LBB0_1188
.LBB0_1187:
	v_cvt_pk_bf16_f32 v130, v126, v127
	v_cvt_pk_bf16_f32 v131, v128, v129
	v_cvt_pk_bf16_f32 v132, v122, v123
	v_cvt_pk_bf16_f32 v133, v124, v125
	global_store_dwordx4 v[182:183], v[130:133], off sc0 sc1
.LBB0_1188:
	global_load_dwordx4 v[212:215], v[182:183], off offset:256
	s_nop 0
	global_load_dwordx4 v[130:133], v[184:185], off offset:256
	v_mul_f32_e32 v118, v118, v208
	v_mul_f32_e32 v119, v119, v208
	v_mul_f32_e32 v118, 0xbfb8aa3b, v118
	v_mul_f32_e32 v114, v114, v208
	v_mul_f32_e32 v119, 0xbfb8aa3b, v119
	v_mul_f32_e32 v115, v115, v208
	v_exp_f32_e32 v118, v118
	v_mul_f32_e32 v114, 0xbfb8aa3b, v114
	v_exp_f32_e32 v119, v119
	v_mul_f32_e32 v115, 0xbfb8aa3b, v115
	v_mul_f32_e32 v120, v120, v208
	v_mul_f32_e32 v121, v121, v208
	v_exp_f32_e32 v114, v114
	v_exp_f32_e32 v115, v115
	v_mul_f32_e32 v120, 0xbfb8aa3b, v120
	v_mul_f32_e32 v116, v116, v208
	v_mul_f32_e32 v121, 0xbfb8aa3b, v121
	v_mul_f32_e32 v117, v117, v208
	v_exp_f32_e32 v120, v120
	v_mul_f32_e32 v116, 0xbfb8aa3b, v116
	v_exp_f32_e32 v121, v121
	v_mul_f32_e32 v117, 0xbfb8aa3b, v117
	v_exp_f32_e32 v116, v116
	v_exp_f32_e32 v117, v117
	v_add_f32_e32 v118, 1.0, v118
	v_add_f32_e32 v119, 1.0, v119
	v_rcp_f32_e32 v118, v118
	v_add_f32_e32 v114, 1.0, v114
	v_rcp_f32_e32 v119, v119
	v_add_f32_e32 v115, 1.0, v115
	v_rcp_f32_e32 v114, v114
	v_rcp_f32_e32 v115, v115
	v_add_f32_e32 v120, 1.0, v120
	v_add_f32_e32 v121, 1.0, v121
	v_rcp_f32_e32 v120, v120
	v_add_f32_e32 v116, 1.0, v116
	v_rcp_f32_e32 v121, v121
	v_add_f32_e32 v117, 1.0, v117
	v_rcp_f32_e32 v116, v116
	v_rcp_f32_e32 v117, v117
	s_and_b64 vcc, exec, s[42:43]
	s_waitcnt vmcnt(1)
	v_lshlrev_b32_e32 v136, 16, v212
	v_and_b32_e32 v137, 0xffff0000, v212
	s_waitcnt vmcnt(0)
	v_lshlrev_b32_e32 v184, 16, v130
	v_and_b32_e32 v185, 0xffff0000, v130
	v_pk_fma_f32 v[118:119], v[118:119], v[136:137], v[184:185]
	v_lshlrev_b32_e32 v136, 16, v214
	v_and_b32_e32 v137, 0xffff0000, v214
	v_lshlrev_b32_e32 v184, 16, v132
	v_and_b32_e32 v185, 0xffff0000, v132
	v_pk_fma_f32 v[114:115], v[114:115], v[136:137], v[184:185]
	v_lshlrev_b32_e32 v136, 16, v213
	v_and_b32_e32 v137, 0xffff0000, v213
	v_lshlrev_b32_e32 v130, 16, v131
	v_and_b32_e32 v131, 0xffff0000, v131
	v_pk_fma_f32 v[120:121], v[120:121], v[136:137], v[130:131]
	v_lshlrev_b32_e32 v130, 16, v215
	v_and_b32_e32 v131, 0xffff0000, v215
	v_lshlrev_b32_e32 v132, 16, v133
	v_and_b32_e32 v133, 0xffff0000, v133
	v_pk_fma_f32 v[116:117], v[116:117], v[130:131], v[132:133]
	s_cbranch_vccnz .LBB0_1269
	global_store_dwordx4 v[134:135], v[118:121], off offset:512 sc0 sc1
	global_store_dwordx4 v[134:135], v[114:117], off offset:528 sc0 sc1
	s_cbranch_execnz .LBB0_1191
.LBB0_1190:
	v_cvt_pk_bf16_f32 v130, v118, v119
	v_cvt_pk_bf16_f32 v131, v120, v121
	v_cvt_pk_bf16_f32 v132, v114, v115
	v_cvt_pk_bf16_f32 v133, v116, v117
	global_store_dwordx4 v[182:183], v[130:133], off offset:256 sc0 sc1

.LBB0_1195:
	v_add_f32_e32 v114, v206, v207
	v_fmamk_f32 v114, v114, 0x3a800000, v243
	s_waitcnt lgkmcnt(0)
	v_rsq_f32_e32 v128, v114
	s_nop 0
	v_lshlrev_b64 v[114:115], 10, v[180:181]
	v_lshl_add_u64 v[126:127], v[114:115], 0, v[154:155]
	v_lshlrev_b64 v[114:115], 1, v[126:127]
	v_lshl_add_u64 v[122:123], s[20:21], 0, v[114:115]
	v_lshl_add_u64 v[124:125], s[22:23], 0, v[114:115]
	global_load_dwordx4 v[118:121], v[122:123], off
	global_load_dwordx4 v[114:117], v[124:125], off
	v_mul_f32_e32 v110, v110, v128
	v_mul_f32_e32 v111, v111, v128
	v_mul_f32_e32 v112, v112, v128
	v_mul_f32_e32 v113, v113, v128
	v_mul_f32_e32 v110, 0xbfb8aa3b, v110
	v_mul_f32_e32 v106, v106, v128
	v_mul_f32_e32 v111, 0xbfb8aa3b, v111
	v_mul_f32_e32 v107, v107, v128
	v_mul_f32_e32 v112, 0xbfb8aa3b, v112
	v_mul_f32_e32 v108, v108, v128
	v_mul_f32_e32 v113, 0xbfb8aa3b, v113
	v_mul_f32_e32 v109, v109, v128
	v_exp_f32_e32 v110, v110
	v_mul_f32_e32 v106, 0xbfb8aa3b, v106
	v_exp_f32_e32 v111, v111
	v_mul_f32_e32 v107, 0xbfb8aa3b, v107
	v_exp_f32_e32 v112, v112
	v_mul_f32_e32 v108, 0xbfb8aa3b, v108
	v_exp_f32_e32 v113, v113
	v_mul_f32_e32 v109, 0xbfb8aa3b, v109
	v_exp_f32_e32 v106, v106
	v_exp_f32_e32 v107, v107
	v_exp_f32_e32 v108, v108
	v_exp_f32_e32 v109, v109
	v_add_f32_e32 v110, 1.0, v110
	v_add_f32_e32 v111, 1.0, v111
	v_add_f32_e32 v112, 1.0, v112
	v_add_f32_e32 v113, 1.0, v113
	v_rcp_f32_e32 v110, v110
	v_add_f32_e32 v106, 1.0, v106
	v_rcp_f32_e32 v111, v111
	v_add_f32_e32 v107, 1.0, v107
	v_rcp_f32_e32 v112, v112
	v_add_f32_e32 v108, 1.0, v108
	v_rcp_f32_e32 v113, v113
	v_add_f32_e32 v109, 1.0, v109
	v_rcp_f32_e32 v106, v106
	v_rcp_f32_e32 v107, v107
	v_rcp_f32_e32 v108, v108
	v_rcp_f32_e32 v109, v109
	s_and_b64 vcc, exec, s[42:43]
	s_waitcnt vmcnt(1)
	v_lshlrev_b32_e32 v130, 16, v118
	v_and_b32_e32 v131, 0xffff0000, v118
	s_waitcnt vmcnt(0)
	v_lshlrev_b32_e32 v132, 16, v114
	v_and_b32_e32 v133, 0xffff0000, v114
	v_lshlrev_b32_e32 v118, 16, v119
	v_and_b32_e32 v119, 0xffff0000, v119
	v_lshlrev_b32_e32 v114, 16, v115
	v_and_b32_e32 v115, 0xffff0000, v115
	v_pk_fma_f32 v[110:111], v[110:111], v[130:131], v[132:133]
	v_lshlrev_b32_e32 v130, 16, v120
	v_and_b32_e32 v131, 0xffff0000, v120
	v_lshlrev_b32_e32 v132, 16, v116
	v_and_b32_e32 v133, 0xffff0000, v116
	v_pk_fma_f32 v[112:113], v[112:113], v[118:119], v[114:115]
	v_lshlrev_b32_e32 v114, 16, v121
	v_and_b32_e32 v115, 0xffff0000, v121
	v_lshlrev_b32_e32 v116, 16, v117
	v_and_b32_e32 v117, 0xffff0000, v117
	v_pk_fma_f32 v[106:107], v[106:107], v[130:131], v[132:133]
	v_pk_fma_f32 v[108:109], v[108:109], v[114:115], v[116:117]
	v_lshl_add_u64 v[118:119], v[126:127], 2, s[54:55]
	s_cbranch_vccnz .LBB0_1270
	global_store_dwordx4 v[118:119], v[110:113], off sc0 sc1
	global_store_dwordx4 v[118:119], v[106:109], off offset:16 sc0 sc1
	s_cbranch_execnz .LBB0_1198
.LBB0_1197:
	v_cvt_pk_bf16_f32 v114, v110, v111
	v_cvt_pk_bf16_f32 v115, v112, v113
	v_cvt_pk_bf16_f32 v116, v106, v107
	v_cvt_pk_bf16_f32 v117, v108, v109
	global_store_dwordx4 v[122:123], v[114:117], off sc0 sc1
.LBB0_1198:
	global_load_dwordx4 v[130:133], v[122:123], off offset:256
	s_nop 0
	global_load_dwordx4 v[114:117], v[124:125], off offset:256
	v_mul_f32_e32 v102, v102, v128
	v_mul_f32_e32 v103, v103, v128
	v_mul_f32_e32 v102, 0xbfb8aa3b, v102
	v_mul_f32_e32 v98, v98, v128
	v_mul_f32_e32 v103, 0xbfb8aa3b, v103
	v_mul_f32_e32 v99, v99, v128
	v_exp_f32_e32 v102, v102
	v_mul_f32_e32 v98, 0xbfb8aa3b, v98
	v_exp_f32_e32 v103, v103
	v_mul_f32_e32 v99, 0xbfb8aa3b, v99
	v_mul_f32_e32 v104, v104, v128
	v_mul_f32_e32 v105, v105, v128
	v_exp_f32_e32 v98, v98
	v_exp_f32_e32 v99, v99
	v_mul_f32_e32 v104, 0xbfb8aa3b, v104
	v_mul_f32_e32 v100, v100, v128
	v_mul_f32_e32 v105, 0xbfb8aa3b, v105
	v_mul_f32_e32 v101, v101, v128
	v_exp_f32_e32 v104, v104
	v_mul_f32_e32 v100, 0xbfb8aa3b, v100
	v_exp_f32_e32 v105, v105
	v_mul_f32_e32 v101, 0xbfb8aa3b, v101
	v_exp_f32_e32 v100, v100
	v_exp_f32_e32 v101, v101
	v_add_f32_e32 v102, 1.0, v102
	v_add_f32_e32 v103, 1.0, v103
	v_rcp_f32_e32 v102, v102
	v_add_f32_e32 v98, 1.0, v98
	v_rcp_f32_e32 v103, v103
	v_add_f32_e32 v99, 1.0, v99
	v_rcp_f32_e32 v98, v98
	v_rcp_f32_e32 v99, v99
	v_add_f32_e32 v104, 1.0, v104
	v_add_f32_e32 v105, 1.0, v105
	v_rcp_f32_e32 v104, v104
	v_add_f32_e32 v100, 1.0, v100
	v_rcp_f32_e32 v105, v105
	v_add_f32_e32 v101, 1.0, v101
	v_rcp_f32_e32 v100, v100
	v_rcp_f32_e32 v101, v101
	s_and_b64 vcc, exec, s[42:43]
	s_waitcnt vmcnt(1)
	v_lshlrev_b32_e32 v120, 16, v130
	v_and_b32_e32 v121, 0xffff0000, v130
	s_waitcnt vmcnt(0)
	v_lshlrev_b32_e32 v124, 16, v114
	v_and_b32_e32 v125, 0xffff0000, v114
	v_pk_fma_f32 v[102:103], v[102:103], v[120:121], v[124:125]
	v_lshlrev_b32_e32 v120, 16, v132
	v_and_b32_e32 v121, 0xffff0000, v132
	v_lshlrev_b32_e32 v124, 16, v116
	v_and_b32_e32 v125, 0xffff0000, v116
	v_pk_fma_f32 v[98:99], v[98:99], v[120:121], v[124:125]
	v_lshlrev_b32_e32 v120, 16, v131
	v_and_b32_e32 v121, 0xffff0000, v131
	v_lshlrev_b32_e32 v114, 16, v115
	v_and_b32_e32 v115, 0xffff0000, v115
	v_pk_fma_f32 v[104:105], v[104:105], v[120:121], v[114:115]
	v_lshlrev_b32_e32 v114, 16, v133
	v_and_b32_e32 v115, 0xffff0000, v133
	v_lshlrev_b32_e32 v116, 16, v117
	v_and_b32_e32 v117, 0xffff0000, v117
	v_pk_fma_f32 v[100:101], v[100:101], v[114:115], v[116:117]
	s_cbranch_vccnz .LBB0_1271
	global_store_dwordx4 v[118:119], v[102:105], off offset:512 sc0 sc1
	global_store_dwordx4 v[118:119], v[98:101], off offset:528 sc0 sc1
	s_cbranch_execnz .LBB0_1201
.LBB0_1200:
	v_cvt_pk_bf16_f32 v114, v102, v103
	v_cvt_pk_bf16_f32 v115, v104, v105
	v_cvt_pk_bf16_f32 v116, v98, v99
	v_cvt_pk_bf16_f32 v117, v100, v101
	global_store_dwordx4 v[122:123], v[114:117], off offset:256 sc0 sc1

.LBB0_1205:
	v_add_f32_e32 v98, v203, v204
	v_fmamk_f32 v98, v98, 0x3a800000, v243
	s_waitcnt lgkmcnt(0)
	v_rsq_f32_e32 v112, v98
	s_nop 0
	v_lshlrev_b64 v[98:99], 10, v[174:175]
	v_lshl_add_u64 v[110:111], v[98:99], 0, v[154:155]
	v_lshlrev_b64 v[98:99], 1, v[110:111]
	v_lshl_add_u64 v[106:107], s[20:21], 0, v[98:99]
	v_lshl_add_u64 v[108:109], s[22:23], 0, v[98:99]
	global_load_dwordx4 v[102:105], v[106:107], off
	global_load_dwordx4 v[98:101], v[108:109], off
	v_mul_f32_e32 v94, v94, v112
	v_mul_f32_e32 v95, v95, v112
	v_mul_f32_e32 v96, v96, v112
	v_mul_f32_e32 v97, v97, v112
	v_mul_f32_e32 v94, 0xbfb8aa3b, v94
	v_mul_f32_e32 v90, v90, v112
	v_mul_f32_e32 v95, 0xbfb8aa3b, v95
	v_mul_f32_e32 v91, v91, v112
	v_mul_f32_e32 v96, 0xbfb8aa3b, v96
	v_mul_f32_e32 v92, v92, v112
	v_mul_f32_e32 v97, 0xbfb8aa3b, v97
	v_mul_f32_e32 v93, v93, v112
	v_exp_f32_e32 v94, v94
	v_mul_f32_e32 v90, 0xbfb8aa3b, v90
	v_exp_f32_e32 v95, v95
	v_mul_f32_e32 v91, 0xbfb8aa3b, v91
	v_exp_f32_e32 v96, v96
	v_mul_f32_e32 v92, 0xbfb8aa3b, v92
	v_exp_f32_e32 v97, v97
	v_mul_f32_e32 v93, 0xbfb8aa3b, v93
	v_exp_f32_e32 v90, v90
	v_exp_f32_e32 v91, v91
	v_exp_f32_e32 v92, v92
	v_exp_f32_e32 v93, v93
	v_add_f32_e32 v94, 1.0, v94
	v_add_f32_e32 v95, 1.0, v95
	v_add_f32_e32 v96, 1.0, v96
	v_add_f32_e32 v97, 1.0, v97
	v_rcp_f32_e32 v94, v94
	v_add_f32_e32 v90, 1.0, v90
	v_rcp_f32_e32 v95, v95
	v_add_f32_e32 v91, 1.0, v91
	v_rcp_f32_e32 v96, v96
	v_add_f32_e32 v92, 1.0, v92
	v_rcp_f32_e32 v97, v97
	v_add_f32_e32 v93, 1.0, v93
	v_rcp_f32_e32 v90, v90
	v_rcp_f32_e32 v91, v91
	v_rcp_f32_e32 v92, v92
	v_rcp_f32_e32 v93, v93
	s_and_b64 vcc, exec, s[42:43]
	s_waitcnt vmcnt(1)
	v_lshlrev_b32_e32 v114, 16, v102
	v_and_b32_e32 v115, 0xffff0000, v102
	s_waitcnt vmcnt(0)
	v_lshlrev_b32_e32 v116, 16, v98
	v_and_b32_e32 v117, 0xffff0000, v98
	v_lshlrev_b32_e32 v102, 16, v103
	v_and_b32_e32 v103, 0xffff0000, v103
	v_lshlrev_b32_e32 v98, 16, v99
	v_and_b32_e32 v99, 0xffff0000, v99
	v_pk_fma_f32 v[94:95], v[94:95], v[114:115], v[116:117]
	v_lshlrev_b32_e32 v114, 16, v104
	v_and_b32_e32 v115, 0xffff0000, v104
	v_lshlrev_b32_e32 v116, 16, v100
	v_and_b32_e32 v117, 0xffff0000, v100
	v_pk_fma_f32 v[96:97], v[96:97], v[102:103], v[98:99]
	v_lshlrev_b32_e32 v98, 16, v105
	v_and_b32_e32 v99, 0xffff0000, v105
	v_lshlrev_b32_e32 v100, 16, v101
	v_and_b32_e32 v101, 0xffff0000, v101
	v_pk_fma_f32 v[90:91], v[90:91], v[114:115], v[116:117]
	v_pk_fma_f32 v[92:93], v[92:93], v[98:99], v[100:101]
	v_lshl_add_u64 v[102:103], v[110:111], 2, s[54:55]
	s_cbranch_vccnz .LBB0_1272
	global_store_dwordx4 v[102:103], v[94:97], off sc0 sc1
	global_store_dwordx4 v[102:103], v[90:93], off offset:16 sc0 sc1
	s_cbranch_execnz .LBB0_1208
.LBB0_1207:
	v_cvt_pk_bf16_f32 v98, v94, v95
	v_cvt_pk_bf16_f32 v99, v96, v97
	v_cvt_pk_bf16_f32 v100, v90, v91
	v_cvt_pk_bf16_f32 v101, v92, v93
	global_store_dwordx4 v[106:107], v[98:101], off sc0 sc1
.LBB0_1208:
	global_load_dwordx4 v[114:117], v[106:107], off offset:256
	s_nop 0
	global_load_dwordx4 v[98:101], v[108:109], off offset:256
	v_mul_f32_e32 v86, v86, v112
	v_mul_f32_e32 v87, v87, v112
	v_mul_f32_e32 v86, 0xbfb8aa3b, v86
	v_mul_f32_e32 v82, v82, v112
	v_mul_f32_e32 v87, 0xbfb8aa3b, v87
	v_mul_f32_e32 v83, v83, v112
	v_exp_f32_e32 v86, v86
	v_mul_f32_e32 v82, 0xbfb8aa3b, v82
	v_exp_f32_e32 v87, v87
	v_mul_f32_e32 v83, 0xbfb8aa3b, v83
	v_mul_f32_e32 v88, v88, v112
	v_mul_f32_e32 v89, v89, v112
	v_exp_f32_e32 v82, v82
	v_exp_f32_e32 v83, v83
	v_mul_f32_e32 v88, 0xbfb8aa3b, v88
	v_mul_f32_e32 v84, v84, v112
	v_mul_f32_e32 v89, 0xbfb8aa3b, v89
	v_mul_f32_e32 v85, v85, v112
	v_exp_f32_e32 v88, v88
	v_mul_f32_e32 v84, 0xbfb8aa3b, v84
	v_exp_f32_e32 v89, v89
	v_mul_f32_e32 v85, 0xbfb8aa3b, v85
	v_exp_f32_e32 v84, v84
	v_exp_f32_e32 v85, v85
	v_add_f32_e32 v86, 1.0, v86
	v_add_f32_e32 v87, 1.0, v87
	v_rcp_f32_e32 v86, v86
	v_add_f32_e32 v82, 1.0, v82
	v_rcp_f32_e32 v87, v87
	v_add_f32_e32 v83, 1.0, v83
	v_rcp_f32_e32 v82, v82
	v_rcp_f32_e32 v83, v83
	v_add_f32_e32 v88, 1.0, v88
	v_add_f32_e32 v89, 1.0, v89
	v_rcp_f32_e32 v88, v88
	v_add_f32_e32 v84, 1.0, v84
	v_rcp_f32_e32 v89, v89
	v_add_f32_e32 v85, 1.0, v85
	v_rcp_f32_e32 v84, v84
	v_rcp_f32_e32 v85, v85
	s_and_b64 vcc, exec, s[42:43]
	s_waitcnt vmcnt(1)
	v_lshlrev_b32_e32 v104, 16, v114
	v_and_b32_e32 v105, 0xffff0000, v114
	s_waitcnt vmcnt(0)
	v_lshlrev_b32_e32 v108, 16, v98
	v_and_b32_e32 v109, 0xffff0000, v98
	v_pk_fma_f32 v[86:87], v[86:87], v[104:105], v[108:109]
	v_lshlrev_b32_e32 v104, 16, v116
	v_and_b32_e32 v105, 0xffff0000, v116
	v_lshlrev_b32_e32 v108, 16, v100
	v_and_b32_e32 v109, 0xffff0000, v100
	v_pk_fma_f32 v[82:83], v[82:83], v[104:105], v[108:109]
	v_lshlrev_b32_e32 v104, 16, v115
	v_and_b32_e32 v105, 0xffff0000, v115
	v_lshlrev_b32_e32 v98, 16, v99
	v_and_b32_e32 v99, 0xffff0000, v99
	v_pk_fma_f32 v[88:89], v[88:89], v[104:105], v[98:99]
	v_lshlrev_b32_e32 v98, 16, v117
	v_and_b32_e32 v99, 0xffff0000, v117
	v_lshlrev_b32_e32 v100, 16, v101
	v_and_b32_e32 v101, 0xffff0000, v101
	v_pk_fma_f32 v[84:85], v[84:85], v[98:99], v[100:101]
	s_cbranch_vccnz .LBB0_1273
	global_store_dwordx4 v[102:103], v[86:89], off offset:512 sc0 sc1
	global_store_dwordx4 v[102:103], v[82:85], off offset:528 sc0 sc1
	s_cbranch_execnz .LBB0_1211
.LBB0_1210:
	v_cvt_pk_bf16_f32 v98, v86, v87
	v_cvt_pk_bf16_f32 v99, v88, v89
	v_cvt_pk_bf16_f32 v100, v82, v83
	v_cvt_pk_bf16_f32 v101, v84, v85
	global_store_dwordx4 v[106:107], v[98:101], off offset:256 sc0 sc1

.LBB0_1215:
	v_add_f32_e32 v82, v201, v202
	v_fmamk_f32 v82, v82, 0x3a800000, v243
	s_waitcnt lgkmcnt(0)
	v_rsq_f32_e32 v96, v82
	s_nop 0
	v_lshlrev_b64 v[82:83], 10, v[170:171]
	v_lshl_add_u64 v[94:95], v[82:83], 0, v[154:155]
	v_lshlrev_b64 v[82:83], 1, v[94:95]
	v_lshl_add_u64 v[90:91], s[20:21], 0, v[82:83]
	v_lshl_add_u64 v[92:93], s[22:23], 0, v[82:83]
	global_load_dwordx4 v[86:89], v[90:91], off
	global_load_dwordx4 v[82:85], v[92:93], off
	v_mul_f32_e32 v78, v78, v96
	v_mul_f32_e32 v79, v79, v96
	v_mul_f32_e32 v80, v80, v96
	v_mul_f32_e32 v81, v81, v96
	v_mul_f32_e32 v78, 0xbfb8aa3b, v78
	v_mul_f32_e32 v74, v74, v96
	v_mul_f32_e32 v79, 0xbfb8aa3b, v79
	v_mul_f32_e32 v75, v75, v96
	v_mul_f32_e32 v80, 0xbfb8aa3b, v80
	v_mul_f32_e32 v76, v76, v96
	v_mul_f32_e32 v81, 0xbfb8aa3b, v81
	v_mul_f32_e32 v77, v77, v96
	v_exp_f32_e32 v78, v78
	v_mul_f32_e32 v74, 0xbfb8aa3b, v74
	v_exp_f32_e32 v79, v79
	v_mul_f32_e32 v75, 0xbfb8aa3b, v75
	v_exp_f32_e32 v80, v80
	v_mul_f32_e32 v76, 0xbfb8aa3b, v76
	v_exp_f32_e32 v81, v81
	v_mul_f32_e32 v77, 0xbfb8aa3b, v77
	v_exp_f32_e32 v74, v74
	v_exp_f32_e32 v75, v75
	v_exp_f32_e32 v76, v76
	v_exp_f32_e32 v77, v77
	v_add_f32_e32 v78, 1.0, v78
	v_add_f32_e32 v79, 1.0, v79
	v_add_f32_e32 v80, 1.0, v80
	v_add_f32_e32 v81, 1.0, v81
	v_rcp_f32_e32 v78, v78
	v_add_f32_e32 v74, 1.0, v74
	v_rcp_f32_e32 v79, v79
	v_add_f32_e32 v75, 1.0, v75
	v_rcp_f32_e32 v80, v80
	v_add_f32_e32 v76, 1.0, v76
	v_rcp_f32_e32 v81, v81
	v_add_f32_e32 v77, 1.0, v77
	v_rcp_f32_e32 v74, v74
	v_rcp_f32_e32 v75, v75
	v_rcp_f32_e32 v76, v76
	v_rcp_f32_e32 v77, v77
	s_and_b64 vcc, exec, s[42:43]
	s_waitcnt vmcnt(1)
	v_lshlrev_b32_e32 v98, 16, v86
	v_and_b32_e32 v99, 0xffff0000, v86
	s_waitcnt vmcnt(0)
	v_lshlrev_b32_e32 v100, 16, v82
	v_and_b32_e32 v101, 0xffff0000, v82
	v_lshlrev_b32_e32 v86, 16, v87
	v_and_b32_e32 v87, 0xffff0000, v87
	v_lshlrev_b32_e32 v82, 16, v83
	v_and_b32_e32 v83, 0xffff0000, v83
	v_pk_fma_f32 v[78:79], v[78:79], v[98:99], v[100:101]
	v_lshlrev_b32_e32 v98, 16, v88
	v_and_b32_e32 v99, 0xffff0000, v88
	v_lshlrev_b32_e32 v100, 16, v84
	v_and_b32_e32 v101, 0xffff0000, v84
	v_pk_fma_f32 v[80:81], v[80:81], v[86:87], v[82:83]
	v_lshlrev_b32_e32 v82, 16, v89
	v_and_b32_e32 v83, 0xffff0000, v89
	v_lshlrev_b32_e32 v84, 16, v85
	v_and_b32_e32 v85, 0xffff0000, v85
	v_pk_fma_f32 v[74:75], v[74:75], v[98:99], v[100:101]
	v_pk_fma_f32 v[76:77], v[76:77], v[82:83], v[84:85]
	v_lshl_add_u64 v[86:87], v[94:95], 2, s[54:55]
	s_cbranch_vccnz .LBB0_1274
	global_store_dwordx4 v[86:87], v[78:81], off sc0 sc1
	global_store_dwordx4 v[86:87], v[74:77], off offset:16 sc0 sc1
	s_cbranch_execnz .LBB0_1218
.LBB0_1217:
	v_cvt_pk_bf16_f32 v82, v78, v79
	v_cvt_pk_bf16_f32 v83, v80, v81
	v_cvt_pk_bf16_f32 v84, v74, v75
	v_cvt_pk_bf16_f32 v85, v76, v77
	global_store_dwordx4 v[90:91], v[82:85], off sc0 sc1
.LBB0_1218:
	global_load_dwordx4 v[98:101], v[90:91], off offset:256
	s_nop 0
	global_load_dwordx4 v[82:85], v[92:93], off offset:256
	v_mul_f32_e32 v70, v70, v96
	v_mul_f32_e32 v71, v71, v96
	v_mul_f32_e32 v70, 0xbfb8aa3b, v70
	v_mul_f32_e32 v66, v66, v96
	v_mul_f32_e32 v71, 0xbfb8aa3b, v71
	v_mul_f32_e32 v67, v67, v96
	v_exp_f32_e32 v70, v70
	v_mul_f32_e32 v66, 0xbfb8aa3b, v66
	v_exp_f32_e32 v71, v71
	v_mul_f32_e32 v67, 0xbfb8aa3b, v67
	v_mul_f32_e32 v72, v72, v96
	v_mul_f32_e32 v73, v73, v96
	v_exp_f32_e32 v66, v66
	v_exp_f32_e32 v67, v67
	v_mul_f32_e32 v72, 0xbfb8aa3b, v72
	v_mul_f32_e32 v68, v68, v96
	v_mul_f32_e32 v73, 0xbfb8aa3b, v73
	v_mul_f32_e32 v69, v69, v96
	v_exp_f32_e32 v72, v72
	v_mul_f32_e32 v68, 0xbfb8aa3b, v68
	v_exp_f32_e32 v73, v73
	v_mul_f32_e32 v69, 0xbfb8aa3b, v69
	v_exp_f32_e32 v68, v68
	v_exp_f32_e32 v69, v69
	v_add_f32_e32 v70, 1.0, v70
	v_add_f32_e32 v71, 1.0, v71
	v_rcp_f32_e32 v70, v70
	v_add_f32_e32 v66, 1.0, v66
	v_rcp_f32_e32 v71, v71
	v_add_f32_e32 v67, 1.0, v67
	v_rcp_f32_e32 v66, v66
	v_rcp_f32_e32 v67, v67
	v_add_f32_e32 v72, 1.0, v72
	v_add_f32_e32 v73, 1.0, v73
	v_rcp_f32_e32 v72, v72
	v_add_f32_e32 v68, 1.0, v68
	v_rcp_f32_e32 v73, v73
	v_add_f32_e32 v69, 1.0, v69
	v_rcp_f32_e32 v68, v68
	v_rcp_f32_e32 v69, v69
	s_and_b64 vcc, exec, s[42:43]
	s_waitcnt vmcnt(1)
	v_lshlrev_b32_e32 v88, 16, v98
	v_and_b32_e32 v89, 0xffff0000, v98
	s_waitcnt vmcnt(0)
	v_lshlrev_b32_e32 v92, 16, v82
	v_and_b32_e32 v93, 0xffff0000, v82
	v_pk_fma_f32 v[70:71], v[70:71], v[88:89], v[92:93]
	v_lshlrev_b32_e32 v88, 16, v100
	v_and_b32_e32 v89, 0xffff0000, v100
	v_lshlrev_b32_e32 v92, 16, v84
	v_and_b32_e32 v93, 0xffff0000, v84
	v_pk_fma_f32 v[66:67], v[66:67], v[88:89], v[92:93]
	v_lshlrev_b32_e32 v88, 16, v99
	v_and_b32_e32 v89, 0xffff0000, v99
	v_lshlrev_b32_e32 v82, 16, v83
	v_and_b32_e32 v83, 0xffff0000, v83
	v_pk_fma_f32 v[72:73], v[72:73], v[88:89], v[82:83]
	v_lshlrev_b32_e32 v82, 16, v101
	v_and_b32_e32 v83, 0xffff0000, v101
	v_lshlrev_b32_e32 v84, 16, v85
	v_and_b32_e32 v85, 0xffff0000, v85
	v_pk_fma_f32 v[68:69], v[68:69], v[82:83], v[84:85]
	s_cbranch_vccnz .LBB0_1275
	global_store_dwordx4 v[86:87], v[70:73], off offset:512 sc0 sc1
	global_store_dwordx4 v[86:87], v[66:69], off offset:528 sc0 sc1
	s_cbranch_execnz .LBB0_1221
.LBB0_1220:
	v_cvt_pk_bf16_f32 v82, v70, v71
	v_cvt_pk_bf16_f32 v83, v72, v73
	v_cvt_pk_bf16_f32 v84, v66, v67
	v_cvt_pk_bf16_f32 v85, v68, v69
	global_store_dwordx4 v[90:91], v[82:85], off offset:256 sc0 sc1

.LBB0_1225:
	v_add_f32_e32 v66, v199, v200
	v_fmamk_f32 v66, v66, 0x3a800000, v243
	s_waitcnt lgkmcnt(0)
	v_rsq_f32_e32 v80, v66
	s_nop 0
	v_lshlrev_b64 v[66:67], 10, v[166:167]
	v_lshl_add_u64 v[78:79], v[66:67], 0, v[154:155]
	v_lshlrev_b64 v[66:67], 1, v[78:79]
	v_lshl_add_u64 v[74:75], s[20:21], 0, v[66:67]
	v_lshl_add_u64 v[76:77], s[22:23], 0, v[66:67]
	global_load_dwordx4 v[70:73], v[74:75], off
	global_load_dwordx4 v[66:69], v[76:77], off
	v_mul_f32_e32 v62, v62, v80
	v_mul_f32_e32 v63, v63, v80
	v_mul_f32_e32 v64, v64, v80
	v_mul_f32_e32 v65, v65, v80
	v_mul_f32_e32 v62, 0xbfb8aa3b, v62
	v_mul_f32_e32 v58, v58, v80
	v_mul_f32_e32 v63, 0xbfb8aa3b, v63
	v_mul_f32_e32 v59, v59, v80
	v_mul_f32_e32 v64, 0xbfb8aa3b, v64
	v_mul_f32_e32 v60, v60, v80
	v_mul_f32_e32 v65, 0xbfb8aa3b, v65
	v_mul_f32_e32 v61, v61, v80
	v_exp_f32_e32 v62, v62
	v_mul_f32_e32 v58, 0xbfb8aa3b, v58
	v_exp_f32_e32 v63, v63
	v_mul_f32_e32 v59, 0xbfb8aa3b, v59
	v_exp_f32_e32 v64, v64
	v_mul_f32_e32 v60, 0xbfb8aa3b, v60
	v_exp_f32_e32 v65, v65
	v_mul_f32_e32 v61, 0xbfb8aa3b, v61
	v_exp_f32_e32 v58, v58
	v_exp_f32_e32 v59, v59
	v_exp_f32_e32 v60, v60
	v_exp_f32_e32 v61, v61
	v_add_f32_e32 v62, 1.0, v62
	v_add_f32_e32 v63, 1.0, v63
	v_add_f32_e32 v64, 1.0, v64
	v_add_f32_e32 v65, 1.0, v65
	v_rcp_f32_e32 v62, v62
	v_add_f32_e32 v58, 1.0, v58
	v_rcp_f32_e32 v63, v63
	v_add_f32_e32 v59, 1.0, v59
	v_rcp_f32_e32 v64, v64
	v_add_f32_e32 v60, 1.0, v60
	v_rcp_f32_e32 v65, v65
	v_add_f32_e32 v61, 1.0, v61
	v_rcp_f32_e32 v58, v58
	v_rcp_f32_e32 v59, v59
	v_rcp_f32_e32 v60, v60
	v_rcp_f32_e32 v61, v61
	s_and_b64 vcc, exec, s[42:43]
	s_waitcnt vmcnt(1)
	v_lshlrev_b32_e32 v82, 16, v70
	v_and_b32_e32 v83, 0xffff0000, v70
	s_waitcnt vmcnt(0)
	v_lshlrev_b32_e32 v84, 16, v66
	v_and_b32_e32 v85, 0xffff0000, v66
	v_lshlrev_b32_e32 v70, 16, v71
	v_and_b32_e32 v71, 0xffff0000, v71
	v_lshlrev_b32_e32 v66, 16, v67
	v_and_b32_e32 v67, 0xffff0000, v67
	v_pk_fma_f32 v[62:63], v[62:63], v[82:83], v[84:85]
	v_lshlrev_b32_e32 v82, 16, v72
	v_and_b32_e32 v83, 0xffff0000, v72
	v_lshlrev_b32_e32 v84, 16, v68
	v_and_b32_e32 v85, 0xffff0000, v68
	v_pk_fma_f32 v[64:65], v[64:65], v[70:71], v[66:67]
	v_lshlrev_b32_e32 v66, 16, v73
	v_and_b32_e32 v67, 0xffff0000, v73
	v_lshlrev_b32_e32 v68, 16, v69
	v_and_b32_e32 v69, 0xffff0000, v69
	v_pk_fma_f32 v[58:59], v[58:59], v[82:83], v[84:85]
	v_pk_fma_f32 v[60:61], v[60:61], v[66:67], v[68:69]
	v_lshl_add_u64 v[70:71], v[78:79], 2, s[54:55]
	s_cbranch_vccnz .LBB0_1276
	global_store_dwordx4 v[70:71], v[62:65], off sc0 sc1
	global_store_dwordx4 v[70:71], v[58:61], off offset:16 sc0 sc1
	s_cbranch_execnz .LBB0_1228
.LBB0_1227:
	v_cvt_pk_bf16_f32 v66, v62, v63
	v_cvt_pk_bf16_f32 v67, v64, v65
	v_cvt_pk_bf16_f32 v68, v58, v59
	v_cvt_pk_bf16_f32 v69, v60, v61
	global_store_dwordx4 v[74:75], v[66:69], off sc0 sc1
.LBB0_1228:
	global_load_dwordx4 v[82:85], v[74:75], off offset:256
	s_nop 0
	global_load_dwordx4 v[66:69], v[76:77], off offset:256
	v_mul_f32_e32 v54, v54, v80
	v_mul_f32_e32 v55, v55, v80
	v_mul_f32_e32 v54, 0xbfb8aa3b, v54
	v_mul_f32_e32 v50, v50, v80
	v_mul_f32_e32 v55, 0xbfb8aa3b, v55
	v_mul_f32_e32 v51, v51, v80
	v_exp_f32_e32 v54, v54
	v_mul_f32_e32 v50, 0xbfb8aa3b, v50
	v_exp_f32_e32 v55, v55
	v_mul_f32_e32 v51, 0xbfb8aa3b, v51
	v_mul_f32_e32 v56, v56, v80
	v_mul_f32_e32 v57, v57, v80
	v_exp_f32_e32 v50, v50
	v_exp_f32_e32 v51, v51
	v_mul_f32_e32 v56, 0xbfb8aa3b, v56
	v_mul_f32_e32 v52, v52, v80
	v_mul_f32_e32 v57, 0xbfb8aa3b, v57
	v_mul_f32_e32 v53, v53, v80
	v_exp_f32_e32 v56, v56
	v_mul_f32_e32 v52, 0xbfb8aa3b, v52
	v_exp_f32_e32 v57, v57
	v_mul_f32_e32 v53, 0xbfb8aa3b, v53
	v_exp_f32_e32 v52, v52
	v_exp_f32_e32 v53, v53
	v_add_f32_e32 v54, 1.0, v54
	v_add_f32_e32 v55, 1.0, v55
	v_rcp_f32_e32 v54, v54
	v_add_f32_e32 v50, 1.0, v50
	v_rcp_f32_e32 v55, v55
	v_add_f32_e32 v51, 1.0, v51
	v_rcp_f32_e32 v50, v50
	v_rcp_f32_e32 v51, v51
	v_add_f32_e32 v56, 1.0, v56
	v_add_f32_e32 v57, 1.0, v57
	v_rcp_f32_e32 v56, v56
	v_add_f32_e32 v52, 1.0, v52
	v_rcp_f32_e32 v57, v57
	v_add_f32_e32 v53, 1.0, v53
	v_rcp_f32_e32 v52, v52
	v_rcp_f32_e32 v53, v53
	s_and_b64 vcc, exec, s[42:43]
	s_waitcnt vmcnt(1)
	v_lshlrev_b32_e32 v72, 16, v82
	v_and_b32_e32 v73, 0xffff0000, v82
	s_waitcnt vmcnt(0)
	v_lshlrev_b32_e32 v76, 16, v66
	v_and_b32_e32 v77, 0xffff0000, v66
	v_pk_fma_f32 v[54:55], v[54:55], v[72:73], v[76:77]
	v_lshlrev_b32_e32 v72, 16, v84
	v_and_b32_e32 v73, 0xffff0000, v84
	v_lshlrev_b32_e32 v76, 16, v68
	v_and_b32_e32 v77, 0xffff0000, v68
	v_pk_fma_f32 v[50:51], v[50:51], v[72:73], v[76:77]
	v_lshlrev_b32_e32 v72, 16, v83
	v_and_b32_e32 v73, 0xffff0000, v83
	v_lshlrev_b32_e32 v66, 16, v67
	v_and_b32_e32 v67, 0xffff0000, v67
	v_pk_fma_f32 v[56:57], v[56:57], v[72:73], v[66:67]
	v_lshlrev_b32_e32 v66, 16, v85
	v_and_b32_e32 v67, 0xffff0000, v85
	v_lshlrev_b32_e32 v68, 16, v69
	v_and_b32_e32 v69, 0xffff0000, v69
	v_pk_fma_f32 v[52:53], v[52:53], v[66:67], v[68:69]
	s_cbranch_vccnz .LBB0_1277
	global_store_dwordx4 v[70:71], v[54:57], off offset:512 sc0 sc1
	global_store_dwordx4 v[70:71], v[50:53], off offset:528 sc0 sc1
	s_cbranch_execnz .LBB0_1231
.LBB0_1230:
	v_cvt_pk_bf16_f32 v66, v54, v55
	v_cvt_pk_bf16_f32 v67, v56, v57
	v_cvt_pk_bf16_f32 v68, v50, v51
	v_cvt_pk_bf16_f32 v69, v52, v53
	global_store_dwordx4 v[74:75], v[66:69], off offset:256 sc0 sc1

.LBB0_1235:
	v_add_f32_e32 v50, v197, v198
	v_fmamk_f32 v50, v50, 0x3a800000, v243
	s_waitcnt lgkmcnt(0)
	v_rsq_f32_e32 v64, v50
	s_nop 0
	v_lshlrev_b64 v[50:51], 10, v[162:163]
	v_lshl_add_u64 v[62:63], v[50:51], 0, v[154:155]
	v_lshlrev_b64 v[50:51], 1, v[62:63]
	v_lshl_add_u64 v[58:59], s[20:21], 0, v[50:51]
	v_lshl_add_u64 v[60:61], s[22:23], 0, v[50:51]
	global_load_dwordx4 v[54:57], v[58:59], off
	global_load_dwordx4 v[50:53], v[60:61], off
	v_mul_f32_e32 v46, v46, v64
	v_mul_f32_e32 v47, v47, v64
	v_mul_f32_e32 v48, v48, v64
	v_mul_f32_e32 v49, v49, v64
	v_mul_f32_e32 v46, 0xbfb8aa3b, v46
	v_mul_f32_e32 v42, v42, v64
	v_mul_f32_e32 v47, 0xbfb8aa3b, v47
	v_mul_f32_e32 v43, v43, v64
	v_mul_f32_e32 v48, 0xbfb8aa3b, v48
	v_mul_f32_e32 v44, v44, v64
	v_mul_f32_e32 v49, 0xbfb8aa3b, v49
	v_mul_f32_e32 v45, v45, v64
	v_exp_f32_e32 v46, v46
	v_mul_f32_e32 v42, 0xbfb8aa3b, v42
	v_exp_f32_e32 v47, v47
	v_mul_f32_e32 v43, 0xbfb8aa3b, v43
	v_exp_f32_e32 v48, v48
	v_mul_f32_e32 v44, 0xbfb8aa3b, v44
	v_exp_f32_e32 v49, v49
	v_mul_f32_e32 v45, 0xbfb8aa3b, v45
	v_exp_f32_e32 v42, v42
	v_exp_f32_e32 v43, v43
	v_exp_f32_e32 v44, v44
	v_exp_f32_e32 v45, v45
	v_add_f32_e32 v46, 1.0, v46
	v_add_f32_e32 v47, 1.0, v47
	v_add_f32_e32 v48, 1.0, v48
	v_add_f32_e32 v49, 1.0, v49
	v_rcp_f32_e32 v46, v46
	v_add_f32_e32 v42, 1.0, v42
	v_rcp_f32_e32 v47, v47
	v_add_f32_e32 v43, 1.0, v43
	v_rcp_f32_e32 v48, v48
	v_add_f32_e32 v44, 1.0, v44
	v_rcp_f32_e32 v49, v49
	v_add_f32_e32 v45, 1.0, v45
	v_rcp_f32_e32 v42, v42
	v_rcp_f32_e32 v43, v43
	v_rcp_f32_e32 v44, v44
	v_rcp_f32_e32 v45, v45
	s_and_b64 vcc, exec, s[42:43]
	s_waitcnt vmcnt(1)
	v_lshlrev_b32_e32 v66, 16, v54
	v_and_b32_e32 v67, 0xffff0000, v54
	s_waitcnt vmcnt(0)
	v_lshlrev_b32_e32 v68, 16, v50
	v_and_b32_e32 v69, 0xffff0000, v50
	v_lshlrev_b32_e32 v54, 16, v55
	v_and_b32_e32 v55, 0xffff0000, v55
	v_lshlrev_b32_e32 v50, 16, v51
	v_and_b32_e32 v51, 0xffff0000, v51
	v_pk_fma_f32 v[46:47], v[46:47], v[66:67], v[68:69]
	v_lshlrev_b32_e32 v66, 16, v56
	v_and_b32_e32 v67, 0xffff0000, v56
	v_lshlrev_b32_e32 v68, 16, v52
	v_and_b32_e32 v69, 0xffff0000, v52
	v_pk_fma_f32 v[48:49], v[48:49], v[54:55], v[50:51]
	v_lshlrev_b32_e32 v50, 16, v57
	v_and_b32_e32 v51, 0xffff0000, v57
	v_lshlrev_b32_e32 v52, 16, v53
	v_and_b32_e32 v53, 0xffff0000, v53
	v_pk_fma_f32 v[42:43], v[42:43], v[66:67], v[68:69]
	v_pk_fma_f32 v[44:45], v[44:45], v[50:51], v[52:53]
	v_lshl_add_u64 v[54:55], v[62:63], 2, s[54:55]
	s_cbranch_vccnz .LBB0_1278
	global_store_dwordx4 v[54:55], v[46:49], off sc0 sc1
	global_store_dwordx4 v[54:55], v[42:45], off offset:16 sc0 sc1
	s_cbranch_execnz .LBB0_1238
.LBB0_1237:
	v_cvt_pk_bf16_f32 v50, v46, v47
	v_cvt_pk_bf16_f32 v51, v48, v49
	v_cvt_pk_bf16_f32 v52, v42, v43
	v_cvt_pk_bf16_f32 v53, v44, v45
	global_store_dwordx4 v[58:59], v[50:53], off sc0 sc1
.LBB0_1238:
	global_load_dwordx4 v[66:69], v[58:59], off offset:256
	s_nop 0
	global_load_dwordx4 v[50:53], v[60:61], off offset:256
	v_mul_f32_e32 v38, v38, v64
	v_mul_f32_e32 v39, v39, v64
	v_mul_f32_e32 v38, 0xbfb8aa3b, v38
	v_mul_f32_e32 v34, v34, v64
	v_mul_f32_e32 v39, 0xbfb8aa3b, v39
	v_mul_f32_e32 v35, v35, v64
	v_exp_f32_e32 v38, v38
	v_mul_f32_e32 v34, 0xbfb8aa3b, v34
	v_exp_f32_e32 v39, v39
	v_mul_f32_e32 v35, 0xbfb8aa3b, v35
	v_mul_f32_e32 v40, v40, v64
	v_mul_f32_e32 v41, v41, v64
	v_exp_f32_e32 v34, v34
	v_exp_f32_e32 v35, v35
	v_mul_f32_e32 v40, 0xbfb8aa3b, v40
	v_mul_f32_e32 v36, v36, v64
	v_mul_f32_e32 v41, 0xbfb8aa3b, v41
	v_mul_f32_e32 v37, v37, v64
	v_exp_f32_e32 v40, v40
	v_mul_f32_e32 v36, 0xbfb8aa3b, v36
	v_exp_f32_e32 v41, v41
	v_mul_f32_e32 v37, 0xbfb8aa3b, v37
	v_exp_f32_e32 v36, v36
	v_exp_f32_e32 v37, v37
	v_add_f32_e32 v38, 1.0, v38
	v_add_f32_e32 v39, 1.0, v39
	v_rcp_f32_e32 v38, v38
	v_add_f32_e32 v34, 1.0, v34
	v_rcp_f32_e32 v39, v39
	v_add_f32_e32 v35, 1.0, v35
	v_rcp_f32_e32 v34, v34
	v_rcp_f32_e32 v35, v35
	v_add_f32_e32 v40, 1.0, v40
	v_add_f32_e32 v41, 1.0, v41
	v_rcp_f32_e32 v40, v40
	v_add_f32_e32 v36, 1.0, v36
	v_rcp_f32_e32 v41, v41
	v_add_f32_e32 v37, 1.0, v37
	v_rcp_f32_e32 v36, v36
	v_rcp_f32_e32 v37, v37
	s_and_b64 vcc, exec, s[42:43]
	s_waitcnt vmcnt(1)
	v_lshlrev_b32_e32 v56, 16, v66
	v_and_b32_e32 v57, 0xffff0000, v66
	s_waitcnt vmcnt(0)
	v_lshlrev_b32_e32 v60, 16, v50
	v_and_b32_e32 v61, 0xffff0000, v50
	v_pk_fma_f32 v[38:39], v[38:39], v[56:57], v[60:61]
	v_lshlrev_b32_e32 v56, 16, v68
	v_and_b32_e32 v57, 0xffff0000, v68
	v_lshlrev_b32_e32 v60, 16, v52
	v_and_b32_e32 v61, 0xffff0000, v52
	v_pk_fma_f32 v[34:35], v[34:35], v[56:57], v[60:61]
	v_lshlrev_b32_e32 v56, 16, v67
	v_and_b32_e32 v57, 0xffff0000, v67
	v_lshlrev_b32_e32 v50, 16, v51
	v_and_b32_e32 v51, 0xffff0000, v51
	v_pk_fma_f32 v[40:41], v[40:41], v[56:57], v[50:51]
	v_lshlrev_b32_e32 v50, 16, v69
	v_and_b32_e32 v51, 0xffff0000, v69
	v_lshlrev_b32_e32 v52, 16, v53
	v_and_b32_e32 v53, 0xffff0000, v53
	v_pk_fma_f32 v[36:37], v[36:37], v[50:51], v[52:53]
	s_cbranch_vccnz .LBB0_1279
	global_store_dwordx4 v[54:55], v[38:41], off offset:512 sc0 sc1
	global_store_dwordx4 v[54:55], v[34:37], off offset:528 sc0 sc1
	s_cbranch_execnz .LBB0_1241
.LBB0_1240:
	v_cvt_pk_bf16_f32 v50, v38, v39
	v_cvt_pk_bf16_f32 v51, v40, v41
	v_cvt_pk_bf16_f32 v52, v34, v35
	v_cvt_pk_bf16_f32 v53, v36, v37
	global_store_dwordx4 v[58:59], v[50:53], off offset:256 sc0 sc1

.LBB0_1245:
	v_add_f32_e32 v34, v195, v196
	v_fmamk_f32 v34, v34, 0x3a800000, v243
	s_waitcnt lgkmcnt(0)
	v_rsq_f32_e32 v48, v34
	s_nop 0
	v_lshlrev_b64 v[34:35], 10, v[158:159]
	v_lshl_add_u64 v[46:47], v[34:35], 0, v[154:155]
	v_lshlrev_b64 v[34:35], 1, v[46:47]
	v_lshl_add_u64 v[42:43], s[20:21], 0, v[34:35]
	v_lshl_add_u64 v[44:45], s[22:23], 0, v[34:35]
	global_load_dwordx4 v[38:41], v[42:43], off
	global_load_dwordx4 v[34:37], v[44:45], off
	v_mul_f32_e32 v30, v30, v48
	v_mul_f32_e32 v31, v31, v48
	v_mul_f32_e32 v32, v32, v48
	v_mul_f32_e32 v33, v33, v48
	v_mul_f32_e32 v30, 0xbfb8aa3b, v30
	v_mul_f32_e32 v26, v26, v48
	v_mul_f32_e32 v31, 0xbfb8aa3b, v31
	v_mul_f32_e32 v27, v27, v48
	v_mul_f32_e32 v32, 0xbfb8aa3b, v32
	v_mul_f32_e32 v28, v28, v48
	v_mul_f32_e32 v33, 0xbfb8aa3b, v33
	v_mul_f32_e32 v29, v29, v48
	v_exp_f32_e32 v30, v30
	v_mul_f32_e32 v26, 0xbfb8aa3b, v26
	v_exp_f32_e32 v31, v31
	v_mul_f32_e32 v27, 0xbfb8aa3b, v27
	v_exp_f32_e32 v32, v32
	v_mul_f32_e32 v28, 0xbfb8aa3b, v28
	v_exp_f32_e32 v33, v33
	v_mul_f32_e32 v29, 0xbfb8aa3b, v29
	v_exp_f32_e32 v26, v26
	v_exp_f32_e32 v27, v27
	v_exp_f32_e32 v28, v28
	v_exp_f32_e32 v29, v29
	v_add_f32_e32 v30, 1.0, v30
	v_add_f32_e32 v31, 1.0, v31
	v_add_f32_e32 v32, 1.0, v32
	v_add_f32_e32 v33, 1.0, v33
	v_rcp_f32_e32 v30, v30
	v_add_f32_e32 v26, 1.0, v26
	v_rcp_f32_e32 v31, v31
	v_add_f32_e32 v27, 1.0, v27
	v_rcp_f32_e32 v32, v32
	v_add_f32_e32 v28, 1.0, v28
	v_rcp_f32_e32 v33, v33
	v_add_f32_e32 v29, 1.0, v29
	v_rcp_f32_e32 v26, v26
	v_rcp_f32_e32 v27, v27
	v_rcp_f32_e32 v28, v28
	v_rcp_f32_e32 v29, v29
	s_and_b64 vcc, exec, s[42:43]
	s_waitcnt vmcnt(1)
	v_lshlrev_b32_e32 v50, 16, v38
	v_and_b32_e32 v51, 0xffff0000, v38
	s_waitcnt vmcnt(0)
	v_lshlrev_b32_e32 v52, 16, v34
	v_and_b32_e32 v53, 0xffff0000, v34
	v_lshlrev_b32_e32 v38, 16, v39
	v_and_b32_e32 v39, 0xffff0000, v39
	v_lshlrev_b32_e32 v34, 16, v35
	v_and_b32_e32 v35, 0xffff0000, v35
	v_pk_fma_f32 v[30:31], v[30:31], v[50:51], v[52:53]
	v_lshlrev_b32_e32 v50, 16, v40
	v_and_b32_e32 v51, 0xffff0000, v40
	v_lshlrev_b32_e32 v52, 16, v36
	v_and_b32_e32 v53, 0xffff0000, v36
	v_pk_fma_f32 v[32:33], v[32:33], v[38:39], v[34:35]
	v_lshlrev_b32_e32 v34, 16, v41
	v_and_b32_e32 v35, 0xffff0000, v41
	v_lshlrev_b32_e32 v36, 16, v37
	v_and_b32_e32 v37, 0xffff0000, v37
	v_pk_fma_f32 v[26:27], v[26:27], v[50:51], v[52:53]
	v_pk_fma_f32 v[28:29], v[28:29], v[34:35], v[36:37]
	v_lshl_add_u64 v[38:39], v[46:47], 2, s[54:55]
	s_cbranch_vccnz .LBB0_1280
	global_store_dwordx4 v[38:39], v[30:33], off sc0 sc1
	global_store_dwordx4 v[38:39], v[26:29], off offset:16 sc0 sc1
	s_cbranch_execnz .LBB0_1248
.LBB0_1247:
	v_cvt_pk_bf16_f32 v34, v30, v31
	v_cvt_pk_bf16_f32 v35, v32, v33
	v_cvt_pk_bf16_f32 v36, v26, v27
	v_cvt_pk_bf16_f32 v37, v28, v29
	global_store_dwordx4 v[42:43], v[34:37], off sc0 sc1
.LBB0_1248:
	global_load_dwordx4 v[50:53], v[42:43], off offset:256
	s_nop 0
	global_load_dwordx4 v[34:37], v[44:45], off offset:256
	v_mul_f32_e32 v22, v22, v48
	v_mul_f32_e32 v23, v23, v48
	v_mul_f32_e32 v22, 0xbfb8aa3b, v22
	v_mul_f32_e32 v18, v18, v48
	v_mul_f32_e32 v23, 0xbfb8aa3b, v23
	v_mul_f32_e32 v19, v19, v48
	v_exp_f32_e32 v22, v22
	v_mul_f32_e32 v18, 0xbfb8aa3b, v18
	v_exp_f32_e32 v23, v23
	v_mul_f32_e32 v19, 0xbfb8aa3b, v19
	v_mul_f32_e32 v24, v24, v48
	v_mul_f32_e32 v25, v25, v48
	v_exp_f32_e32 v18, v18
	v_exp_f32_e32 v19, v19
	v_mul_f32_e32 v24, 0xbfb8aa3b, v24
	v_mul_f32_e32 v20, v20, v48
	v_mul_f32_e32 v25, 0xbfb8aa3b, v25
	v_mul_f32_e32 v21, v21, v48
	v_exp_f32_e32 v24, v24
	v_mul_f32_e32 v20, 0xbfb8aa3b, v20
	v_exp_f32_e32 v25, v25
	v_mul_f32_e32 v21, 0xbfb8aa3b, v21
	v_exp_f32_e32 v20, v20
	v_exp_f32_e32 v21, v21
	v_add_f32_e32 v22, 1.0, v22
	v_add_f32_e32 v23, 1.0, v23
	v_rcp_f32_e32 v22, v22
	v_add_f32_e32 v18, 1.0, v18
	v_rcp_f32_e32 v23, v23
	v_add_f32_e32 v19, 1.0, v19
	v_rcp_f32_e32 v18, v18
	v_rcp_f32_e32 v19, v19
	v_add_f32_e32 v24, 1.0, v24
	v_add_f32_e32 v25, 1.0, v25
	v_rcp_f32_e32 v24, v24
	v_add_f32_e32 v20, 1.0, v20
	v_rcp_f32_e32 v25, v25
	v_add_f32_e32 v21, 1.0, v21
	v_rcp_f32_e32 v20, v20
	v_rcp_f32_e32 v21, v21
	s_and_b64 vcc, exec, s[42:43]
	s_waitcnt vmcnt(1)
	v_lshlrev_b32_e32 v40, 16, v50
	v_and_b32_e32 v41, 0xffff0000, v50
	s_waitcnt vmcnt(0)
	v_lshlrev_b32_e32 v44, 16, v34
	v_and_b32_e32 v45, 0xffff0000, v34
	v_pk_fma_f32 v[22:23], v[22:23], v[40:41], v[44:45]
	v_lshlrev_b32_e32 v40, 16, v52
	v_and_b32_e32 v41, 0xffff0000, v52
	v_lshlrev_b32_e32 v44, 16, v36
	v_and_b32_e32 v45, 0xffff0000, v36
	v_pk_fma_f32 v[18:19], v[18:19], v[40:41], v[44:45]
	v_lshlrev_b32_e32 v40, 16, v51
	v_and_b32_e32 v41, 0xffff0000, v51
	v_lshlrev_b32_e32 v34, 16, v35
	v_and_b32_e32 v35, 0xffff0000, v35
	v_pk_fma_f32 v[24:25], v[24:25], v[40:41], v[34:35]
	v_lshlrev_b32_e32 v34, 16, v53
	v_and_b32_e32 v35, 0xffff0000, v53
	v_lshlrev_b32_e32 v36, 16, v37
	v_and_b32_e32 v37, 0xffff0000, v37
	v_pk_fma_f32 v[20:21], v[20:21], v[34:35], v[36:37]
	s_cbranch_vccnz .LBB0_1281
	global_store_dwordx4 v[38:39], v[22:25], off offset:512 sc0 sc1
	global_store_dwordx4 v[38:39], v[18:21], off offset:528 sc0 sc1
	s_cbranch_execnz .LBB0_1251
.LBB0_1250:
	v_cvt_pk_bf16_f32 v34, v22, v23
	v_cvt_pk_bf16_f32 v35, v24, v25
	v_cvt_pk_bf16_f32 v36, v18, v19
	v_cvt_pk_bf16_f32 v37, v20, v21
	global_store_dwordx4 v[42:43], v[34:37], off offset:256 sc0 sc1

.LBB0_1255:
	v_add_f32_e32 v18, v193, v194
	v_fmamk_f32 v18, v18, 0x3a800000, v243
	s_waitcnt lgkmcnt(0)
	v_rsq_f32_e32 v32, v18
	s_nop 0
	v_lshlrev_b64 v[18:19], 10, v[152:153]
	v_lshl_add_u64 v[30:31], v[18:19], 0, v[154:155]
	v_lshlrev_b64 v[18:19], 1, v[30:31]
	v_lshl_add_u64 v[26:27], s[20:21], 0, v[18:19]
	v_lshl_add_u64 v[28:29], s[22:23], 0, v[18:19]
	global_load_dwordx4 v[22:25], v[26:27], off
	global_load_dwordx4 v[18:21], v[28:29], off
	v_mul_f32_e32 v14, v14, v32
	v_mul_f32_e32 v15, v15, v32
	v_mul_f32_e32 v16, v16, v32
	v_mul_f32_e32 v17, v17, v32
	v_mul_f32_e32 v14, 0xbfb8aa3b, v14
	v_mul_f32_e32 v10, v10, v32
	v_mul_f32_e32 v15, 0xbfb8aa3b, v15
	v_mul_f32_e32 v11, v11, v32
	v_mul_f32_e32 v16, 0xbfb8aa3b, v16
	v_mul_f32_e32 v12, v12, v32
	v_mul_f32_e32 v17, 0xbfb8aa3b, v17
	v_mul_f32_e32 v13, v13, v32
	v_exp_f32_e32 v14, v14
	v_mul_f32_e32 v10, 0xbfb8aa3b, v10
	v_exp_f32_e32 v15, v15
	v_mul_f32_e32 v11, 0xbfb8aa3b, v11
	v_exp_f32_e32 v16, v16
	v_mul_f32_e32 v12, 0xbfb8aa3b, v12
	v_exp_f32_e32 v17, v17
	v_mul_f32_e32 v13, 0xbfb8aa3b, v13
	v_exp_f32_e32 v10, v10
	v_exp_f32_e32 v11, v11
	v_exp_f32_e32 v12, v12
	v_exp_f32_e32 v13, v13
	v_add_f32_e32 v14, 1.0, v14
	v_add_f32_e32 v15, 1.0, v15
	v_add_f32_e32 v16, 1.0, v16
	v_add_f32_e32 v17, 1.0, v17
	v_rcp_f32_e32 v14, v14
	v_add_f32_e32 v10, 1.0, v10
	v_rcp_f32_e32 v15, v15
	v_add_f32_e32 v11, 1.0, v11
	v_rcp_f32_e32 v16, v16
	v_add_f32_e32 v12, 1.0, v12
	v_rcp_f32_e32 v17, v17
	v_add_f32_e32 v13, 1.0, v13
	v_rcp_f32_e32 v10, v10
	v_rcp_f32_e32 v11, v11
	v_rcp_f32_e32 v12, v12
	v_rcp_f32_e32 v13, v13
	s_and_b64 vcc, exec, s[42:43]
	s_waitcnt vmcnt(1)
	v_lshlrev_b32_e32 v34, 16, v22
	v_and_b32_e32 v35, 0xffff0000, v22
	s_waitcnt vmcnt(0)
	v_lshlrev_b32_e32 v36, 16, v18
	v_and_b32_e32 v37, 0xffff0000, v18
	v_lshlrev_b32_e32 v22, 16, v23
	v_and_b32_e32 v23, 0xffff0000, v23
	v_lshlrev_b32_e32 v18, 16, v19
	v_and_b32_e32 v19, 0xffff0000, v19
	v_pk_fma_f32 v[14:15], v[14:15], v[34:35], v[36:37]
	v_lshlrev_b32_e32 v34, 16, v24
	v_and_b32_e32 v35, 0xffff0000, v24
	v_lshlrev_b32_e32 v36, 16, v20
	v_and_b32_e32 v37, 0xffff0000, v20
	v_pk_fma_f32 v[16:17], v[16:17], v[22:23], v[18:19]
	v_lshlrev_b32_e32 v18, 16, v25
	v_and_b32_e32 v19, 0xffff0000, v25
	v_lshlrev_b32_e32 v20, 16, v21
	v_and_b32_e32 v21, 0xffff0000, v21
	v_pk_fma_f32 v[10:11], v[10:11], v[34:35], v[36:37]
	v_pk_fma_f32 v[12:13], v[12:13], v[18:19], v[20:21]
	v_lshl_add_u64 v[22:23], v[30:31], 2, s[54:55]
	s_cbranch_vccnz .LBB0_1282
	global_store_dwordx4 v[22:23], v[14:17], off sc0 sc1
	global_store_dwordx4 v[22:23], v[10:13], off offset:16 sc0 sc1
	s_cbranch_execnz .LBB0_1258
.LBB0_1257:
	v_cvt_pk_bf16_f32 v18, v14, v15
	v_cvt_pk_bf16_f32 v19, v16, v17
	v_cvt_pk_bf16_f32 v20, v10, v11
	v_cvt_pk_bf16_f32 v21, v12, v13
	global_store_dwordx4 v[26:27], v[18:21], off sc0 sc1
.LBB0_1258:
	global_load_dwordx4 v[34:37], v[26:27], off offset:256
	s_nop 0
	global_load_dwordx4 v[18:21], v[28:29], off offset:256
	v_mul_f32_e32 v6, v6, v32
	v_mul_f32_e32 v7, v7, v32
	v_mul_f32_e32 v6, 0xbfb8aa3b, v6
	v_mul_f32_e32 v2, v2, v32
	v_mul_f32_e32 v7, 0xbfb8aa3b, v7
	v_mul_f32_e32 v3, v3, v32
	v_exp_f32_e32 v6, v6
	v_mul_f32_e32 v2, 0xbfb8aa3b, v2
	v_exp_f32_e32 v7, v7
	v_mul_f32_e32 v3, 0xbfb8aa3b, v3
	v_mul_f32_e32 v8, v8, v32
	v_mul_f32_e32 v9, v9, v32
	v_exp_f32_e32 v2, v2
	v_exp_f32_e32 v3, v3
	v_mul_f32_e32 v8, 0xbfb8aa3b, v8
	v_mul_f32_e32 v4, v4, v32
	v_mul_f32_e32 v9, 0xbfb8aa3b, v9
	v_mul_f32_e32 v5, v5, v32
	v_exp_f32_e32 v8, v8
	v_mul_f32_e32 v4, 0xbfb8aa3b, v4
	v_exp_f32_e32 v9, v9
	v_mul_f32_e32 v5, 0xbfb8aa3b, v5
	v_exp_f32_e32 v4, v4
	v_exp_f32_e32 v5, v5
	v_add_f32_e32 v6, 1.0, v6
	v_add_f32_e32 v7, 1.0, v7
	v_rcp_f32_e32 v6, v6
	v_add_f32_e32 v2, 1.0, v2
	v_rcp_f32_e32 v7, v7
	v_add_f32_e32 v3, 1.0, v3
	v_rcp_f32_e32 v2, v2
	v_rcp_f32_e32 v3, v3
	v_add_f32_e32 v8, 1.0, v8
	v_add_f32_e32 v9, 1.0, v9
	v_rcp_f32_e32 v8, v8
	v_add_f32_e32 v4, 1.0, v4
	v_rcp_f32_e32 v9, v9
	v_add_f32_e32 v5, 1.0, v5
	v_rcp_f32_e32 v4, v4
	v_rcp_f32_e32 v5, v5
	s_and_b64 vcc, exec, s[42:43]
	s_waitcnt vmcnt(1)
	v_lshlrev_b32_e32 v24, 16, v34
	v_and_b32_e32 v25, 0xffff0000, v34
	s_waitcnt vmcnt(0)
	v_lshlrev_b32_e32 v28, 16, v18
	v_and_b32_e32 v29, 0xffff0000, v18
	v_pk_fma_f32 v[6:7], v[6:7], v[24:25], v[28:29]
	v_lshlrev_b32_e32 v24, 16, v36
	v_and_b32_e32 v25, 0xffff0000, v36
	v_lshlrev_b32_e32 v28, 16, v20
	v_and_b32_e32 v29, 0xffff0000, v20
	v_pk_fma_f32 v[2:3], v[2:3], v[24:25], v[28:29]
	v_lshlrev_b32_e32 v24, 16, v35
	v_and_b32_e32 v25, 0xffff0000, v35
	v_lshlrev_b32_e32 v18, 16, v19
	v_and_b32_e32 v19, 0xffff0000, v19
	v_pk_fma_f32 v[8:9], v[8:9], v[24:25], v[18:19]
	v_lshlrev_b32_e32 v18, 16, v37
	v_and_b32_e32 v19, 0xffff0000, v37
	v_lshlrev_b32_e32 v20, 16, v21
	v_and_b32_e32 v21, 0xffff0000, v21
	v_pk_fma_f32 v[4:5], v[4:5], v[18:19], v[20:21]
	s_cbranch_vccnz .LBB0_1283
	global_store_dwordx4 v[22:23], v[6:9], off offset:512 sc0 sc1
	global_store_dwordx4 v[22:23], v[2:5], off offset:528 sc0 sc1
	s_cbranch_execnz .LBB0_1261
.LBB0_1260:
	v_cvt_pk_bf16_f32 v18, v6, v7
	v_cvt_pk_bf16_f32 v19, v8, v9
	v_cvt_pk_bf16_f32 v20, v2, v3
	v_cvt_pk_bf16_f32 v21, v4, v5
	global_store_dwordx4 v[26:27], v[18:21], off offset:256 sc0 sc1
